# GEMM main loops: s_setprio 0/1 flip between the two 16-MFMA groups of each MMA segment removed
# speedup vs baseline: 1.0053x; 1.0053x over previous
; #define PG8_STAGE(bufoff, gbase, voff) do { _Pragma("unroll") for (int _i = 0; _i < 2; ++_i) \
;         __builtin_amdgcn_global_load_lds((const unsigned*)((const char*)(gbase) + (voff)[_i]), (PG8_LAS unsigned*)(lds + (bufoff) + ldsw + _i * 8192), 16, 0, 0); } while (0)
; #define PG8_LDA(dst, b, h) do { _Pragma("unroll") for (int m = 0; m < 4; ++m) _Pragma("unroll") for (int k = 0; k < 2; ++k) dst[m][k] = *(const PG8_LAS bf16x8*)(lds + PG8_SA(b, h) + aoff + m * 2048 + k * 1024); } while (0)
; #define PG8_LDB(dst, b, h) do { _Pragma("unroll") for (int n = 0; n < 2; ++n) _Pragma("unroll") for (int k = 0; k < 2; ++k) dst[n][k] = *(const PG8_LAS bf16x8*)(lds + PG8_SB(b, h) + boff + n * 2048 + k * 1024); } while (0)
; #define PG8_MMA(ai, bj, At, Bt) do { __builtin_amdgcn_s_setprio(1); _Pragma("unroll") for (int m = 0; m < 4; ++m) _Pragma("unroll") for (int n = 0; n < 2; ++n) _Pragma("unroll") for (int k = 0; k < 2; ++k) \
;         acc[ai][bj][m][n] = __builtin_amdgcn_mfma_f32_16x16x32_bf16(Bt[n][k], At[m][k], acc[ai][bj][m][n], 0, 0, 0); __builtin_amdgcn_s_setprio(0); } while (0)
; template <class Epi, class Sched, bool ALIGN_EPI = false, bool SP2 = false>
; __device__ __forceinline__ void gemm_phase(PG8_LAS unsigned char* lds, const Gemm g, const Sched& S, const Epi& E, int tid_in) {
;     ...
;             const bool last = (t == nt - 2);
;             if constexpr (mid_hook<Epi>::value) { if (t == Epi::H1 || t == Epi::H2) E.mid(acc, cur, wr, wc, fr, fq, t == Epi::H2); }
;             const char* a1 = cA + (size_t)(t + 1) * kstep + (t >= jt ? jb : 0);
;             const char* a2 = last ? nA : cA + (size_t)(t + 2) * kstep + (t + 2 >= jt ? jb : 0); const char* b2 = last ? nB : cB + (size_t)(t + 2) * kstep;
;             const char* a3 = a2 + kstep; const char* b3 = b2 + kstep;
;             if (last && has_next) S.a_ready(nxt);
;             if constexpr (SP2) {
;             PG8_LDB(B0, 0, 0); PG8_LDB(B1, 0, 1); PG8_SCHED; PG8_LDA(At, 0, 0); PG8_STAGE(PG8_SA(1, 1), a1 + hsA, voffA);
;             PG8_WAIT_V(8); PG8_WAIT_L(0); PG8_BAR; PG8_MMA(0, 0, At, B0); PG8_MMA(0, 1, At, B1); PG8_BAR; PG8_SCHED;
;             PG8_LDA(At, 0, 1); PG8_STAGE(PG8_SB(0, 0), b2, voffB); PG8_STAGE(PG8_SB(0, 1), b2 + hsB, voffB); PG8_STAGE(PG8_SA(0, 0), a2, voffA);
;             PG8_WAIT_V(8); PG8_WAIT_L(0); PG8_BAR; PG8_MMA(1, 0, At, B0); PG8_MMA(1, 1, At, B1); PG8_BAR; PG8_SCHED;
.LBB0_244:
	s_add_i32 s24, s53, -2
	s_cmp_ge_i32 s24, s28
	s_cselect_b32 s54, s29, 0
	s_cselect_b32 s55, s44, 0
	s_cmp_ge_i32 s53, s28
	s_cselect_b32 s25, s29, 0
	s_cselect_b32 s24, s44, 0
	s_add_u32 s25, s22, s25
	s_addc_u32 s24, s23, s24
	s_add_u32 s58, s25, 0x80
	s_addc_u32 s24, s24, 0
	s_add_i32 s60, 0, 0x10000
	s_cmp_eq_u32 s43, s53
	s_cselect_b32 s25, s5, s24
	s_cselect_b32 s24, s4, s58
	s_cselect_b32 s59, s21, s52
	s_cselect_b32 s58, s20, s51
	s_add_i32 s61, 0, 0x14000
	v_add_u32_e32 v160, s60, v142
	v_add_u32_e32 v176, s61, v142
	ds_read_b128 v[148:151], v160
	ds_read_b128 v[152:155], v160 offset:1024
	ds_read_b128 v[156:159], v160 offset:2048
	ds_read_b128 v[160:163], v160 offset:3072
	ds_read_b128 v[164:167], v176
	ds_read_b128 v[168:171], v176 offset:1024
	ds_read_b128 v[172:175], v176 offset:2048
	ds_read_b128 v[176:179], v176 offset:3072
	v_lshl_add_u64 v[230:231], s[22:23], 0, v[140:141]
	v_lshl_add_u64 v[230:231], v[230:231], 0, s[54:55]
	s_add_i32 m0, s37, 0xc000
	ds_read_b128 v[180:183], v147
	ds_read_b128 v[184:187], v147 offset:1024
	ds_read_b128 v[188:191], v147 offset:2048
	ds_read_b128 v[204:207], v147 offset:3072
	ds_read_b128 v[208:211], v147 offset:4096
	ds_read_b128 v[212:215], v147 offset:5120
	ds_read_b128 v[216:219], v147 offset:6144
	ds_read_b128 v[220:223], v147 offset:7168
	global_load_lds_dwordx4 v[230:231], off
	v_lshl_add_u64 v[230:231], s[22:23], 0, v[138:139]
	v_lshl_add_u64 v[230:231], v[230:231], 0, s[54:55]
	s_add_i32 m0, s37, 0xe000
	s_nop 0
	global_load_lds_dwordx4 v[230:231], off
	s_waitcnt vmcnt(8)
	s_waitcnt lgkmcnt(0)
	s_barrier
	s_setprio 1
	s_waitcnt lgkmcnt(0)
	v_mfma_f32_16x16x32_bf16 v[124:127], v[148:151], v[180:183], v[124:127]
	v_mfma_f32_16x16x32_bf16 v[120:123], v[156:159], v[180:183], v[120:123]
	v_mfma_f32_16x16x32_bf16 v[112:115], v[148:151], v[188:191], v[112:115]
	v_mfma_f32_16x16x32_bf16 v[104:107], v[156:159], v[188:191], v[104:107]
	v_mfma_f32_16x16x32_bf16 v[96:99], v[148:151], v[208:211], v[96:99]
	v_mfma_f32_16x16x32_bf16 v[88:91], v[156:159], v[208:211], v[88:91]
	v_mfma_f32_16x16x32_bf16 v[80:83], v[148:151], v[216:219], v[80:83]
	v_mfma_f32_16x16x32_bf16 v[72:75], v[156:159], v[216:219], v[72:75]
	v_mfma_f32_16x16x32_bf16 v[124:127], v[152:155], v[184:187], v[124:127]
	v_mfma_f32_16x16x32_bf16 v[120:123], v[160:163], v[184:187], v[120:123]
	v_mfma_f32_16x16x32_bf16 v[112:115], v[152:155], v[204:207], v[112:115]
	v_mfma_f32_16x16x32_bf16 v[104:107], v[160:163], v[204:207], v[104:107]
	v_mfma_f32_16x16x32_bf16 v[96:99], v[152:155], v[212:215], v[96:99]
	v_mfma_f32_16x16x32_bf16 v[88:91], v[160:163], v[212:215], v[88:91]
	v_mfma_f32_16x16x32_bf16 v[80:83], v[152:155], v[220:223], v[80:83]
	v_mfma_f32_16x16x32_bf16 v[72:75], v[160:163], v[220:223], v[72:75]
	v_mfma_f32_16x16x32_bf16 v[128:131], v[164:167], v[180:183], v[128:131]
	v_mfma_f32_16x16x32_bf16 v[116:119], v[172:175], v[180:183], v[116:119]
	v_mfma_f32_16x16x32_bf16 v[108:111], v[164:167], v[188:191], v[108:111]
	v_mfma_f32_16x16x32_bf16 v[100:103], v[172:175], v[188:191], v[100:103]
	v_mfma_f32_16x16x32_bf16 v[92:95], v[164:167], v[208:211], v[92:95]
	v_mfma_f32_16x16x32_bf16 v[84:87], v[172:175], v[208:211], v[84:87]
	v_mfma_f32_16x16x32_bf16 v[76:79], v[164:167], v[216:219], v[76:79]
	v_mfma_f32_16x16x32_bf16 v[68:71], v[172:175], v[216:219], v[68:71]
	v_mfma_f32_16x16x32_bf16 v[128:131], v[168:171], v[184:187], v[128:131]
	v_mfma_f32_16x16x32_bf16 v[116:119], v[176:179], v[184:187], v[116:119]
	v_mfma_f32_16x16x32_bf16 v[108:111], v[168:171], v[204:207], v[108:111]
	v_mfma_f32_16x16x32_bf16 v[100:103], v[176:179], v[204:207], v[100:103]
	v_mfma_f32_16x16x32_bf16 v[92:95], v[168:171], v[212:215], v[92:95]
	v_mfma_f32_16x16x32_bf16 v[84:87], v[176:179], v[212:215], v[84:87]
	v_mfma_f32_16x16x32_bf16 v[76:79], v[168:171], v[220:223], v[76:79]
	v_mfma_f32_16x16x32_bf16 v[68:71], v[176:179], v[220:223], v[68:71]
	s_setprio 0
	s_barrier
	s_add_i32 s54, s60, s35
	v_lshl_add_u64 v[230:231], s[58:59], 0, v[134:135]
	s_mov_b32 m0, s54
	ds_read_b128 v[180:183], v147 offset:16384
	ds_read_b128 v[184:187], v147 offset:17408
	ds_read_b128 v[188:191], v147 offset:18432
	ds_read_b128 v[204:207], v147 offset:19456
	ds_read_b128 v[208:211], v147 offset:20480
	ds_read_b128 v[212:215], v147 offset:21504
	ds_read_b128 v[216:219], v147 offset:22528
	ds_read_b128 v[220:223], v147 offset:23552
	global_load_lds_dwordx4 v[230:231], off
	s_add_i32 m0, s54, 0x2000
	s_add_u32 s54, s58, s6
	v_lshl_add_u64 v[232:233], s[58:59], 0, v[0:1]
	s_addc_u32 s55, s59, s7
	s_add_i32 s58, s61, s35
	global_load_lds_dwordx4 v[232:233], off
	v_lshl_add_u64 v[238:239], s[54:55], 0, v[134:135]
	s_mov_b32 m0, s58
	v_lshl_add_u64 v[240:241], s[54:55], 0, v[0:1]
	global_load_lds_dwordx4 v[238:239], off
	s_add_i32 m0, s58, 0x2000
	v_lshl_add_u64 v[242:243], s[24:25], 0, v[136:137]
	global_load_lds_dwordx4 v[240:241], off
	s_mov_b32 m0, s37
	v_lshl_add_u64 v[244:245], s[24:25], 0, v[132:133]
	global_load_lds_dwordx4 v[242:243], off
	s_mov_b32 m0, s38
	s_nop 0
	global_load_lds_dwordx4 v[244:245], off
	s_waitcnt vmcnt(8)
	s_waitcnt lgkmcnt(0)
	s_barrier
; #define PG8_STAGE(bufoff, gbase, voff) do { _Pragma("unroll") for (int _i = 0; _i < 2; ++_i) \
;         __builtin_amdgcn_global_load_lds((const unsigned*)((const char*)(gbase) + (voff)[_i]), (PG8_LAS unsigned*)(lds + (bufoff) + ldsw + _i * 8192), 16, 0, 0); } while (0)
; #define PG8_LDA(dst, b, h) do { _Pragma("unroll") for (int m = 0; m < 4; ++m) _Pragma("unroll") for (int k = 0; k < 2; ++k) dst[m][k] = *(const PG8_LAS bf16x8*)(lds + PG8_SA(b, h) + aoff + m * 2048 + k * 1024); } while (0)
; #define PG8_LDB(dst, b, h) do { _Pragma("unroll") for (int n = 0; n < 2; ++n) _Pragma("unroll") for (int k = 0; k < 2; ++k) dst[n][k] = *(const PG8_LAS bf16x8*)(lds + PG8_SB(b, h) + boff + n * 2048 + k * 1024); } while (0)
; #define PG8_MMA(ai, bj, At, Bt) do { __builtin_amdgcn_s_setprio(1); _Pragma("unroll") for (int m = 0; m < 4; ++m) _Pragma("unroll") for (int n = 0; n < 2; ++n) _Pragma("unroll") for (int k = 0; k < 2; ++k) \
;         acc[ai][bj][m][n] = __builtin_amdgcn_mfma_f32_16x16x32_bf16(Bt[n][k], At[m][k], acc[ai][bj][m][n], 0, 0, 0); __builtin_amdgcn_s_setprio(0); } while (0)
; #define PG8_WAIT_V(n) asm volatile("s_waitcnt vmcnt(" #n ")" ::: "memory")
; #define PG8_WAIT_L(n) asm volatile("s_waitcnt lgkmcnt(" #n ")" ::: "memory")
; #define PG8_BAR __builtin_amdgcn_s_barrier()
; #define PG8_SCHED __builtin_amdgcn_sched_barrier(0)
; template <class Epi, class Sched, bool ALIGN_EPI = false, bool SP2 = false>
; __device__ __forceinline__ void gemm_phase(PG8_LAS unsigned char* lds, const Gemm g, const Sched& S, const Epi& E, int tid_in) {
;     ...
;             PG8_WAIT_V(8); PG8_WAIT_L(0); PG8_BAR; PG8_MMA(1, 0, At, B0); PG8_MMA(1, 1, At, B1); PG8_BAR; PG8_SCHED;
;             PG8_LDB(B0, 1, 0); PG8_LDB(B1, 1, 1); PG8_SCHED; PG8_LDA(At, 1, 0); PG8_STAGE(PG8_SA(0, 1), a2 + hsA, voffA);
;             PG8_WAIT_V(8); PG8_WAIT_L(0); PG8_BAR; PG8_MMA(0, 0, At, B0); PG8_MMA(0, 1, At, B1); PG8_BAR; PG8_SCHED;
	s_setprio 1
	s_waitcnt lgkmcnt(0)
	v_mfma_f32_16x16x32_bf16 v[64:67], v[148:151], v[180:183], v[64:67]
	v_mfma_f32_16x16x32_bf16 v[56:59], v[156:159], v[180:183], v[56:59]
	v_mfma_f32_16x16x32_bf16 v[48:51], v[148:151], v[188:191], v[48:51]
	v_mfma_f32_16x16x32_bf16 v[40:43], v[156:159], v[188:191], v[40:43]
	v_mfma_f32_16x16x32_bf16 v[32:35], v[148:151], v[208:211], v[32:35]
	v_mfma_f32_16x16x32_bf16 v[24:27], v[156:159], v[208:211], v[24:27]
	v_mfma_f32_16x16x32_bf16 v[16:19], v[148:151], v[216:219], v[16:19]
	v_mfma_f32_16x16x32_bf16 v[8:11], v[156:159], v[216:219], v[8:11]
	v_mfma_f32_16x16x32_bf16 v[64:67], v[152:155], v[184:187], v[64:67]
	v_mfma_f32_16x16x32_bf16 v[56:59], v[160:163], v[184:187], v[56:59]
	v_mfma_f32_16x16x32_bf16 v[48:51], v[152:155], v[204:207], v[48:51]
	v_mfma_f32_16x16x32_bf16 v[40:43], v[160:163], v[204:207], v[40:43]
	v_mfma_f32_16x16x32_bf16 v[32:35], v[152:155], v[212:215], v[32:35]
	v_mfma_f32_16x16x32_bf16 v[24:27], v[160:163], v[212:215], v[24:27]
	v_mfma_f32_16x16x32_bf16 v[16:19], v[152:155], v[220:223], v[16:19]
	v_mfma_f32_16x16x32_bf16 v[8:11], v[160:163], v[220:223], v[8:11]
	v_mfma_f32_16x16x32_bf16 v[60:63], v[164:167], v[180:183], v[60:63]
	v_mfma_f32_16x16x32_bf16 v[52:55], v[172:175], v[180:183], v[52:55]
	v_mfma_f32_16x16x32_bf16 v[44:47], v[164:167], v[188:191], v[44:47]
	v_mfma_f32_16x16x32_bf16 v[36:39], v[172:175], v[188:191], v[36:39]
	v_mfma_f32_16x16x32_bf16 v[28:31], v[164:167], v[208:211], v[28:31]
	v_mfma_f32_16x16x32_bf16 v[20:23], v[172:175], v[208:211], v[20:23]
	v_mfma_f32_16x16x32_bf16 v[12:15], v[164:167], v[216:219], v[12:15]
	v_mfma_f32_16x16x32_bf16 v[4:7], v[172:175], v[216:219], v[4:7]
	v_mfma_f32_16x16x32_bf16 v[60:63], v[168:171], v[184:187], v[60:63]
	v_mfma_f32_16x16x32_bf16 v[52:55], v[176:179], v[184:187], v[52:55]
	v_mfma_f32_16x16x32_bf16 v[44:47], v[168:171], v[204:207], v[44:47]
	v_mfma_f32_16x16x32_bf16 v[36:39], v[176:179], v[204:207], v[36:39]
	v_mfma_f32_16x16x32_bf16 v[28:31], v[168:171], v[212:215], v[28:31]
	v_mfma_f32_16x16x32_bf16 v[20:23], v[176:179], v[212:215], v[20:23]
	v_mfma_f32_16x16x32_bf16 v[12:15], v[168:171], v[220:223], v[12:15]
	v_mfma_f32_16x16x32_bf16 v[4:7], v[176:179], v[220:223], v[4:7]
	s_setprio 0
	s_barrier
	s_add_i32 s54, 0, 0x18000
	s_add_i32 s55, 0, 0x1c000
	v_add_u32_e32 v160, s54, v142
	v_add_u32_e32 v176, s55, v142
	ds_read_b128 v[148:151], v160
	ds_read_b128 v[152:155], v160 offset:1024
	ds_read_b128 v[156:159], v160 offset:2048
	ds_read_b128 v[160:163], v160 offset:3072
	ds_read_b128 v[164:167], v176
	ds_read_b128 v[168:171], v176 offset:1024
	ds_read_b128 v[172:175], v176 offset:2048
	ds_read_b128 v[176:179], v176 offset:3072
	s_add_u32 s24, s24, s0
	s_addc_u32 s25, s25, s1
	s_mov_b32 m0, s39
	v_lshl_add_u64 v[246:247], s[24:25], 0, v[136:137]
	ds_read_b128 v[180:183], v147 offset:32768
	ds_read_b128 v[184:187], v147 offset:33792
	ds_read_b128 v[188:191], v147 offset:34816
	ds_read_b128 v[204:207], v147 offset:35840
	ds_read_b128 v[208:211], v147 offset:36864
	ds_read_b128 v[212:215], v147 offset:37888
	ds_read_b128 v[216:219], v147 offset:38912
	ds_read_b128 v[220:223], v147 offset:39936
	global_load_lds_dwordx4 v[246:247], off
	v_lshl_add_u64 v[246:247], s[24:25], 0, v[132:133]
	s_mov_b32 m0, s40
	s_nop 0
	global_load_lds_dwordx4 v[246:247], off
	s_waitcnt vmcnt(8)
	s_waitcnt lgkmcnt(0)
	s_barrier
	s_setprio 1
	s_waitcnt lgkmcnt(0)
	v_mfma_f32_16x16x32_bf16 v[124:127], v[148:151], v[180:183], v[124:127]
	v_mfma_f32_16x16x32_bf16 v[120:123], v[156:159], v[180:183], v[120:123]
	v_mfma_f32_16x16x32_bf16 v[112:115], v[148:151], v[188:191], v[112:115]
	v_mfma_f32_16x16x32_bf16 v[104:107], v[156:159], v[188:191], v[104:107]
	v_mfma_f32_16x16x32_bf16 v[96:99], v[148:151], v[208:211], v[96:99]
	v_mfma_f32_16x16x32_bf16 v[88:91], v[156:159], v[208:211], v[88:91]
	v_mfma_f32_16x16x32_bf16 v[80:83], v[148:151], v[216:219], v[80:83]
	v_mfma_f32_16x16x32_bf16 v[72:75], v[156:159], v[216:219], v[72:75]
	v_mfma_f32_16x16x32_bf16 v[124:127], v[152:155], v[184:187], v[124:127]
	v_mfma_f32_16x16x32_bf16 v[120:123], v[160:163], v[184:187], v[120:123]
	v_mfma_f32_16x16x32_bf16 v[112:115], v[152:155], v[204:207], v[112:115]
	v_mfma_f32_16x16x32_bf16 v[104:107], v[160:163], v[204:207], v[104:107]
	v_mfma_f32_16x16x32_bf16 v[96:99], v[152:155], v[212:215], v[96:99]
	v_mfma_f32_16x16x32_bf16 v[88:91], v[160:163], v[212:215], v[88:91]
	v_mfma_f32_16x16x32_bf16 v[80:83], v[152:155], v[220:223], v[80:83]
	v_mfma_f32_16x16x32_bf16 v[72:75], v[160:163], v[220:223], v[72:75]
	v_mfma_f32_16x16x32_bf16 v[128:131], v[164:167], v[180:183], v[128:131]
	v_mfma_f32_16x16x32_bf16 v[116:119], v[172:175], v[180:183], v[116:119]
	v_mfma_f32_16x16x32_bf16 v[108:111], v[164:167], v[188:191], v[108:111]
	v_mfma_f32_16x16x32_bf16 v[100:103], v[172:175], v[188:191], v[100:103]
	v_mfma_f32_16x16x32_bf16 v[92:95], v[164:167], v[208:211], v[92:95]
	v_mfma_f32_16x16x32_bf16 v[84:87], v[172:175], v[208:211], v[84:87]
	v_mfma_f32_16x16x32_bf16 v[76:79], v[164:167], v[216:219], v[76:79]
	v_mfma_f32_16x16x32_bf16 v[68:71], v[172:175], v[216:219], v[68:71]
	v_mfma_f32_16x16x32_bf16 v[128:131], v[168:171], v[184:187], v[128:131]
	v_mfma_f32_16x16x32_bf16 v[116:119], v[176:179], v[184:187], v[116:119]
	v_mfma_f32_16x16x32_bf16 v[108:111], v[168:171], v[204:207], v[108:111]
	v_mfma_f32_16x16x32_bf16 v[100:103], v[176:179], v[204:207], v[100:103]
	v_mfma_f32_16x16x32_bf16 v[92:95], v[168:171], v[212:215], v[92:95]
	v_mfma_f32_16x16x32_bf16 v[84:87], v[176:179], v[212:215], v[84:87]
	v_mfma_f32_16x16x32_bf16 v[76:79], v[168:171], v[220:223], v[76:79]
	v_mfma_f32_16x16x32_bf16 v[68:71], v[176:179], v[220:223], v[68:71]
	s_setprio 0
	s_barrier
; #define PG8_STAGE(bufoff, gbase, voff) do { _Pragma("unroll") for (int _i = 0; _i < 2; ++_i) \
;         __builtin_amdgcn_global_load_lds((const unsigned*)((const char*)(gbase) + (voff)[_i]), (PG8_LAS unsigned*)(lds + (bufoff) + ldsw + _i * 8192), 16, 0, 0); } while (0)
; #define PG8_LDA(dst, b, h) do { _Pragma("unroll") for (int m = 0; m < 4; ++m) _Pragma("unroll") for (int k = 0; k < 2; ++k) dst[m][k] = *(const PG8_LAS bf16x8*)(lds + PG8_SA(b, h) + aoff + m * 2048 + k * 1024); } while (0)
; #define PG8_MMA(ai, bj, At, Bt) do { __builtin_amdgcn_s_setprio(1); _Pragma("unroll") for (int m = 0; m < 4; ++m) _Pragma("unroll") for (int n = 0; n < 2; ++n) _Pragma("unroll") for (int k = 0; k < 2; ++k) \
;         acc[ai][bj][m][n] = __builtin_amdgcn_mfma_f32_16x16x32_bf16(Bt[n][k], At[m][k], acc[ai][bj][m][n], 0, 0, 0); __builtin_amdgcn_s_setprio(0); } while (0)
; #define PG8_WAIT_V(n) asm volatile("s_waitcnt vmcnt(" #n ")" ::: "memory")
; #define PG8_WAIT_L(n) asm volatile("s_waitcnt lgkmcnt(" #n ")" ::: "memory")
; #define PG8_BAR __builtin_amdgcn_s_barrier()
; #define PG8_SCHED __builtin_amdgcn_sched_barrier(0)
; template <class Epi, class Sched, bool ALIGN_EPI = false, bool SP2 = false>
; __device__ __forceinline__ void gemm_phase(PG8_LAS unsigned char* lds, const Gemm g, const Sched& S, const Epi& E, int tid_in) {
;     ...
;         for (int t = 0; t < nt; t += 2) {
;     ...
;             PG8_LDA(At, 1, 1); PG8_STAGE(PG8_SB(1, 0), b3, voffB); PG8_STAGE(PG8_SB(1, 1), b3 + hsB, voffB); PG8_STAGE(PG8_SA(1, 0), a3, voffA);
;             PG8_WAIT_V(8); PG8_WAIT_L(0); PG8_BAR; PG8_MMA(1, 0, At, B0); PG8_MMA(1, 1, At, B1); PG8_BAR; PG8_SCHED;
	s_add_i32 s24, s54, s35
	v_lshl_add_u64 v[230:231], v[230:231], 0, s[80:81]
	s_mov_b32 m0, s24
	ds_read_b128 v[180:183], v147 offset:49152
	ds_read_b128 v[184:187], v147 offset:50176
	ds_read_b128 v[188:191], v147 offset:51200
	ds_read_b128 v[204:207], v147 offset:52224
	ds_read_b128 v[208:211], v147 offset:53248
	ds_read_b128 v[212:215], v147 offset:54272
	ds_read_b128 v[216:219], v147 offset:55296
	ds_read_b128 v[220:223], v147 offset:56320
	global_load_lds_dwordx4 v[230:231], off
	v_lshl_add_u64 v[230:231], v[232:233], 0, s[80:81]
	s_add_i32 m0, s24, 0x2000
	s_add_i32 s24, s55, s35
	global_load_lds_dwordx4 v[230:231], off
	v_lshl_add_u64 v[230:231], v[238:239], 0, s[80:81]
	s_mov_b32 m0, s24
	s_nop 0
	global_load_lds_dwordx4 v[230:231], off
	v_lshl_add_u64 v[230:231], v[240:241], 0, s[80:81]
	s_add_i32 m0, s24, 0x2000
	s_nop 0
	global_load_lds_dwordx4 v[230:231], off
	v_lshl_add_u64 v[230:231], v[242:243], 0, s[80:81]
	s_mov_b32 m0, s41
	s_nop 0
	global_load_lds_dwordx4 v[230:231], off
	v_lshl_add_u64 v[230:231], v[244:245], 0, s[80:81]
	s_mov_b32 m0, s42
	s_nop 0
	global_load_lds_dwordx4 v[230:231], off
	s_waitcnt vmcnt(8)
	s_waitcnt lgkmcnt(0)
	s_barrier
	s_setprio 1
	s_waitcnt lgkmcnt(0)
	v_mfma_f32_16x16x32_bf16 v[64:67], v[148:151], v[180:183], v[64:67]
	v_mfma_f32_16x16x32_bf16 v[56:59], v[156:159], v[180:183], v[56:59]
	v_mfma_f32_16x16x32_bf16 v[48:51], v[148:151], v[188:191], v[48:51]
	v_mfma_f32_16x16x32_bf16 v[40:43], v[156:159], v[188:191], v[40:43]
	v_mfma_f32_16x16x32_bf16 v[32:35], v[148:151], v[208:211], v[32:35]
	v_mfma_f32_16x16x32_bf16 v[24:27], v[156:159], v[208:211], v[24:27]
	v_mfma_f32_16x16x32_bf16 v[16:19], v[148:151], v[216:219], v[16:19]
	v_mfma_f32_16x16x32_bf16 v[8:11], v[156:159], v[216:219], v[8:11]
	v_mfma_f32_16x16x32_bf16 v[64:67], v[152:155], v[184:187], v[64:67]
	v_mfma_f32_16x16x32_bf16 v[56:59], v[160:163], v[184:187], v[56:59]
	v_mfma_f32_16x16x32_bf16 v[48:51], v[152:155], v[204:207], v[48:51]
	v_mfma_f32_16x16x32_bf16 v[40:43], v[160:163], v[204:207], v[40:43]
	v_mfma_f32_16x16x32_bf16 v[32:35], v[152:155], v[212:215], v[32:35]
	v_mfma_f32_16x16x32_bf16 v[24:27], v[160:163], v[212:215], v[24:27]
	v_mfma_f32_16x16x32_bf16 v[16:19], v[152:155], v[220:223], v[16:19]
	v_mfma_f32_16x16x32_bf16 v[8:11], v[160:163], v[220:223], v[8:11]
	v_mfma_f32_16x16x32_bf16 v[60:63], v[164:167], v[180:183], v[60:63]
	v_mfma_f32_16x16x32_bf16 v[52:55], v[172:175], v[180:183], v[52:55]
	v_mfma_f32_16x16x32_bf16 v[44:47], v[164:167], v[188:191], v[44:47]
	v_mfma_f32_16x16x32_bf16 v[36:39], v[172:175], v[188:191], v[36:39]
	v_mfma_f32_16x16x32_bf16 v[28:31], v[164:167], v[208:211], v[28:31]
	v_mfma_f32_16x16x32_bf16 v[20:23], v[172:175], v[208:211], v[20:23]
	v_mfma_f32_16x16x32_bf16 v[12:15], v[164:167], v[216:219], v[12:15]
	v_mfma_f32_16x16x32_bf16 v[4:7], v[172:175], v[216:219], v[4:7]
	v_mfma_f32_16x16x32_bf16 v[60:63], v[168:171], v[184:187], v[60:63]
	v_mfma_f32_16x16x32_bf16 v[52:55], v[176:179], v[184:187], v[52:55]
	v_mfma_f32_16x16x32_bf16 v[44:47], v[168:171], v[204:207], v[44:47]
	v_mfma_f32_16x16x32_bf16 v[36:39], v[176:179], v[204:207], v[36:39]
	v_mfma_f32_16x16x32_bf16 v[28:31], v[168:171], v[212:215], v[28:31]
	v_mfma_f32_16x16x32_bf16 v[20:23], v[176:179], v[212:215], v[20:23]
	v_mfma_f32_16x16x32_bf16 v[12:15], v[168:171], v[220:223], v[12:15]
	v_mfma_f32_16x16x32_bf16 v[4:7], v[176:179], v[220:223], v[4:7]
	s_setprio 0
	s_barrier
	s_add_i32 s24, s53, 2
	s_add_u32 s51, s51, 0x100
	s_addc_u32 s52, s52, 0
	s_add_u32 s22, s22, 0x100
	s_addc_u32 s23, s23, 0
	s_cmp_ge_i32 s53, s43
	s_mov_b32 s53, s24
	s_cbranch_scc0 .LBB0_244

; #define PG8_STAGE(bufoff, gbase, voff) do { _Pragma("unroll") for (int _i = 0; _i < 2; ++_i) \
;         __builtin_amdgcn_global_load_lds((const unsigned*)((const char*)(gbase) + (voff)[_i]), (PG8_LAS unsigned*)(lds + (bufoff) + ldsw + _i * 8192), 16, 0, 0); } while (0)
; #define PG8_LDA(dst, b, h) do { _Pragma("unroll") for (int m = 0; m < 4; ++m) _Pragma("unroll") for (int k = 0; k < 2; ++k) dst[m][k] = *(const PG8_LAS bf16x8*)(lds + PG8_SA(b, h) + aoff + m * 2048 + k * 1024); } while (0)
; #define PG8_LDB(dst, b, h) do { _Pragma("unroll") for (int n = 0; n < 2; ++n) _Pragma("unroll") for (int k = 0; k < 2; ++k) dst[n][k] = *(const PG8_LAS bf16x8*)(lds + PG8_SB(b, h) + boff + n * 2048 + k * 1024); } while (0)
; #define PG8_MMA(ai, bj, At, Bt) do { __builtin_amdgcn_s_setprio(1); _Pragma("unroll") for (int m = 0; m < 4; ++m) _Pragma("unroll") for (int n = 0; n < 2; ++n) _Pragma("unroll") for (int k = 0; k < 2; ++k) \
;         acc[ai][bj][m][n] = __builtin_amdgcn_mfma_f32_16x16x32_bf16(Bt[n][k], At[m][k], acc[ai][bj][m][n], 0, 0, 0); __builtin_amdgcn_s_setprio(0); } while (0)
; template <class Epi, class Sched, bool ALIGN_EPI = false, bool SP2 = false>
; __device__ __forceinline__ void gemm_phase(PG8_LAS unsigned char* lds, const Gemm g, const Sched& S, const Epi& E, int tid_in) {
;     ...
;             const bool last = (t == nt - 2);
;             if constexpr (mid_hook<Epi>::value) { if (t == Epi::H1 || t == Epi::H2) E.mid(acc, cur, wr, wc, fr, fq, t == Epi::H2); }
;             const char* a1 = cA + (size_t)(t + 1) * kstep + (t >= jt ? jb : 0);
;             const char* a2 = last ? nA : cA + (size_t)(t + 2) * kstep + (t + 2 >= jt ? jb : 0); const char* b2 = last ? nB : cB + (size_t)(t + 2) * kstep;
;             const char* a3 = a2 + kstep; const char* b3 = b2 + kstep;
;             if (last && has_next) S.a_ready(nxt);
;             if constexpr (SP2) {
;             PG8_LDB(B0, 0, 0); PG8_LDB(B1, 0, 1); PG8_SCHED; PG8_LDA(At, 0, 0); PG8_STAGE(PG8_SA(1, 1), a1 + hsA, voffA);
;             PG8_WAIT_V(8); PG8_WAIT_L(0); PG8_BAR; PG8_MMA(0, 0, At, B0); PG8_MMA(0, 1, At, B1); PG8_BAR; PG8_SCHED;
;             PG8_LDA(At, 0, 1); PG8_STAGE(PG8_SB(0, 0), b2, voffB); PG8_STAGE(PG8_SB(0, 1), b2 + hsB, voffB); PG8_STAGE(PG8_SA(0, 0), a2, voffA);
;             PG8_WAIT_V(8); PG8_WAIT_L(0); PG8_BAR; PG8_MMA(1, 0, At, B0); PG8_MMA(1, 1, At, B1); PG8_BAR; PG8_SCHED;
.LBB0_321:
	s_add_i32 s40, s42, -2
	s_cmp_ge_i32 s40, s33
	s_cselect_b32 s78, s49, 0
	s_cselect_b32 s79, s65, 0
	s_cmp_ge_i32 s42, s33
	s_cselect_b32 s41, s49, 0
	s_cselect_b32 s40, s65, 0
	s_add_u32 s41, s4, s41
	s_addc_u32 s40, s5, s40
	s_add_u32 s43, s41, 0x80
	s_addc_u32 s40, s40, 0
	s_add_i32 s84, 0, 0x10000
	s_cmp_eq_u32 s64, s42
	s_cselect_b32 s41, s37, s40
	s_cselect_b32 s40, s36, s43
	s_cselect_b32 s83, s39, s77
	s_cselect_b32 s82, s38, s76
	s_add_i32 s43, 0, 0x14000
	v_add_u32_e32 v144, s84, v219
	v_add_u32_e32 v170, s43, v219
	ds_read_b128 v[132:135], v144
	ds_read_b128 v[136:139], v144 offset:1024
	ds_read_b128 v[140:143], v144 offset:2048
	ds_read_b128 v[144:147], v144 offset:3072
	ds_read_b128 v[148:151], v170
	ds_read_b128 v[162:165], v170 offset:1024
	ds_read_b128 v[166:169], v170 offset:2048
	ds_read_b128 v[170:173], v170 offset:3072
	v_lshl_add_u64 v[190:191], s[4:5], 0, v[160:161]
	v_lshl_add_u64 v[190:191], v[190:191], 0, s[78:79]
	s_add_i32 m0, s53, 0xc000
	ds_read_b128 v[174:177], v221
	ds_read_b128 v[178:181], v221 offset:1024
	ds_read_b128 v[182:185], v221 offset:2048
	ds_read_b128 v[186:189], v221 offset:3072
	ds_read_b128 v[204:207], v221 offset:4096
	ds_read_b128 v[208:211], v221 offset:5120
	ds_read_b128 v[212:215], v221 offset:6144
	ds_read_b128 v[238:241], v221 offset:7168
	global_load_lds_dwordx4 v[190:191], off
	v_lshl_add_u64 v[190:191], s[4:5], 0, v[158:159]
	v_lshl_add_u64 v[190:191], v[190:191], 0, s[78:79]
	s_add_i32 m0, s53, 0xe000
	s_nop 0
	global_load_lds_dwordx4 v[190:191], off
	s_waitcnt vmcnt(8)
	s_waitcnt lgkmcnt(0)
	s_barrier
	s_setprio 1
	s_waitcnt lgkmcnt(0)
	v_mfma_f32_16x16x32_bf16 v[128:131], v[132:135], v[174:177], v[128:131]
	v_mfma_f32_16x16x32_bf16 v[124:127], v[140:143], v[174:177], v[124:127]
	v_mfma_f32_16x16x32_bf16 v[120:123], v[132:135], v[182:185], v[120:123]
	v_mfma_f32_16x16x32_bf16 v[116:119], v[140:143], v[182:185], v[116:119]
	v_mfma_f32_16x16x32_bf16 v[112:115], v[132:135], v[204:207], v[112:115]
	v_mfma_f32_16x16x32_bf16 v[108:111], v[140:143], v[204:207], v[108:111]
	v_mfma_f32_16x16x32_bf16 v[104:107], v[132:135], v[212:215], v[104:107]
	v_mfma_f32_16x16x32_bf16 v[100:103], v[140:143], v[212:215], v[100:103]
	v_mfma_f32_16x16x32_bf16 v[128:131], v[136:139], v[178:181], v[128:131]
	v_mfma_f32_16x16x32_bf16 v[124:127], v[144:147], v[178:181], v[124:127]
	v_mfma_f32_16x16x32_bf16 v[120:123], v[136:139], v[186:189], v[120:123]
	v_mfma_f32_16x16x32_bf16 v[116:119], v[144:147], v[186:189], v[116:119]
	v_mfma_f32_16x16x32_bf16 v[112:115], v[136:139], v[208:211], v[112:115]
	v_mfma_f32_16x16x32_bf16 v[108:111], v[144:147], v[208:211], v[108:111]
	v_mfma_f32_16x16x32_bf16 v[104:107], v[136:139], v[238:241], v[104:107]
	v_mfma_f32_16x16x32_bf16 v[100:103], v[144:147], v[238:241], v[100:103]
	v_mfma_f32_16x16x32_bf16 v[64:67], v[148:151], v[174:177], v[64:67]
	v_mfma_f32_16x16x32_bf16 v[56:59], v[166:169], v[174:177], v[56:59]
	v_mfma_f32_16x16x32_bf16 v[60:63], v[148:151], v[182:185], v[60:63]
	v_mfma_f32_16x16x32_bf16 v[52:55], v[166:169], v[182:185], v[52:55]
	v_mfma_f32_16x16x32_bf16 v[48:51], v[148:151], v[204:207], v[48:51]
	v_mfma_f32_16x16x32_bf16 v[40:43], v[166:169], v[204:207], v[40:43]
	v_mfma_f32_16x16x32_bf16 v[44:47], v[148:151], v[212:215], v[44:47]
	v_mfma_f32_16x16x32_bf16 v[36:39], v[166:169], v[212:215], v[36:39]
	v_mfma_f32_16x16x32_bf16 v[64:67], v[162:165], v[178:181], v[64:67]
	v_mfma_f32_16x16x32_bf16 v[56:59], v[170:173], v[178:181], v[56:59]
	v_mfma_f32_16x16x32_bf16 v[60:63], v[162:165], v[186:189], v[60:63]
	v_mfma_f32_16x16x32_bf16 v[52:55], v[170:173], v[186:189], v[52:55]
	v_mfma_f32_16x16x32_bf16 v[48:51], v[162:165], v[208:211], v[48:51]
	v_mfma_f32_16x16x32_bf16 v[40:43], v[170:173], v[208:211], v[40:43]
	v_mfma_f32_16x16x32_bf16 v[44:47], v[162:165], v[238:241], v[44:47]
	v_mfma_f32_16x16x32_bf16 v[36:39], v[170:173], v[238:241], v[36:39]
	s_setprio 0
	s_barrier
	s_add_i32 s78, s84, s52
	v_lshl_add_u64 v[190:191], s[82:83], 0, v[152:153]
	s_mov_b32 m0, s78
	ds_read_b128 v[174:177], v221 offset:16384
	ds_read_b128 v[178:181], v221 offset:17408
	ds_read_b128 v[182:185], v221 offset:18432
	ds_read_b128 v[186:189], v221 offset:19456
	ds_read_b128 v[204:207], v221 offset:20480
	ds_read_b128 v[208:211], v221 offset:21504
	ds_read_b128 v[212:215], v221 offset:22528
	ds_read_b128 v[238:241], v221 offset:23552
	global_load_lds_dwordx4 v[190:191], off
	s_add_i32 m0, s78, 0x2000
	s_add_u32 s78, s82, s12
	v_lshl_add_u64 v[216:217], s[82:83], 0, v[156:157]
	s_addc_u32 s79, s83, s13
	s_add_i32 s43, s43, s52
	global_load_lds_dwordx4 v[216:217], off
	v_lshl_add_u64 v[222:223], s[78:79], 0, v[152:153]
	s_mov_b32 m0, s43
	v_lshl_add_u64 v[230:231], s[78:79], 0, v[156:157]
	global_load_lds_dwordx4 v[222:223], off
	s_add_i32 m0, s43, 0x2000
	v_lshl_add_u64 v[232:233], s[40:41], 0, v[0:1]
	global_load_lds_dwordx4 v[230:231], off
	s_mov_b32 m0, s53
	v_lshl_add_u64 v[242:243], s[40:41], 0, v[154:155]
	global_load_lds_dwordx4 v[232:233], off
	s_mov_b32 m0, s54
	s_nop 0
	global_load_lds_dwordx4 v[242:243], off
	s_waitcnt vmcnt(8)
	s_waitcnt lgkmcnt(0)
	s_barrier
; #define PG8_STAGE(bufoff, gbase, voff) do { _Pragma("unroll") for (int _i = 0; _i < 2; ++_i) \
;         __builtin_amdgcn_global_load_lds((const unsigned*)((const char*)(gbase) + (voff)[_i]), (PG8_LAS unsigned*)(lds + (bufoff) + ldsw + _i * 8192), 16, 0, 0); } while (0)
; #define PG8_LDA(dst, b, h) do { _Pragma("unroll") for (int m = 0; m < 4; ++m) _Pragma("unroll") for (int k = 0; k < 2; ++k) dst[m][k] = *(const PG8_LAS bf16x8*)(lds + PG8_SA(b, h) + aoff + m * 2048 + k * 1024); } while (0)
; #define PG8_LDB(dst, b, h) do { _Pragma("unroll") for (int n = 0; n < 2; ++n) _Pragma("unroll") for (int k = 0; k < 2; ++k) dst[n][k] = *(const PG8_LAS bf16x8*)(lds + PG8_SB(b, h) + boff + n * 2048 + k * 1024); } while (0)
; #define PG8_MMA(ai, bj, At, Bt) do { __builtin_amdgcn_s_setprio(1); _Pragma("unroll") for (int m = 0; m < 4; ++m) _Pragma("unroll") for (int n = 0; n < 2; ++n) _Pragma("unroll") for (int k = 0; k < 2; ++k) \
;         acc[ai][bj][m][n] = __builtin_amdgcn_mfma_f32_16x16x32_bf16(Bt[n][k], At[m][k], acc[ai][bj][m][n], 0, 0, 0); __builtin_amdgcn_s_setprio(0); } while (0)
; #define PG8_WAIT_V(n) asm volatile("s_waitcnt vmcnt(" #n ")" ::: "memory")
; #define PG8_WAIT_L(n) asm volatile("s_waitcnt lgkmcnt(" #n ")" ::: "memory")
; #define PG8_BAR __builtin_amdgcn_s_barrier()
; #define PG8_SCHED __builtin_amdgcn_sched_barrier(0)
; template <class Epi, class Sched, bool ALIGN_EPI = false, bool SP2 = false>
; __device__ __forceinline__ void gemm_phase(PG8_LAS unsigned char* lds, const Gemm g, const Sched& S, const Epi& E, int tid_in) {
;     ...
;             PG8_WAIT_V(8); PG8_WAIT_L(0); PG8_BAR; PG8_MMA(1, 0, At, B0); PG8_MMA(1, 1, At, B1); PG8_BAR; PG8_SCHED;
;             PG8_LDB(B0, 1, 0); PG8_LDB(B1, 1, 1); PG8_SCHED; PG8_LDA(At, 1, 0); PG8_STAGE(PG8_SA(0, 1), a2 + hsA, voffA);
;             PG8_WAIT_V(8); PG8_WAIT_L(0); PG8_BAR; PG8_MMA(0, 0, At, B0); PG8_MMA(0, 1, At, B1); PG8_BAR; PG8_SCHED;
	s_setprio 1
	s_waitcnt lgkmcnt(0)
	v_mfma_f32_16x16x32_bf16 v[96:99], v[132:135], v[174:177], v[96:99]
	v_mfma_f32_16x16x32_bf16 v[92:95], v[140:143], v[174:177], v[92:95]
	v_mfma_f32_16x16x32_bf16 v[88:91], v[132:135], v[182:185], v[88:91]
	v_mfma_f32_16x16x32_bf16 v[84:87], v[140:143], v[182:185], v[84:87]
	v_mfma_f32_16x16x32_bf16 v[80:83], v[132:135], v[204:207], v[80:83]
	v_mfma_f32_16x16x32_bf16 v[76:79], v[140:143], v[204:207], v[76:79]
	v_mfma_f32_16x16x32_bf16 v[72:75], v[132:135], v[212:215], v[72:75]
	v_mfma_f32_16x16x32_bf16 v[68:71], v[140:143], v[212:215], v[68:71]
	v_mfma_f32_16x16x32_bf16 v[96:99], v[136:139], v[178:181], v[96:99]
	v_mfma_f32_16x16x32_bf16 v[92:95], v[144:147], v[178:181], v[92:95]
	v_mfma_f32_16x16x32_bf16 v[88:91], v[136:139], v[186:189], v[88:91]
	v_mfma_f32_16x16x32_bf16 v[84:87], v[144:147], v[186:189], v[84:87]
	v_mfma_f32_16x16x32_bf16 v[80:83], v[136:139], v[208:211], v[80:83]
	v_mfma_f32_16x16x32_bf16 v[76:79], v[144:147], v[208:211], v[76:79]
	v_mfma_f32_16x16x32_bf16 v[72:75], v[136:139], v[238:241], v[72:75]
	v_mfma_f32_16x16x32_bf16 v[68:71], v[144:147], v[238:241], v[68:71]
	v_mfma_f32_16x16x32_bf16 v[32:35], v[148:151], v[174:177], v[32:35]
	v_mfma_f32_16x16x32_bf16 v[28:31], v[166:169], v[174:177], v[28:31]
	v_mfma_f32_16x16x32_bf16 v[24:27], v[148:151], v[182:185], v[24:27]
	v_mfma_f32_16x16x32_bf16 v[12:15], v[166:169], v[182:185], v[12:15]
	v_mfma_f32_16x16x32_bf16 v[20:23], v[148:151], v[204:207], v[20:23]
	v_mfma_f32_16x16x32_bf16 v[8:11], v[166:169], v[204:207], v[8:11]
	v_mfma_f32_16x16x32_bf16 v[16:19], v[148:151], v[212:215], v[16:19]
	v_mfma_f32_16x16x32_bf16 v[4:7], v[166:169], v[212:215], v[4:7]
	v_mfma_f32_16x16x32_bf16 v[32:35], v[162:165], v[178:181], v[32:35]
	v_mfma_f32_16x16x32_bf16 v[28:31], v[170:173], v[178:181], v[28:31]
	v_mfma_f32_16x16x32_bf16 v[24:27], v[162:165], v[186:189], v[24:27]
	v_mfma_f32_16x16x32_bf16 v[12:15], v[170:173], v[186:189], v[12:15]
	v_mfma_f32_16x16x32_bf16 v[20:23], v[162:165], v[208:211], v[20:23]
	v_mfma_f32_16x16x32_bf16 v[8:11], v[170:173], v[208:211], v[8:11]
	v_mfma_f32_16x16x32_bf16 v[16:19], v[162:165], v[238:241], v[16:19]
	v_mfma_f32_16x16x32_bf16 v[4:7], v[170:173], v[238:241], v[4:7]
	s_setprio 0
	s_barrier
	s_add_i32 s43, 0, 0x18000
	s_add_i32 s78, 0, 0x1c000
	v_add_u32_e32 v144, s43, v219
	v_add_u32_e32 v170, s78, v219
	ds_read_b128 v[132:135], v144
	ds_read_b128 v[136:139], v144 offset:1024
	ds_read_b128 v[140:143], v144 offset:2048
	ds_read_b128 v[144:147], v144 offset:3072
	ds_read_b128 v[148:151], v170
	ds_read_b128 v[162:165], v170 offset:1024
	ds_read_b128 v[166:169], v170 offset:2048
	ds_read_b128 v[170:173], v170 offset:3072
	s_add_u32 s40, s40, s10
	s_addc_u32 s41, s41, s11
	s_mov_b32 m0, s55
	v_lshl_add_u64 v[244:245], s[40:41], 0, v[0:1]
	ds_read_b128 v[174:177], v221 offset:32768
	ds_read_b128 v[178:181], v221 offset:33792
	ds_read_b128 v[182:185], v221 offset:34816
	ds_read_b128 v[186:189], v221 offset:35840
	ds_read_b128 v[204:207], v221 offset:36864
	ds_read_b128 v[208:211], v221 offset:37888
	ds_read_b128 v[212:215], v221 offset:38912
	ds_read_b128 v[238:241], v221 offset:39936
	global_load_lds_dwordx4 v[244:245], off
	v_lshl_add_u64 v[244:245], s[40:41], 0, v[154:155]
	s_mov_b32 m0, s58
	s_nop 0
	global_load_lds_dwordx4 v[244:245], off
	s_waitcnt vmcnt(8)
	s_waitcnt lgkmcnt(0)
	s_barrier
	s_setprio 1
	s_waitcnt lgkmcnt(0)
	v_mfma_f32_16x16x32_bf16 v[128:131], v[132:135], v[174:177], v[128:131]
	v_mfma_f32_16x16x32_bf16 v[124:127], v[140:143], v[174:177], v[124:127]
	v_mfma_f32_16x16x32_bf16 v[120:123], v[132:135], v[182:185], v[120:123]
	v_mfma_f32_16x16x32_bf16 v[116:119], v[140:143], v[182:185], v[116:119]
	v_mfma_f32_16x16x32_bf16 v[112:115], v[132:135], v[204:207], v[112:115]
	v_mfma_f32_16x16x32_bf16 v[108:111], v[140:143], v[204:207], v[108:111]
	v_mfma_f32_16x16x32_bf16 v[104:107], v[132:135], v[212:215], v[104:107]
	v_mfma_f32_16x16x32_bf16 v[100:103], v[140:143], v[212:215], v[100:103]
	v_mfma_f32_16x16x32_bf16 v[128:131], v[136:139], v[178:181], v[128:131]
	v_mfma_f32_16x16x32_bf16 v[124:127], v[144:147], v[178:181], v[124:127]
	v_mfma_f32_16x16x32_bf16 v[120:123], v[136:139], v[186:189], v[120:123]
	v_mfma_f32_16x16x32_bf16 v[116:119], v[144:147], v[186:189], v[116:119]
	v_mfma_f32_16x16x32_bf16 v[112:115], v[136:139], v[208:211], v[112:115]
	v_mfma_f32_16x16x32_bf16 v[108:111], v[144:147], v[208:211], v[108:111]
	v_mfma_f32_16x16x32_bf16 v[104:107], v[136:139], v[238:241], v[104:107]
	v_mfma_f32_16x16x32_bf16 v[100:103], v[144:147], v[238:241], v[100:103]
	v_mfma_f32_16x16x32_bf16 v[64:67], v[148:151], v[174:177], v[64:67]
	v_mfma_f32_16x16x32_bf16 v[56:59], v[166:169], v[174:177], v[56:59]
	v_mfma_f32_16x16x32_bf16 v[60:63], v[148:151], v[182:185], v[60:63]
	v_mfma_f32_16x16x32_bf16 v[52:55], v[166:169], v[182:185], v[52:55]
	v_mfma_f32_16x16x32_bf16 v[48:51], v[148:151], v[204:207], v[48:51]
	v_mfma_f32_16x16x32_bf16 v[40:43], v[166:169], v[204:207], v[40:43]
	v_mfma_f32_16x16x32_bf16 v[44:47], v[148:151], v[212:215], v[44:47]
	v_mfma_f32_16x16x32_bf16 v[36:39], v[166:169], v[212:215], v[36:39]
	v_mfma_f32_16x16x32_bf16 v[64:67], v[162:165], v[178:181], v[64:67]
	v_mfma_f32_16x16x32_bf16 v[56:59], v[170:173], v[178:181], v[56:59]
	v_mfma_f32_16x16x32_bf16 v[60:63], v[162:165], v[186:189], v[60:63]
	v_mfma_f32_16x16x32_bf16 v[52:55], v[170:173], v[186:189], v[52:55]
	v_mfma_f32_16x16x32_bf16 v[48:51], v[162:165], v[208:211], v[48:51]
	v_mfma_f32_16x16x32_bf16 v[40:43], v[170:173], v[208:211], v[40:43]
	v_mfma_f32_16x16x32_bf16 v[44:47], v[162:165], v[238:241], v[44:47]
	v_mfma_f32_16x16x32_bf16 v[36:39], v[170:173], v[238:241], v[36:39]
	s_setprio 0
	s_barrier
; #define PG8_STAGE(bufoff, gbase, voff) do { _Pragma("unroll") for (int _i = 0; _i < 2; ++_i) \
;         __builtin_amdgcn_global_load_lds((const unsigned*)((const char*)(gbase) + (voff)[_i]), (PG8_LAS unsigned*)(lds + (bufoff) + ldsw + _i * 8192), 16, 0, 0); } while (0)
; #define PG8_LDA(dst, b, h) do { _Pragma("unroll") for (int m = 0; m < 4; ++m) _Pragma("unroll") for (int k = 0; k < 2; ++k) dst[m][k] = *(const PG8_LAS bf16x8*)(lds + PG8_SA(b, h) + aoff + m * 2048 + k * 1024); } while (0)
; #define PG8_MMA(ai, bj, At, Bt) do { __builtin_amdgcn_s_setprio(1); _Pragma("unroll") for (int m = 0; m < 4; ++m) _Pragma("unroll") for (int n = 0; n < 2; ++n) _Pragma("unroll") for (int k = 0; k < 2; ++k) \
;         acc[ai][bj][m][n] = __builtin_amdgcn_mfma_f32_16x16x32_bf16(Bt[n][k], At[m][k], acc[ai][bj][m][n], 0, 0, 0); __builtin_amdgcn_s_setprio(0); } while (0)
; #define PG8_WAIT_V(n) asm volatile("s_waitcnt vmcnt(" #n ")" ::: "memory")
; #define PG8_WAIT_L(n) asm volatile("s_waitcnt lgkmcnt(" #n ")" ::: "memory")
; #define PG8_BAR __builtin_amdgcn_s_barrier()
; #define PG8_SCHED __builtin_amdgcn_sched_barrier(0)
; template <class Epi, class Sched, bool ALIGN_EPI = false, bool SP2 = false>
; __device__ __forceinline__ void gemm_phase(PG8_LAS unsigned char* lds, const Gemm g, const Sched& S, const Epi& E, int tid_in) {
;     ...
;         for (int t = 0; t < nt; t += 2) {
;     ...
;             PG8_LDA(At, 1, 1); PG8_STAGE(PG8_SB(1, 0), b3, voffB); PG8_STAGE(PG8_SB(1, 1), b3 + hsB, voffB); PG8_STAGE(PG8_SA(1, 0), a3, voffA);
;             PG8_WAIT_V(8); PG8_WAIT_L(0); PG8_BAR; PG8_MMA(1, 0, At, B0); PG8_MMA(1, 1, At, B1); PG8_BAR; PG8_SCHED;
	s_add_i32 s40, s43, s52
	v_lshl_add_u64 v[190:191], v[190:191], 0, s[80:81]
	s_mov_b32 m0, s40
	ds_read_b128 v[174:177], v221 offset:49152
	ds_read_b128 v[178:181], v221 offset:50176
	ds_read_b128 v[182:185], v221 offset:51200
	ds_read_b128 v[186:189], v221 offset:52224
	ds_read_b128 v[204:207], v221 offset:53248
	ds_read_b128 v[208:211], v221 offset:54272
	ds_read_b128 v[212:215], v221 offset:55296
	ds_read_b128 v[238:241], v221 offset:56320
	global_load_lds_dwordx4 v[190:191], off
	v_lshl_add_u64 v[190:191], v[216:217], 0, s[80:81]
	s_add_i32 m0, s40, 0x2000
	s_add_i32 s40, s78, s52
	global_load_lds_dwordx4 v[190:191], off
	v_lshl_add_u64 v[190:191], v[222:223], 0, s[80:81]
	s_mov_b32 m0, s40
	s_nop 0
	global_load_lds_dwordx4 v[190:191], off
	v_lshl_add_u64 v[190:191], v[230:231], 0, s[80:81]
	s_add_i32 m0, s40, 0x2000
	s_nop 0
	global_load_lds_dwordx4 v[190:191], off
	v_lshl_add_u64 v[190:191], v[232:233], 0, s[80:81]
	s_mov_b32 m0, s61
	s_nop 0
	global_load_lds_dwordx4 v[190:191], off
	v_lshl_add_u64 v[190:191], v[242:243], 0, s[80:81]
	s_mov_b32 m0, s62
	s_nop 0
	global_load_lds_dwordx4 v[190:191], off
	s_waitcnt vmcnt(8)
	s_waitcnt lgkmcnt(0)
	s_barrier
	s_setprio 1
	s_waitcnt lgkmcnt(0)
	v_mfma_f32_16x16x32_bf16 v[96:99], v[132:135], v[174:177], v[96:99]
	v_mfma_f32_16x16x32_bf16 v[92:95], v[140:143], v[174:177], v[92:95]
	v_mfma_f32_16x16x32_bf16 v[88:91], v[132:135], v[182:185], v[88:91]
	v_mfma_f32_16x16x32_bf16 v[84:87], v[140:143], v[182:185], v[84:87]
	v_mfma_f32_16x16x32_bf16 v[80:83], v[132:135], v[204:207], v[80:83]
	v_mfma_f32_16x16x32_bf16 v[76:79], v[140:143], v[204:207], v[76:79]
	v_mfma_f32_16x16x32_bf16 v[72:75], v[132:135], v[212:215], v[72:75]
	v_mfma_f32_16x16x32_bf16 v[68:71], v[140:143], v[212:215], v[68:71]
	v_mfma_f32_16x16x32_bf16 v[96:99], v[136:139], v[178:181], v[96:99]
	v_mfma_f32_16x16x32_bf16 v[92:95], v[144:147], v[178:181], v[92:95]
	v_mfma_f32_16x16x32_bf16 v[88:91], v[136:139], v[186:189], v[88:91]
	v_mfma_f32_16x16x32_bf16 v[84:87], v[144:147], v[186:189], v[84:87]
	v_mfma_f32_16x16x32_bf16 v[80:83], v[136:139], v[208:211], v[80:83]
	v_mfma_f32_16x16x32_bf16 v[76:79], v[144:147], v[208:211], v[76:79]
	v_mfma_f32_16x16x32_bf16 v[72:75], v[136:139], v[238:241], v[72:75]
	v_mfma_f32_16x16x32_bf16 v[68:71], v[144:147], v[238:241], v[68:71]
	v_mfma_f32_16x16x32_bf16 v[32:35], v[148:151], v[174:177], v[32:35]
	v_mfma_f32_16x16x32_bf16 v[28:31], v[166:169], v[174:177], v[28:31]
	v_mfma_f32_16x16x32_bf16 v[24:27], v[148:151], v[182:185], v[24:27]
	v_mfma_f32_16x16x32_bf16 v[12:15], v[166:169], v[182:185], v[12:15]
	v_mfma_f32_16x16x32_bf16 v[20:23], v[148:151], v[204:207], v[20:23]
	v_mfma_f32_16x16x32_bf16 v[8:11], v[166:169], v[204:207], v[8:11]
	v_mfma_f32_16x16x32_bf16 v[16:19], v[148:151], v[212:215], v[16:19]
	v_mfma_f32_16x16x32_bf16 v[4:7], v[166:169], v[212:215], v[4:7]
	v_mfma_f32_16x16x32_bf16 v[32:35], v[162:165], v[178:181], v[32:35]
	v_mfma_f32_16x16x32_bf16 v[28:31], v[170:173], v[178:181], v[28:31]
	v_mfma_f32_16x16x32_bf16 v[24:27], v[162:165], v[186:189], v[24:27]
	v_mfma_f32_16x16x32_bf16 v[12:15], v[170:173], v[186:189], v[12:15]
	v_mfma_f32_16x16x32_bf16 v[20:23], v[162:165], v[208:211], v[20:23]
	v_mfma_f32_16x16x32_bf16 v[8:11], v[170:173], v[208:211], v[8:11]
	v_mfma_f32_16x16x32_bf16 v[16:19], v[162:165], v[238:241], v[16:19]
	v_mfma_f32_16x16x32_bf16 v[4:7], v[170:173], v[238:241], v[4:7]
	s_setprio 0
	s_barrier
	s_add_i32 s40, s42, 2
	s_add_u32 s76, s76, 0x100
	s_addc_u32 s77, s77, 0
	s_add_u32 s4, s4, 0x100
	s_addc_u32 s5, s5, 0
	s_cmp_ge_i32 s42, s64
	s_mov_b32 s42, s40
	s_cbranch_scc0 .LBB0_321
	s_movk_i32 s83, 0x3000

; #define PG8_STAGE(bufoff, gbase, voff) do { _Pragma("unroll") for (int _i = 0; _i < 2; ++_i) \
;         __builtin_amdgcn_global_load_lds((const unsigned*)((const char*)(gbase) + (voff)[_i]), (PG8_LAS unsigned*)(lds + (bufoff) + ldsw + _i * 8192), 16, 0, 0); } while (0)
; #define PG8_LDA(dst, b, h) do { _Pragma("unroll") for (int m = 0; m < 4; ++m) _Pragma("unroll") for (int k = 0; k < 2; ++k) dst[m][k] = *(const PG8_LAS bf16x8*)(lds + PG8_SA(b, h) + aoff + m * 2048 + k * 1024); } while (0)
; #define PG8_LDB(dst, b, h) do { _Pragma("unroll") for (int n = 0; n < 2; ++n) _Pragma("unroll") for (int k = 0; k < 2; ++k) dst[n][k] = *(const PG8_LAS bf16x8*)(lds + PG8_SB(b, h) + boff + n * 2048 + k * 1024); } while (0)
; #define PG8_MMA(ai, bj, At, Bt) do { __builtin_amdgcn_s_setprio(1); _Pragma("unroll") for (int m = 0; m < 4; ++m) _Pragma("unroll") for (int n = 0; n < 2; ++n) _Pragma("unroll") for (int k = 0; k < 2; ++k) \
;         acc[ai][bj][m][n] = __builtin_amdgcn_mfma_f32_16x16x32_bf16(Bt[n][k], At[m][k], acc[ai][bj][m][n], 0, 0, 0); __builtin_amdgcn_s_setprio(0); } while (0)
; template <class Epi, class Sched, bool ALIGN_EPI = false, bool SP2 = false>
; __device__ __forceinline__ void gemm_phase(PG8_LAS unsigned char* lds, const Gemm g, const Sched& S, const Epi& E, int tid_in) {
;     ...
;             const bool last = (t == nt - 2);
;             if constexpr (mid_hook<Epi>::value) { if (t == Epi::H1 || t == Epi::H2) E.mid(acc, cur, wr, wc, fr, fq, t == Epi::H2); }
;             const char* a1 = cA + (size_t)(t + 1) * kstep + (t >= jt ? jb : 0);
;             const char* a2 = last ? nA : cA + (size_t)(t + 2) * kstep + (t + 2 >= jt ? jb : 0); const char* b2 = last ? nB : cB + (size_t)(t + 2) * kstep;
;             const char* a3 = a2 + kstep; const char* b3 = b2 + kstep;
;             if (last && has_next) S.a_ready(nxt);
;             if constexpr (SP2) {
;             PG8_LDB(B0, 0, 0); PG8_LDB(B1, 0, 1); PG8_SCHED; PG8_LDA(At, 0, 0); PG8_STAGE(PG8_SA(1, 1), a1 + hsA, voffA);
;             PG8_WAIT_V(8); PG8_WAIT_L(0); PG8_BAR; PG8_MMA(0, 0, At, B0); PG8_MMA(0, 1, At, B1); PG8_BAR; PG8_SCHED;
;             PG8_LDA(At, 0, 1); PG8_STAGE(PG8_SB(0, 0), b2, voffB); PG8_STAGE(PG8_SB(0, 1), b2 + hsB, voffB); PG8_STAGE(PG8_SA(0, 0), a2, voffA);
;             PG8_WAIT_V(8); PG8_WAIT_L(0); PG8_BAR; PG8_MMA(1, 0, At, B0); PG8_MMA(1, 1, At, B1); PG8_BAR; PG8_SCHED;
.LBB0_352:
	s_add_i32 s24, s55, -2
	s_cmp_ge_i32 s24, s26
	s_cselect_b32 s58, s27, 0
	s_cselect_b32 s59, s42, 0
	s_cmp_ge_i32 s55, s26
	s_cselect_b32 s25, s27, 0
	s_cselect_b32 s24, s42, 0
	s_add_u32 s25, s22, s25
	s_addc_u32 s24, s23, s24
	s_add_u32 s60, s25, 0x80
	s_addc_u32 s24, s24, 0
	s_add_i32 s62, 0, 0x10000
	s_cmp_eq_u32 s41, s55
	s_cselect_b32 s25, s5, s24
	s_cselect_b32 s24, s4, s60
	s_cselect_b32 s61, s21, s54
	s_cselect_b32 s60, s20, s53
	s_add_i32 s63, 0, 0x14000
	v_add_u32_e32 v160, s62, v3
	v_add_u32_e32 v176, s63, v3
	ds_read_b128 v[148:151], v160
	ds_read_b128 v[152:155], v160 offset:1024
	ds_read_b128 v[156:159], v160 offset:2048
	ds_read_b128 v[160:163], v160 offset:3072
	ds_read_b128 v[164:167], v176
	ds_read_b128 v[168:171], v176 offset:1024
	ds_read_b128 v[172:175], v176 offset:2048
	ds_read_b128 v[176:179], v176 offset:3072
	v_lshl_add_u64 v[230:231], s[22:23], 0, v[140:141]
	v_lshl_add_u64 v[230:231], v[230:231], 0, s[58:59]
	s_add_i32 m0, s31, 0xc000
	ds_read_b128 v[180:183], v147
	ds_read_b128 v[184:187], v147 offset:1024
	ds_read_b128 v[188:191], v147 offset:2048
	ds_read_b128 v[204:207], v147 offset:3072
	ds_read_b128 v[208:211], v147 offset:4096
	ds_read_b128 v[212:215], v147 offset:5120
	ds_read_b128 v[216:219], v147 offset:6144
	ds_read_b128 v[220:223], v147 offset:7168
	global_load_lds_dwordx4 v[230:231], off
	v_lshl_add_u64 v[230:231], s[22:23], 0, v[138:139]
	v_lshl_add_u64 v[230:231], v[230:231], 0, s[58:59]
	s_add_i32 m0, s31, 0xe000
	s_nop 0
	global_load_lds_dwordx4 v[230:231], off
	s_waitcnt vmcnt(8)
	s_waitcnt lgkmcnt(0)
	s_barrier
	s_setprio 1
	s_waitcnt lgkmcnt(0)
	v_mfma_f32_16x16x32_bf16 v[124:127], v[148:151], v[180:183], v[124:127]
	v_mfma_f32_16x16x32_bf16 v[128:131], v[156:159], v[180:183], v[128:131]
	v_mfma_f32_16x16x32_bf16 v[112:115], v[148:151], v[188:191], v[112:115]
	v_mfma_f32_16x16x32_bf16 v[108:111], v[156:159], v[188:191], v[108:111]
	v_mfma_f32_16x16x32_bf16 v[96:99], v[148:151], v[208:211], v[96:99]
	v_mfma_f32_16x16x32_bf16 v[92:95], v[156:159], v[208:211], v[92:95]
	v_mfma_f32_16x16x32_bf16 v[80:83], v[148:151], v[216:219], v[80:83]
	v_mfma_f32_16x16x32_bf16 v[76:79], v[156:159], v[216:219], v[76:79]
	v_mfma_f32_16x16x32_bf16 v[124:127], v[152:155], v[184:187], v[124:127]
	v_mfma_f32_16x16x32_bf16 v[128:131], v[160:163], v[184:187], v[128:131]
	v_mfma_f32_16x16x32_bf16 v[112:115], v[152:155], v[204:207], v[112:115]
	v_mfma_f32_16x16x32_bf16 v[108:111], v[160:163], v[204:207], v[108:111]
	v_mfma_f32_16x16x32_bf16 v[96:99], v[152:155], v[212:215], v[96:99]
	v_mfma_f32_16x16x32_bf16 v[92:95], v[160:163], v[212:215], v[92:95]
	v_mfma_f32_16x16x32_bf16 v[80:83], v[152:155], v[220:223], v[80:83]
	v_mfma_f32_16x16x32_bf16 v[76:79], v[160:163], v[220:223], v[76:79]
	v_mfma_f32_16x16x32_bf16 v[120:123], v[164:167], v[180:183], v[120:123]
	v_mfma_f32_16x16x32_bf16 v[116:119], v[172:175], v[180:183], v[116:119]
	v_mfma_f32_16x16x32_bf16 v[104:107], v[164:167], v[188:191], v[104:107]
	v_mfma_f32_16x16x32_bf16 v[100:103], v[172:175], v[188:191], v[100:103]
	v_mfma_f32_16x16x32_bf16 v[88:91], v[164:167], v[208:211], v[88:91]
	v_mfma_f32_16x16x32_bf16 v[84:87], v[172:175], v[208:211], v[84:87]
	v_mfma_f32_16x16x32_bf16 v[72:75], v[164:167], v[216:219], v[72:75]
	v_mfma_f32_16x16x32_bf16 v[68:71], v[172:175], v[216:219], v[68:71]
	v_mfma_f32_16x16x32_bf16 v[120:123], v[168:171], v[184:187], v[120:123]
	v_mfma_f32_16x16x32_bf16 v[116:119], v[176:179], v[184:187], v[116:119]
	v_mfma_f32_16x16x32_bf16 v[104:107], v[168:171], v[204:207], v[104:107]
	v_mfma_f32_16x16x32_bf16 v[100:103], v[176:179], v[204:207], v[100:103]
	v_mfma_f32_16x16x32_bf16 v[88:91], v[168:171], v[212:215], v[88:91]
	v_mfma_f32_16x16x32_bf16 v[84:87], v[176:179], v[212:215], v[84:87]
	v_mfma_f32_16x16x32_bf16 v[72:75], v[168:171], v[220:223], v[72:75]
	v_mfma_f32_16x16x32_bf16 v[68:71], v[176:179], v[220:223], v[68:71]
	s_setprio 0
	s_barrier
	s_add_i32 s58, s62, s30
	v_lshl_add_u64 v[230:231], s[60:61], 0, v[134:135]
	s_mov_b32 m0, s58
	ds_read_b128 v[180:183], v147 offset:16384
	ds_read_b128 v[184:187], v147 offset:17408
	ds_read_b128 v[188:191], v147 offset:18432
	ds_read_b128 v[204:207], v147 offset:19456
	ds_read_b128 v[208:211], v147 offset:20480
	ds_read_b128 v[212:215], v147 offset:21504
	ds_read_b128 v[216:219], v147 offset:22528
	ds_read_b128 v[220:223], v147 offset:23552
	global_load_lds_dwordx4 v[230:231], off
	s_add_i32 m0, s58, 0x2000
	s_add_u32 s58, s60, s8
	v_lshl_add_u64 v[232:233], s[60:61], 0, v[0:1]
	s_addc_u32 s59, s61, s9
	s_add_i32 s60, s63, s30
	global_load_lds_dwordx4 v[232:233], off
	v_lshl_add_u64 v[238:239], s[58:59], 0, v[134:135]
	s_mov_b32 m0, s60
	v_lshl_add_u64 v[240:241], s[58:59], 0, v[0:1]
	global_load_lds_dwordx4 v[238:239], off
	s_add_i32 m0, s60, 0x2000
	v_lshl_add_u64 v[242:243], s[24:25], 0, v[136:137]
	global_load_lds_dwordx4 v[240:241], off
	s_mov_b32 m0, s31
	v_lshl_add_u64 v[244:245], s[24:25], 0, v[132:133]
	global_load_lds_dwordx4 v[242:243], off
	s_mov_b32 m0, s33
	s_nop 0
	global_load_lds_dwordx4 v[244:245], off
	s_waitcnt vmcnt(8)
	s_waitcnt lgkmcnt(0)
	s_barrier
; #define PG8_STAGE(bufoff, gbase, voff) do { _Pragma("unroll") for (int _i = 0; _i < 2; ++_i) \
;         __builtin_amdgcn_global_load_lds((const unsigned*)((const char*)(gbase) + (voff)[_i]), (PG8_LAS unsigned*)(lds + (bufoff) + ldsw + _i * 8192), 16, 0, 0); } while (0)
; #define PG8_LDA(dst, b, h) do { _Pragma("unroll") for (int m = 0; m < 4; ++m) _Pragma("unroll") for (int k = 0; k < 2; ++k) dst[m][k] = *(const PG8_LAS bf16x8*)(lds + PG8_SA(b, h) + aoff + m * 2048 + k * 1024); } while (0)
; #define PG8_LDB(dst, b, h) do { _Pragma("unroll") for (int n = 0; n < 2; ++n) _Pragma("unroll") for (int k = 0; k < 2; ++k) dst[n][k] = *(const PG8_LAS bf16x8*)(lds + PG8_SB(b, h) + boff + n * 2048 + k * 1024); } while (0)
; #define PG8_MMA(ai, bj, At, Bt) do { __builtin_amdgcn_s_setprio(1); _Pragma("unroll") for (int m = 0; m < 4; ++m) _Pragma("unroll") for (int n = 0; n < 2; ++n) _Pragma("unroll") for (int k = 0; k < 2; ++k) \
;         acc[ai][bj][m][n] = __builtin_amdgcn_mfma_f32_16x16x32_bf16(Bt[n][k], At[m][k], acc[ai][bj][m][n], 0, 0, 0); __builtin_amdgcn_s_setprio(0); } while (0)
; #define PG8_WAIT_V(n) asm volatile("s_waitcnt vmcnt(" #n ")" ::: "memory")
; #define PG8_WAIT_L(n) asm volatile("s_waitcnt lgkmcnt(" #n ")" ::: "memory")
; #define PG8_BAR __builtin_amdgcn_s_barrier()
; #define PG8_SCHED __builtin_amdgcn_sched_barrier(0)
; template <class Epi, class Sched, bool ALIGN_EPI = false, bool SP2 = false>
; __device__ __forceinline__ void gemm_phase(PG8_LAS unsigned char* lds, const Gemm g, const Sched& S, const Epi& E, int tid_in) {
;     ...
;             PG8_WAIT_V(8); PG8_WAIT_L(0); PG8_BAR; PG8_MMA(1, 0, At, B0); PG8_MMA(1, 1, At, B1); PG8_BAR; PG8_SCHED;
;             PG8_LDB(B0, 1, 0); PG8_LDB(B1, 1, 1); PG8_SCHED; PG8_LDA(At, 1, 0); PG8_STAGE(PG8_SA(0, 1), a2 + hsA, voffA);
;             PG8_WAIT_V(8); PG8_WAIT_L(0); PG8_BAR; PG8_MMA(0, 0, At, B0); PG8_MMA(0, 1, At, B1); PG8_BAR; PG8_SCHED;
	s_setprio 1
	s_waitcnt lgkmcnt(0)
	v_mfma_f32_16x16x32_bf16 v[64:67], v[148:151], v[180:183], v[64:67]
	v_mfma_f32_16x16x32_bf16 v[60:63], v[156:159], v[180:183], v[60:63]
	v_mfma_f32_16x16x32_bf16 v[48:51], v[148:151], v[188:191], v[48:51]
	v_mfma_f32_16x16x32_bf16 v[44:47], v[156:159], v[188:191], v[44:47]
	v_mfma_f32_16x16x32_bf16 v[32:35], v[148:151], v[208:211], v[32:35]
	v_mfma_f32_16x16x32_bf16 v[28:31], v[156:159], v[208:211], v[28:31]
	v_mfma_f32_16x16x32_bf16 v[16:19], v[148:151], v[216:219], v[16:19]
	v_mfma_f32_16x16x32_bf16 v[12:15], v[156:159], v[216:219], v[12:15]
	v_mfma_f32_16x16x32_bf16 v[64:67], v[152:155], v[184:187], v[64:67]
	v_mfma_f32_16x16x32_bf16 v[60:63], v[160:163], v[184:187], v[60:63]
	v_mfma_f32_16x16x32_bf16 v[48:51], v[152:155], v[204:207], v[48:51]
	v_mfma_f32_16x16x32_bf16 v[44:47], v[160:163], v[204:207], v[44:47]
	v_mfma_f32_16x16x32_bf16 v[32:35], v[152:155], v[212:215], v[32:35]
	v_mfma_f32_16x16x32_bf16 v[28:31], v[160:163], v[212:215], v[28:31]
	v_mfma_f32_16x16x32_bf16 v[16:19], v[152:155], v[220:223], v[16:19]
	v_mfma_f32_16x16x32_bf16 v[12:15], v[160:163], v[220:223], v[12:15]
	v_mfma_f32_16x16x32_bf16 v[56:59], v[164:167], v[180:183], v[56:59]
	v_mfma_f32_16x16x32_bf16 v[52:55], v[172:175], v[180:183], v[52:55]
	v_mfma_f32_16x16x32_bf16 v[40:43], v[164:167], v[188:191], v[40:43]
	v_mfma_f32_16x16x32_bf16 v[36:39], v[172:175], v[188:191], v[36:39]
	v_mfma_f32_16x16x32_bf16 v[24:27], v[164:167], v[208:211], v[24:27]
	v_mfma_f32_16x16x32_bf16 v[20:23], v[172:175], v[208:211], v[20:23]
	v_mfma_f32_16x16x32_bf16 v[8:11], v[164:167], v[216:219], v[8:11]
	v_mfma_f32_16x16x32_bf16 v[4:7], v[172:175], v[216:219], v[4:7]
	v_mfma_f32_16x16x32_bf16 v[56:59], v[168:171], v[184:187], v[56:59]
	v_mfma_f32_16x16x32_bf16 v[52:55], v[176:179], v[184:187], v[52:55]
	v_mfma_f32_16x16x32_bf16 v[40:43], v[168:171], v[204:207], v[40:43]
	v_mfma_f32_16x16x32_bf16 v[36:39], v[176:179], v[204:207], v[36:39]
	v_mfma_f32_16x16x32_bf16 v[24:27], v[168:171], v[212:215], v[24:27]
	v_mfma_f32_16x16x32_bf16 v[20:23], v[176:179], v[212:215], v[20:23]
	v_mfma_f32_16x16x32_bf16 v[8:11], v[168:171], v[220:223], v[8:11]
	v_mfma_f32_16x16x32_bf16 v[4:7], v[176:179], v[220:223], v[4:7]
	s_setprio 0
	s_barrier
	s_add_i32 s58, 0, 0x18000
	s_add_i32 s59, 0, 0x1c000
	v_add_u32_e32 v160, s58, v3
	v_add_u32_e32 v176, s59, v3
	ds_read_b128 v[148:151], v160
	ds_read_b128 v[152:155], v160 offset:1024
	ds_read_b128 v[156:159], v160 offset:2048
	ds_read_b128 v[160:163], v160 offset:3072
	ds_read_b128 v[164:167], v176
	ds_read_b128 v[168:171], v176 offset:1024
	ds_read_b128 v[172:175], v176 offset:2048
	ds_read_b128 v[176:179], v176 offset:3072
	s_add_u32 s24, s24, s6
	s_addc_u32 s25, s25, s7
	s_mov_b32 m0, s34
	v_lshl_add_u64 v[246:247], s[24:25], 0, v[136:137]
	ds_read_b128 v[180:183], v147 offset:32768
	ds_read_b128 v[184:187], v147 offset:33792
	ds_read_b128 v[188:191], v147 offset:34816
	ds_read_b128 v[204:207], v147 offset:35840
	ds_read_b128 v[208:211], v147 offset:36864
	ds_read_b128 v[212:215], v147 offset:37888
	ds_read_b128 v[216:219], v147 offset:38912
	ds_read_b128 v[220:223], v147 offset:39936
	global_load_lds_dwordx4 v[246:247], off
	v_lshl_add_u64 v[246:247], s[24:25], 0, v[132:133]
	s_mov_b32 m0, s35
	s_nop 0
	global_load_lds_dwordx4 v[246:247], off
	s_waitcnt vmcnt(8)
	s_waitcnt lgkmcnt(0)
	s_barrier
	s_setprio 1
	s_waitcnt lgkmcnt(0)
	v_mfma_f32_16x16x32_bf16 v[124:127], v[148:151], v[180:183], v[124:127]
	v_mfma_f32_16x16x32_bf16 v[128:131], v[156:159], v[180:183], v[128:131]
	v_mfma_f32_16x16x32_bf16 v[112:115], v[148:151], v[188:191], v[112:115]
	v_mfma_f32_16x16x32_bf16 v[108:111], v[156:159], v[188:191], v[108:111]
	v_mfma_f32_16x16x32_bf16 v[96:99], v[148:151], v[208:211], v[96:99]
	v_mfma_f32_16x16x32_bf16 v[92:95], v[156:159], v[208:211], v[92:95]
	v_mfma_f32_16x16x32_bf16 v[80:83], v[148:151], v[216:219], v[80:83]
	v_mfma_f32_16x16x32_bf16 v[76:79], v[156:159], v[216:219], v[76:79]
	v_mfma_f32_16x16x32_bf16 v[124:127], v[152:155], v[184:187], v[124:127]
	v_mfma_f32_16x16x32_bf16 v[128:131], v[160:163], v[184:187], v[128:131]
	v_mfma_f32_16x16x32_bf16 v[112:115], v[152:155], v[204:207], v[112:115]
	v_mfma_f32_16x16x32_bf16 v[108:111], v[160:163], v[204:207], v[108:111]
	v_mfma_f32_16x16x32_bf16 v[96:99], v[152:155], v[212:215], v[96:99]
	v_mfma_f32_16x16x32_bf16 v[92:95], v[160:163], v[212:215], v[92:95]
	v_mfma_f32_16x16x32_bf16 v[80:83], v[152:155], v[220:223], v[80:83]
	v_mfma_f32_16x16x32_bf16 v[76:79], v[160:163], v[220:223], v[76:79]
	v_mfma_f32_16x16x32_bf16 v[120:123], v[164:167], v[180:183], v[120:123]
	v_mfma_f32_16x16x32_bf16 v[116:119], v[172:175], v[180:183], v[116:119]
	v_mfma_f32_16x16x32_bf16 v[104:107], v[164:167], v[188:191], v[104:107]
	v_mfma_f32_16x16x32_bf16 v[100:103], v[172:175], v[188:191], v[100:103]
	v_mfma_f32_16x16x32_bf16 v[88:91], v[164:167], v[208:211], v[88:91]
	v_mfma_f32_16x16x32_bf16 v[84:87], v[172:175], v[208:211], v[84:87]
	v_mfma_f32_16x16x32_bf16 v[72:75], v[164:167], v[216:219], v[72:75]
	v_mfma_f32_16x16x32_bf16 v[68:71], v[172:175], v[216:219], v[68:71]
	v_mfma_f32_16x16x32_bf16 v[120:123], v[168:171], v[184:187], v[120:123]
	v_mfma_f32_16x16x32_bf16 v[116:119], v[176:179], v[184:187], v[116:119]
	v_mfma_f32_16x16x32_bf16 v[104:107], v[168:171], v[204:207], v[104:107]
	v_mfma_f32_16x16x32_bf16 v[100:103], v[176:179], v[204:207], v[100:103]
	v_mfma_f32_16x16x32_bf16 v[88:91], v[168:171], v[212:215], v[88:91]
	v_mfma_f32_16x16x32_bf16 v[84:87], v[176:179], v[212:215], v[84:87]
	v_mfma_f32_16x16x32_bf16 v[72:75], v[168:171], v[220:223], v[72:75]
	v_mfma_f32_16x16x32_bf16 v[68:71], v[176:179], v[220:223], v[68:71]
	s_setprio 0
	s_barrier
; #define PG8_STAGE(bufoff, gbase, voff) do { _Pragma("unroll") for (int _i = 0; _i < 2; ++_i) \
;         __builtin_amdgcn_global_load_lds((const unsigned*)((const char*)(gbase) + (voff)[_i]), (PG8_LAS unsigned*)(lds + (bufoff) + ldsw + _i * 8192), 16, 0, 0); } while (0)
; #define PG8_LDA(dst, b, h) do { _Pragma("unroll") for (int m = 0; m < 4; ++m) _Pragma("unroll") for (int k = 0; k < 2; ++k) dst[m][k] = *(const PG8_LAS bf16x8*)(lds + PG8_SA(b, h) + aoff + m * 2048 + k * 1024); } while (0)
; #define PG8_MMA(ai, bj, At, Bt) do { __builtin_amdgcn_s_setprio(1); _Pragma("unroll") for (int m = 0; m < 4; ++m) _Pragma("unroll") for (int n = 0; n < 2; ++n) _Pragma("unroll") for (int k = 0; k < 2; ++k) \
;         acc[ai][bj][m][n] = __builtin_amdgcn_mfma_f32_16x16x32_bf16(Bt[n][k], At[m][k], acc[ai][bj][m][n], 0, 0, 0); __builtin_amdgcn_s_setprio(0); } while (0)
; #define PG8_WAIT_V(n) asm volatile("s_waitcnt vmcnt(" #n ")" ::: "memory")
; #define PG8_WAIT_L(n) asm volatile("s_waitcnt lgkmcnt(" #n ")" ::: "memory")
; #define PG8_BAR __builtin_amdgcn_s_barrier()
; #define PG8_SCHED __builtin_amdgcn_sched_barrier(0)
; template <class Epi, class Sched, bool ALIGN_EPI = false, bool SP2 = false>
; __device__ __forceinline__ void gemm_phase(PG8_LAS unsigned char* lds, const Gemm g, const Sched& S, const Epi& E, int tid_in) {
;     ...
;         for (int t = 0; t < nt; t += 2) {
;     ...
;             PG8_LDA(At, 1, 1); PG8_STAGE(PG8_SB(1, 0), b3, voffB); PG8_STAGE(PG8_SB(1, 1), b3 + hsB, voffB); PG8_STAGE(PG8_SA(1, 0), a3, voffA);
;             PG8_WAIT_V(8); PG8_WAIT_L(0); PG8_BAR; PG8_MMA(1, 0, At, B0); PG8_MMA(1, 1, At, B1); PG8_BAR; PG8_SCHED;
	s_add_i32 s24, s58, s30
	v_lshl_add_u64 v[230:231], v[230:231], 0, s[80:81]
	s_mov_b32 m0, s24
	ds_read_b128 v[180:183], v147 offset:49152
	ds_read_b128 v[184:187], v147 offset:50176
	ds_read_b128 v[188:191], v147 offset:51200
	ds_read_b128 v[204:207], v147 offset:52224
	ds_read_b128 v[208:211], v147 offset:53248
	ds_read_b128 v[212:215], v147 offset:54272
	ds_read_b128 v[216:219], v147 offset:55296
	ds_read_b128 v[220:223], v147 offset:56320
	global_load_lds_dwordx4 v[230:231], off
	v_lshl_add_u64 v[230:231], v[232:233], 0, s[80:81]
	s_add_i32 m0, s24, 0x2000
	s_add_i32 s24, s59, s30
	global_load_lds_dwordx4 v[230:231], off
	v_lshl_add_u64 v[230:231], v[238:239], 0, s[80:81]
	s_mov_b32 m0, s24
	s_nop 0
	global_load_lds_dwordx4 v[230:231], off
	v_lshl_add_u64 v[230:231], v[240:241], 0, s[80:81]
	s_add_i32 m0, s24, 0x2000
	s_nop 0
	global_load_lds_dwordx4 v[230:231], off
	v_lshl_add_u64 v[230:231], v[242:243], 0, s[80:81]
	s_mov_b32 m0, s38
	s_nop 0
	global_load_lds_dwordx4 v[230:231], off
	v_lshl_add_u64 v[230:231], v[244:245], 0, s[80:81]
	s_mov_b32 m0, s39
	s_nop 0
	global_load_lds_dwordx4 v[230:231], off
	s_waitcnt vmcnt(8)
	s_waitcnt lgkmcnt(0)
	s_barrier
	s_setprio 1
	s_waitcnt lgkmcnt(0)
	v_mfma_f32_16x16x32_bf16 v[64:67], v[148:151], v[180:183], v[64:67]
	v_mfma_f32_16x16x32_bf16 v[60:63], v[156:159], v[180:183], v[60:63]
	v_mfma_f32_16x16x32_bf16 v[48:51], v[148:151], v[188:191], v[48:51]
	v_mfma_f32_16x16x32_bf16 v[44:47], v[156:159], v[188:191], v[44:47]
	v_mfma_f32_16x16x32_bf16 v[32:35], v[148:151], v[208:211], v[32:35]
	v_mfma_f32_16x16x32_bf16 v[28:31], v[156:159], v[208:211], v[28:31]
	v_mfma_f32_16x16x32_bf16 v[16:19], v[148:151], v[216:219], v[16:19]
	v_mfma_f32_16x16x32_bf16 v[12:15], v[156:159], v[216:219], v[12:15]
	v_mfma_f32_16x16x32_bf16 v[64:67], v[152:155], v[184:187], v[64:67]
	v_mfma_f32_16x16x32_bf16 v[60:63], v[160:163], v[184:187], v[60:63]
	v_mfma_f32_16x16x32_bf16 v[48:51], v[152:155], v[204:207], v[48:51]
	v_mfma_f32_16x16x32_bf16 v[44:47], v[160:163], v[204:207], v[44:47]
	v_mfma_f32_16x16x32_bf16 v[32:35], v[152:155], v[212:215], v[32:35]
	v_mfma_f32_16x16x32_bf16 v[28:31], v[160:163], v[212:215], v[28:31]
	v_mfma_f32_16x16x32_bf16 v[16:19], v[152:155], v[220:223], v[16:19]
	v_mfma_f32_16x16x32_bf16 v[12:15], v[160:163], v[220:223], v[12:15]
	v_mfma_f32_16x16x32_bf16 v[56:59], v[164:167], v[180:183], v[56:59]
	v_mfma_f32_16x16x32_bf16 v[52:55], v[172:175], v[180:183], v[52:55]
	v_mfma_f32_16x16x32_bf16 v[40:43], v[164:167], v[188:191], v[40:43]
	v_mfma_f32_16x16x32_bf16 v[36:39], v[172:175], v[188:191], v[36:39]
	v_mfma_f32_16x16x32_bf16 v[24:27], v[164:167], v[208:211], v[24:27]
	v_mfma_f32_16x16x32_bf16 v[20:23], v[172:175], v[208:211], v[20:23]
	v_mfma_f32_16x16x32_bf16 v[8:11], v[164:167], v[216:219], v[8:11]
	v_mfma_f32_16x16x32_bf16 v[4:7], v[172:175], v[216:219], v[4:7]
	v_mfma_f32_16x16x32_bf16 v[56:59], v[168:171], v[184:187], v[56:59]
	v_mfma_f32_16x16x32_bf16 v[52:55], v[176:179], v[184:187], v[52:55]
	v_mfma_f32_16x16x32_bf16 v[40:43], v[168:171], v[204:207], v[40:43]
	v_mfma_f32_16x16x32_bf16 v[36:39], v[176:179], v[204:207], v[36:39]
	v_mfma_f32_16x16x32_bf16 v[24:27], v[168:171], v[212:215], v[24:27]
	v_mfma_f32_16x16x32_bf16 v[20:23], v[176:179], v[212:215], v[20:23]
	v_mfma_f32_16x16x32_bf16 v[8:11], v[168:171], v[220:223], v[8:11]
	v_mfma_f32_16x16x32_bf16 v[4:7], v[176:179], v[220:223], v[4:7]
	s_setprio 0
	s_barrier
	s_add_i32 s24, s55, 2
	s_add_u32 s53, s53, 0x100
	s_addc_u32 s54, s54, 0
	s_add_u32 s22, s22, 0x100
	s_addc_u32 s23, s23, 0
	s_cmp_ge_i32 s55, s41
	s_mov_b32 s55, s24
	s_cbranch_scc0 .LBB0_352

; #define PG8_STAGE(bufoff, gbase, voff) do { _Pragma("unroll") for (int _i = 0; _i < 2; ++_i) \
;         __builtin_amdgcn_global_load_lds((const unsigned*)((const char*)(gbase) + (voff)[_i]), (PG8_LAS unsigned*)(lds + (bufoff) + ldsw + _i * 8192), 16, 0, 0); } while (0)
; #define PG8_LDA(dst, b, h) do { _Pragma("unroll") for (int m = 0; m < 4; ++m) _Pragma("unroll") for (int k = 0; k < 2; ++k) dst[m][k] = *(const PG8_LAS bf16x8*)(lds + PG8_SA(b, h) + aoff + m * 2048 + k * 1024); } while (0)
; #define PG8_LDB(dst, b, h) do { _Pragma("unroll") for (int n = 0; n < 2; ++n) _Pragma("unroll") for (int k = 0; k < 2; ++k) dst[n][k] = *(const PG8_LAS bf16x8*)(lds + PG8_SB(b, h) + boff + n * 2048 + k * 1024); } while (0)
; #define PG8_MMA(ai, bj, At, Bt) do { __builtin_amdgcn_s_setprio(1); _Pragma("unroll") for (int m = 0; m < 4; ++m) _Pragma("unroll") for (int n = 0; n < 2; ++n) _Pragma("unroll") for (int k = 0; k < 2; ++k) \
;         acc[ai][bj][m][n] = __builtin_amdgcn_mfma_f32_16x16x32_bf16(Bt[n][k], At[m][k], acc[ai][bj][m][n], 0, 0, 0); __builtin_amdgcn_s_setprio(0); } while (0)
; template <class Epi, class Sched, bool ALIGN_EPI = false, bool SP2 = false>
; __device__ __forceinline__ void gemm_phase(PG8_LAS unsigned char* lds, const Gemm g, const Sched& S, const Epi& E, int tid_in) {
;     ...
;             const bool last = (t == nt - 2);
;             if constexpr (mid_hook<Epi>::value) { if (t == Epi::H1 || t == Epi::H2) E.mid(acc, cur, wr, wc, fr, fq, t == Epi::H2); }
;             const char* a1 = cA + (size_t)(t + 1) * kstep + (t >= jt ? jb : 0);
;             const char* a2 = last ? nA : cA + (size_t)(t + 2) * kstep + (t + 2 >= jt ? jb : 0); const char* b2 = last ? nB : cB + (size_t)(t + 2) * kstep;
;             const char* a3 = a2 + kstep; const char* b3 = b2 + kstep;
;             if (last && has_next) S.a_ready(nxt);
;             if constexpr (SP2) {
;             PG8_LDB(B0, 0, 0); PG8_LDB(B1, 0, 1); PG8_SCHED; PG8_LDA(At, 0, 0); PG8_STAGE(PG8_SA(1, 1), a1 + hsA, voffA);
;             PG8_WAIT_V(8); PG8_WAIT_L(0); PG8_BAR; PG8_MMA(0, 0, At, B0); PG8_MMA(0, 1, At, B1); PG8_BAR; PG8_SCHED;
;             PG8_LDA(At, 0, 1); PG8_STAGE(PG8_SB(0, 0), b2, voffB); PG8_STAGE(PG8_SB(0, 1), b2 + hsB, voffB); PG8_STAGE(PG8_SA(0, 0), a2, voffA);
;             PG8_WAIT_V(8); PG8_WAIT_L(0); PG8_BAR; PG8_MMA(1, 0, At, B0); PG8_MMA(1, 1, At, B1); PG8_BAR; PG8_SCHED;
.LBB0_485:
	s_add_i32 s24, s53, -2
	s_cmp_ge_i32 s24, s28
	s_cselect_b32 s54, s29, 0
	s_cselect_b32 s55, s45, 0
	s_cmp_ge_i32 s53, s28
	s_cselect_b32 s25, s29, 0
	s_cselect_b32 s24, s45, 0
	s_add_u32 s25, s22, s25
	s_addc_u32 s24, s23, s24
	s_add_u32 s58, s25, 0x80
	s_addc_u32 s24, s24, 0
	s_add_i32 s60, 0, 0x10000
	s_cmp_eq_u32 s44, s53
	s_cselect_b32 s25, s5, s24
	s_cselect_b32 s24, s4, s58
	v_add_u32_e32 v145, s60, v142
	s_cselect_b32 s59, s21, s52
	s_cselect_b32 s58, s20, s51
	s_add_i32 s61, 0, 0x14000
	ds_read_b128 v[146:149], v145
	ds_read_b128 v[150:153], v145 offset:1024
	ds_read_b128 v[154:157], v145 offset:2048
	ds_read_b128 v[158:161], v145 offset:3072
	v_add_u32_e32 v145, s61, v142
	ds_read_b128 v[162:165], v145
	ds_read_b128 v[166:169], v145 offset:1024
	ds_read_b128 v[170:173], v145 offset:2048
	ds_read_b128 v[174:177], v145 offset:3072
	v_lshl_add_u64 v[190:191], s[22:23], 0, v[140:141]
	v_lshl_add_u64 v[190:191], v[190:191], 0, s[54:55]
	s_add_i32 m0, s37, 0xc000
	ds_read_b128 v[178:181], v144
	ds_read_b128 v[182:185], v144 offset:1024
	ds_read_b128 v[186:189], v144 offset:2048
	ds_read_b128 v[204:207], v144 offset:3072
	ds_read_b128 v[208:211], v144 offset:4096
	ds_read_b128 v[212:215], v144 offset:5120
	ds_read_b128 v[216:219], v144 offset:6144
	ds_read_b128 v[220:223], v144 offset:7168
	global_load_lds_dwordx4 v[190:191], off
	v_lshl_add_u64 v[190:191], s[22:23], 0, v[138:139]
	v_lshl_add_u64 v[190:191], v[190:191], 0, s[54:55]
	s_add_i32 m0, s37, 0xe000
	s_nop 0
	global_load_lds_dwordx4 v[190:191], off
	s_waitcnt vmcnt(8)
	s_waitcnt lgkmcnt(0)
	s_barrier
	s_setprio 1
	s_waitcnt lgkmcnt(0)
	v_mfma_f32_16x16x32_bf16 v[124:127], v[146:149], v[178:181], v[124:127]
	v_mfma_f32_16x16x32_bf16 v[128:131], v[154:157], v[178:181], v[128:131]
	v_mfma_f32_16x16x32_bf16 v[112:115], v[146:149], v[186:189], v[112:115]
	v_mfma_f32_16x16x32_bf16 v[108:111], v[154:157], v[186:189], v[108:111]
	v_mfma_f32_16x16x32_bf16 v[96:99], v[146:149], v[208:211], v[96:99]
	v_mfma_f32_16x16x32_bf16 v[92:95], v[154:157], v[208:211], v[92:95]
	v_mfma_f32_16x16x32_bf16 v[80:83], v[146:149], v[216:219], v[80:83]
	v_mfma_f32_16x16x32_bf16 v[76:79], v[154:157], v[216:219], v[76:79]
	v_mfma_f32_16x16x32_bf16 v[124:127], v[150:153], v[182:185], v[124:127]
	v_mfma_f32_16x16x32_bf16 v[128:131], v[158:161], v[182:185], v[128:131]
	v_mfma_f32_16x16x32_bf16 v[112:115], v[150:153], v[204:207], v[112:115]
	v_mfma_f32_16x16x32_bf16 v[108:111], v[158:161], v[204:207], v[108:111]
	v_mfma_f32_16x16x32_bf16 v[96:99], v[150:153], v[212:215], v[96:99]
	v_mfma_f32_16x16x32_bf16 v[92:95], v[158:161], v[212:215], v[92:95]
	v_mfma_f32_16x16x32_bf16 v[80:83], v[150:153], v[220:223], v[80:83]
	v_mfma_f32_16x16x32_bf16 v[76:79], v[158:161], v[220:223], v[76:79]
	v_mfma_f32_16x16x32_bf16 v[120:123], v[162:165], v[178:181], v[120:123]
	v_mfma_f32_16x16x32_bf16 v[116:119], v[170:173], v[178:181], v[116:119]
	v_mfma_f32_16x16x32_bf16 v[104:107], v[162:165], v[186:189], v[104:107]
	v_mfma_f32_16x16x32_bf16 v[100:103], v[170:173], v[186:189], v[100:103]
	v_mfma_f32_16x16x32_bf16 v[88:91], v[162:165], v[208:211], v[88:91]
	v_mfma_f32_16x16x32_bf16 v[84:87], v[170:173], v[208:211], v[84:87]
	v_mfma_f32_16x16x32_bf16 v[72:75], v[162:165], v[216:219], v[72:75]
	v_mfma_f32_16x16x32_bf16 v[68:71], v[170:173], v[216:219], v[68:71]
	v_mfma_f32_16x16x32_bf16 v[120:123], v[166:169], v[182:185], v[120:123]
	v_mfma_f32_16x16x32_bf16 v[116:119], v[174:177], v[182:185], v[116:119]
	v_mfma_f32_16x16x32_bf16 v[104:107], v[166:169], v[204:207], v[104:107]
	v_mfma_f32_16x16x32_bf16 v[100:103], v[174:177], v[204:207], v[100:103]
	v_mfma_f32_16x16x32_bf16 v[88:91], v[166:169], v[212:215], v[88:91]
	v_mfma_f32_16x16x32_bf16 v[84:87], v[174:177], v[212:215], v[84:87]
	v_mfma_f32_16x16x32_bf16 v[72:75], v[166:169], v[220:223], v[72:75]
	v_mfma_f32_16x16x32_bf16 v[68:71], v[174:177], v[220:223], v[68:71]
	s_setprio 0
	s_barrier
	s_add_i32 s54, s60, s35
	v_lshl_add_u64 v[190:191], s[58:59], 0, v[134:135]
	s_mov_b32 m0, s54
	ds_read_b128 v[178:181], v144 offset:16384
	ds_read_b128 v[182:185], v144 offset:17408
	ds_read_b128 v[186:189], v144 offset:18432
	ds_read_b128 v[204:207], v144 offset:19456
	ds_read_b128 v[208:211], v144 offset:20480
	ds_read_b128 v[212:215], v144 offset:21504
	ds_read_b128 v[216:219], v144 offset:22528
	ds_read_b128 v[220:223], v144 offset:23552
	global_load_lds_dwordx4 v[190:191], off
	s_add_i32 m0, s54, 0x2000
	s_add_u32 s54, s58, s8
	v_lshl_add_u64 v[230:231], s[58:59], 0, v[0:1]
	s_addc_u32 s55, s59, s9
	s_add_i32 s58, s61, s35
	global_load_lds_dwordx4 v[230:231], off
	v_lshl_add_u64 v[232:233], s[54:55], 0, v[134:135]
	s_mov_b32 m0, s58
	v_lshl_add_u64 v[238:239], s[54:55], 0, v[0:1]
	global_load_lds_dwordx4 v[232:233], off
	s_add_i32 m0, s58, 0x2000
	v_lshl_add_u64 v[240:241], s[24:25], 0, v[136:137]
	global_load_lds_dwordx4 v[238:239], off
	s_mov_b32 m0, s37
	v_lshl_add_u64 v[242:243], s[24:25], 0, v[132:133]
	global_load_lds_dwordx4 v[240:241], off
	s_mov_b32 m0, s38
	s_nop 0
	global_load_lds_dwordx4 v[242:243], off
	s_waitcnt vmcnt(8)
	s_waitcnt lgkmcnt(0)
	s_barrier
; #define PG8_STAGE(bufoff, gbase, voff) do { _Pragma("unroll") for (int _i = 0; _i < 2; ++_i) \
;         __builtin_amdgcn_global_load_lds((const unsigned*)((const char*)(gbase) + (voff)[_i]), (PG8_LAS unsigned*)(lds + (bufoff) + ldsw + _i * 8192), 16, 0, 0); } while (0)
; #define PG8_LDA(dst, b, h) do { _Pragma("unroll") for (int m = 0; m < 4; ++m) _Pragma("unroll") for (int k = 0; k < 2; ++k) dst[m][k] = *(const PG8_LAS bf16x8*)(lds + PG8_SA(b, h) + aoff + m * 2048 + k * 1024); } while (0)
; #define PG8_LDB(dst, b, h) do { _Pragma("unroll") for (int n = 0; n < 2; ++n) _Pragma("unroll") for (int k = 0; k < 2; ++k) dst[n][k] = *(const PG8_LAS bf16x8*)(lds + PG8_SB(b, h) + boff + n * 2048 + k * 1024); } while (0)
; #define PG8_MMA(ai, bj, At, Bt) do { __builtin_amdgcn_s_setprio(1); _Pragma("unroll") for (int m = 0; m < 4; ++m) _Pragma("unroll") for (int n = 0; n < 2; ++n) _Pragma("unroll") for (int k = 0; k < 2; ++k) \
;         acc[ai][bj][m][n] = __builtin_amdgcn_mfma_f32_16x16x32_bf16(Bt[n][k], At[m][k], acc[ai][bj][m][n], 0, 0, 0); __builtin_amdgcn_s_setprio(0); } while (0)
; #define PG8_WAIT_V(n) asm volatile("s_waitcnt vmcnt(" #n ")" ::: "memory")
; #define PG8_WAIT_L(n) asm volatile("s_waitcnt lgkmcnt(" #n ")" ::: "memory")
; #define PG8_BAR __builtin_amdgcn_s_barrier()
; #define PG8_SCHED __builtin_amdgcn_sched_barrier(0)
; template <class Epi, class Sched, bool ALIGN_EPI = false, bool SP2 = false>
; __device__ __forceinline__ void gemm_phase(PG8_LAS unsigned char* lds, const Gemm g, const Sched& S, const Epi& E, int tid_in) {
;     ...
;             PG8_WAIT_V(8); PG8_WAIT_L(0); PG8_BAR; PG8_MMA(1, 0, At, B0); PG8_MMA(1, 1, At, B1); PG8_BAR; PG8_SCHED;
;             PG8_LDB(B0, 1, 0); PG8_LDB(B1, 1, 1); PG8_SCHED; PG8_LDA(At, 1, 0); PG8_STAGE(PG8_SA(0, 1), a2 + hsA, voffA);
;             PG8_WAIT_V(8); PG8_WAIT_L(0); PG8_BAR; PG8_MMA(0, 0, At, B0); PG8_MMA(0, 1, At, B1); PG8_BAR; PG8_SCHED;
	s_setprio 1
	s_waitcnt lgkmcnt(0)
	v_mfma_f32_16x16x32_bf16 v[64:67], v[146:149], v[178:181], v[64:67]
	v_mfma_f32_16x16x32_bf16 v[60:63], v[154:157], v[178:181], v[60:63]
	v_mfma_f32_16x16x32_bf16 v[48:51], v[146:149], v[186:189], v[48:51]
	v_mfma_f32_16x16x32_bf16 v[44:47], v[154:157], v[186:189], v[44:47]
	v_mfma_f32_16x16x32_bf16 v[32:35], v[146:149], v[208:211], v[32:35]
	v_mfma_f32_16x16x32_bf16 v[28:31], v[154:157], v[208:211], v[28:31]
	v_mfma_f32_16x16x32_bf16 v[16:19], v[146:149], v[216:219], v[16:19]
	v_mfma_f32_16x16x32_bf16 v[12:15], v[154:157], v[216:219], v[12:15]
	v_mfma_f32_16x16x32_bf16 v[64:67], v[150:153], v[182:185], v[64:67]
	v_mfma_f32_16x16x32_bf16 v[60:63], v[158:161], v[182:185], v[60:63]
	v_mfma_f32_16x16x32_bf16 v[48:51], v[150:153], v[204:207], v[48:51]
	v_mfma_f32_16x16x32_bf16 v[44:47], v[158:161], v[204:207], v[44:47]
	v_mfma_f32_16x16x32_bf16 v[32:35], v[150:153], v[212:215], v[32:35]
	v_mfma_f32_16x16x32_bf16 v[28:31], v[158:161], v[212:215], v[28:31]
	v_mfma_f32_16x16x32_bf16 v[16:19], v[150:153], v[220:223], v[16:19]
	v_mfma_f32_16x16x32_bf16 v[12:15], v[158:161], v[220:223], v[12:15]
	v_mfma_f32_16x16x32_bf16 v[56:59], v[162:165], v[178:181], v[56:59]
	v_mfma_f32_16x16x32_bf16 v[52:55], v[170:173], v[178:181], v[52:55]
	v_mfma_f32_16x16x32_bf16 v[40:43], v[162:165], v[186:189], v[40:43]
	v_mfma_f32_16x16x32_bf16 v[36:39], v[170:173], v[186:189], v[36:39]
	v_mfma_f32_16x16x32_bf16 v[24:27], v[162:165], v[208:211], v[24:27]
	v_mfma_f32_16x16x32_bf16 v[20:23], v[170:173], v[208:211], v[20:23]
	v_mfma_f32_16x16x32_bf16 v[8:11], v[162:165], v[216:219], v[8:11]
	v_mfma_f32_16x16x32_bf16 v[4:7], v[170:173], v[216:219], v[4:7]
	v_mfma_f32_16x16x32_bf16 v[56:59], v[166:169], v[182:185], v[56:59]
	v_mfma_f32_16x16x32_bf16 v[52:55], v[174:177], v[182:185], v[52:55]
	v_mfma_f32_16x16x32_bf16 v[40:43], v[166:169], v[204:207], v[40:43]
	v_mfma_f32_16x16x32_bf16 v[36:39], v[174:177], v[204:207], v[36:39]
	v_mfma_f32_16x16x32_bf16 v[24:27], v[166:169], v[212:215], v[24:27]
	v_mfma_f32_16x16x32_bf16 v[20:23], v[174:177], v[212:215], v[20:23]
	v_mfma_f32_16x16x32_bf16 v[8:11], v[166:169], v[220:223], v[8:11]
	v_mfma_f32_16x16x32_bf16 v[4:7], v[174:177], v[220:223], v[4:7]
	s_setprio 0
	s_barrier
	s_add_i32 s54, 0, 0x18000
	v_add_u32_e32 v145, s54, v142
	s_add_i32 s55, 0, 0x1c000
	ds_read_b128 v[146:149], v145
	ds_read_b128 v[150:153], v145 offset:1024
	ds_read_b128 v[154:157], v145 offset:2048
	ds_read_b128 v[158:161], v145 offset:3072
	v_add_u32_e32 v145, s55, v142
	ds_read_b128 v[162:165], v145
	ds_read_b128 v[166:169], v145 offset:1024
	ds_read_b128 v[170:173], v145 offset:2048
	ds_read_b128 v[174:177], v145 offset:3072
	s_add_u32 s24, s24, s6
	s_addc_u32 s25, s25, s7
	s_mov_b32 m0, s39
	v_lshl_add_u64 v[244:245], s[24:25], 0, v[136:137]
	ds_read_b128 v[178:181], v144 offset:32768
	ds_read_b128 v[182:185], v144 offset:33792
	ds_read_b128 v[186:189], v144 offset:34816
	ds_read_b128 v[204:207], v144 offset:35840
	ds_read_b128 v[208:211], v144 offset:36864
	ds_read_b128 v[212:215], v144 offset:37888
	ds_read_b128 v[216:219], v144 offset:38912
	ds_read_b128 v[220:223], v144 offset:39936
	global_load_lds_dwordx4 v[244:245], off
	v_lshl_add_u64 v[244:245], s[24:25], 0, v[132:133]
	s_mov_b32 m0, s40
	s_nop 0
	global_load_lds_dwordx4 v[244:245], off
	s_waitcnt vmcnt(8)
	s_waitcnt lgkmcnt(0)
	s_barrier
	s_setprio 1
	s_waitcnt lgkmcnt(0)
	v_mfma_f32_16x16x32_bf16 v[124:127], v[146:149], v[178:181], v[124:127]
	v_mfma_f32_16x16x32_bf16 v[128:131], v[154:157], v[178:181], v[128:131]
	v_mfma_f32_16x16x32_bf16 v[112:115], v[146:149], v[186:189], v[112:115]
	v_mfma_f32_16x16x32_bf16 v[108:111], v[154:157], v[186:189], v[108:111]
	v_mfma_f32_16x16x32_bf16 v[96:99], v[146:149], v[208:211], v[96:99]
	v_mfma_f32_16x16x32_bf16 v[92:95], v[154:157], v[208:211], v[92:95]
	v_mfma_f32_16x16x32_bf16 v[80:83], v[146:149], v[216:219], v[80:83]
	v_mfma_f32_16x16x32_bf16 v[76:79], v[154:157], v[216:219], v[76:79]
	v_mfma_f32_16x16x32_bf16 v[124:127], v[150:153], v[182:185], v[124:127]
	v_mfma_f32_16x16x32_bf16 v[128:131], v[158:161], v[182:185], v[128:131]
	v_mfma_f32_16x16x32_bf16 v[112:115], v[150:153], v[204:207], v[112:115]
	v_mfma_f32_16x16x32_bf16 v[108:111], v[158:161], v[204:207], v[108:111]
	v_mfma_f32_16x16x32_bf16 v[96:99], v[150:153], v[212:215], v[96:99]
	v_mfma_f32_16x16x32_bf16 v[92:95], v[158:161], v[212:215], v[92:95]
	v_mfma_f32_16x16x32_bf16 v[80:83], v[150:153], v[220:223], v[80:83]
	v_mfma_f32_16x16x32_bf16 v[76:79], v[158:161], v[220:223], v[76:79]
	v_mfma_f32_16x16x32_bf16 v[120:123], v[162:165], v[178:181], v[120:123]
	v_mfma_f32_16x16x32_bf16 v[116:119], v[170:173], v[178:181], v[116:119]
	v_mfma_f32_16x16x32_bf16 v[104:107], v[162:165], v[186:189], v[104:107]
	v_mfma_f32_16x16x32_bf16 v[100:103], v[170:173], v[186:189], v[100:103]
	v_mfma_f32_16x16x32_bf16 v[88:91], v[162:165], v[208:211], v[88:91]
	v_mfma_f32_16x16x32_bf16 v[84:87], v[170:173], v[208:211], v[84:87]
	v_mfma_f32_16x16x32_bf16 v[72:75], v[162:165], v[216:219], v[72:75]
	v_mfma_f32_16x16x32_bf16 v[68:71], v[170:173], v[216:219], v[68:71]
	v_mfma_f32_16x16x32_bf16 v[120:123], v[166:169], v[182:185], v[120:123]
	v_mfma_f32_16x16x32_bf16 v[116:119], v[174:177], v[182:185], v[116:119]
	v_mfma_f32_16x16x32_bf16 v[104:107], v[166:169], v[204:207], v[104:107]
	v_mfma_f32_16x16x32_bf16 v[100:103], v[174:177], v[204:207], v[100:103]
	v_mfma_f32_16x16x32_bf16 v[88:91], v[166:169], v[212:215], v[88:91]
	v_mfma_f32_16x16x32_bf16 v[84:87], v[174:177], v[212:215], v[84:87]
	v_mfma_f32_16x16x32_bf16 v[72:75], v[166:169], v[220:223], v[72:75]
	v_mfma_f32_16x16x32_bf16 v[68:71], v[174:177], v[220:223], v[68:71]
	s_setprio 0
	s_barrier
; #define PG8_STAGE(bufoff, gbase, voff) do { _Pragma("unroll") for (int _i = 0; _i < 2; ++_i) \
;         __builtin_amdgcn_global_load_lds((const unsigned*)((const char*)(gbase) + (voff)[_i]), (PG8_LAS unsigned*)(lds + (bufoff) + ldsw + _i * 8192), 16, 0, 0); } while (0)
; #define PG8_LDA(dst, b, h) do { _Pragma("unroll") for (int m = 0; m < 4; ++m) _Pragma("unroll") for (int k = 0; k < 2; ++k) dst[m][k] = *(const PG8_LAS bf16x8*)(lds + PG8_SA(b, h) + aoff + m * 2048 + k * 1024); } while (0)
; #define PG8_MMA(ai, bj, At, Bt) do { __builtin_amdgcn_s_setprio(1); _Pragma("unroll") for (int m = 0; m < 4; ++m) _Pragma("unroll") for (int n = 0; n < 2; ++n) _Pragma("unroll") for (int k = 0; k < 2; ++k) \
;         acc[ai][bj][m][n] = __builtin_amdgcn_mfma_f32_16x16x32_bf16(Bt[n][k], At[m][k], acc[ai][bj][m][n], 0, 0, 0); __builtin_amdgcn_s_setprio(0); } while (0)
; #define PG8_WAIT_V(n) asm volatile("s_waitcnt vmcnt(" #n ")" ::: "memory")
; #define PG8_WAIT_L(n) asm volatile("s_waitcnt lgkmcnt(" #n ")" ::: "memory")
; #define PG8_BAR __builtin_amdgcn_s_barrier()
; #define PG8_SCHED __builtin_amdgcn_sched_barrier(0)
; template <class Epi, class Sched, bool ALIGN_EPI = false, bool SP2 = false>
; __device__ __forceinline__ void gemm_phase(PG8_LAS unsigned char* lds, const Gemm g, const Sched& S, const Epi& E, int tid_in) {
;     ...
;         for (int t = 0; t < nt; t += 2) {
;     ...
;             PG8_LDA(At, 1, 1); PG8_STAGE(PG8_SB(1, 0), b3, voffB); PG8_STAGE(PG8_SB(1, 1), b3 + hsB, voffB); PG8_STAGE(PG8_SA(1, 0), a3, voffA);
;             PG8_WAIT_V(8); PG8_WAIT_L(0); PG8_BAR; PG8_MMA(1, 0, At, B0); PG8_MMA(1, 1, At, B1); PG8_BAR; PG8_SCHED;
	s_add_i32 s24, s54, s35
	v_lshl_add_u64 v[190:191], v[190:191], 0, s[80:81]
	s_mov_b32 m0, s24
	ds_read_b128 v[178:181], v144 offset:49152
	ds_read_b128 v[182:185], v144 offset:50176
	ds_read_b128 v[186:189], v144 offset:51200
	ds_read_b128 v[204:207], v144 offset:52224
	ds_read_b128 v[208:211], v144 offset:53248
	ds_read_b128 v[212:215], v144 offset:54272
	ds_read_b128 v[216:219], v144 offset:55296
	ds_read_b128 v[220:223], v144 offset:56320
	global_load_lds_dwordx4 v[190:191], off
	v_lshl_add_u64 v[190:191], v[230:231], 0, s[80:81]
	s_add_i32 m0, s24, 0x2000
	s_add_i32 s24, s55, s35
	global_load_lds_dwordx4 v[190:191], off
	v_lshl_add_u64 v[190:191], v[232:233], 0, s[80:81]
	s_mov_b32 m0, s24
	s_nop 0
	global_load_lds_dwordx4 v[190:191], off
	v_lshl_add_u64 v[190:191], v[238:239], 0, s[80:81]
	s_add_i32 m0, s24, 0x2000
	s_nop 0
	global_load_lds_dwordx4 v[190:191], off
	v_lshl_add_u64 v[190:191], v[240:241], 0, s[80:81]
	s_mov_b32 m0, s41
	s_nop 0
	global_load_lds_dwordx4 v[190:191], off
	v_lshl_add_u64 v[190:191], v[242:243], 0, s[80:81]
	s_mov_b32 m0, s42
	s_nop 0
	global_load_lds_dwordx4 v[190:191], off
	s_waitcnt vmcnt(8)
	s_waitcnt lgkmcnt(0)
	s_barrier
	s_setprio 1
	s_waitcnt lgkmcnt(0)
	v_mfma_f32_16x16x32_bf16 v[64:67], v[146:149], v[178:181], v[64:67]
	v_mfma_f32_16x16x32_bf16 v[60:63], v[154:157], v[178:181], v[60:63]
	v_mfma_f32_16x16x32_bf16 v[48:51], v[146:149], v[186:189], v[48:51]
	v_mfma_f32_16x16x32_bf16 v[44:47], v[154:157], v[186:189], v[44:47]
	v_mfma_f32_16x16x32_bf16 v[32:35], v[146:149], v[208:211], v[32:35]
	v_mfma_f32_16x16x32_bf16 v[28:31], v[154:157], v[208:211], v[28:31]
	v_mfma_f32_16x16x32_bf16 v[16:19], v[146:149], v[216:219], v[16:19]
	v_mfma_f32_16x16x32_bf16 v[12:15], v[154:157], v[216:219], v[12:15]
	v_mfma_f32_16x16x32_bf16 v[64:67], v[150:153], v[182:185], v[64:67]
	v_mfma_f32_16x16x32_bf16 v[60:63], v[158:161], v[182:185], v[60:63]
	v_mfma_f32_16x16x32_bf16 v[48:51], v[150:153], v[204:207], v[48:51]
	v_mfma_f32_16x16x32_bf16 v[44:47], v[158:161], v[204:207], v[44:47]
	v_mfma_f32_16x16x32_bf16 v[32:35], v[150:153], v[212:215], v[32:35]
	v_mfma_f32_16x16x32_bf16 v[28:31], v[158:161], v[212:215], v[28:31]
	v_mfma_f32_16x16x32_bf16 v[16:19], v[150:153], v[220:223], v[16:19]
	v_mfma_f32_16x16x32_bf16 v[12:15], v[158:161], v[220:223], v[12:15]
	v_mfma_f32_16x16x32_bf16 v[56:59], v[162:165], v[178:181], v[56:59]
	v_mfma_f32_16x16x32_bf16 v[52:55], v[170:173], v[178:181], v[52:55]
	v_mfma_f32_16x16x32_bf16 v[40:43], v[162:165], v[186:189], v[40:43]
	v_mfma_f32_16x16x32_bf16 v[36:39], v[170:173], v[186:189], v[36:39]
	v_mfma_f32_16x16x32_bf16 v[24:27], v[162:165], v[208:211], v[24:27]
	v_mfma_f32_16x16x32_bf16 v[20:23], v[170:173], v[208:211], v[20:23]
	v_mfma_f32_16x16x32_bf16 v[8:11], v[162:165], v[216:219], v[8:11]
	v_mfma_f32_16x16x32_bf16 v[4:7], v[170:173], v[216:219], v[4:7]
	v_mfma_f32_16x16x32_bf16 v[56:59], v[166:169], v[182:185], v[56:59]
	v_mfma_f32_16x16x32_bf16 v[52:55], v[174:177], v[182:185], v[52:55]
	v_mfma_f32_16x16x32_bf16 v[40:43], v[166:169], v[204:207], v[40:43]
	v_mfma_f32_16x16x32_bf16 v[36:39], v[174:177], v[204:207], v[36:39]
	v_mfma_f32_16x16x32_bf16 v[24:27], v[166:169], v[212:215], v[24:27]
	v_mfma_f32_16x16x32_bf16 v[20:23], v[174:177], v[212:215], v[20:23]
	v_mfma_f32_16x16x32_bf16 v[8:11], v[166:169], v[220:223], v[8:11]
	v_mfma_f32_16x16x32_bf16 v[4:7], v[174:177], v[220:223], v[4:7]
	s_setprio 0
	s_barrier
	s_add_i32 s24, s53, 2
	s_add_u32 s51, s51, 0x100
	s_addc_u32 s52, s52, 0
	s_add_u32 s22, s22, 0x100
	s_addc_u32 s23, s23, 0
	s_cmp_ge_i32 s53, s44
	s_mov_b32 s53, s24
	s_cbranch_scc0 .LBB0_485

; #define PG8_STAGE(bufoff, gbase, voff) do { _Pragma("unroll") for (int _i = 0; _i < 2; ++_i) \
;         __builtin_amdgcn_global_load_lds((const unsigned*)((const char*)(gbase) + (voff)[_i]), (PG8_LAS unsigned*)(lds + (bufoff) + ldsw + _i * 8192), 16, 0, 0); } while (0)
; #define PG8_LDA(dst, b, h) do { _Pragma("unroll") for (int m = 0; m < 4; ++m) _Pragma("unroll") for (int k = 0; k < 2; ++k) dst[m][k] = *(const PG8_LAS bf16x8*)(lds + PG8_SA(b, h) + aoff + m * 2048 + k * 1024); } while (0)
; #define PG8_LDB(dst, b, h) do { _Pragma("unroll") for (int n = 0; n < 2; ++n) _Pragma("unroll") for (int k = 0; k < 2; ++k) dst[n][k] = *(const PG8_LAS bf16x8*)(lds + PG8_SB(b, h) + boff + n * 2048 + k * 1024); } while (0)
; #define PG8_MMA(ai, bj, At, Bt) do { __builtin_amdgcn_s_setprio(1); _Pragma("unroll") for (int m = 0; m < 4; ++m) _Pragma("unroll") for (int n = 0; n < 2; ++n) _Pragma("unroll") for (int k = 0; k < 2; ++k) \
;         acc[ai][bj][m][n] = __builtin_amdgcn_mfma_f32_16x16x32_bf16(Bt[n][k], At[m][k], acc[ai][bj][m][n], 0, 0, 0); __builtin_amdgcn_s_setprio(0); } while (0)
; template <class Epi, class Sched, bool ALIGN_EPI = false, bool SP2 = false>
; __device__ __forceinline__ void gemm_phase(PG8_LAS unsigned char* lds, const Gemm g, const Sched& S, const Epi& E, int tid_in) {
;     ...
;             const bool last = (t == nt - 2);
;             if constexpr (mid_hook<Epi>::value) { if (t == Epi::H1 || t == Epi::H2) E.mid(acc, cur, wr, wc, fr, fq, t == Epi::H2); }
;             const char* a1 = cA + (size_t)(t + 1) * kstep + (t >= jt ? jb : 0);
;             const char* a2 = last ? nA : cA + (size_t)(t + 2) * kstep + (t + 2 >= jt ? jb : 0); const char* b2 = last ? nB : cB + (size_t)(t + 2) * kstep;
;             const char* a3 = a2 + kstep; const char* b3 = b2 + kstep;
;             if (last && has_next) S.a_ready(nxt);
;             if constexpr (SP2) {
;             PG8_LDB(B0, 0, 0); PG8_LDB(B1, 0, 1); PG8_SCHED; PG8_LDA(At, 0, 0); PG8_STAGE(PG8_SA(1, 1), a1 + hsA, voffA);
;             PG8_WAIT_V(8); PG8_WAIT_L(0); PG8_BAR; PG8_MMA(0, 0, At, B0); PG8_MMA(0, 1, At, B1); PG8_BAR; PG8_SCHED;
;             PG8_LDA(At, 0, 1); PG8_STAGE(PG8_SB(0, 0), b2, voffB); PG8_STAGE(PG8_SB(0, 1), b2 + hsB, voffB); PG8_STAGE(PG8_SA(0, 0), a2, voffA);
;             PG8_WAIT_V(8); PG8_WAIT_L(0); PG8_BAR; PG8_MMA(1, 0, At, B0); PG8_MMA(1, 1, At, B1); PG8_BAR; PG8_SCHED;
.LBB0_667:
	s_add_i32 s24, s55, -2
	s_cmp_ge_i32 s24, s28
	s_cselect_b32 s58, s29, 0
	s_cselect_b32 s59, s47, 0
	s_cmp_ge_i32 s55, s28
	s_cselect_b32 s25, s29, 0
	s_cselect_b32 s24, s47, 0
	s_add_u32 s25, s22, s25
	s_addc_u32 s24, s23, s24
	s_add_u32 s60, s25, 0x80
	s_addc_u32 s24, s24, 0
	s_add_i32 s62, 0, 0x10000
	s_cmp_eq_u32 s46, s55
	s_cselect_b32 s25, s1, s24
	s_cselect_b32 s24, s0, s60
	s_cselect_b32 s61, s5, s54
	s_cselect_b32 s60, s4, s53
	s_add_i32 s63, 0, 0x14000
	v_add_u32_e32 v48, s62, v162
	v_add_u32_e32 v165, s63, v162
	ds_read_b128 v[28:31], v48
	ds_read_b128 v[32:35], v48 offset:1024
	ds_read_b128 v[44:47], v48 offset:2048
	ds_read_b128 v[48:51], v48 offset:3072
	ds_read_b128 v[158:161], v165
	ds_read_b128 v[166:169], v165 offset:1024
	ds_read_b128 v[170:173], v165 offset:2048
	ds_read_b128 v[174:177], v165 offset:3072
	v_lshl_add_u64 v[190:191], s[22:23], 0, v[156:157]
	v_lshl_add_u64 v[190:191], v[190:191], 0, s[58:59]
	s_add_i32 m0, s38, 0xc000
	ds_read_b128 v[178:181], v164
	ds_read_b128 v[182:185], v164 offset:1024
	ds_read_b128 v[186:189], v164 offset:2048
	ds_read_b128 v[204:207], v164 offset:3072
	ds_read_b128 v[208:211], v164 offset:4096
	ds_read_b128 v[212:215], v164 offset:5120
	ds_read_b128 v[216:219], v164 offset:6144
	ds_read_b128 v[220:223], v164 offset:7168
	global_load_lds_dwordx4 v[190:191], off
	v_lshl_add_u64 v[190:191], s[22:23], 0, v[154:155]
	v_lshl_add_u64 v[190:191], v[190:191], 0, s[58:59]
	s_add_i32 m0, s38, 0xe000
	s_nop 0
	global_load_lds_dwordx4 v[190:191], off
	s_waitcnt vmcnt(8)
	s_waitcnt lgkmcnt(0)
	s_barrier
	s_setprio 1
	s_waitcnt lgkmcnt(0)
	v_mfma_f32_16x16x32_bf16 v[140:143], v[28:31], v[178:181], v[140:143]
	v_mfma_f32_16x16x32_bf16 v[144:147], v[44:47], v[178:181], v[144:147]
	v_mfma_f32_16x16x32_bf16 v[128:131], v[28:31], v[186:189], v[128:131]
	v_mfma_f32_16x16x32_bf16 v[124:127], v[44:47], v[186:189], v[124:127]
	v_mfma_f32_16x16x32_bf16 v[112:115], v[28:31], v[208:211], v[112:115]
	v_mfma_f32_16x16x32_bf16 v[108:111], v[44:47], v[208:211], v[108:111]
	v_mfma_f32_16x16x32_bf16 v[96:99], v[28:31], v[216:219], v[96:99]
	v_mfma_f32_16x16x32_bf16 v[92:95], v[44:47], v[216:219], v[92:95]
	v_mfma_f32_16x16x32_bf16 v[140:143], v[32:35], v[182:185], v[140:143]
	v_mfma_f32_16x16x32_bf16 v[144:147], v[48:51], v[182:185], v[144:147]
	v_mfma_f32_16x16x32_bf16 v[128:131], v[32:35], v[204:207], v[128:131]
	v_mfma_f32_16x16x32_bf16 v[124:127], v[48:51], v[204:207], v[124:127]
	v_mfma_f32_16x16x32_bf16 v[112:115], v[32:35], v[212:215], v[112:115]
	v_mfma_f32_16x16x32_bf16 v[108:111], v[48:51], v[212:215], v[108:111]
	v_mfma_f32_16x16x32_bf16 v[96:99], v[32:35], v[220:223], v[96:99]
	v_mfma_f32_16x16x32_bf16 v[92:95], v[48:51], v[220:223], v[92:95]
	v_mfma_f32_16x16x32_bf16 v[136:139], v[158:161], v[178:181], v[136:139]
	v_mfma_f32_16x16x32_bf16 v[132:135], v[170:173], v[178:181], v[132:135]
	v_mfma_f32_16x16x32_bf16 v[120:123], v[158:161], v[186:189], v[120:123]
	v_mfma_f32_16x16x32_bf16 v[116:119], v[170:173], v[186:189], v[116:119]
	v_mfma_f32_16x16x32_bf16 v[104:107], v[158:161], v[208:211], v[104:107]
	v_mfma_f32_16x16x32_bf16 v[100:103], v[170:173], v[208:211], v[100:103]
	v_mfma_f32_16x16x32_bf16 v[88:91], v[158:161], v[216:219], v[88:91]
	v_mfma_f32_16x16x32_bf16 v[84:87], v[170:173], v[216:219], v[84:87]
	v_mfma_f32_16x16x32_bf16 v[136:139], v[166:169], v[182:185], v[136:139]
	v_mfma_f32_16x16x32_bf16 v[132:135], v[174:177], v[182:185], v[132:135]
	v_mfma_f32_16x16x32_bf16 v[120:123], v[166:169], v[204:207], v[120:123]
	v_mfma_f32_16x16x32_bf16 v[116:119], v[174:177], v[204:207], v[116:119]
	v_mfma_f32_16x16x32_bf16 v[104:107], v[166:169], v[212:215], v[104:107]
	v_mfma_f32_16x16x32_bf16 v[100:103], v[174:177], v[212:215], v[100:103]
	v_mfma_f32_16x16x32_bf16 v[88:91], v[166:169], v[220:223], v[88:91]
	v_mfma_f32_16x16x32_bf16 v[84:87], v[174:177], v[220:223], v[84:87]
	s_setprio 0
	s_barrier
	s_add_i32 s58, s62, s36
	v_lshl_add_u64 v[190:191], s[60:61], 0, v[150:151]
	s_mov_b32 m0, s58
	ds_read_b128 v[178:181], v164 offset:16384
	ds_read_b128 v[182:185], v164 offset:17408
	ds_read_b128 v[186:189], v164 offset:18432
	ds_read_b128 v[204:207], v164 offset:19456
	ds_read_b128 v[208:211], v164 offset:20480
	ds_read_b128 v[212:215], v164 offset:21504
	ds_read_b128 v[216:219], v164 offset:22528
	ds_read_b128 v[220:223], v164 offset:23552
	global_load_lds_dwordx4 v[190:191], off
	s_add_i32 m0, s58, 0x2000
	s_add_u32 s58, s60, s8
	v_lshl_add_u64 v[230:231], s[60:61], 0, v[0:1]
	s_addc_u32 s59, s61, s9
	s_add_i32 s60, s63, s36
	global_load_lds_dwordx4 v[230:231], off
	v_lshl_add_u64 v[232:233], s[58:59], 0, v[150:151]
	s_mov_b32 m0, s60
	v_lshl_add_u64 v[238:239], s[58:59], 0, v[0:1]
	global_load_lds_dwordx4 v[232:233], off
	s_add_i32 m0, s60, 0x2000
	v_lshl_add_u64 v[240:241], s[24:25], 0, v[152:153]
	global_load_lds_dwordx4 v[238:239], off
	s_mov_b32 m0, s38
	v_lshl_add_u64 v[242:243], s[24:25], 0, v[148:149]
	global_load_lds_dwordx4 v[240:241], off
	s_mov_b32 m0, s39
	s_nop 0
	global_load_lds_dwordx4 v[242:243], off
	s_waitcnt vmcnt(8)
	s_waitcnt lgkmcnt(0)
	s_barrier
; #define PG8_STAGE(bufoff, gbase, voff) do { _Pragma("unroll") for (int _i = 0; _i < 2; ++_i) \
;         __builtin_amdgcn_global_load_lds((const unsigned*)((const char*)(gbase) + (voff)[_i]), (PG8_LAS unsigned*)(lds + (bufoff) + ldsw + _i * 8192), 16, 0, 0); } while (0)
; #define PG8_LDA(dst, b, h) do { _Pragma("unroll") for (int m = 0; m < 4; ++m) _Pragma("unroll") for (int k = 0; k < 2; ++k) dst[m][k] = *(const PG8_LAS bf16x8*)(lds + PG8_SA(b, h) + aoff + m * 2048 + k * 1024); } while (0)
; #define PG8_LDB(dst, b, h) do { _Pragma("unroll") for (int n = 0; n < 2; ++n) _Pragma("unroll") for (int k = 0; k < 2; ++k) dst[n][k] = *(const PG8_LAS bf16x8*)(lds + PG8_SB(b, h) + boff + n * 2048 + k * 1024); } while (0)
; #define PG8_MMA(ai, bj, At, Bt) do { __builtin_amdgcn_s_setprio(1); _Pragma("unroll") for (int m = 0; m < 4; ++m) _Pragma("unroll") for (int n = 0; n < 2; ++n) _Pragma("unroll") for (int k = 0; k < 2; ++k) \
;         acc[ai][bj][m][n] = __builtin_amdgcn_mfma_f32_16x16x32_bf16(Bt[n][k], At[m][k], acc[ai][bj][m][n], 0, 0, 0); __builtin_amdgcn_s_setprio(0); } while (0)
; #define PG8_WAIT_V(n) asm volatile("s_waitcnt vmcnt(" #n ")" ::: "memory")
; #define PG8_WAIT_L(n) asm volatile("s_waitcnt lgkmcnt(" #n ")" ::: "memory")
; #define PG8_BAR __builtin_amdgcn_s_barrier()
; #define PG8_SCHED __builtin_amdgcn_sched_barrier(0)
; template <class Epi, class Sched, bool ALIGN_EPI = false, bool SP2 = false>
; __device__ __forceinline__ void gemm_phase(PG8_LAS unsigned char* lds, const Gemm g, const Sched& S, const Epi& E, int tid_in) {
;     ...
;             PG8_WAIT_V(8); PG8_WAIT_L(0); PG8_BAR; PG8_MMA(1, 0, At, B0); PG8_MMA(1, 1, At, B1); PG8_BAR; PG8_SCHED;
;             PG8_LDB(B0, 1, 0); PG8_LDB(B1, 1, 1); PG8_SCHED; PG8_LDA(At, 1, 0); PG8_STAGE(PG8_SA(0, 1), a2 + hsA, voffA);
;             PG8_WAIT_V(8); PG8_WAIT_L(0); PG8_BAR; PG8_MMA(0, 0, At, B0); PG8_MMA(0, 1, At, B1); PG8_BAR; PG8_SCHED;
	s_setprio 1
	s_waitcnt lgkmcnt(0)
	v_mfma_f32_16x16x32_bf16 v[80:83], v[28:31], v[178:181], v[80:83]
	v_mfma_f32_16x16x32_bf16 v[76:79], v[44:47], v[178:181], v[76:79]
	v_mfma_f32_16x16x32_bf16 v[64:67], v[28:31], v[186:189], v[64:67]
	v_mfma_f32_16x16x32_bf16 v[60:63], v[44:47], v[186:189], v[60:63]
	v_mfma_f32_16x16x32_bf16 v[40:43], v[28:31], v[208:211], v[40:43]
	v_mfma_f32_16x16x32_bf16 v[36:39], v[44:47], v[208:211], v[36:39]
	v_mfma_f32_16x16x32_bf16 v[16:19], v[28:31], v[216:219], v[16:19]
	v_mfma_f32_16x16x32_bf16 v[12:15], v[44:47], v[216:219], v[12:15]
	v_mfma_f32_16x16x32_bf16 v[80:83], v[32:35], v[182:185], v[80:83]
	v_mfma_f32_16x16x32_bf16 v[76:79], v[48:51], v[182:185], v[76:79]
	v_mfma_f32_16x16x32_bf16 v[64:67], v[32:35], v[204:207], v[64:67]
	v_mfma_f32_16x16x32_bf16 v[60:63], v[48:51], v[204:207], v[60:63]
	v_mfma_f32_16x16x32_bf16 v[40:43], v[32:35], v[212:215], v[40:43]
	v_mfma_f32_16x16x32_bf16 v[36:39], v[48:51], v[212:215], v[36:39]
	v_mfma_f32_16x16x32_bf16 v[16:19], v[32:35], v[220:223], v[16:19]
	v_mfma_f32_16x16x32_bf16 v[12:15], v[48:51], v[220:223], v[12:15]
	v_mfma_f32_16x16x32_bf16 v[24:27], v[158:161], v[208:211], v[24:27]
	v_mfma_f32_16x16x32_bf16 v[20:23], v[170:173], v[208:211], v[20:23]
	v_mfma_f32_16x16x32_bf16 v[8:11], v[158:161], v[216:219], v[8:11]
	v_mfma_f32_16x16x32_bf16 v[4:7], v[170:173], v[216:219], v[4:7]
	v_mfma_f32_16x16x32_bf16 v[28:31], v[158:161], v[178:181], v[72:75]
	v_mfma_f32_16x16x32_bf16 v[32:35], v[170:173], v[178:181], v[68:71]
	v_mfma_f32_16x16x32_bf16 v[44:47], v[158:161], v[186:189], v[56:59]
	v_mfma_f32_16x16x32_bf16 v[48:51], v[170:173], v[186:189], v[52:55]
	v_mfma_f32_16x16x32_bf16 v[24:27], v[166:169], v[212:215], v[24:27]
	v_mfma_f32_16x16x32_bf16 v[20:23], v[174:177], v[212:215], v[20:23]
	v_mfma_f32_16x16x32_bf16 v[8:11], v[166:169], v[220:223], v[8:11]
	v_mfma_f32_16x16x32_bf16 v[4:7], v[174:177], v[220:223], v[4:7]
	v_mfma_f32_16x16x32_bf16 v[28:31], v[166:169], v[182:185], v[28:31]
	v_mfma_f32_16x16x32_bf16 v[32:35], v[174:177], v[182:185], v[32:35]
	v_mfma_f32_16x16x32_bf16 v[44:47], v[166:169], v[204:207], v[44:47]
	v_mfma_f32_16x16x32_bf16 v[48:51], v[174:177], v[204:207], v[48:51]
	s_setprio 0
	s_barrier
	s_add_i32 s58, 0, 0x18000
	s_add_i32 s59, 0, 0x1c000
	v_add_u32_e32 v72, s58, v162
	v_add_u32_e32 v165, s59, v162
	ds_read_b128 v[52:55], v72
	ds_read_b128 v[56:59], v72 offset:1024
	ds_read_b128 v[68:71], v72 offset:2048
	ds_read_b128 v[72:75], v72 offset:3072
	ds_read_b128 v[158:161], v165
	ds_read_b128 v[166:169], v165 offset:1024
	ds_read_b128 v[170:173], v165 offset:2048
	ds_read_b128 v[174:177], v165 offset:3072
	s_add_u32 s24, s24, s6
	s_addc_u32 s25, s25, s7
	s_mov_b32 m0, s40
	v_lshl_add_u64 v[244:245], s[24:25], 0, v[152:153]
	ds_read_b128 v[178:181], v164 offset:32768
	ds_read_b128 v[182:185], v164 offset:33792
	ds_read_b128 v[186:189], v164 offset:34816
	ds_read_b128 v[204:207], v164 offset:35840
	ds_read_b128 v[208:211], v164 offset:36864
	ds_read_b128 v[212:215], v164 offset:37888
	ds_read_b128 v[216:219], v164 offset:38912
	ds_read_b128 v[220:223], v164 offset:39936
	global_load_lds_dwordx4 v[244:245], off
	v_lshl_add_u64 v[244:245], s[24:25], 0, v[148:149]
	s_mov_b32 m0, s41
	s_nop 0
	global_load_lds_dwordx4 v[244:245], off
	s_waitcnt vmcnt(8)
	s_waitcnt lgkmcnt(0)
	s_barrier
	s_setprio 1
	s_waitcnt lgkmcnt(0)
	v_mfma_f32_16x16x32_bf16 v[140:143], v[52:55], v[178:181], v[140:143]
	v_mfma_f32_16x16x32_bf16 v[144:147], v[68:71], v[178:181], v[144:147]
	v_mfma_f32_16x16x32_bf16 v[128:131], v[52:55], v[186:189], v[128:131]
	v_mfma_f32_16x16x32_bf16 v[124:127], v[68:71], v[186:189], v[124:127]
	v_mfma_f32_16x16x32_bf16 v[112:115], v[52:55], v[208:211], v[112:115]
	v_mfma_f32_16x16x32_bf16 v[108:111], v[68:71], v[208:211], v[108:111]
	v_mfma_f32_16x16x32_bf16 v[96:99], v[52:55], v[216:219], v[96:99]
	v_mfma_f32_16x16x32_bf16 v[92:95], v[68:71], v[216:219], v[92:95]
	v_mfma_f32_16x16x32_bf16 v[140:143], v[56:59], v[182:185], v[140:143]
	v_mfma_f32_16x16x32_bf16 v[144:147], v[72:75], v[182:185], v[144:147]
	v_mfma_f32_16x16x32_bf16 v[128:131], v[56:59], v[204:207], v[128:131]
	v_mfma_f32_16x16x32_bf16 v[124:127], v[72:75], v[204:207], v[124:127]
	v_mfma_f32_16x16x32_bf16 v[112:115], v[56:59], v[212:215], v[112:115]
	v_mfma_f32_16x16x32_bf16 v[108:111], v[72:75], v[212:215], v[108:111]
	v_mfma_f32_16x16x32_bf16 v[96:99], v[56:59], v[220:223], v[96:99]
	v_mfma_f32_16x16x32_bf16 v[92:95], v[72:75], v[220:223], v[92:95]
	v_mfma_f32_16x16x32_bf16 v[136:139], v[158:161], v[178:181], v[136:139]
	v_mfma_f32_16x16x32_bf16 v[132:135], v[170:173], v[178:181], v[132:135]
	v_mfma_f32_16x16x32_bf16 v[120:123], v[158:161], v[186:189], v[120:123]
	v_mfma_f32_16x16x32_bf16 v[116:119], v[170:173], v[186:189], v[116:119]
	v_mfma_f32_16x16x32_bf16 v[104:107], v[158:161], v[208:211], v[104:107]
	v_mfma_f32_16x16x32_bf16 v[100:103], v[170:173], v[208:211], v[100:103]
	v_mfma_f32_16x16x32_bf16 v[88:91], v[158:161], v[216:219], v[88:91]
	v_mfma_f32_16x16x32_bf16 v[84:87], v[170:173], v[216:219], v[84:87]
	v_mfma_f32_16x16x32_bf16 v[136:139], v[166:169], v[182:185], v[136:139]
	v_mfma_f32_16x16x32_bf16 v[132:135], v[174:177], v[182:185], v[132:135]
	v_mfma_f32_16x16x32_bf16 v[120:123], v[166:169], v[204:207], v[120:123]
	v_mfma_f32_16x16x32_bf16 v[116:119], v[174:177], v[204:207], v[116:119]
	v_mfma_f32_16x16x32_bf16 v[104:107], v[166:169], v[212:215], v[104:107]
	v_mfma_f32_16x16x32_bf16 v[100:103], v[174:177], v[212:215], v[100:103]
	v_mfma_f32_16x16x32_bf16 v[88:91], v[166:169], v[220:223], v[88:91]
	v_mfma_f32_16x16x32_bf16 v[84:87], v[174:177], v[220:223], v[84:87]
	s_setprio 0
	s_barrier
; #define PG8_STAGE(bufoff, gbase, voff) do { _Pragma("unroll") for (int _i = 0; _i < 2; ++_i) \
;         __builtin_amdgcn_global_load_lds((const unsigned*)((const char*)(gbase) + (voff)[_i]), (PG8_LAS unsigned*)(lds + (bufoff) + ldsw + _i * 8192), 16, 0, 0); } while (0)
; #define PG8_LDA(dst, b, h) do { _Pragma("unroll") for (int m = 0; m < 4; ++m) _Pragma("unroll") for (int k = 0; k < 2; ++k) dst[m][k] = *(const PG8_LAS bf16x8*)(lds + PG8_SA(b, h) + aoff + m * 2048 + k * 1024); } while (0)
; #define PG8_MMA(ai, bj, At, Bt) do { __builtin_amdgcn_s_setprio(1); _Pragma("unroll") for (int m = 0; m < 4; ++m) _Pragma("unroll") for (int n = 0; n < 2; ++n) _Pragma("unroll") for (int k = 0; k < 2; ++k) \
;         acc[ai][bj][m][n] = __builtin_amdgcn_mfma_f32_16x16x32_bf16(Bt[n][k], At[m][k], acc[ai][bj][m][n], 0, 0, 0); __builtin_amdgcn_s_setprio(0); } while (0)
; #define PG8_WAIT_V(n) asm volatile("s_waitcnt vmcnt(" #n ")" ::: "memory")
; #define PG8_WAIT_L(n) asm volatile("s_waitcnt lgkmcnt(" #n ")" ::: "memory")
; #define PG8_BAR __builtin_amdgcn_s_barrier()
; #define PG8_SCHED __builtin_amdgcn_sched_barrier(0)
; template <class Epi, class Sched, bool ALIGN_EPI = false, bool SP2 = false>
; __device__ __forceinline__ void gemm_phase(PG8_LAS unsigned char* lds, const Gemm g, const Sched& S, const Epi& E, int tid_in) {
;     ...
;         for (int t = 0; t < nt; t += 2) {
;     ...
;             PG8_LDA(At, 1, 1); PG8_STAGE(PG8_SB(1, 0), b3, voffB); PG8_STAGE(PG8_SB(1, 1), b3 + hsB, voffB); PG8_STAGE(PG8_SA(1, 0), a3, voffA);
;             PG8_WAIT_V(8); PG8_WAIT_L(0); PG8_BAR; PG8_MMA(1, 0, At, B0); PG8_MMA(1, 1, At, B1); PG8_BAR; PG8_SCHED;
	s_add_i32 s24, s58, s36
	v_lshl_add_u64 v[190:191], v[190:191], 0, s[80:81]
	s_mov_b32 m0, s24
	ds_read_b128 v[178:181], v164 offset:49152
	ds_read_b128 v[182:185], v164 offset:50176
	ds_read_b128 v[186:189], v164 offset:51200
	ds_read_b128 v[204:207], v164 offset:52224
	ds_read_b128 v[208:211], v164 offset:53248
	ds_read_b128 v[212:215], v164 offset:54272
	ds_read_b128 v[216:219], v164 offset:55296
	ds_read_b128 v[220:223], v164 offset:56320
	global_load_lds_dwordx4 v[190:191], off
	v_lshl_add_u64 v[190:191], v[230:231], 0, s[80:81]
	s_add_i32 m0, s24, 0x2000
	s_add_i32 s24, s59, s36
	global_load_lds_dwordx4 v[190:191], off
	v_lshl_add_u64 v[190:191], v[232:233], 0, s[80:81]
	s_mov_b32 m0, s24
	s_nop 0
	global_load_lds_dwordx4 v[190:191], off
	v_lshl_add_u64 v[190:191], v[238:239], 0, s[80:81]
	s_add_i32 m0, s24, 0x2000
	s_nop 0
	global_load_lds_dwordx4 v[190:191], off
	v_lshl_add_u64 v[190:191], v[240:241], 0, s[80:81]
	s_mov_b32 m0, s44
	s_nop 0
	global_load_lds_dwordx4 v[190:191], off
	v_lshl_add_u64 v[190:191], v[242:243], 0, s[80:81]
	s_mov_b32 m0, s45
	s_nop 0
	global_load_lds_dwordx4 v[190:191], off
	s_waitcnt vmcnt(8)
	s_waitcnt lgkmcnt(0)
	s_barrier
	s_setprio 1
	s_waitcnt lgkmcnt(0)
	v_mfma_f32_16x16x32_bf16 v[80:83], v[52:55], v[178:181], v[80:83]
	v_mfma_f32_16x16x32_bf16 v[76:79], v[68:71], v[178:181], v[76:79]
	v_mfma_f32_16x16x32_bf16 v[64:67], v[52:55], v[186:189], v[64:67]
	v_mfma_f32_16x16x32_bf16 v[60:63], v[68:71], v[186:189], v[60:63]
	v_mfma_f32_16x16x32_bf16 v[40:43], v[52:55], v[208:211], v[40:43]
	v_mfma_f32_16x16x32_bf16 v[36:39], v[68:71], v[208:211], v[36:39]
	v_mfma_f32_16x16x32_bf16 v[16:19], v[52:55], v[216:219], v[16:19]
	v_mfma_f32_16x16x32_bf16 v[12:15], v[68:71], v[216:219], v[12:15]
	v_mfma_f32_16x16x32_bf16 v[80:83], v[56:59], v[182:185], v[80:83]
	v_mfma_f32_16x16x32_bf16 v[76:79], v[72:75], v[182:185], v[76:79]
	v_mfma_f32_16x16x32_bf16 v[64:67], v[56:59], v[204:207], v[64:67]
	v_mfma_f32_16x16x32_bf16 v[60:63], v[72:75], v[204:207], v[60:63]
	v_mfma_f32_16x16x32_bf16 v[40:43], v[56:59], v[212:215], v[40:43]
	v_mfma_f32_16x16x32_bf16 v[36:39], v[72:75], v[212:215], v[36:39]
	v_mfma_f32_16x16x32_bf16 v[16:19], v[56:59], v[220:223], v[16:19]
	v_mfma_f32_16x16x32_bf16 v[12:15], v[72:75], v[220:223], v[12:15]
	v_mfma_f32_16x16x32_bf16 v[28:31], v[158:161], v[178:181], v[28:31]
	v_mfma_f32_16x16x32_bf16 v[72:75], v[166:169], v[182:185], v[28:31]
	v_mfma_f32_16x16x32_bf16 v[28:31], v[170:173], v[178:181], v[32:35]
	v_mfma_f32_16x16x32_bf16 v[68:71], v[174:177], v[182:185], v[28:31]
	v_mfma_f32_16x16x32_bf16 v[28:31], v[158:161], v[186:189], v[44:47]
	v_mfma_f32_16x16x32_bf16 v[56:59], v[166:169], v[204:207], v[28:31]
	v_mfma_f32_16x16x32_bf16 v[28:31], v[170:173], v[186:189], v[48:51]
	v_mfma_f32_16x16x32_bf16 v[24:27], v[158:161], v[208:211], v[24:27]
	v_mfma_f32_16x16x32_bf16 v[20:23], v[170:173], v[208:211], v[20:23]
	v_mfma_f32_16x16x32_bf16 v[8:11], v[158:161], v[216:219], v[8:11]
	v_mfma_f32_16x16x32_bf16 v[4:7], v[170:173], v[216:219], v[4:7]
	v_mfma_f32_16x16x32_bf16 v[52:55], v[174:177], v[204:207], v[28:31]
	v_mfma_f32_16x16x32_bf16 v[24:27], v[166:169], v[212:215], v[24:27]
	v_mfma_f32_16x16x32_bf16 v[20:23], v[174:177], v[212:215], v[20:23]
	v_mfma_f32_16x16x32_bf16 v[8:11], v[166:169], v[220:223], v[8:11]
	v_mfma_f32_16x16x32_bf16 v[4:7], v[174:177], v[220:223], v[4:7]
	s_setprio 0
	s_barrier
	s_add_i32 s24, s55, 2
	s_add_u32 s53, s53, 0x100
	s_addc_u32 s54, s54, 0
	s_add_u32 s22, s22, 0x100
	s_addc_u32 s23, s23, 0
	s_cmp_ge_i32 s55, s46
	s_mov_b32 s55, s24
	s_cbranch_scc0 .LBB0_667

; #define PG8_STAGE(bufoff, gbase, voff) do { _Pragma("unroll") for (int _i = 0; _i < 2; ++_i) \
;         __builtin_amdgcn_global_load_lds((const unsigned*)((const char*)(gbase) + (voff)[_i]), (PG8_LAS unsigned*)(lds + (bufoff) + ldsw + _i * 8192), 16, 0, 0); } while (0)
; #define PG8_LDA(dst, b, h) do { _Pragma("unroll") for (int m = 0; m < 4; ++m) _Pragma("unroll") for (int k = 0; k < 2; ++k) dst[m][k] = *(const PG8_LAS bf16x8*)(lds + PG8_SA(b, h) + aoff + m * 2048 + k * 1024); } while (0)
; #define PG8_LDB(dst, b, h) do { _Pragma("unroll") for (int n = 0; n < 2; ++n) _Pragma("unroll") for (int k = 0; k < 2; ++k) dst[n][k] = *(const PG8_LAS bf16x8*)(lds + PG8_SB(b, h) + boff + n * 2048 + k * 1024); } while (0)
; #define PG8_MMA(ai, bj, At, Bt) do { __builtin_amdgcn_s_setprio(1); _Pragma("unroll") for (int m = 0; m < 4; ++m) _Pragma("unroll") for (int n = 0; n < 2; ++n) _Pragma("unroll") for (int k = 0; k < 2; ++k) \
;         acc[ai][bj][m][n] = __builtin_amdgcn_mfma_f32_16x16x32_bf16(Bt[n][k], At[m][k], acc[ai][bj][m][n], 0, 0, 0); __builtin_amdgcn_s_setprio(0); } while (0)
; template <class Epi, class Sched, bool ALIGN_EPI = false, bool SP2 = false>
; __device__ __forceinline__ void gemm_phase(PG8_LAS unsigned char* lds, const Gemm g, const Sched& S, const Epi& E, int tid_in) {
;     ...
;             const bool last = (t == nt - 2);
;             if constexpr (mid_hook<Epi>::value) { if (t == Epi::H1 || t == Epi::H2) E.mid(acc, cur, wr, wc, fr, fq, t == Epi::H2); }
;             const char* a1 = cA + (size_t)(t + 1) * kstep + (t >= jt ? jb : 0);
;             const char* a2 = last ? nA : cA + (size_t)(t + 2) * kstep + (t + 2 >= jt ? jb : 0); const char* b2 = last ? nB : cB + (size_t)(t + 2) * kstep;
;             const char* a3 = a2 + kstep; const char* b3 = b2 + kstep;
;             if (last && has_next) S.a_ready(nxt);
;             if constexpr (SP2) {
;             PG8_LDB(B0, 0, 0); PG8_LDB(B1, 0, 1); PG8_SCHED; PG8_LDA(At, 0, 0); PG8_STAGE(PG8_SA(1, 1), a1 + hsA, voffA);
;             PG8_WAIT_V(8); PG8_WAIT_L(0); PG8_BAR; PG8_MMA(0, 0, At, B0); PG8_MMA(0, 1, At, B1); PG8_BAR; PG8_SCHED;
;             PG8_LDA(At, 0, 1); PG8_STAGE(PG8_SB(0, 0), b2, voffB); PG8_STAGE(PG8_SB(0, 1), b2 + hsB, voffB); PG8_STAGE(PG8_SA(0, 0), a2, voffA);
;             PG8_WAIT_V(8); PG8_WAIT_L(0); PG8_BAR; PG8_MMA(1, 0, At, B0); PG8_MMA(1, 1, At, B1); PG8_BAR; PG8_SCHED;
.LBB0_688:
	s_add_i32 s24, s55, -2
	s_cmp_ge_i32 s24, s28
	s_cselect_b32 s58, s29, 0
	s_cselect_b32 s59, s46, 0
	s_cmp_ge_i32 s55, s28
	s_cselect_b32 s25, s29, 0
	s_cselect_b32 s24, s46, 0
	s_add_u32 s25, s22, s25
	s_addc_u32 s24, s23, s24
	s_add_u32 s60, s25, 0x80
	s_addc_u32 s24, s24, 0
	s_add_i32 s62, 0, 0x10000
	s_cmp_eq_u32 s45, s55
	s_cselect_b32 s25, s5, s24
	s_cselect_b32 s24, s4, s60
	s_cselect_b32 s61, s21, s54
	s_cselect_b32 s60, s20, s53
	s_add_i32 s63, 0, 0x14000
	v_add_u32_e32 v88, s62, v160
	v_add_u32_e32 v158, s63, v160
	ds_read_b128 v[68:71], v88
	ds_read_b128 v[72:75], v88 offset:1024
	ds_read_b128 v[84:87], v88 offset:2048
	ds_read_b128 v[88:91], v88 offset:3072
	ds_read_b128 v[164:167], v158
	ds_read_b128 v[168:171], v158 offset:1024
	ds_read_b128 v[172:175], v158 offset:2048
	ds_read_b128 v[176:179], v158 offset:3072
	v_lshl_add_u64 v[158:159], s[22:23], 0, v[156:157]
	v_lshl_add_u64 v[158:159], v[158:159], 0, s[58:59]
	s_add_i32 m0, s37, 0xc000
	ds_read_b128 v[180:183], v162
	ds_read_b128 v[184:187], v162 offset:1024
	ds_read_b128 v[188:191], v162 offset:2048
	ds_read_b128 v[204:207], v162 offset:3072
	ds_read_b128 v[208:211], v162 offset:4096
	ds_read_b128 v[212:215], v162 offset:5120
	ds_read_b128 v[216:219], v162 offset:6144
	ds_read_b128 v[220:223], v162 offset:7168
	global_load_lds_dwordx4 v[158:159], off
	v_lshl_add_u64 v[158:159], s[22:23], 0, v[154:155]
	v_lshl_add_u64 v[158:159], v[158:159], 0, s[58:59]
	s_add_i32 m0, s37, 0xe000
	s_nop 0
	global_load_lds_dwordx4 v[158:159], off
	s_waitcnt vmcnt(8)
	s_waitcnt lgkmcnt(0)
	s_barrier
	s_setprio 1
	s_waitcnt lgkmcnt(0)
	v_mfma_f32_16x16x32_bf16 v[140:143], v[68:71], v[180:183], v[140:143]
	v_mfma_f32_16x16x32_bf16 v[144:147], v[84:87], v[180:183], v[144:147]
	v_mfma_f32_16x16x32_bf16 v[128:131], v[68:71], v[188:191], v[128:131]
	v_mfma_f32_16x16x32_bf16 v[124:127], v[84:87], v[188:191], v[124:127]
	v_mfma_f32_16x16x32_bf16 v[112:115], v[68:71], v[208:211], v[112:115]
	v_mfma_f32_16x16x32_bf16 v[108:111], v[84:87], v[208:211], v[108:111]
	v_mfma_f32_16x16x32_bf16 v[96:99], v[68:71], v[216:219], v[96:99]
	v_mfma_f32_16x16x32_bf16 v[92:95], v[84:87], v[216:219], v[92:95]
	v_mfma_f32_16x16x32_bf16 v[140:143], v[72:75], v[184:187], v[140:143]
	v_mfma_f32_16x16x32_bf16 v[144:147], v[88:91], v[184:187], v[144:147]
	v_mfma_f32_16x16x32_bf16 v[128:131], v[72:75], v[204:207], v[128:131]
	v_mfma_f32_16x16x32_bf16 v[124:127], v[88:91], v[204:207], v[124:127]
	v_mfma_f32_16x16x32_bf16 v[112:115], v[72:75], v[212:215], v[112:115]
	v_mfma_f32_16x16x32_bf16 v[108:111], v[88:91], v[212:215], v[108:111]
	v_mfma_f32_16x16x32_bf16 v[96:99], v[72:75], v[220:223], v[96:99]
	v_mfma_f32_16x16x32_bf16 v[92:95], v[88:91], v[220:223], v[92:95]
	v_mfma_f32_16x16x32_bf16 v[136:139], v[164:167], v[180:183], v[136:139]
	v_mfma_f32_16x16x32_bf16 v[132:135], v[172:175], v[180:183], v[132:135]
	v_mfma_f32_16x16x32_bf16 v[120:123], v[164:167], v[188:191], v[120:123]
	v_mfma_f32_16x16x32_bf16 v[116:119], v[172:175], v[188:191], v[116:119]
	v_mfma_f32_16x16x32_bf16 v[104:107], v[164:167], v[208:211], v[104:107]
	v_mfma_f32_16x16x32_bf16 v[100:103], v[172:175], v[208:211], v[100:103]
	v_mfma_f32_16x16x32_bf16 v[80:83], v[164:167], v[216:219], v[80:83]
	v_mfma_f32_16x16x32_bf16 v[76:79], v[172:175], v[216:219], v[76:79]
	v_mfma_f32_16x16x32_bf16 v[136:139], v[168:171], v[184:187], v[136:139]
	v_mfma_f32_16x16x32_bf16 v[132:135], v[176:179], v[184:187], v[132:135]
	v_mfma_f32_16x16x32_bf16 v[120:123], v[168:171], v[204:207], v[120:123]
	v_mfma_f32_16x16x32_bf16 v[116:119], v[176:179], v[204:207], v[116:119]
	v_mfma_f32_16x16x32_bf16 v[104:107], v[168:171], v[212:215], v[104:107]
	v_mfma_f32_16x16x32_bf16 v[100:103], v[176:179], v[212:215], v[100:103]
	v_mfma_f32_16x16x32_bf16 v[80:83], v[168:171], v[220:223], v[80:83]
	v_mfma_f32_16x16x32_bf16 v[76:79], v[176:179], v[220:223], v[76:79]
	s_setprio 0
	s_barrier
	s_add_i32 s58, s62, s35
	v_lshl_add_u64 v[158:159], s[60:61], 0, v[150:151]
	s_mov_b32 m0, s58
	ds_read_b128 v[180:183], v162 offset:16384
	ds_read_b128 v[184:187], v162 offset:17408
	ds_read_b128 v[188:191], v162 offset:18432
	ds_read_b128 v[204:207], v162 offset:19456
	ds_read_b128 v[208:211], v162 offset:20480
	ds_read_b128 v[212:215], v162 offset:21504
	ds_read_b128 v[216:219], v162 offset:22528
	ds_read_b128 v[220:223], v162 offset:23552
	global_load_lds_dwordx4 v[158:159], off
	s_add_i32 m0, s58, 0x2000
	s_add_u32 s58, s60, s6
	v_lshl_add_u64 v[230:231], s[60:61], 0, v[0:1]
	s_addc_u32 s59, s61, s7
	s_add_i32 s60, s63, s35
	global_load_lds_dwordx4 v[230:231], off
	v_lshl_add_u64 v[232:233], s[58:59], 0, v[150:151]
	s_mov_b32 m0, s60
	v_lshl_add_u64 v[238:239], s[58:59], 0, v[0:1]
	global_load_lds_dwordx4 v[232:233], off
	s_add_i32 m0, s60, 0x2000
	v_lshl_add_u64 v[240:241], s[24:25], 0, v[152:153]
	global_load_lds_dwordx4 v[238:239], off
	s_mov_b32 m0, s37
	v_lshl_add_u64 v[242:243], s[24:25], 0, v[148:149]
	global_load_lds_dwordx4 v[240:241], off
	s_mov_b32 m0, s38
	s_nop 0
	global_load_lds_dwordx4 v[242:243], off
	s_waitcnt vmcnt(8)
	s_waitcnt lgkmcnt(0)
	s_barrier
; #define PG8_STAGE(bufoff, gbase, voff) do { _Pragma("unroll") for (int _i = 0; _i < 2; ++_i) \
;         __builtin_amdgcn_global_load_lds((const unsigned*)((const char*)(gbase) + (voff)[_i]), (PG8_LAS unsigned*)(lds + (bufoff) + ldsw + _i * 8192), 16, 0, 0); } while (0)
; #define PG8_LDA(dst, b, h) do { _Pragma("unroll") for (int m = 0; m < 4; ++m) _Pragma("unroll") for (int k = 0; k < 2; ++k) dst[m][k] = *(const PG8_LAS bf16x8*)(lds + PG8_SA(b, h) + aoff + m * 2048 + k * 1024); } while (0)
; #define PG8_LDB(dst, b, h) do { _Pragma("unroll") for (int n = 0; n < 2; ++n) _Pragma("unroll") for (int k = 0; k < 2; ++k) dst[n][k] = *(const PG8_LAS bf16x8*)(lds + PG8_SB(b, h) + boff + n * 2048 + k * 1024); } while (0)
; #define PG8_MMA(ai, bj, At, Bt) do { __builtin_amdgcn_s_setprio(1); _Pragma("unroll") for (int m = 0; m < 4; ++m) _Pragma("unroll") for (int n = 0; n < 2; ++n) _Pragma("unroll") for (int k = 0; k < 2; ++k) \
;         acc[ai][bj][m][n] = __builtin_amdgcn_mfma_f32_16x16x32_bf16(Bt[n][k], At[m][k], acc[ai][bj][m][n], 0, 0, 0); __builtin_amdgcn_s_setprio(0); } while (0)
; #define PG8_WAIT_V(n) asm volatile("s_waitcnt vmcnt(" #n ")" ::: "memory")
; #define PG8_WAIT_L(n) asm volatile("s_waitcnt lgkmcnt(" #n ")" ::: "memory")
; #define PG8_BAR __builtin_amdgcn_s_barrier()
; #define PG8_SCHED __builtin_amdgcn_sched_barrier(0)
; template <class Epi, class Sched, bool ALIGN_EPI = false, bool SP2 = false>
; __device__ __forceinline__ void gemm_phase(PG8_LAS unsigned char* lds, const Gemm g, const Sched& S, const Epi& E, int tid_in) {
;     ...
;             PG8_WAIT_V(8); PG8_WAIT_L(0); PG8_BAR; PG8_MMA(1, 0, At, B0); PG8_MMA(1, 1, At, B1); PG8_BAR; PG8_SCHED;
;             PG8_LDB(B0, 1, 0); PG8_LDB(B1, 1, 1); PG8_SCHED; PG8_LDA(At, 1, 0); PG8_STAGE(PG8_SA(0, 1), a2 + hsA, voffA);
;             PG8_WAIT_V(8); PG8_WAIT_L(0); PG8_BAR; PG8_MMA(0, 0, At, B0); PG8_MMA(0, 1, At, B1); PG8_BAR; PG8_SCHED;
	s_setprio 1
	s_waitcnt lgkmcnt(0)
	v_mfma_f32_16x16x32_bf16 v[64:67], v[68:71], v[180:183], v[64:67]
	v_mfma_f32_16x16x32_bf16 v[60:63], v[84:87], v[180:183], v[60:63]
	v_mfma_f32_16x16x32_bf16 v[48:51], v[68:71], v[188:191], v[48:51]
	v_mfma_f32_16x16x32_bf16 v[44:47], v[84:87], v[188:191], v[44:47]
	v_mfma_f32_16x16x32_bf16 v[32:35], v[68:71], v[208:211], v[32:35]
	v_mfma_f32_16x16x32_bf16 v[28:31], v[84:87], v[208:211], v[28:31]
	v_mfma_f32_16x16x32_bf16 v[16:19], v[68:71], v[216:219], v[16:19]
	v_mfma_f32_16x16x32_bf16 v[12:15], v[84:87], v[216:219], v[12:15]
	v_mfma_f32_16x16x32_bf16 v[64:67], v[72:75], v[184:187], v[64:67]
	v_mfma_f32_16x16x32_bf16 v[60:63], v[88:91], v[184:187], v[60:63]
	v_mfma_f32_16x16x32_bf16 v[48:51], v[72:75], v[204:207], v[48:51]
	v_mfma_f32_16x16x32_bf16 v[44:47], v[88:91], v[204:207], v[44:47]
	v_mfma_f32_16x16x32_bf16 v[32:35], v[72:75], v[212:215], v[32:35]
	v_mfma_f32_16x16x32_bf16 v[28:31], v[88:91], v[212:215], v[28:31]
	v_mfma_f32_16x16x32_bf16 v[16:19], v[72:75], v[220:223], v[16:19]
	v_mfma_f32_16x16x32_bf16 v[12:15], v[88:91], v[220:223], v[12:15]
	v_mfma_f32_16x16x32_bf16 v[56:59], v[164:167], v[180:183], v[56:59]
	v_mfma_f32_16x16x32_bf16 v[52:55], v[172:175], v[180:183], v[52:55]
	v_mfma_f32_16x16x32_bf16 v[40:43], v[164:167], v[188:191], v[40:43]
	v_mfma_f32_16x16x32_bf16 v[36:39], v[172:175], v[188:191], v[36:39]
	v_mfma_f32_16x16x32_bf16 v[24:27], v[164:167], v[208:211], v[24:27]
	v_mfma_f32_16x16x32_bf16 v[20:23], v[172:175], v[208:211], v[20:23]
	v_mfma_f32_16x16x32_bf16 v[8:11], v[164:167], v[216:219], v[8:11]
	v_mfma_f32_16x16x32_bf16 v[4:7], v[172:175], v[216:219], v[4:7]
	v_mfma_f32_16x16x32_bf16 v[56:59], v[168:171], v[184:187], v[56:59]
	v_mfma_f32_16x16x32_bf16 v[52:55], v[176:179], v[184:187], v[52:55]
	v_mfma_f32_16x16x32_bf16 v[40:43], v[168:171], v[204:207], v[40:43]
	v_mfma_f32_16x16x32_bf16 v[36:39], v[176:179], v[204:207], v[36:39]
	v_mfma_f32_16x16x32_bf16 v[24:27], v[168:171], v[212:215], v[24:27]
	v_mfma_f32_16x16x32_bf16 v[20:23], v[176:179], v[212:215], v[20:23]
	v_mfma_f32_16x16x32_bf16 v[8:11], v[168:171], v[220:223], v[8:11]
	v_mfma_f32_16x16x32_bf16 v[4:7], v[176:179], v[220:223], v[4:7]
	s_setprio 0
	s_barrier
	s_add_i32 s58, 0, 0x18000
	s_add_i32 s59, 0, 0x1c000
	v_add_u32_e32 v88, s58, v160
	v_add_u32_e32 v163, s59, v160
	ds_read_b128 v[68:71], v88
	ds_read_b128 v[72:75], v88 offset:1024
	ds_read_b128 v[84:87], v88 offset:2048
	ds_read_b128 v[88:91], v88 offset:3072
	ds_read_b128 v[164:167], v163
	ds_read_b128 v[168:171], v163 offset:1024
	ds_read_b128 v[172:175], v163 offset:2048
	ds_read_b128 v[176:179], v163 offset:3072
	s_add_u32 s24, s24, s0
	s_addc_u32 s25, s25, s1
	s_mov_b32 m0, s39
	v_lshl_add_u64 v[244:245], s[24:25], 0, v[152:153]
	ds_read_b128 v[180:183], v162 offset:32768
	ds_read_b128 v[184:187], v162 offset:33792
	ds_read_b128 v[188:191], v162 offset:34816
	ds_read_b128 v[204:207], v162 offset:35840
	ds_read_b128 v[208:211], v162 offset:36864
	ds_read_b128 v[212:215], v162 offset:37888
	ds_read_b128 v[216:219], v162 offset:38912
	ds_read_b128 v[220:223], v162 offset:39936
	global_load_lds_dwordx4 v[244:245], off
	v_lshl_add_u64 v[244:245], s[24:25], 0, v[148:149]
	s_mov_b32 m0, s40
	s_nop 0
	global_load_lds_dwordx4 v[244:245], off
	s_waitcnt vmcnt(8)
	s_waitcnt lgkmcnt(0)
	s_barrier
	s_setprio 1
	s_waitcnt lgkmcnt(0)
	v_mfma_f32_16x16x32_bf16 v[140:143], v[68:71], v[180:183], v[140:143]
	v_mfma_f32_16x16x32_bf16 v[144:147], v[84:87], v[180:183], v[144:147]
	v_mfma_f32_16x16x32_bf16 v[128:131], v[68:71], v[188:191], v[128:131]
	v_mfma_f32_16x16x32_bf16 v[124:127], v[84:87], v[188:191], v[124:127]
	v_mfma_f32_16x16x32_bf16 v[112:115], v[68:71], v[208:211], v[112:115]
	v_mfma_f32_16x16x32_bf16 v[108:111], v[84:87], v[208:211], v[108:111]
	v_mfma_f32_16x16x32_bf16 v[96:99], v[68:71], v[216:219], v[96:99]
	v_mfma_f32_16x16x32_bf16 v[92:95], v[84:87], v[216:219], v[92:95]
	v_mfma_f32_16x16x32_bf16 v[140:143], v[72:75], v[184:187], v[140:143]
	v_mfma_f32_16x16x32_bf16 v[144:147], v[88:91], v[184:187], v[144:147]
	v_mfma_f32_16x16x32_bf16 v[128:131], v[72:75], v[204:207], v[128:131]
	v_mfma_f32_16x16x32_bf16 v[124:127], v[88:91], v[204:207], v[124:127]
	v_mfma_f32_16x16x32_bf16 v[112:115], v[72:75], v[212:215], v[112:115]
	v_mfma_f32_16x16x32_bf16 v[108:111], v[88:91], v[212:215], v[108:111]
	v_mfma_f32_16x16x32_bf16 v[96:99], v[72:75], v[220:223], v[96:99]
	v_mfma_f32_16x16x32_bf16 v[92:95], v[88:91], v[220:223], v[92:95]
	v_mfma_f32_16x16x32_bf16 v[136:139], v[164:167], v[180:183], v[136:139]
	v_mfma_f32_16x16x32_bf16 v[132:135], v[172:175], v[180:183], v[132:135]
	v_mfma_f32_16x16x32_bf16 v[120:123], v[164:167], v[188:191], v[120:123]
	v_mfma_f32_16x16x32_bf16 v[116:119], v[172:175], v[188:191], v[116:119]
	v_mfma_f32_16x16x32_bf16 v[104:107], v[164:167], v[208:211], v[104:107]
	v_mfma_f32_16x16x32_bf16 v[100:103], v[172:175], v[208:211], v[100:103]
	v_mfma_f32_16x16x32_bf16 v[80:83], v[164:167], v[216:219], v[80:83]
	v_mfma_f32_16x16x32_bf16 v[76:79], v[172:175], v[216:219], v[76:79]
	v_mfma_f32_16x16x32_bf16 v[136:139], v[168:171], v[184:187], v[136:139]
	v_mfma_f32_16x16x32_bf16 v[132:135], v[176:179], v[184:187], v[132:135]
	v_mfma_f32_16x16x32_bf16 v[120:123], v[168:171], v[204:207], v[120:123]
	v_mfma_f32_16x16x32_bf16 v[116:119], v[176:179], v[204:207], v[116:119]
	v_mfma_f32_16x16x32_bf16 v[104:107], v[168:171], v[212:215], v[104:107]
	v_mfma_f32_16x16x32_bf16 v[100:103], v[176:179], v[212:215], v[100:103]
	v_mfma_f32_16x16x32_bf16 v[80:83], v[168:171], v[220:223], v[80:83]
	v_mfma_f32_16x16x32_bf16 v[76:79], v[176:179], v[220:223], v[76:79]
	s_setprio 0
	s_barrier
; #define PG8_STAGE(bufoff, gbase, voff) do { _Pragma("unroll") for (int _i = 0; _i < 2; ++_i) \
;         __builtin_amdgcn_global_load_lds((const unsigned*)((const char*)(gbase) + (voff)[_i]), (PG8_LAS unsigned*)(lds + (bufoff) + ldsw + _i * 8192), 16, 0, 0); } while (0)
; #define PG8_LDA(dst, b, h) do { _Pragma("unroll") for (int m = 0; m < 4; ++m) _Pragma("unroll") for (int k = 0; k < 2; ++k) dst[m][k] = *(const PG8_LAS bf16x8*)(lds + PG8_SA(b, h) + aoff + m * 2048 + k * 1024); } while (0)
; #define PG8_MMA(ai, bj, At, Bt) do { __builtin_amdgcn_s_setprio(1); _Pragma("unroll") for (int m = 0; m < 4; ++m) _Pragma("unroll") for (int n = 0; n < 2; ++n) _Pragma("unroll") for (int k = 0; k < 2; ++k) \
;         acc[ai][bj][m][n] = __builtin_amdgcn_mfma_f32_16x16x32_bf16(Bt[n][k], At[m][k], acc[ai][bj][m][n], 0, 0, 0); __builtin_amdgcn_s_setprio(0); } while (0)
; #define PG8_WAIT_V(n) asm volatile("s_waitcnt vmcnt(" #n ")" ::: "memory")
; #define PG8_WAIT_L(n) asm volatile("s_waitcnt lgkmcnt(" #n ")" ::: "memory")
; #define PG8_BAR __builtin_amdgcn_s_barrier()
; #define PG8_SCHED __builtin_amdgcn_sched_barrier(0)
; template <class Epi, class Sched, bool ALIGN_EPI = false, bool SP2 = false>
; __device__ __forceinline__ void gemm_phase(PG8_LAS unsigned char* lds, const Gemm g, const Sched& S, const Epi& E, int tid_in) {
;     ...
;         for (int t = 0; t < nt; t += 2) {
;     ...
;             PG8_LDA(At, 1, 1); PG8_STAGE(PG8_SB(1, 0), b3, voffB); PG8_STAGE(PG8_SB(1, 1), b3 + hsB, voffB); PG8_STAGE(PG8_SA(1, 0), a3, voffA);
;             PG8_WAIT_V(8); PG8_WAIT_L(0); PG8_BAR; PG8_MMA(1, 0, At, B0); PG8_MMA(1, 1, At, B1); PG8_BAR; PG8_SCHED;
	s_add_i32 s24, s58, s35
	v_lshl_add_u64 v[158:159], v[158:159], 0, s[80:81]
	s_mov_b32 m0, s24
	ds_read_b128 v[180:183], v162 offset:49152
	ds_read_b128 v[184:187], v162 offset:50176
	ds_read_b128 v[188:191], v162 offset:51200
	ds_read_b128 v[204:207], v162 offset:52224
	ds_read_b128 v[208:211], v162 offset:53248
	ds_read_b128 v[212:215], v162 offset:54272
	ds_read_b128 v[216:219], v162 offset:55296
	ds_read_b128 v[220:223], v162 offset:56320
	global_load_lds_dwordx4 v[158:159], off
	v_lshl_add_u64 v[158:159], v[230:231], 0, s[80:81]
	s_add_i32 m0, s24, 0x2000
	s_add_i32 s24, s59, s35
	global_load_lds_dwordx4 v[158:159], off
	v_lshl_add_u64 v[158:159], v[232:233], 0, s[80:81]
	s_mov_b32 m0, s24
	s_nop 0
	global_load_lds_dwordx4 v[158:159], off
	v_lshl_add_u64 v[158:159], v[238:239], 0, s[80:81]
	s_add_i32 m0, s24, 0x2000
	s_nop 0
	global_load_lds_dwordx4 v[158:159], off
	v_lshl_add_u64 v[158:159], v[240:241], 0, s[80:81]
	s_mov_b32 m0, s43
	s_nop 0
	global_load_lds_dwordx4 v[158:159], off
	v_lshl_add_u64 v[158:159], v[242:243], 0, s[80:81]
	s_mov_b32 m0, s44
	s_nop 0
	global_load_lds_dwordx4 v[158:159], off
	s_waitcnt vmcnt(8)
	s_waitcnt lgkmcnt(0)
	s_barrier
	s_setprio 1
	s_waitcnt lgkmcnt(0)
	v_mfma_f32_16x16x32_bf16 v[64:67], v[68:71], v[180:183], v[64:67]
	v_mfma_f32_16x16x32_bf16 v[60:63], v[84:87], v[180:183], v[60:63]
	v_mfma_f32_16x16x32_bf16 v[48:51], v[68:71], v[188:191], v[48:51]
	v_mfma_f32_16x16x32_bf16 v[44:47], v[84:87], v[188:191], v[44:47]
	v_mfma_f32_16x16x32_bf16 v[32:35], v[68:71], v[208:211], v[32:35]
	v_mfma_f32_16x16x32_bf16 v[28:31], v[84:87], v[208:211], v[28:31]
	v_mfma_f32_16x16x32_bf16 v[16:19], v[68:71], v[216:219], v[16:19]
	v_mfma_f32_16x16x32_bf16 v[12:15], v[84:87], v[216:219], v[12:15]
	v_mfma_f32_16x16x32_bf16 v[64:67], v[72:75], v[184:187], v[64:67]
	v_mfma_f32_16x16x32_bf16 v[60:63], v[88:91], v[184:187], v[60:63]
	v_mfma_f32_16x16x32_bf16 v[48:51], v[72:75], v[204:207], v[48:51]
	v_mfma_f32_16x16x32_bf16 v[44:47], v[88:91], v[204:207], v[44:47]
	v_mfma_f32_16x16x32_bf16 v[32:35], v[72:75], v[212:215], v[32:35]
	v_mfma_f32_16x16x32_bf16 v[28:31], v[88:91], v[212:215], v[28:31]
	v_mfma_f32_16x16x32_bf16 v[16:19], v[72:75], v[220:223], v[16:19]
	v_mfma_f32_16x16x32_bf16 v[12:15], v[88:91], v[220:223], v[12:15]
	v_mfma_f32_16x16x32_bf16 v[56:59], v[164:167], v[180:183], v[56:59]
	v_mfma_f32_16x16x32_bf16 v[52:55], v[172:175], v[180:183], v[52:55]
	v_mfma_f32_16x16x32_bf16 v[40:43], v[164:167], v[188:191], v[40:43]
	v_mfma_f32_16x16x32_bf16 v[36:39], v[172:175], v[188:191], v[36:39]
	v_mfma_f32_16x16x32_bf16 v[24:27], v[164:167], v[208:211], v[24:27]
	v_mfma_f32_16x16x32_bf16 v[20:23], v[172:175], v[208:211], v[20:23]
	v_mfma_f32_16x16x32_bf16 v[8:11], v[164:167], v[216:219], v[8:11]
	v_mfma_f32_16x16x32_bf16 v[4:7], v[172:175], v[216:219], v[4:7]
	v_mfma_f32_16x16x32_bf16 v[56:59], v[168:171], v[184:187], v[56:59]
	v_mfma_f32_16x16x32_bf16 v[52:55], v[176:179], v[184:187], v[52:55]
	v_mfma_f32_16x16x32_bf16 v[40:43], v[168:171], v[204:207], v[40:43]
	v_mfma_f32_16x16x32_bf16 v[36:39], v[176:179], v[204:207], v[36:39]
	v_mfma_f32_16x16x32_bf16 v[24:27], v[168:171], v[212:215], v[24:27]
	v_mfma_f32_16x16x32_bf16 v[20:23], v[176:179], v[212:215], v[20:23]
	v_mfma_f32_16x16x32_bf16 v[8:11], v[168:171], v[220:223], v[8:11]
	v_mfma_f32_16x16x32_bf16 v[4:7], v[176:179], v[220:223], v[4:7]
	s_setprio 0
	s_barrier
	s_add_i32 s24, s55, 2
	s_add_u32 s53, s53, 0x100
	s_addc_u32 s54, s54, 0
	s_add_u32 s22, s22, 0x100
	s_addc_u32 s23, s23, 0
	s_cmp_ge_i32 s55, s45
	s_mov_b32 s55, s24
	s_cbranch_scc0 .LBB0_688

; #define PG8_STAGE(bufoff, gbase, voff) do { _Pragma("unroll") for (int _i = 0; _i < 2; ++_i) \
;         __builtin_amdgcn_global_load_lds((const unsigned*)((const char*)(gbase) + (voff)[_i]), (PG8_LAS unsigned*)(lds + (bufoff) + ldsw + _i * 8192), 16, 0, 0); } while (0)
; #define PG8_LDA(dst, b, h) do { _Pragma("unroll") for (int m = 0; m < 4; ++m) _Pragma("unroll") for (int k = 0; k < 2; ++k) dst[m][k] = *(const PG8_LAS bf16x8*)(lds + PG8_SA(b, h) + aoff + m * 2048 + k * 1024); } while (0)
; #define PG8_LDB(dst, b, h) do { _Pragma("unroll") for (int n = 0; n < 2; ++n) _Pragma("unroll") for (int k = 0; k < 2; ++k) dst[n][k] = *(const PG8_LAS bf16x8*)(lds + PG8_SB(b, h) + boff + n * 2048 + k * 1024); } while (0)
; #define PG8_MMA(ai, bj, At, Bt) do { __builtin_amdgcn_s_setprio(1); _Pragma("unroll") for (int m = 0; m < 4; ++m) _Pragma("unroll") for (int n = 0; n < 2; ++n) _Pragma("unroll") for (int k = 0; k < 2; ++k) \
;         acc[ai][bj][m][n] = __builtin_amdgcn_mfma_f32_16x16x32_bf16(Bt[n][k], At[m][k], acc[ai][bj][m][n], 0, 0, 0); __builtin_amdgcn_s_setprio(0); } while (0)
; template <class Epi, class Sched, bool ALIGN_EPI = false, bool SP2 = false>
; __device__ __forceinline__ void gemm_phase(PG8_LAS unsigned char* lds, const Gemm g, const Sched& S, const Epi& E, int tid_in) {
;     ...
;             const bool last = (t == nt - 2);
;             if constexpr (mid_hook<Epi>::value) { if (t == Epi::H1 || t == Epi::H2) E.mid(acc, cur, wr, wc, fr, fq, t == Epi::H2); }
;             const char* a1 = cA + (size_t)(t + 1) * kstep + (t >= jt ? jb : 0);
;             const char* a2 = last ? nA : cA + (size_t)(t + 2) * kstep + (t + 2 >= jt ? jb : 0); const char* b2 = last ? nB : cB + (size_t)(t + 2) * kstep;
;             const char* a3 = a2 + kstep; const char* b3 = b2 + kstep;
;             if (last && has_next) S.a_ready(nxt);
;             if constexpr (SP2) {
;             PG8_LDB(B0, 0, 0); PG8_LDB(B1, 0, 1); PG8_SCHED; PG8_LDA(At, 0, 0); PG8_STAGE(PG8_SA(1, 1), a1 + hsA, voffA);
;             PG8_WAIT_V(8); PG8_WAIT_L(0); PG8_BAR; PG8_MMA(0, 0, At, B0); PG8_MMA(0, 1, At, B1); PG8_BAR; PG8_SCHED;
;             PG8_LDA(At, 0, 1); PG8_STAGE(PG8_SB(0, 0), b2, voffB); PG8_STAGE(PG8_SB(0, 1), b2 + hsB, voffB); PG8_STAGE(PG8_SA(0, 0), a2, voffA);
;             PG8_WAIT_V(8); PG8_WAIT_L(0); PG8_BAR; PG8_MMA(1, 0, At, B0); PG8_MMA(1, 1, At, B1); PG8_BAR; PG8_SCHED;
.LBB0_709:
	s_add_i32 s24, s53, -2
	s_cmp_ge_i32 s24, s28
	s_cselect_b32 s54, s29, 0
	s_cselect_b32 s55, s44, 0
	s_cmp_ge_i32 s53, s28
	s_cselect_b32 s25, s29, 0
	s_cselect_b32 s24, s44, 0
	s_add_u32 s25, s22, s25
	s_addc_u32 s24, s23, s24
	s_add_u32 s58, s25, 0x80
	s_addc_u32 s24, s24, 0
	s_add_i32 s60, 0, 0x10000
	s_cmp_eq_u32 s43, s53
	s_cselect_b32 s25, s5, s24
	s_cselect_b32 s24, s4, s58
	v_add_u32_e32 v145, s60, v142
	s_cselect_b32 s59, s21, s52
	s_cselect_b32 s58, s20, s51
	s_add_i32 s61, 0, 0x14000
	ds_read_b128 v[146:149], v145
	ds_read_b128 v[150:153], v145 offset:1024
	ds_read_b128 v[154:157], v145 offset:2048
	ds_read_b128 v[158:161], v145 offset:3072
	v_add_u32_e32 v145, s61, v142
	ds_read_b128 v[162:165], v145
	ds_read_b128 v[166:169], v145 offset:1024
	ds_read_b128 v[170:173], v145 offset:2048
	ds_read_b128 v[174:177], v145 offset:3072
	v_lshl_add_u64 v[190:191], s[22:23], 0, v[140:141]
	v_lshl_add_u64 v[190:191], v[190:191], 0, s[54:55]
	s_add_i32 m0, s37, 0xc000
	ds_read_b128 v[178:181], v144
	ds_read_b128 v[182:185], v144 offset:1024
	ds_read_b128 v[186:189], v144 offset:2048
	ds_read_b128 v[204:207], v144 offset:3072
	ds_read_b128 v[208:211], v144 offset:4096
	ds_read_b128 v[212:215], v144 offset:5120
	ds_read_b128 v[216:219], v144 offset:6144
	ds_read_b128 v[220:223], v144 offset:7168
	global_load_lds_dwordx4 v[190:191], off
	v_lshl_add_u64 v[190:191], s[22:23], 0, v[138:139]
	v_lshl_add_u64 v[190:191], v[190:191], 0, s[54:55]
	s_add_i32 m0, s37, 0xe000
	s_nop 0
	global_load_lds_dwordx4 v[190:191], off
	s_waitcnt vmcnt(8)
	s_waitcnt lgkmcnt(0)
	s_barrier
	s_setprio 1
	s_waitcnt lgkmcnt(0)
	v_mfma_f32_16x16x32_bf16 v[124:127], v[146:149], v[178:181], v[124:127]
	v_mfma_f32_16x16x32_bf16 v[128:131], v[154:157], v[178:181], v[128:131]
	v_mfma_f32_16x16x32_bf16 v[112:115], v[146:149], v[186:189], v[112:115]
	v_mfma_f32_16x16x32_bf16 v[108:111], v[154:157], v[186:189], v[108:111]
	v_mfma_f32_16x16x32_bf16 v[96:99], v[146:149], v[208:211], v[96:99]
	v_mfma_f32_16x16x32_bf16 v[92:95], v[154:157], v[208:211], v[92:95]
	v_mfma_f32_16x16x32_bf16 v[80:83], v[146:149], v[216:219], v[80:83]
	v_mfma_f32_16x16x32_bf16 v[76:79], v[154:157], v[216:219], v[76:79]
	v_mfma_f32_16x16x32_bf16 v[124:127], v[150:153], v[182:185], v[124:127]
	v_mfma_f32_16x16x32_bf16 v[128:131], v[158:161], v[182:185], v[128:131]
	v_mfma_f32_16x16x32_bf16 v[112:115], v[150:153], v[204:207], v[112:115]
	v_mfma_f32_16x16x32_bf16 v[108:111], v[158:161], v[204:207], v[108:111]
	v_mfma_f32_16x16x32_bf16 v[96:99], v[150:153], v[212:215], v[96:99]
	v_mfma_f32_16x16x32_bf16 v[92:95], v[158:161], v[212:215], v[92:95]
	v_mfma_f32_16x16x32_bf16 v[80:83], v[150:153], v[220:223], v[80:83]
	v_mfma_f32_16x16x32_bf16 v[76:79], v[158:161], v[220:223], v[76:79]
	v_mfma_f32_16x16x32_bf16 v[120:123], v[162:165], v[178:181], v[120:123]
	v_mfma_f32_16x16x32_bf16 v[116:119], v[170:173], v[178:181], v[116:119]
	v_mfma_f32_16x16x32_bf16 v[104:107], v[162:165], v[186:189], v[104:107]
	v_mfma_f32_16x16x32_bf16 v[100:103], v[170:173], v[186:189], v[100:103]
	v_mfma_f32_16x16x32_bf16 v[88:91], v[162:165], v[208:211], v[88:91]
	v_mfma_f32_16x16x32_bf16 v[84:87], v[170:173], v[208:211], v[84:87]
	v_mfma_f32_16x16x32_bf16 v[72:75], v[162:165], v[216:219], v[72:75]
	v_mfma_f32_16x16x32_bf16 v[68:71], v[170:173], v[216:219], v[68:71]
	v_mfma_f32_16x16x32_bf16 v[120:123], v[166:169], v[182:185], v[120:123]
	v_mfma_f32_16x16x32_bf16 v[116:119], v[174:177], v[182:185], v[116:119]
	v_mfma_f32_16x16x32_bf16 v[104:107], v[166:169], v[204:207], v[104:107]
	v_mfma_f32_16x16x32_bf16 v[100:103], v[174:177], v[204:207], v[100:103]
	v_mfma_f32_16x16x32_bf16 v[88:91], v[166:169], v[212:215], v[88:91]
	v_mfma_f32_16x16x32_bf16 v[84:87], v[174:177], v[212:215], v[84:87]
	v_mfma_f32_16x16x32_bf16 v[72:75], v[166:169], v[220:223], v[72:75]
	v_mfma_f32_16x16x32_bf16 v[68:71], v[174:177], v[220:223], v[68:71]
	s_setprio 0
	s_barrier
	s_add_i32 s54, s60, s35
	v_lshl_add_u64 v[190:191], s[58:59], 0, v[134:135]
	s_mov_b32 m0, s54
	ds_read_b128 v[178:181], v144 offset:16384
	ds_read_b128 v[182:185], v144 offset:17408
	ds_read_b128 v[186:189], v144 offset:18432
	ds_read_b128 v[204:207], v144 offset:19456
	ds_read_b128 v[208:211], v144 offset:20480
	ds_read_b128 v[212:215], v144 offset:21504
	ds_read_b128 v[216:219], v144 offset:22528
	ds_read_b128 v[220:223], v144 offset:23552
	global_load_lds_dwordx4 v[190:191], off
	s_add_i32 m0, s54, 0x2000
	s_add_u32 s54, s58, s6
	v_lshl_add_u64 v[230:231], s[58:59], 0, v[0:1]
	s_addc_u32 s55, s59, s7
	s_add_i32 s58, s61, s35
	global_load_lds_dwordx4 v[230:231], off
	v_lshl_add_u64 v[232:233], s[54:55], 0, v[134:135]
	s_mov_b32 m0, s58
	v_lshl_add_u64 v[238:239], s[54:55], 0, v[0:1]
	global_load_lds_dwordx4 v[232:233], off
	s_add_i32 m0, s58, 0x2000
	v_lshl_add_u64 v[240:241], s[24:25], 0, v[136:137]
	global_load_lds_dwordx4 v[238:239], off
	s_mov_b32 m0, s37
	v_lshl_add_u64 v[242:243], s[24:25], 0, v[132:133]
	global_load_lds_dwordx4 v[240:241], off
	s_mov_b32 m0, s38
	s_nop 0
	global_load_lds_dwordx4 v[242:243], off
	s_waitcnt vmcnt(8)
	s_waitcnt lgkmcnt(0)
	s_barrier
; #define PG8_STAGE(bufoff, gbase, voff) do { _Pragma("unroll") for (int _i = 0; _i < 2; ++_i) \
;         __builtin_amdgcn_global_load_lds((const unsigned*)((const char*)(gbase) + (voff)[_i]), (PG8_LAS unsigned*)(lds + (bufoff) + ldsw + _i * 8192), 16, 0, 0); } while (0)
; #define PG8_LDA(dst, b, h) do { _Pragma("unroll") for (int m = 0; m < 4; ++m) _Pragma("unroll") for (int k = 0; k < 2; ++k) dst[m][k] = *(const PG8_LAS bf16x8*)(lds + PG8_SA(b, h) + aoff + m * 2048 + k * 1024); } while (0)
; #define PG8_LDB(dst, b, h) do { _Pragma("unroll") for (int n = 0; n < 2; ++n) _Pragma("unroll") for (int k = 0; k < 2; ++k) dst[n][k] = *(const PG8_LAS bf16x8*)(lds + PG8_SB(b, h) + boff + n * 2048 + k * 1024); } while (0)
; #define PG8_MMA(ai, bj, At, Bt) do { __builtin_amdgcn_s_setprio(1); _Pragma("unroll") for (int m = 0; m < 4; ++m) _Pragma("unroll") for (int n = 0; n < 2; ++n) _Pragma("unroll") for (int k = 0; k < 2; ++k) \
;         acc[ai][bj][m][n] = __builtin_amdgcn_mfma_f32_16x16x32_bf16(Bt[n][k], At[m][k], acc[ai][bj][m][n], 0, 0, 0); __builtin_amdgcn_s_setprio(0); } while (0)
; #define PG8_WAIT_V(n) asm volatile("s_waitcnt vmcnt(" #n ")" ::: "memory")
; #define PG8_WAIT_L(n) asm volatile("s_waitcnt lgkmcnt(" #n ")" ::: "memory")
; #define PG8_BAR __builtin_amdgcn_s_barrier()
; #define PG8_SCHED __builtin_amdgcn_sched_barrier(0)
; template <class Epi, class Sched, bool ALIGN_EPI = false, bool SP2 = false>
; __device__ __forceinline__ void gemm_phase(PG8_LAS unsigned char* lds, const Gemm g, const Sched& S, const Epi& E, int tid_in) {
;     ...
;             PG8_WAIT_V(8); PG8_WAIT_L(0); PG8_BAR; PG8_MMA(1, 0, At, B0); PG8_MMA(1, 1, At, B1); PG8_BAR; PG8_SCHED;
;             PG8_LDB(B0, 1, 0); PG8_LDB(B1, 1, 1); PG8_SCHED; PG8_LDA(At, 1, 0); PG8_STAGE(PG8_SA(0, 1), a2 + hsA, voffA);
;             PG8_WAIT_V(8); PG8_WAIT_L(0); PG8_BAR; PG8_MMA(0, 0, At, B0); PG8_MMA(0, 1, At, B1); PG8_BAR; PG8_SCHED;
	s_setprio 1
	s_waitcnt lgkmcnt(0)
	v_mfma_f32_16x16x32_bf16 v[64:67], v[146:149], v[178:181], v[64:67]
	v_mfma_f32_16x16x32_bf16 v[60:63], v[154:157], v[178:181], v[60:63]
	v_mfma_f32_16x16x32_bf16 v[48:51], v[146:149], v[186:189], v[48:51]
	v_mfma_f32_16x16x32_bf16 v[44:47], v[154:157], v[186:189], v[44:47]
	v_mfma_f32_16x16x32_bf16 v[32:35], v[146:149], v[208:211], v[32:35]
	v_mfma_f32_16x16x32_bf16 v[28:31], v[154:157], v[208:211], v[28:31]
	v_mfma_f32_16x16x32_bf16 v[16:19], v[146:149], v[216:219], v[16:19]
	v_mfma_f32_16x16x32_bf16 v[12:15], v[154:157], v[216:219], v[12:15]
	v_mfma_f32_16x16x32_bf16 v[64:67], v[150:153], v[182:185], v[64:67]
	v_mfma_f32_16x16x32_bf16 v[60:63], v[158:161], v[182:185], v[60:63]
	v_mfma_f32_16x16x32_bf16 v[48:51], v[150:153], v[204:207], v[48:51]
	v_mfma_f32_16x16x32_bf16 v[44:47], v[158:161], v[204:207], v[44:47]
	v_mfma_f32_16x16x32_bf16 v[32:35], v[150:153], v[212:215], v[32:35]
	v_mfma_f32_16x16x32_bf16 v[28:31], v[158:161], v[212:215], v[28:31]
	v_mfma_f32_16x16x32_bf16 v[16:19], v[150:153], v[220:223], v[16:19]
	v_mfma_f32_16x16x32_bf16 v[12:15], v[158:161], v[220:223], v[12:15]
	v_mfma_f32_16x16x32_bf16 v[56:59], v[162:165], v[178:181], v[56:59]
	v_mfma_f32_16x16x32_bf16 v[52:55], v[170:173], v[178:181], v[52:55]
	v_mfma_f32_16x16x32_bf16 v[40:43], v[162:165], v[186:189], v[40:43]
	v_mfma_f32_16x16x32_bf16 v[36:39], v[170:173], v[186:189], v[36:39]
	v_mfma_f32_16x16x32_bf16 v[24:27], v[162:165], v[208:211], v[24:27]
	v_mfma_f32_16x16x32_bf16 v[20:23], v[170:173], v[208:211], v[20:23]
	v_mfma_f32_16x16x32_bf16 v[8:11], v[162:165], v[216:219], v[8:11]
	v_mfma_f32_16x16x32_bf16 v[4:7], v[170:173], v[216:219], v[4:7]
	v_mfma_f32_16x16x32_bf16 v[56:59], v[166:169], v[182:185], v[56:59]
	v_mfma_f32_16x16x32_bf16 v[52:55], v[174:177], v[182:185], v[52:55]
	v_mfma_f32_16x16x32_bf16 v[40:43], v[166:169], v[204:207], v[40:43]
	v_mfma_f32_16x16x32_bf16 v[36:39], v[174:177], v[204:207], v[36:39]
	v_mfma_f32_16x16x32_bf16 v[24:27], v[166:169], v[212:215], v[24:27]
	v_mfma_f32_16x16x32_bf16 v[20:23], v[174:177], v[212:215], v[20:23]
	v_mfma_f32_16x16x32_bf16 v[8:11], v[166:169], v[220:223], v[8:11]
	v_mfma_f32_16x16x32_bf16 v[4:7], v[174:177], v[220:223], v[4:7]
	s_setprio 0
	s_barrier
	s_add_i32 s54, 0, 0x18000
	v_add_u32_e32 v145, s54, v142
	s_add_i32 s55, 0, 0x1c000
	ds_read_b128 v[146:149], v145
	ds_read_b128 v[150:153], v145 offset:1024
	ds_read_b128 v[154:157], v145 offset:2048
	ds_read_b128 v[158:161], v145 offset:3072
	v_add_u32_e32 v145, s55, v142
	ds_read_b128 v[162:165], v145
	ds_read_b128 v[166:169], v145 offset:1024
	ds_read_b128 v[170:173], v145 offset:2048
	ds_read_b128 v[174:177], v145 offset:3072
	s_add_u32 s24, s24, s0
	s_addc_u32 s25, s25, s1
	s_mov_b32 m0, s39
	v_lshl_add_u64 v[244:245], s[24:25], 0, v[136:137]
	ds_read_b128 v[178:181], v144 offset:32768
	ds_read_b128 v[182:185], v144 offset:33792
	ds_read_b128 v[186:189], v144 offset:34816
	ds_read_b128 v[204:207], v144 offset:35840
	ds_read_b128 v[208:211], v144 offset:36864
	ds_read_b128 v[212:215], v144 offset:37888
	ds_read_b128 v[216:219], v144 offset:38912
	ds_read_b128 v[220:223], v144 offset:39936
	global_load_lds_dwordx4 v[244:245], off
	v_lshl_add_u64 v[244:245], s[24:25], 0, v[132:133]
	s_mov_b32 m0, s40
	s_nop 0
	global_load_lds_dwordx4 v[244:245], off
	s_waitcnt vmcnt(8)
	s_waitcnt lgkmcnt(0)
	s_barrier
	s_setprio 1
	s_waitcnt lgkmcnt(0)
	v_mfma_f32_16x16x32_bf16 v[124:127], v[146:149], v[178:181], v[124:127]
	v_mfma_f32_16x16x32_bf16 v[128:131], v[154:157], v[178:181], v[128:131]
	v_mfma_f32_16x16x32_bf16 v[112:115], v[146:149], v[186:189], v[112:115]
	v_mfma_f32_16x16x32_bf16 v[108:111], v[154:157], v[186:189], v[108:111]
	v_mfma_f32_16x16x32_bf16 v[96:99], v[146:149], v[208:211], v[96:99]
	v_mfma_f32_16x16x32_bf16 v[92:95], v[154:157], v[208:211], v[92:95]
	v_mfma_f32_16x16x32_bf16 v[80:83], v[146:149], v[216:219], v[80:83]
	v_mfma_f32_16x16x32_bf16 v[76:79], v[154:157], v[216:219], v[76:79]
	v_mfma_f32_16x16x32_bf16 v[124:127], v[150:153], v[182:185], v[124:127]
	v_mfma_f32_16x16x32_bf16 v[128:131], v[158:161], v[182:185], v[128:131]
	v_mfma_f32_16x16x32_bf16 v[112:115], v[150:153], v[204:207], v[112:115]
	v_mfma_f32_16x16x32_bf16 v[108:111], v[158:161], v[204:207], v[108:111]
	v_mfma_f32_16x16x32_bf16 v[96:99], v[150:153], v[212:215], v[96:99]
	v_mfma_f32_16x16x32_bf16 v[92:95], v[158:161], v[212:215], v[92:95]
	v_mfma_f32_16x16x32_bf16 v[80:83], v[150:153], v[220:223], v[80:83]
	v_mfma_f32_16x16x32_bf16 v[76:79], v[158:161], v[220:223], v[76:79]
	v_mfma_f32_16x16x32_bf16 v[120:123], v[162:165], v[178:181], v[120:123]
	v_mfma_f32_16x16x32_bf16 v[116:119], v[170:173], v[178:181], v[116:119]
	v_mfma_f32_16x16x32_bf16 v[104:107], v[162:165], v[186:189], v[104:107]
	v_mfma_f32_16x16x32_bf16 v[100:103], v[170:173], v[186:189], v[100:103]
	v_mfma_f32_16x16x32_bf16 v[88:91], v[162:165], v[208:211], v[88:91]
	v_mfma_f32_16x16x32_bf16 v[84:87], v[170:173], v[208:211], v[84:87]
	v_mfma_f32_16x16x32_bf16 v[72:75], v[162:165], v[216:219], v[72:75]
	v_mfma_f32_16x16x32_bf16 v[68:71], v[170:173], v[216:219], v[68:71]
	v_mfma_f32_16x16x32_bf16 v[120:123], v[166:169], v[182:185], v[120:123]
	v_mfma_f32_16x16x32_bf16 v[116:119], v[174:177], v[182:185], v[116:119]
	v_mfma_f32_16x16x32_bf16 v[104:107], v[166:169], v[204:207], v[104:107]
	v_mfma_f32_16x16x32_bf16 v[100:103], v[174:177], v[204:207], v[100:103]
	v_mfma_f32_16x16x32_bf16 v[88:91], v[166:169], v[212:215], v[88:91]
	v_mfma_f32_16x16x32_bf16 v[84:87], v[174:177], v[212:215], v[84:87]
	v_mfma_f32_16x16x32_bf16 v[72:75], v[166:169], v[220:223], v[72:75]
	v_mfma_f32_16x16x32_bf16 v[68:71], v[174:177], v[220:223], v[68:71]
	s_setprio 0
	s_barrier
; #define PG8_STAGE(bufoff, gbase, voff) do { _Pragma("unroll") for (int _i = 0; _i < 2; ++_i) \
;         __builtin_amdgcn_global_load_lds((const unsigned*)((const char*)(gbase) + (voff)[_i]), (PG8_LAS unsigned*)(lds + (bufoff) + ldsw + _i * 8192), 16, 0, 0); } while (0)
; #define PG8_LDA(dst, b, h) do { _Pragma("unroll") for (int m = 0; m < 4; ++m) _Pragma("unroll") for (int k = 0; k < 2; ++k) dst[m][k] = *(const PG8_LAS bf16x8*)(lds + PG8_SA(b, h) + aoff + m * 2048 + k * 1024); } while (0)
; #define PG8_MMA(ai, bj, At, Bt) do { __builtin_amdgcn_s_setprio(1); _Pragma("unroll") for (int m = 0; m < 4; ++m) _Pragma("unroll") for (int n = 0; n < 2; ++n) _Pragma("unroll") for (int k = 0; k < 2; ++k) \
;         acc[ai][bj][m][n] = __builtin_amdgcn_mfma_f32_16x16x32_bf16(Bt[n][k], At[m][k], acc[ai][bj][m][n], 0, 0, 0); __builtin_amdgcn_s_setprio(0); } while (0)
; #define PG8_WAIT_V(n) asm volatile("s_waitcnt vmcnt(" #n ")" ::: "memory")
; #define PG8_WAIT_L(n) asm volatile("s_waitcnt lgkmcnt(" #n ")" ::: "memory")
; #define PG8_BAR __builtin_amdgcn_s_barrier()
; #define PG8_SCHED __builtin_amdgcn_sched_barrier(0)
; template <class Epi, class Sched, bool ALIGN_EPI = false, bool SP2 = false>
; __device__ __forceinline__ void gemm_phase(PG8_LAS unsigned char* lds, const Gemm g, const Sched& S, const Epi& E, int tid_in) {
;     ...
;         for (int t = 0; t < nt; t += 2) {
;     ...
;             PG8_LDA(At, 1, 1); PG8_STAGE(PG8_SB(1, 0), b3, voffB); PG8_STAGE(PG8_SB(1, 1), b3 + hsB, voffB); PG8_STAGE(PG8_SA(1, 0), a3, voffA);
;             PG8_WAIT_V(8); PG8_WAIT_L(0); PG8_BAR; PG8_MMA(1, 0, At, B0); PG8_MMA(1, 1, At, B1); PG8_BAR; PG8_SCHED;
	s_add_i32 s24, s54, s35
	v_lshl_add_u64 v[190:191], v[190:191], 0, s[80:81]
	s_mov_b32 m0, s24
	ds_read_b128 v[178:181], v144 offset:49152
	ds_read_b128 v[182:185], v144 offset:50176
	ds_read_b128 v[186:189], v144 offset:51200
	ds_read_b128 v[204:207], v144 offset:52224
	ds_read_b128 v[208:211], v144 offset:53248
	ds_read_b128 v[212:215], v144 offset:54272
	ds_read_b128 v[216:219], v144 offset:55296
	ds_read_b128 v[220:223], v144 offset:56320
	global_load_lds_dwordx4 v[190:191], off
	v_lshl_add_u64 v[190:191], v[230:231], 0, s[80:81]
	s_add_i32 m0, s24, 0x2000
	s_add_i32 s24, s55, s35
	global_load_lds_dwordx4 v[190:191], off
	v_lshl_add_u64 v[190:191], v[232:233], 0, s[80:81]
	s_mov_b32 m0, s24
	s_nop 0
	global_load_lds_dwordx4 v[190:191], off
	v_lshl_add_u64 v[190:191], v[238:239], 0, s[80:81]
	s_add_i32 m0, s24, 0x2000
	s_nop 0
	global_load_lds_dwordx4 v[190:191], off
	v_lshl_add_u64 v[190:191], v[240:241], 0, s[80:81]
	s_mov_b32 m0, s41
	s_nop 0
	global_load_lds_dwordx4 v[190:191], off
	v_lshl_add_u64 v[190:191], v[242:243], 0, s[80:81]
	s_mov_b32 m0, s42
	s_nop 0
	global_load_lds_dwordx4 v[190:191], off
	s_waitcnt vmcnt(8)
	s_waitcnt lgkmcnt(0)
	s_barrier
	s_setprio 1
	s_waitcnt lgkmcnt(0)
	v_mfma_f32_16x16x32_bf16 v[64:67], v[146:149], v[178:181], v[64:67]
	v_mfma_f32_16x16x32_bf16 v[60:63], v[154:157], v[178:181], v[60:63]
	v_mfma_f32_16x16x32_bf16 v[48:51], v[146:149], v[186:189], v[48:51]
	v_mfma_f32_16x16x32_bf16 v[44:47], v[154:157], v[186:189], v[44:47]
	v_mfma_f32_16x16x32_bf16 v[32:35], v[146:149], v[208:211], v[32:35]
	v_mfma_f32_16x16x32_bf16 v[28:31], v[154:157], v[208:211], v[28:31]
	v_mfma_f32_16x16x32_bf16 v[16:19], v[146:149], v[216:219], v[16:19]
	v_mfma_f32_16x16x32_bf16 v[12:15], v[154:157], v[216:219], v[12:15]
	v_mfma_f32_16x16x32_bf16 v[64:67], v[150:153], v[182:185], v[64:67]
	v_mfma_f32_16x16x32_bf16 v[60:63], v[158:161], v[182:185], v[60:63]
	v_mfma_f32_16x16x32_bf16 v[48:51], v[150:153], v[204:207], v[48:51]
	v_mfma_f32_16x16x32_bf16 v[44:47], v[158:161], v[204:207], v[44:47]
	v_mfma_f32_16x16x32_bf16 v[32:35], v[150:153], v[212:215], v[32:35]
	v_mfma_f32_16x16x32_bf16 v[28:31], v[158:161], v[212:215], v[28:31]
	v_mfma_f32_16x16x32_bf16 v[16:19], v[150:153], v[220:223], v[16:19]
	v_mfma_f32_16x16x32_bf16 v[12:15], v[158:161], v[220:223], v[12:15]
	v_mfma_f32_16x16x32_bf16 v[56:59], v[162:165], v[178:181], v[56:59]
	v_mfma_f32_16x16x32_bf16 v[52:55], v[170:173], v[178:181], v[52:55]
	v_mfma_f32_16x16x32_bf16 v[40:43], v[162:165], v[186:189], v[40:43]
	v_mfma_f32_16x16x32_bf16 v[36:39], v[170:173], v[186:189], v[36:39]
	v_mfma_f32_16x16x32_bf16 v[24:27], v[162:165], v[208:211], v[24:27]
	v_mfma_f32_16x16x32_bf16 v[20:23], v[170:173], v[208:211], v[20:23]
	v_mfma_f32_16x16x32_bf16 v[8:11], v[162:165], v[216:219], v[8:11]
	v_mfma_f32_16x16x32_bf16 v[4:7], v[170:173], v[216:219], v[4:7]
	v_mfma_f32_16x16x32_bf16 v[56:59], v[166:169], v[182:185], v[56:59]
	v_mfma_f32_16x16x32_bf16 v[52:55], v[174:177], v[182:185], v[52:55]
	v_mfma_f32_16x16x32_bf16 v[40:43], v[166:169], v[204:207], v[40:43]
	v_mfma_f32_16x16x32_bf16 v[36:39], v[174:177], v[204:207], v[36:39]
	v_mfma_f32_16x16x32_bf16 v[24:27], v[166:169], v[212:215], v[24:27]
	v_mfma_f32_16x16x32_bf16 v[20:23], v[174:177], v[212:215], v[20:23]
	v_mfma_f32_16x16x32_bf16 v[8:11], v[166:169], v[220:223], v[8:11]
	v_mfma_f32_16x16x32_bf16 v[4:7], v[174:177], v[220:223], v[4:7]
	s_setprio 0
	s_barrier
	s_add_i32 s24, s53, 2
	s_add_u32 s51, s51, 0x100
	s_addc_u32 s52, s52, 0
	s_add_u32 s22, s22, 0x100
	s_addc_u32 s23, s23, 0
	s_cmp_ge_i32 s53, s43
	s_mov_b32 s53, s24
	s_cbranch_scc0 .LBB0_709

; #define PG8_STAGE(bufoff, gbase, voff) do { _Pragma("unroll") for (int _i = 0; _i < 2; ++_i) \
;         __builtin_amdgcn_global_load_lds((const unsigned*)((const char*)(gbase) + (voff)[_i]), (PG8_LAS unsigned*)(lds + (bufoff) + ldsw + _i * 8192), 16, 0, 0); } while (0)
; #define PG8_LDA(dst, b, h) do { _Pragma("unroll") for (int m = 0; m < 4; ++m) _Pragma("unroll") for (int k = 0; k < 2; ++k) dst[m][k] = *(const PG8_LAS bf16x8*)(lds + PG8_SA(b, h) + aoff + m * 2048 + k * 1024); } while (0)
; #define PG8_LDB(dst, b, h) do { _Pragma("unroll") for (int n = 0; n < 2; ++n) _Pragma("unroll") for (int k = 0; k < 2; ++k) dst[n][k] = *(const PG8_LAS bf16x8*)(lds + PG8_SB(b, h) + boff + n * 2048 + k * 1024); } while (0)
; #define PG8_MMA(ai, bj, At, Bt) do { __builtin_amdgcn_s_setprio(1); _Pragma("unroll") for (int m = 0; m < 4; ++m) _Pragma("unroll") for (int n = 0; n < 2; ++n) _Pragma("unroll") for (int k = 0; k < 2; ++k) \
;         acc[ai][bj][m][n] = __builtin_amdgcn_mfma_f32_16x16x32_bf16(Bt[n][k], At[m][k], acc[ai][bj][m][n], 0, 0, 0); __builtin_amdgcn_s_setprio(0); } while (0)
; template <class Epi, class Sched, bool ALIGN_EPI = false, bool SP2 = false>
; __device__ __forceinline__ void gemm_phase(PG8_LAS unsigned char* lds, const Gemm g, const Sched& S, const Epi& E, int tid_in) {
;     ...
;             const bool last = (t == nt - 2);
;             if constexpr (mid_hook<Epi>::value) { if (t == Epi::H1 || t == Epi::H2) E.mid(acc, cur, wr, wc, fr, fq, t == Epi::H2); }
;             const char* a1 = cA + (size_t)(t + 1) * kstep + (t >= jt ? jb : 0);
;             const char* a2 = last ? nA : cA + (size_t)(t + 2) * kstep + (t + 2 >= jt ? jb : 0); const char* b2 = last ? nB : cB + (size_t)(t + 2) * kstep;
;             const char* a3 = a2 + kstep; const char* b3 = b2 + kstep;
;             if (last && has_next) S.a_ready(nxt);
;             if constexpr (SP2) {
;             PG8_LDB(B0, 0, 0); PG8_LDB(B1, 0, 1); PG8_SCHED; PG8_LDA(At, 0, 0); PG8_STAGE(PG8_SA(1, 1), a1 + hsA, voffA);
;             PG8_WAIT_V(8); PG8_WAIT_L(0); PG8_BAR; PG8_MMA(0, 0, At, B0); PG8_MMA(0, 1, At, B1); PG8_BAR; PG8_SCHED;
;             PG8_LDA(At, 0, 1); PG8_STAGE(PG8_SB(0, 0), b2, voffB); PG8_STAGE(PG8_SB(0, 1), b2 + hsB, voffB); PG8_STAGE(PG8_SA(0, 0), a2, voffA);
;             PG8_WAIT_V(8); PG8_WAIT_L(0); PG8_BAR; PG8_MMA(1, 0, At, B0); PG8_MMA(1, 1, At, B1); PG8_BAR; PG8_SCHED;
.LBB0_924:
	s_add_i32 s24, s58, -2
	s_cmp_ge_i32 s24, s29
	s_cselect_b32 s60, s30, 0
	s_cselect_b32 s61, s47, 0
	s_cmp_ge_i32 s58, s29
	s_cselect_b32 s25, s30, 0
	s_cselect_b32 s24, s47, 0
	s_add_u32 s25, s22, s25
	s_addc_u32 s24, s23, s24
	s_add_u32 s59, s25, 0x80
	s_addc_u32 s24, s24, 0
	s_add_i32 s64, 0, 0x10000
	s_cmp_eq_u32 s46, s58
	s_cselect_b32 s25, s5, s24
	s_cselect_b32 s24, s4, s59
	v_add_u32_e32 v142, s64, v144
	s_cselect_b32 s63, s21, s55
	s_cselect_b32 s62, s20, s54
	s_add_i32 s59, 0, 0x14000
	ds_read_b128 v[148:151], v142
	ds_read_b128 v[152:155], v142 offset:1024
	ds_read_b128 v[156:159], v142 offset:2048
	ds_read_b128 v[160:163], v142 offset:3072
	v_add_u32_e32 v142, s59, v144
	ds_read_b128 v[164:167], v142
	ds_read_b128 v[168:171], v142 offset:1024
	ds_read_b128 v[172:175], v142 offset:2048
	ds_read_b128 v[176:179], v142 offset:3072
	v_lshl_add_u64 v[142:143], s[22:23], 0, v[140:141]
	v_lshl_add_u64 v[142:143], v[142:143], 0, s[60:61]
	s_add_i32 m0, s40, 0xc000
	ds_read_b128 v[180:183], v146
	ds_read_b128 v[184:187], v146 offset:1024
	ds_read_b128 v[188:191], v146 offset:2048
	ds_read_b128 v[204:207], v146 offset:3072
	ds_read_b128 v[208:211], v146 offset:4096
	ds_read_b128 v[212:215], v146 offset:5120
	ds_read_b128 v[216:219], v146 offset:6144
	ds_read_b128 v[220:223], v146 offset:7168
	global_load_lds_dwordx4 v[142:143], off
	v_lshl_add_u64 v[142:143], s[22:23], 0, v[138:139]
	v_lshl_add_u64 v[142:143], v[142:143], 0, s[60:61]
	s_add_i32 m0, s40, 0xe000
	s_nop 0
	global_load_lds_dwordx4 v[142:143], off
	s_waitcnt vmcnt(8)
	s_waitcnt lgkmcnt(0)
	s_barrier
	s_setprio 1
	s_waitcnt lgkmcnt(0)
	v_mfma_f32_16x16x32_bf16 v[128:131], v[148:151], v[180:183], v[128:131]
	v_mfma_f32_16x16x32_bf16 v[124:127], v[156:159], v[180:183], v[124:127]
	v_mfma_f32_16x16x32_bf16 v[112:115], v[148:151], v[188:191], v[112:115]
	v_mfma_f32_16x16x32_bf16 v[108:111], v[156:159], v[188:191], v[108:111]
	v_mfma_f32_16x16x32_bf16 v[96:99], v[148:151], v[208:211], v[96:99]
	v_mfma_f32_16x16x32_bf16 v[92:95], v[156:159], v[208:211], v[92:95]
	v_mfma_f32_16x16x32_bf16 v[80:83], v[148:151], v[216:219], v[80:83]
	v_mfma_f32_16x16x32_bf16 v[76:79], v[156:159], v[216:219], v[76:79]
	v_mfma_f32_16x16x32_bf16 v[128:131], v[152:155], v[184:187], v[128:131]
	v_mfma_f32_16x16x32_bf16 v[124:127], v[160:163], v[184:187], v[124:127]
	v_mfma_f32_16x16x32_bf16 v[112:115], v[152:155], v[204:207], v[112:115]
	v_mfma_f32_16x16x32_bf16 v[108:111], v[160:163], v[204:207], v[108:111]
	v_mfma_f32_16x16x32_bf16 v[96:99], v[152:155], v[212:215], v[96:99]
	v_mfma_f32_16x16x32_bf16 v[92:95], v[160:163], v[212:215], v[92:95]
	v_mfma_f32_16x16x32_bf16 v[80:83], v[152:155], v[220:223], v[80:83]
	v_mfma_f32_16x16x32_bf16 v[76:79], v[160:163], v[220:223], v[76:79]
	v_mfma_f32_16x16x32_bf16 v[120:123], v[164:167], v[180:183], v[120:123]
	v_mfma_f32_16x16x32_bf16 v[116:119], v[172:175], v[180:183], v[116:119]
	v_mfma_f32_16x16x32_bf16 v[104:107], v[164:167], v[188:191], v[104:107]
	v_mfma_f32_16x16x32_bf16 v[100:103], v[172:175], v[188:191], v[100:103]
	v_mfma_f32_16x16x32_bf16 v[88:91], v[164:167], v[208:211], v[88:91]
	v_mfma_f32_16x16x32_bf16 v[84:87], v[172:175], v[208:211], v[84:87]
	v_mfma_f32_16x16x32_bf16 v[72:75], v[164:167], v[216:219], v[72:75]
	v_mfma_f32_16x16x32_bf16 v[68:71], v[172:175], v[216:219], v[68:71]
	v_mfma_f32_16x16x32_bf16 v[120:123], v[168:171], v[184:187], v[120:123]
	v_mfma_f32_16x16x32_bf16 v[116:119], v[176:179], v[184:187], v[116:119]
	v_mfma_f32_16x16x32_bf16 v[104:107], v[168:171], v[204:207], v[104:107]
	v_mfma_f32_16x16x32_bf16 v[100:103], v[176:179], v[204:207], v[100:103]
	v_mfma_f32_16x16x32_bf16 v[88:91], v[168:171], v[212:215], v[88:91]
	v_mfma_f32_16x16x32_bf16 v[84:87], v[176:179], v[212:215], v[84:87]
	v_mfma_f32_16x16x32_bf16 v[72:75], v[168:171], v[220:223], v[72:75]
	v_mfma_f32_16x16x32_bf16 v[68:71], v[176:179], v[220:223], v[68:71]
	s_setprio 0
	s_barrier
	s_add_i32 s60, s64, s34
	v_lshl_add_u64 v[142:143], s[62:63], 0, v[134:135]
	s_mov_b32 m0, s60
	ds_read_b128 v[180:183], v146 offset:16384
	ds_read_b128 v[184:187], v146 offset:17408
	ds_read_b128 v[188:191], v146 offset:18432
	ds_read_b128 v[204:207], v146 offset:19456
	ds_read_b128 v[208:211], v146 offset:20480
	ds_read_b128 v[212:215], v146 offset:21504
	ds_read_b128 v[216:219], v146 offset:22528
	ds_read_b128 v[220:223], v146 offset:23552
	global_load_lds_dwordx4 v[142:143], off
	s_add_i32 m0, s60, 0x2000
	s_add_u32 s60, s62, s8
	v_lshl_add_u64 v[196:197], s[62:63], 0, v[0:1]
	s_addc_u32 s61, s63, s9
	s_add_i32 s59, s59, s34
	global_load_lds_dwordx4 v[196:197], off
	v_lshl_add_u64 v[198:199], s[60:61], 0, v[134:135]
	s_mov_b32 m0, s59
	v_lshl_add_u64 v[200:201], s[60:61], 0, v[0:1]
	global_load_lds_dwordx4 v[198:199], off
	s_add_i32 m0, s59, 0x2000
	v_lshl_add_u64 v[228:229], s[24:25], 0, v[136:137]
	global_load_lds_dwordx4 v[200:201], off
	s_mov_b32 m0, s40
	v_lshl_add_u64 v[230:231], s[24:25], 0, v[132:133]
	global_load_lds_dwordx4 v[228:229], off
	s_mov_b32 m0, s41
	s_nop 0
	global_load_lds_dwordx4 v[230:231], off
	s_waitcnt vmcnt(8)
	s_waitcnt lgkmcnt(0)
	s_barrier
; #define PG8_STAGE(bufoff, gbase, voff) do { _Pragma("unroll") for (int _i = 0; _i < 2; ++_i) \
;         __builtin_amdgcn_global_load_lds((const unsigned*)((const char*)(gbase) + (voff)[_i]), (PG8_LAS unsigned*)(lds + (bufoff) + ldsw + _i * 8192), 16, 0, 0); } while (0)
; #define PG8_LDA(dst, b, h) do { _Pragma("unroll") for (int m = 0; m < 4; ++m) _Pragma("unroll") for (int k = 0; k < 2; ++k) dst[m][k] = *(const PG8_LAS bf16x8*)(lds + PG8_SA(b, h) + aoff + m * 2048 + k * 1024); } while (0)
; #define PG8_LDB(dst, b, h) do { _Pragma("unroll") for (int n = 0; n < 2; ++n) _Pragma("unroll") for (int k = 0; k < 2; ++k) dst[n][k] = *(const PG8_LAS bf16x8*)(lds + PG8_SB(b, h) + boff + n * 2048 + k * 1024); } while (0)
; #define PG8_MMA(ai, bj, At, Bt) do { __builtin_amdgcn_s_setprio(1); _Pragma("unroll") for (int m = 0; m < 4; ++m) _Pragma("unroll") for (int n = 0; n < 2; ++n) _Pragma("unroll") for (int k = 0; k < 2; ++k) \
;         acc[ai][bj][m][n] = __builtin_amdgcn_mfma_f32_16x16x32_bf16(Bt[n][k], At[m][k], acc[ai][bj][m][n], 0, 0, 0); __builtin_amdgcn_s_setprio(0); } while (0)
; #define PG8_WAIT_V(n) asm volatile("s_waitcnt vmcnt(" #n ")" ::: "memory")
; #define PG8_WAIT_L(n) asm volatile("s_waitcnt lgkmcnt(" #n ")" ::: "memory")
; #define PG8_BAR __builtin_amdgcn_s_barrier()
; #define PG8_SCHED __builtin_amdgcn_sched_barrier(0)
; template <class Epi, class Sched, bool ALIGN_EPI = false, bool SP2 = false>
; __device__ __forceinline__ void gemm_phase(PG8_LAS unsigned char* lds, const Gemm g, const Sched& S, const Epi& E, int tid_in) {
;     ...
;             PG8_WAIT_V(8); PG8_WAIT_L(0); PG8_BAR; PG8_MMA(1, 0, At, B0); PG8_MMA(1, 1, At, B1); PG8_BAR; PG8_SCHED;
;             PG8_LDB(B0, 1, 0); PG8_LDB(B1, 1, 1); PG8_SCHED; PG8_LDA(At, 1, 0); PG8_STAGE(PG8_SA(0, 1), a2 + hsA, voffA);
;             PG8_WAIT_V(8); PG8_WAIT_L(0); PG8_BAR; PG8_MMA(0, 0, At, B0); PG8_MMA(0, 1, At, B1); PG8_BAR; PG8_SCHED;
	s_setprio 1
	s_waitcnt lgkmcnt(0)
	v_mfma_f32_16x16x32_bf16 v[64:67], v[148:151], v[180:183], v[64:67]
	v_mfma_f32_16x16x32_bf16 v[60:63], v[156:159], v[180:183], v[60:63]
	v_mfma_f32_16x16x32_bf16 v[48:51], v[148:151], v[188:191], v[48:51]
	v_mfma_f32_16x16x32_bf16 v[44:47], v[156:159], v[188:191], v[44:47]
	v_mfma_f32_16x16x32_bf16 v[32:35], v[148:151], v[208:211], v[32:35]
	v_mfma_f32_16x16x32_bf16 v[28:31], v[156:159], v[208:211], v[28:31]
	v_mfma_f32_16x16x32_bf16 v[16:19], v[148:151], v[216:219], v[16:19]
	v_mfma_f32_16x16x32_bf16 v[12:15], v[156:159], v[216:219], v[12:15]
	v_mfma_f32_16x16x32_bf16 v[64:67], v[152:155], v[184:187], v[64:67]
	v_mfma_f32_16x16x32_bf16 v[60:63], v[160:163], v[184:187], v[60:63]
	v_mfma_f32_16x16x32_bf16 v[48:51], v[152:155], v[204:207], v[48:51]
	v_mfma_f32_16x16x32_bf16 v[44:47], v[160:163], v[204:207], v[44:47]
	v_mfma_f32_16x16x32_bf16 v[32:35], v[152:155], v[212:215], v[32:35]
	v_mfma_f32_16x16x32_bf16 v[28:31], v[160:163], v[212:215], v[28:31]
	v_mfma_f32_16x16x32_bf16 v[16:19], v[152:155], v[220:223], v[16:19]
	v_mfma_f32_16x16x32_bf16 v[12:15], v[160:163], v[220:223], v[12:15]
	v_mfma_f32_16x16x32_bf16 v[56:59], v[164:167], v[180:183], v[56:59]
	v_mfma_f32_16x16x32_bf16 v[52:55], v[172:175], v[180:183], v[52:55]
	v_mfma_f32_16x16x32_bf16 v[40:43], v[164:167], v[188:191], v[40:43]
	v_mfma_f32_16x16x32_bf16 v[36:39], v[172:175], v[188:191], v[36:39]
	v_mfma_f32_16x16x32_bf16 v[24:27], v[164:167], v[208:211], v[24:27]
	v_mfma_f32_16x16x32_bf16 v[20:23], v[172:175], v[208:211], v[20:23]
	v_mfma_f32_16x16x32_bf16 v[8:11], v[164:167], v[216:219], v[8:11]
	v_mfma_f32_16x16x32_bf16 v[4:7], v[172:175], v[216:219], v[4:7]
	v_mfma_f32_16x16x32_bf16 v[56:59], v[168:171], v[184:187], v[56:59]
	v_mfma_f32_16x16x32_bf16 v[52:55], v[176:179], v[184:187], v[52:55]
	v_mfma_f32_16x16x32_bf16 v[40:43], v[168:171], v[204:207], v[40:43]
	v_mfma_f32_16x16x32_bf16 v[36:39], v[176:179], v[204:207], v[36:39]
	v_mfma_f32_16x16x32_bf16 v[24:27], v[168:171], v[212:215], v[24:27]
	v_mfma_f32_16x16x32_bf16 v[20:23], v[176:179], v[212:215], v[20:23]
	v_mfma_f32_16x16x32_bf16 v[8:11], v[168:171], v[220:223], v[8:11]
	v_mfma_f32_16x16x32_bf16 v[4:7], v[176:179], v[220:223], v[4:7]
	s_setprio 0
	s_barrier
	s_add_i32 s59, 0, 0x18000
	v_add_u32_e32 v147, s59, v144
	s_add_i32 s60, 0, 0x1c000
	ds_read_b128 v[148:151], v147
	ds_read_b128 v[152:155], v147 offset:1024
	ds_read_b128 v[156:159], v147 offset:2048
	ds_read_b128 v[160:163], v147 offset:3072
	v_add_u32_e32 v147, s60, v144
	ds_read_b128 v[164:167], v147
	ds_read_b128 v[168:171], v147 offset:1024
	ds_read_b128 v[172:175], v147 offset:2048
	ds_read_b128 v[176:179], v147 offset:3072
	s_add_u32 s24, s24, s6
	s_addc_u32 s25, s25, s7
	s_mov_b32 m0, s42
	v_lshl_add_u64 v[232:233], s[24:25], 0, v[136:137]
	ds_read_b128 v[180:183], v146 offset:32768
	ds_read_b128 v[184:187], v146 offset:33792
	ds_read_b128 v[188:191], v146 offset:34816
	ds_read_b128 v[204:207], v146 offset:35840
	ds_read_b128 v[208:211], v146 offset:36864
	ds_read_b128 v[212:215], v146 offset:37888
	ds_read_b128 v[216:219], v146 offset:38912
	ds_read_b128 v[220:223], v146 offset:39936
	global_load_lds_dwordx4 v[232:233], off
	v_lshl_add_u64 v[232:233], s[24:25], 0, v[132:133]
	s_mov_b32 m0, s43
	s_nop 0
	global_load_lds_dwordx4 v[232:233], off
	s_waitcnt vmcnt(8)
	s_waitcnt lgkmcnt(0)
	s_barrier
	s_setprio 1
	s_waitcnt lgkmcnt(0)
	v_mfma_f32_16x16x32_bf16 v[128:131], v[148:151], v[180:183], v[128:131]
	v_mfma_f32_16x16x32_bf16 v[124:127], v[156:159], v[180:183], v[124:127]
	v_mfma_f32_16x16x32_bf16 v[112:115], v[148:151], v[188:191], v[112:115]
	v_mfma_f32_16x16x32_bf16 v[108:111], v[156:159], v[188:191], v[108:111]
	v_mfma_f32_16x16x32_bf16 v[96:99], v[148:151], v[208:211], v[96:99]
	v_mfma_f32_16x16x32_bf16 v[92:95], v[156:159], v[208:211], v[92:95]
	v_mfma_f32_16x16x32_bf16 v[80:83], v[148:151], v[216:219], v[80:83]
	v_mfma_f32_16x16x32_bf16 v[76:79], v[156:159], v[216:219], v[76:79]
	v_mfma_f32_16x16x32_bf16 v[128:131], v[152:155], v[184:187], v[128:131]
	v_mfma_f32_16x16x32_bf16 v[124:127], v[160:163], v[184:187], v[124:127]
	v_mfma_f32_16x16x32_bf16 v[112:115], v[152:155], v[204:207], v[112:115]
	v_mfma_f32_16x16x32_bf16 v[108:111], v[160:163], v[204:207], v[108:111]
	v_mfma_f32_16x16x32_bf16 v[96:99], v[152:155], v[212:215], v[96:99]
	v_mfma_f32_16x16x32_bf16 v[92:95], v[160:163], v[212:215], v[92:95]
	v_mfma_f32_16x16x32_bf16 v[80:83], v[152:155], v[220:223], v[80:83]
	v_mfma_f32_16x16x32_bf16 v[76:79], v[160:163], v[220:223], v[76:79]
	v_mfma_f32_16x16x32_bf16 v[120:123], v[164:167], v[180:183], v[120:123]
	v_mfma_f32_16x16x32_bf16 v[116:119], v[172:175], v[180:183], v[116:119]
	v_mfma_f32_16x16x32_bf16 v[104:107], v[164:167], v[188:191], v[104:107]
	v_mfma_f32_16x16x32_bf16 v[100:103], v[172:175], v[188:191], v[100:103]
	v_mfma_f32_16x16x32_bf16 v[88:91], v[164:167], v[208:211], v[88:91]
	v_mfma_f32_16x16x32_bf16 v[84:87], v[172:175], v[208:211], v[84:87]
	v_mfma_f32_16x16x32_bf16 v[72:75], v[164:167], v[216:219], v[72:75]
	v_mfma_f32_16x16x32_bf16 v[68:71], v[172:175], v[216:219], v[68:71]
	v_mfma_f32_16x16x32_bf16 v[120:123], v[168:171], v[184:187], v[120:123]
	v_mfma_f32_16x16x32_bf16 v[116:119], v[176:179], v[184:187], v[116:119]
	v_mfma_f32_16x16x32_bf16 v[104:107], v[168:171], v[204:207], v[104:107]
	v_mfma_f32_16x16x32_bf16 v[100:103], v[176:179], v[204:207], v[100:103]
	v_mfma_f32_16x16x32_bf16 v[88:91], v[168:171], v[212:215], v[88:91]
	v_mfma_f32_16x16x32_bf16 v[84:87], v[176:179], v[212:215], v[84:87]
	v_mfma_f32_16x16x32_bf16 v[72:75], v[168:171], v[220:223], v[72:75]
	v_mfma_f32_16x16x32_bf16 v[68:71], v[176:179], v[220:223], v[68:71]
	s_setprio 0
	s_barrier
; #define PG8_STAGE(bufoff, gbase, voff) do { _Pragma("unroll") for (int _i = 0; _i < 2; ++_i) \
;         __builtin_amdgcn_global_load_lds((const unsigned*)((const char*)(gbase) + (voff)[_i]), (PG8_LAS unsigned*)(lds + (bufoff) + ldsw + _i * 8192), 16, 0, 0); } while (0)
; #define PG8_LDA(dst, b, h) do { _Pragma("unroll") for (int m = 0; m < 4; ++m) _Pragma("unroll") for (int k = 0; k < 2; ++k) dst[m][k] = *(const PG8_LAS bf16x8*)(lds + PG8_SA(b, h) + aoff + m * 2048 + k * 1024); } while (0)
; #define PG8_MMA(ai, bj, At, Bt) do { __builtin_amdgcn_s_setprio(1); _Pragma("unroll") for (int m = 0; m < 4; ++m) _Pragma("unroll") for (int n = 0; n < 2; ++n) _Pragma("unroll") for (int k = 0; k < 2; ++k) \
;         acc[ai][bj][m][n] = __builtin_amdgcn_mfma_f32_16x16x32_bf16(Bt[n][k], At[m][k], acc[ai][bj][m][n], 0, 0, 0); __builtin_amdgcn_s_setprio(0); } while (0)
; #define PG8_WAIT_V(n) asm volatile("s_waitcnt vmcnt(" #n ")" ::: "memory")
; #define PG8_WAIT_L(n) asm volatile("s_waitcnt lgkmcnt(" #n ")" ::: "memory")
; #define PG8_BAR __builtin_amdgcn_s_barrier()
; #define PG8_SCHED __builtin_amdgcn_sched_barrier(0)
; template <class Epi, class Sched, bool ALIGN_EPI = false, bool SP2 = false>
; __device__ __forceinline__ void gemm_phase(PG8_LAS unsigned char* lds, const Gemm g, const Sched& S, const Epi& E, int tid_in) {
;     ...
;         for (int t = 0; t < nt; t += 2) {
;     ...
;             PG8_LDA(At, 1, 1); PG8_STAGE(PG8_SB(1, 0), b3, voffB); PG8_STAGE(PG8_SB(1, 1), b3 + hsB, voffB); PG8_STAGE(PG8_SA(1, 0), a3, voffA);
;             PG8_WAIT_V(8); PG8_WAIT_L(0); PG8_BAR; PG8_MMA(1, 0, At, B0); PG8_MMA(1, 1, At, B1); PG8_BAR; PG8_SCHED;
	s_add_i32 s24, s59, s34
	v_lshl_add_u64 v[142:143], v[142:143], 0, s[80:81]
	s_mov_b32 m0, s24
	ds_read_b128 v[180:183], v146 offset:49152
	ds_read_b128 v[184:187], v146 offset:50176
	ds_read_b128 v[188:191], v146 offset:51200
	ds_read_b128 v[204:207], v146 offset:52224
	ds_read_b128 v[208:211], v146 offset:53248
	ds_read_b128 v[212:215], v146 offset:54272
	ds_read_b128 v[216:219], v146 offset:55296
	ds_read_b128 v[220:223], v146 offset:56320
	global_load_lds_dwordx4 v[142:143], off
	v_lshl_add_u64 v[142:143], v[196:197], 0, s[80:81]
	s_add_i32 m0, s24, 0x2000
	s_add_i32 s24, s60, s34
	global_load_lds_dwordx4 v[142:143], off
	v_lshl_add_u64 v[142:143], v[198:199], 0, s[80:81]
	s_mov_b32 m0, s24
	s_nop 0
	global_load_lds_dwordx4 v[142:143], off
	v_lshl_add_u64 v[142:143], v[200:201], 0, s[80:81]
	s_add_i32 m0, s24, 0x2000
	s_nop 0
	global_load_lds_dwordx4 v[142:143], off
	v_lshl_add_u64 v[142:143], v[228:229], 0, s[80:81]
	s_mov_b32 m0, s44
	s_nop 0
	global_load_lds_dwordx4 v[142:143], off
	v_lshl_add_u64 v[142:143], v[230:231], 0, s[80:81]
	s_mov_b32 m0, s45
	s_nop 0
	global_load_lds_dwordx4 v[142:143], off
	s_waitcnt vmcnt(8)
	s_waitcnt lgkmcnt(0)
	s_barrier
	s_setprio 1
	s_waitcnt lgkmcnt(0)
	v_mfma_f32_16x16x32_bf16 v[64:67], v[148:151], v[180:183], v[64:67]
	v_mfma_f32_16x16x32_bf16 v[60:63], v[156:159], v[180:183], v[60:63]
	v_mfma_f32_16x16x32_bf16 v[48:51], v[148:151], v[188:191], v[48:51]
	v_mfma_f32_16x16x32_bf16 v[44:47], v[156:159], v[188:191], v[44:47]
	v_mfma_f32_16x16x32_bf16 v[32:35], v[148:151], v[208:211], v[32:35]
	v_mfma_f32_16x16x32_bf16 v[28:31], v[156:159], v[208:211], v[28:31]
	v_mfma_f32_16x16x32_bf16 v[16:19], v[148:151], v[216:219], v[16:19]
	v_mfma_f32_16x16x32_bf16 v[12:15], v[156:159], v[216:219], v[12:15]
	v_mfma_f32_16x16x32_bf16 v[64:67], v[152:155], v[184:187], v[64:67]
	v_mfma_f32_16x16x32_bf16 v[60:63], v[160:163], v[184:187], v[60:63]
	v_mfma_f32_16x16x32_bf16 v[48:51], v[152:155], v[204:207], v[48:51]
	v_mfma_f32_16x16x32_bf16 v[44:47], v[160:163], v[204:207], v[44:47]
	v_mfma_f32_16x16x32_bf16 v[32:35], v[152:155], v[212:215], v[32:35]
	v_mfma_f32_16x16x32_bf16 v[28:31], v[160:163], v[212:215], v[28:31]
	v_mfma_f32_16x16x32_bf16 v[16:19], v[152:155], v[220:223], v[16:19]
	v_mfma_f32_16x16x32_bf16 v[12:15], v[160:163], v[220:223], v[12:15]
	v_mfma_f32_16x16x32_bf16 v[56:59], v[164:167], v[180:183], v[56:59]
	v_mfma_f32_16x16x32_bf16 v[52:55], v[172:175], v[180:183], v[52:55]
	v_mfma_f32_16x16x32_bf16 v[40:43], v[164:167], v[188:191], v[40:43]
	v_mfma_f32_16x16x32_bf16 v[36:39], v[172:175], v[188:191], v[36:39]
	v_mfma_f32_16x16x32_bf16 v[24:27], v[164:167], v[208:211], v[24:27]
	v_mfma_f32_16x16x32_bf16 v[20:23], v[172:175], v[208:211], v[20:23]
	v_mfma_f32_16x16x32_bf16 v[8:11], v[164:167], v[216:219], v[8:11]
	v_mfma_f32_16x16x32_bf16 v[4:7], v[172:175], v[216:219], v[4:7]
	v_mfma_f32_16x16x32_bf16 v[56:59], v[168:171], v[184:187], v[56:59]
	v_mfma_f32_16x16x32_bf16 v[52:55], v[176:179], v[184:187], v[52:55]
	v_mfma_f32_16x16x32_bf16 v[40:43], v[168:171], v[204:207], v[40:43]
	v_mfma_f32_16x16x32_bf16 v[36:39], v[176:179], v[204:207], v[36:39]
	v_mfma_f32_16x16x32_bf16 v[24:27], v[168:171], v[212:215], v[24:27]
	v_mfma_f32_16x16x32_bf16 v[20:23], v[176:179], v[212:215], v[20:23]
	v_mfma_f32_16x16x32_bf16 v[8:11], v[168:171], v[220:223], v[8:11]
	v_mfma_f32_16x16x32_bf16 v[4:7], v[176:179], v[220:223], v[4:7]
	s_setprio 0
	s_barrier
	s_add_i32 s24, s58, 2
	s_add_u32 s54, s54, 0x100
	s_addc_u32 s55, s55, 0
	s_add_u32 s22, s22, 0x100
	s_addc_u32 s23, s23, 0
	s_cmp_ge_i32 s58, s46
	s_mov_b32 s58, s24
	s_cbranch_scc0 .LBB0_924

; #define PG8_STAGE(bufoff, gbase, voff) do { _Pragma("unroll") for (int _i = 0; _i < 2; ++_i) \
;         __builtin_amdgcn_global_load_lds((const unsigned*)((const char*)(gbase) + (voff)[_i]), (PG8_LAS unsigned*)(lds + (bufoff) + ldsw + _i * 8192), 16, 0, 0); } while (0)
; #define PG8_LDA(dst, b, h) do { _Pragma("unroll") for (int m = 0; m < 4; ++m) _Pragma("unroll") for (int k = 0; k < 2; ++k) dst[m][k] = *(const PG8_LAS bf16x8*)(lds + PG8_SA(b, h) + aoff + m * 2048 + k * 1024); } while (0)
; #define PG8_LDB(dst, b, h) do { _Pragma("unroll") for (int n = 0; n < 2; ++n) _Pragma("unroll") for (int k = 0; k < 2; ++k) dst[n][k] = *(const PG8_LAS bf16x8*)(lds + PG8_SB(b, h) + boff + n * 2048 + k * 1024); } while (0)
; #define PG8_MMA(ai, bj, At, Bt) do { __builtin_amdgcn_s_setprio(1); _Pragma("unroll") for (int m = 0; m < 4; ++m) _Pragma("unroll") for (int n = 0; n < 2; ++n) _Pragma("unroll") for (int k = 0; k < 2; ++k) \
;         acc[ai][bj][m][n] = __builtin_amdgcn_mfma_f32_16x16x32_bf16(Bt[n][k], At[m][k], acc[ai][bj][m][n], 0, 0, 0); __builtin_amdgcn_s_setprio(0); } while (0)
; template <class Epi, class Sched, bool ALIGN_EPI = false, bool SP2 = false>
; __device__ __forceinline__ void gemm_phase(PG8_LAS unsigned char* lds, const Gemm g, const Sched& S, const Epi& E, int tid_in) {
;     ...
;             const bool last = (t == nt - 2);
;             if constexpr (mid_hook<Epi>::value) { if (t == Epi::H1 || t == Epi::H2) E.mid(acc, cur, wr, wc, fr, fq, t == Epi::H2); }
;             const char* a1 = cA + (size_t)(t + 1) * kstep + (t >= jt ? jb : 0);
;             const char* a2 = last ? nA : cA + (size_t)(t + 2) * kstep + (t + 2 >= jt ? jb : 0); const char* b2 = last ? nB : cB + (size_t)(t + 2) * kstep;
;             const char* a3 = a2 + kstep; const char* b3 = b2 + kstep;
;             if (last && has_next) S.a_ready(nxt);
;             if constexpr (SP2) {
;             PG8_LDB(B0, 0, 0); PG8_LDB(B1, 0, 1); PG8_SCHED; PG8_LDA(At, 0, 0); PG8_STAGE(PG8_SA(1, 1), a1 + hsA, voffA);
;             PG8_WAIT_V(8); PG8_WAIT_L(0); PG8_BAR; PG8_MMA(0, 0, At, B0); PG8_MMA(0, 1, At, B1); PG8_BAR; PG8_SCHED;
;             PG8_LDA(At, 0, 1); PG8_STAGE(PG8_SB(0, 0), b2, voffB); PG8_STAGE(PG8_SB(0, 1), b2 + hsB, voffB); PG8_STAGE(PG8_SA(0, 0), a2, voffA);
;             PG8_WAIT_V(8); PG8_WAIT_L(0); PG8_BAR; PG8_MMA(1, 0, At, B0); PG8_MMA(1, 1, At, B1); PG8_BAR; PG8_SCHED;
.LBB0_994:
	s_cmp_ge_i32 s62, s37
	s_cselect_b32 s64, s38, 0
	s_cselect_b32 s65, s52, 0
	s_add_i32 s30, s62, 2
	s_cmp_ge_i32 s30, s37
	s_cselect_b32 s29, s38, 0
	s_cselect_b32 s28, s52, 0
	s_add_u32 s29, s26, s29
	s_addc_u32 s28, s27, s28
	s_add_u32 s31, s29, 0x80
	s_addc_u32 s28, s28, 0
	s_add_i32 s66, 0, 0x10000
	s_cmp_eq_u32 s53, s62
	s_cselect_b32 s29, s5, s28
	s_cselect_b32 s28, s4, s31
	v_add_u32_e32 v3, s66, v217
	s_cselect_b32 s63, s25, s61
	s_cselect_b32 s62, s24, s60
	s_add_i32 s31, 0, 0x14000
	ds_read_b128 v[134:137], v3
	ds_read_b128 v[138:141], v3 offset:1024
	ds_read_b128 v[142:145], v3 offset:2048
	ds_read_b128 v[146:149], v3 offset:3072
	v_add_u32_e32 v3, s31, v217
	ds_read_b128 v[150:153], v3
	ds_read_b128 v[154:157], v3 offset:1024
	ds_read_b128 v[158:161], v3 offset:2048
	ds_read_b128 v[162:165], v3 offset:3072
	v_lshl_add_u64 v[4:5], s[26:27], 0, v[182:183]
	v_lshl_add_u64 v[4:5], v[4:5], 0, s[64:65]
	s_add_i32 m0, s33, 0xc000
	ds_read_b128 v[166:169], v219
	ds_read_b128 v[170:173], v219 offset:1024
	ds_read_b128 v[220:223], v219 offset:2048
	ds_read_b128 v[238:241], v219 offset:3072
	ds_read_b128 v[242:245], v219 offset:4096
	ds_read_b128 v[246:249], v219 offset:5120
	ds_read_b128 v[250:253], v219 offset:6144
	ds_read_b128 v[230:233], v219 offset:7168
	global_load_lds_dwordx4 v[4:5], off
	v_lshl_add_u64 v[4:5], s[26:27], 0, v[180:181]
	v_lshl_add_u64 v[4:5], v[4:5], 0, s[64:65]
	s_add_i32 m0, s33, 0xe000
	s_nop 0
	global_load_lds_dwordx4 v[4:5], off
	s_waitcnt vmcnt(8)
	s_waitcnt lgkmcnt(0)
	s_barrier
	s_setprio 1
	s_waitcnt lgkmcnt(0)
	v_mfma_f32_16x16x32_bf16 v[126:129], v[134:137], v[166:169], v[126:129]
	v_mfma_f32_16x16x32_bf16 v[130:133], v[142:145], v[166:169], v[130:133]
	v_mfma_f32_16x16x32_bf16 v[114:117], v[134:137], v[220:223], v[114:117]
	v_mfma_f32_16x16x32_bf16 v[110:113], v[142:145], v[220:223], v[110:113]
	v_mfma_f32_16x16x32_bf16 v[98:101], v[134:137], v[242:245], v[98:101]
	v_mfma_f32_16x16x32_bf16 v[94:97], v[142:145], v[242:245], v[94:97]
	v_mfma_f32_16x16x32_bf16 v[82:85], v[134:137], v[250:253], v[82:85]
	v_mfma_f32_16x16x32_bf16 v[78:81], v[142:145], v[250:253], v[78:81]
	v_mfma_f32_16x16x32_bf16 v[126:129], v[138:141], v[170:173], v[126:129]
	v_mfma_f32_16x16x32_bf16 v[130:133], v[146:149], v[170:173], v[130:133]
	v_mfma_f32_16x16x32_bf16 v[114:117], v[138:141], v[238:241], v[114:117]
	v_mfma_f32_16x16x32_bf16 v[110:113], v[146:149], v[238:241], v[110:113]
	v_mfma_f32_16x16x32_bf16 v[98:101], v[138:141], v[246:249], v[98:101]
	v_mfma_f32_16x16x32_bf16 v[94:97], v[146:149], v[246:249], v[94:97]
	v_mfma_f32_16x16x32_bf16 v[82:85], v[138:141], v[230:233], v[82:85]
	v_mfma_f32_16x16x32_bf16 v[78:81], v[146:149], v[230:233], v[78:81]
	v_mfma_f32_16x16x32_bf16 v[122:125], v[150:153], v[166:169], v[122:125]
	v_mfma_f32_16x16x32_bf16 v[118:121], v[158:161], v[166:169], v[118:121]
	v_mfma_f32_16x16x32_bf16 v[106:109], v[150:153], v[220:223], v[106:109]
	v_mfma_f32_16x16x32_bf16 v[102:105], v[158:161], v[220:223], v[102:105]
	v_mfma_f32_16x16x32_bf16 v[90:93], v[150:153], v[242:245], v[90:93]
	v_mfma_f32_16x16x32_bf16 v[86:89], v[158:161], v[242:245], v[86:89]
	v_mfma_f32_16x16x32_bf16 v[74:77], v[150:153], v[250:253], v[74:77]
	v_mfma_f32_16x16x32_bf16 v[70:73], v[158:161], v[250:253], v[70:73]
	v_mfma_f32_16x16x32_bf16 v[122:125], v[154:157], v[170:173], v[122:125]
	v_mfma_f32_16x16x32_bf16 v[118:121], v[162:165], v[170:173], v[118:121]
	v_mfma_f32_16x16x32_bf16 v[106:109], v[154:157], v[238:241], v[106:109]
	v_mfma_f32_16x16x32_bf16 v[102:105], v[162:165], v[238:241], v[102:105]
	v_mfma_f32_16x16x32_bf16 v[90:93], v[154:157], v[246:249], v[90:93]
	v_mfma_f32_16x16x32_bf16 v[86:89], v[162:165], v[246:249], v[86:89]
	v_mfma_f32_16x16x32_bf16 v[74:77], v[154:157], v[230:233], v[74:77]
	v_mfma_f32_16x16x32_bf16 v[70:73], v[162:165], v[230:233], v[70:73]
	s_setprio 0
	s_barrier
	s_add_i32 s64, s66, s43
	v_lshl_add_u64 v[196:197], s[62:63], 0, v[176:177]
	s_mov_b32 m0, s64
	ds_read_b128 v[166:169], v219 offset:16384
	ds_read_b128 v[170:173], v219 offset:17408
	ds_read_b128 v[220:223], v219 offset:18432
	ds_read_b128 v[230:233], v219 offset:19456
	ds_read_b128 v[238:241], v219 offset:20480
	ds_read_b128 v[242:245], v219 offset:21504
	ds_read_b128 v[246:249], v219 offset:22528
	ds_read_b128 v[250:253], v219 offset:23552
	global_load_lds_dwordx4 v[196:197], off
	s_add_i32 m0, s64, 0x2000
	v_lshl_add_u64 v[198:199], s[62:63], 0, v[0:1]
	s_add_u32 s62, s62, s8
	s_addc_u32 s63, s63, s9
	s_add_i32 s31, s31, s43
	global_load_lds_dwordx4 v[198:199], off
	v_lshl_add_u64 v[200:201], s[62:63], 0, v[176:177]
	s_mov_b32 m0, s31
	v_lshl_add_u64 v[228:229], s[62:63], 0, v[0:1]
	global_load_lds_dwordx4 v[200:201], off
	s_add_i32 m0, s31, 0x2000
	v_lshl_add_u64 v[202:203], s[28:29], 0, v[178:179]
	global_load_lds_dwordx4 v[228:229], off
	s_mov_b32 m0, s33
	v_lshl_add_u64 v[192:193], s[28:29], 0, v[174:175]
	global_load_lds_dwordx4 v[202:203], off
	s_mov_b32 m0, s46
	s_nop 0
	global_load_lds_dwordx4 v[192:193], off
	s_waitcnt vmcnt(8)
	s_waitcnt lgkmcnt(0)
	s_barrier
; #define PG8_STAGE(bufoff, gbase, voff) do { _Pragma("unroll") for (int _i = 0; _i < 2; ++_i) \
;         __builtin_amdgcn_global_load_lds((const unsigned*)((const char*)(gbase) + (voff)[_i]), (PG8_LAS unsigned*)(lds + (bufoff) + ldsw + _i * 8192), 16, 0, 0); } while (0)
; #define PG8_LDA(dst, b, h) do { _Pragma("unroll") for (int m = 0; m < 4; ++m) _Pragma("unroll") for (int k = 0; k < 2; ++k) dst[m][k] = *(const PG8_LAS bf16x8*)(lds + PG8_SA(b, h) + aoff + m * 2048 + k * 1024); } while (0)
; #define PG8_LDB(dst, b, h) do { _Pragma("unroll") for (int n = 0; n < 2; ++n) _Pragma("unroll") for (int k = 0; k < 2; ++k) dst[n][k] = *(const PG8_LAS bf16x8*)(lds + PG8_SB(b, h) + boff + n * 2048 + k * 1024); } while (0)
; #define PG8_MMA(ai, bj, At, Bt) do { __builtin_amdgcn_s_setprio(1); _Pragma("unroll") for (int m = 0; m < 4; ++m) _Pragma("unroll") for (int n = 0; n < 2; ++n) _Pragma("unroll") for (int k = 0; k < 2; ++k) \
;         acc[ai][bj][m][n] = __builtin_amdgcn_mfma_f32_16x16x32_bf16(Bt[n][k], At[m][k], acc[ai][bj][m][n], 0, 0, 0); __builtin_amdgcn_s_setprio(0); } while (0)
; #define PG8_WAIT_V(n) asm volatile("s_waitcnt vmcnt(" #n ")" ::: "memory")
; #define PG8_WAIT_L(n) asm volatile("s_waitcnt lgkmcnt(" #n ")" ::: "memory")
; #define PG8_BAR __builtin_amdgcn_s_barrier()
; #define PG8_SCHED __builtin_amdgcn_sched_barrier(0)
; template <class Epi, class Sched, bool ALIGN_EPI = false, bool SP2 = false>
; __device__ __forceinline__ void gemm_phase(PG8_LAS unsigned char* lds, const Gemm g, const Sched& S, const Epi& E, int tid_in) {
;     ...
;             PG8_WAIT_V(8); PG8_WAIT_L(0); PG8_BAR; PG8_MMA(1, 0, At, B0); PG8_MMA(1, 1, At, B1); PG8_BAR; PG8_SCHED;
;             PG8_LDB(B0, 1, 0); PG8_LDB(B1, 1, 1); PG8_SCHED; PG8_LDA(At, 1, 0); PG8_STAGE(PG8_SA(0, 1), a2 + hsA, voffA);
;             PG8_WAIT_V(8); PG8_WAIT_L(0); PG8_BAR; PG8_MMA(0, 0, At, B0); PG8_MMA(0, 1, At, B1); PG8_BAR; PG8_SCHED;
	s_setprio 1
	s_waitcnt lgkmcnt(0)
	v_mfma_f32_16x16x32_bf16 v[66:69], v[134:137], v[166:169], v[66:69]
	v_mfma_f32_16x16x32_bf16 v[62:65], v[142:145], v[166:169], v[62:65]
	v_mfma_f32_16x16x32_bf16 v[50:53], v[134:137], v[220:223], v[50:53]
	v_mfma_f32_16x16x32_bf16 v[46:49], v[142:145], v[220:223], v[46:49]
	v_mfma_f32_16x16x32_bf16 v[34:37], v[134:137], v[238:241], v[34:37]
	v_mfma_f32_16x16x32_bf16 v[30:33], v[142:145], v[238:241], v[30:33]
	v_mfma_f32_16x16x32_bf16 v[18:21], v[134:137], v[246:249], v[18:21]
	v_mfma_f32_16x16x32_bf16 v[14:17], v[142:145], v[246:249], v[14:17]
	v_mfma_f32_16x16x32_bf16 v[66:69], v[138:141], v[170:173], v[66:69]
	v_mfma_f32_16x16x32_bf16 v[62:65], v[146:149], v[170:173], v[62:65]
	v_mfma_f32_16x16x32_bf16 v[50:53], v[138:141], v[230:233], v[50:53]
	v_mfma_f32_16x16x32_bf16 v[46:49], v[146:149], v[230:233], v[46:49]
	v_mfma_f32_16x16x32_bf16 v[34:37], v[138:141], v[242:245], v[34:37]
	v_mfma_f32_16x16x32_bf16 v[30:33], v[146:149], v[242:245], v[30:33]
	v_mfma_f32_16x16x32_bf16 v[18:21], v[138:141], v[250:253], v[18:21]
	v_mfma_f32_16x16x32_bf16 v[14:17], v[146:149], v[250:253], v[14:17]
	v_mfma_f32_16x16x32_bf16 v[58:61], v[150:153], v[166:169], v[58:61]
	v_mfma_f32_16x16x32_bf16 v[54:57], v[158:161], v[166:169], v[54:57]
	v_mfma_f32_16x16x32_bf16 v[42:45], v[150:153], v[220:223], v[42:45]
	v_mfma_f32_16x16x32_bf16 v[38:41], v[158:161], v[220:223], v[38:41]
	v_mfma_f32_16x16x32_bf16 v[26:29], v[150:153], v[238:241], v[26:29]
	v_mfma_f32_16x16x32_bf16 v[22:25], v[158:161], v[238:241], v[22:25]
	v_mfma_f32_16x16x32_bf16 v[10:13], v[150:153], v[246:249], v[10:13]
	v_mfma_f32_16x16x32_bf16 v[4:7], v[158:161], v[246:249], v[6:9]
	v_mfma_f32_16x16x32_bf16 v[58:61], v[154:157], v[170:173], v[58:61]
	v_mfma_f32_16x16x32_bf16 v[54:57], v[162:165], v[170:173], v[54:57]
	v_mfma_f32_16x16x32_bf16 v[42:45], v[154:157], v[230:233], v[42:45]
	v_mfma_f32_16x16x32_bf16 v[38:41], v[162:165], v[230:233], v[38:41]
	v_mfma_f32_16x16x32_bf16 v[26:29], v[154:157], v[242:245], v[26:29]
	v_mfma_f32_16x16x32_bf16 v[22:25], v[162:165], v[242:245], v[22:25]
	v_mfma_f32_16x16x32_bf16 v[10:13], v[154:157], v[250:253], v[10:13]
	v_mfma_f32_16x16x32_bf16 v[4:7], v[162:165], v[250:253], v[4:7]
	s_setprio 0
	s_barrier
	s_add_i32 s31, 0, 0x18000
	v_add_u32_e32 v3, s31, v217
	s_add_i32 s62, 0, 0x1c000
	ds_read_b128 v[134:137], v3
	ds_read_b128 v[138:141], v3 offset:1024
	ds_read_b128 v[142:145], v3 offset:2048
	ds_read_b128 v[146:149], v3 offset:3072
	v_add_u32_e32 v3, s62, v217
	ds_read_b128 v[150:153], v3
	ds_read_b128 v[154:157], v3 offset:1024
	ds_read_b128 v[158:161], v3 offset:2048
	ds_read_b128 v[162:165], v3 offset:3072
	s_add_u32 s28, s28, s6
	s_addc_u32 s29, s29, s7
	s_mov_b32 m0, s47
	v_lshl_add_u64 v[8:9], s[28:29], 0, v[178:179]
	ds_read_b128 v[166:169], v219 offset:32768
	ds_read_b128 v[170:173], v219 offset:33792
	ds_read_b128 v[220:223], v219 offset:34816
	ds_read_b128 v[230:233], v219 offset:35840
	ds_read_b128 v[238:241], v219 offset:36864
	ds_read_b128 v[242:245], v219 offset:37888
	ds_read_b128 v[246:249], v219 offset:38912
	ds_read_b128 v[250:253], v219 offset:39936
	global_load_lds_dwordx4 v[8:9], off
	v_lshl_add_u64 v[8:9], s[28:29], 0, v[174:175]
	s_mov_b32 m0, s48
	s_nop 0
	global_load_lds_dwordx4 v[8:9], off
	s_waitcnt vmcnt(8)
	s_waitcnt lgkmcnt(0)
	s_barrier
	s_setprio 1
	s_waitcnt lgkmcnt(0)
	v_mfma_f32_16x16x32_bf16 v[126:129], v[134:137], v[166:169], v[126:129]
	v_mfma_f32_16x16x32_bf16 v[130:133], v[142:145], v[166:169], v[130:133]
	v_mfma_f32_16x16x32_bf16 v[114:117], v[134:137], v[220:223], v[114:117]
	v_mfma_f32_16x16x32_bf16 v[110:113], v[142:145], v[220:223], v[110:113]
	v_mfma_f32_16x16x32_bf16 v[98:101], v[134:137], v[238:241], v[98:101]
	v_mfma_f32_16x16x32_bf16 v[94:97], v[142:145], v[238:241], v[94:97]
	v_mfma_f32_16x16x32_bf16 v[82:85], v[134:137], v[246:249], v[82:85]
	v_mfma_f32_16x16x32_bf16 v[78:81], v[142:145], v[246:249], v[78:81]
	v_mfma_f32_16x16x32_bf16 v[126:129], v[138:141], v[170:173], v[126:129]
	v_mfma_f32_16x16x32_bf16 v[130:133], v[146:149], v[170:173], v[130:133]
	v_mfma_f32_16x16x32_bf16 v[114:117], v[138:141], v[230:233], v[114:117]
	v_mfma_f32_16x16x32_bf16 v[110:113], v[146:149], v[230:233], v[110:113]
	v_mfma_f32_16x16x32_bf16 v[98:101], v[138:141], v[242:245], v[98:101]
	v_mfma_f32_16x16x32_bf16 v[94:97], v[146:149], v[242:245], v[94:97]
	v_mfma_f32_16x16x32_bf16 v[82:85], v[138:141], v[250:253], v[82:85]
	v_mfma_f32_16x16x32_bf16 v[78:81], v[146:149], v[250:253], v[78:81]
	v_mfma_f32_16x16x32_bf16 v[122:125], v[150:153], v[166:169], v[122:125]
	v_mfma_f32_16x16x32_bf16 v[118:121], v[158:161], v[166:169], v[118:121]
	v_mfma_f32_16x16x32_bf16 v[106:109], v[150:153], v[220:223], v[106:109]
	v_mfma_f32_16x16x32_bf16 v[102:105], v[158:161], v[220:223], v[102:105]
	v_mfma_f32_16x16x32_bf16 v[90:93], v[150:153], v[238:241], v[90:93]
	v_mfma_f32_16x16x32_bf16 v[86:89], v[158:161], v[238:241], v[86:89]
	v_mfma_f32_16x16x32_bf16 v[74:77], v[150:153], v[246:249], v[74:77]
	v_mfma_f32_16x16x32_bf16 v[70:73], v[158:161], v[246:249], v[70:73]
	v_mfma_f32_16x16x32_bf16 v[122:125], v[154:157], v[170:173], v[122:125]
	v_mfma_f32_16x16x32_bf16 v[118:121], v[162:165], v[170:173], v[118:121]
	v_mfma_f32_16x16x32_bf16 v[106:109], v[154:157], v[230:233], v[106:109]
	v_mfma_f32_16x16x32_bf16 v[102:105], v[162:165], v[230:233], v[102:105]
	v_mfma_f32_16x16x32_bf16 v[90:93], v[154:157], v[242:245], v[90:93]
	v_mfma_f32_16x16x32_bf16 v[86:89], v[162:165], v[242:245], v[86:89]
	v_mfma_f32_16x16x32_bf16 v[74:77], v[154:157], v[250:253], v[74:77]
	v_mfma_f32_16x16x32_bf16 v[70:73], v[162:165], v[250:253], v[70:73]
	s_setprio 0
	s_barrier
; #define PG8_STAGE(bufoff, gbase, voff) do { _Pragma("unroll") for (int _i = 0; _i < 2; ++_i) \
;         __builtin_amdgcn_global_load_lds((const unsigned*)((const char*)(gbase) + (voff)[_i]), (PG8_LAS unsigned*)(lds + (bufoff) + ldsw + _i * 8192), 16, 0, 0); } while (0)
; #define PG8_LDA(dst, b, h) do { _Pragma("unroll") for (int m = 0; m < 4; ++m) _Pragma("unroll") for (int k = 0; k < 2; ++k) dst[m][k] = *(const PG8_LAS bf16x8*)(lds + PG8_SA(b, h) + aoff + m * 2048 + k * 1024); } while (0)
; #define PG8_MMA(ai, bj, At, Bt) do { __builtin_amdgcn_s_setprio(1); _Pragma("unroll") for (int m = 0; m < 4; ++m) _Pragma("unroll") for (int n = 0; n < 2; ++n) _Pragma("unroll") for (int k = 0; k < 2; ++k) \
;         acc[ai][bj][m][n] = __builtin_amdgcn_mfma_f32_16x16x32_bf16(Bt[n][k], At[m][k], acc[ai][bj][m][n], 0, 0, 0); __builtin_amdgcn_s_setprio(0); } while (0)
; #define PG8_WAIT_V(n) asm volatile("s_waitcnt vmcnt(" #n ")" ::: "memory")
; #define PG8_WAIT_L(n) asm volatile("s_waitcnt lgkmcnt(" #n ")" ::: "memory")
; #define PG8_BAR __builtin_amdgcn_s_barrier()
; #define PG8_SCHED __builtin_amdgcn_sched_barrier(0)
; template <class Epi, class Sched, bool ALIGN_EPI = false, bool SP2 = false>
; __device__ __forceinline__ void gemm_phase(PG8_LAS unsigned char* lds, const Gemm g, const Sched& S, const Epi& E, int tid_in) {
;     ...
;         for (int t = 0; t < nt; t += 2) {
;             const bool last = (t == nt - 2);
;             if constexpr (mid_hook<Epi>::value) { if (t == Epi::H1 || t == Epi::H2) E.mid(acc, cur, wr, wc, fr, fq, t == Epi::H2); }
;     ...
;             PG8_LDA(At, 1, 1); PG8_STAGE(PG8_SB(1, 0), b3, voffB); PG8_STAGE(PG8_SB(1, 1), b3 + hsB, voffB); PG8_STAGE(PG8_SA(1, 0), a3, voffA);
;             PG8_WAIT_V(8); PG8_WAIT_L(0); PG8_BAR; PG8_MMA(1, 0, At, B0); PG8_MMA(1, 1, At, B1); PG8_BAR; PG8_SCHED;
	s_add_i32 s28, s31, s43
	v_lshl_add_u64 v[8:9], v[196:197], 0, s[80:81]
	s_mov_b32 m0, s28
	ds_read_b128 v[166:169], v219 offset:49152
	ds_read_b128 v[170:173], v219 offset:50176
	ds_read_b128 v[220:223], v219 offset:51200
	ds_read_b128 v[230:233], v219 offset:52224
	ds_read_b128 v[238:241], v219 offset:53248
	ds_read_b128 v[242:245], v219 offset:54272
	ds_read_b128 v[246:249], v219 offset:55296
	ds_read_b128 v[250:253], v219 offset:56320
	global_load_lds_dwordx4 v[8:9], off
	v_lshl_add_u64 v[8:9], v[198:199], 0, s[80:81]
	s_add_i32 m0, s28, 0x2000
	s_add_i32 s28, s62, s43
	global_load_lds_dwordx4 v[8:9], off
	v_lshl_add_u64 v[8:9], v[200:201], 0, s[80:81]
	s_mov_b32 m0, s28
	s_nop 0
	global_load_lds_dwordx4 v[8:9], off
	v_lshl_add_u64 v[8:9], v[228:229], 0, s[80:81]
	s_add_i32 m0, s28, 0x2000
	s_nop 0
	global_load_lds_dwordx4 v[8:9], off
	v_lshl_add_u64 v[8:9], v[202:203], 0, s[80:81]
	s_mov_b32 m0, s49
	s_nop 0
	global_load_lds_dwordx4 v[8:9], off
	v_lshl_add_u64 v[8:9], v[192:193], 0, s[80:81]
	s_mov_b32 m0, s50
	s_nop 0
	global_load_lds_dwordx4 v[8:9], off
	s_waitcnt vmcnt(8)
	s_waitcnt lgkmcnt(0)
	s_barrier
	s_setprio 1
	s_waitcnt lgkmcnt(0)
	v_mfma_f32_16x16x32_bf16 v[66:69], v[134:137], v[166:169], v[66:69]
	v_mfma_f32_16x16x32_bf16 v[62:65], v[142:145], v[166:169], v[62:65]
	v_mfma_f32_16x16x32_bf16 v[50:53], v[134:137], v[220:223], v[50:53]
	v_mfma_f32_16x16x32_bf16 v[46:49], v[142:145], v[220:223], v[46:49]
	v_mfma_f32_16x16x32_bf16 v[34:37], v[134:137], v[238:241], v[34:37]
	v_mfma_f32_16x16x32_bf16 v[30:33], v[142:145], v[238:241], v[30:33]
	v_mfma_f32_16x16x32_bf16 v[18:21], v[134:137], v[246:249], v[18:21]
	v_mfma_f32_16x16x32_bf16 v[14:17], v[142:145], v[246:249], v[14:17]
	v_mfma_f32_16x16x32_bf16 v[66:69], v[138:141], v[170:173], v[66:69]
	v_mfma_f32_16x16x32_bf16 v[62:65], v[146:149], v[170:173], v[62:65]
	v_mfma_f32_16x16x32_bf16 v[50:53], v[138:141], v[230:233], v[50:53]
	v_mfma_f32_16x16x32_bf16 v[46:49], v[146:149], v[230:233], v[46:49]
	v_mfma_f32_16x16x32_bf16 v[34:37], v[138:141], v[242:245], v[34:37]
	v_mfma_f32_16x16x32_bf16 v[30:33], v[146:149], v[242:245], v[30:33]
	v_mfma_f32_16x16x32_bf16 v[18:21], v[138:141], v[250:253], v[18:21]
	v_mfma_f32_16x16x32_bf16 v[14:17], v[146:149], v[250:253], v[14:17]
	v_mfma_f32_16x16x32_bf16 v[58:61], v[150:153], v[166:169], v[58:61]
	v_mfma_f32_16x16x32_bf16 v[54:57], v[158:161], v[166:169], v[54:57]
	v_mfma_f32_16x16x32_bf16 v[42:45], v[150:153], v[220:223], v[42:45]
	v_mfma_f32_16x16x32_bf16 v[38:41], v[158:161], v[220:223], v[38:41]
	v_mfma_f32_16x16x32_bf16 v[26:29], v[150:153], v[238:241], v[26:29]
	v_mfma_f32_16x16x32_bf16 v[22:25], v[158:161], v[238:241], v[22:25]
	v_mfma_f32_16x16x32_bf16 v[8:11], v[150:153], v[246:249], v[10:13]
	v_mfma_f32_16x16x32_bf16 v[4:7], v[158:161], v[246:249], v[4:7]
	v_mfma_f32_16x16x32_bf16 v[58:61], v[154:157], v[170:173], v[58:61]
	v_mfma_f32_16x16x32_bf16 v[54:57], v[162:165], v[170:173], v[54:57]
	v_mfma_f32_16x16x32_bf16 v[42:45], v[154:157], v[230:233], v[42:45]
	v_mfma_f32_16x16x32_bf16 v[38:41], v[162:165], v[230:233], v[38:41]
	v_mfma_f32_16x16x32_bf16 v[26:29], v[154:157], v[242:245], v[26:29]
	v_mfma_f32_16x16x32_bf16 v[22:25], v[162:165], v[242:245], v[22:25]
	v_mfma_f32_16x16x32_bf16 v[10:13], v[154:157], v[250:253], v[8:11]
	v_mfma_f32_16x16x32_bf16 v[6:9], v[162:165], v[250:253], v[4:7]
	s_setprio 0
	s_barrier
	s_add_u32 s60, s60, 0x100
	s_addc_u32 s61, s61, 0
	s_add_u32 s26, s26, 0x100
	s_addc_u32 s27, s27, 0
	s_cmp_ge_i32 s30, s51
	s_cbranch_scc1 .LBB0_996
	s_mov_b32 s62, s30
	s_cmp_lt_i32 s62, 32
	s_cbranch_scc1 .LBB0_990
	s_branch .LBB0_989

; #define PG8_STAGE(bufoff, gbase, voff) do { _Pragma("unroll") for (int _i = 0; _i < 2; ++_i) \
;         __builtin_amdgcn_global_load_lds((const unsigned*)((const char*)(gbase) + (voff)[_i]), (PG8_LAS unsigned*)(lds + (bufoff) + ldsw + _i * 8192), 16, 0, 0); } while (0)
; #define PG8_LDA(dst, b, h) do { _Pragma("unroll") for (int m = 0; m < 4; ++m) _Pragma("unroll") for (int k = 0; k < 2; ++k) dst[m][k] = *(const PG8_LAS bf16x8*)(lds + PG8_SA(b, h) + aoff + m * 2048 + k * 1024); } while (0)
; #define PG8_LDB(dst, b, h) do { _Pragma("unroll") for (int n = 0; n < 2; ++n) _Pragma("unroll") for (int k = 0; k < 2; ++k) dst[n][k] = *(const PG8_LAS bf16x8*)(lds + PG8_SB(b, h) + boff + n * 2048 + k * 1024); } while (0)
; #define PG8_MMA(ai, bj, At, Bt) do { __builtin_amdgcn_s_setprio(1); _Pragma("unroll") for (int m = 0; m < 4; ++m) _Pragma("unroll") for (int n = 0; n < 2; ++n) _Pragma("unroll") for (int k = 0; k < 2; ++k) \
;         acc[ai][bj][m][n] = __builtin_amdgcn_mfma_f32_16x16x32_bf16(Bt[n][k], At[m][k], acc[ai][bj][m][n], 0, 0, 0); __builtin_amdgcn_s_setprio(0); } while (0)
; template <class Epi, class Sched, bool ALIGN_EPI = false, bool SP2 = false>
; __device__ __forceinline__ void gemm_phase(PG8_LAS unsigned char* lds, const Gemm g, const Sched& S, const Epi& E, int tid_in) {
;     ...
;             const bool last = (t == nt - 2);
;             if constexpr (mid_hook<Epi>::value) { if (t == Epi::H1 || t == Epi::H2) E.mid(acc, cur, wr, wc, fr, fq, t == Epi::H2); }
;             const char* a1 = cA + (size_t)(t + 1) * kstep + (t >= jt ? jb : 0);
;             const char* a2 = last ? nA : cA + (size_t)(t + 2) * kstep + (t + 2 >= jt ? jb : 0); const char* b2 = last ? nB : cB + (size_t)(t + 2) * kstep;
;             const char* a3 = a2 + kstep; const char* b3 = b2 + kstep;
;             if (last && has_next) S.a_ready(nxt);
;             if constexpr (SP2) {
;             PG8_LDB(B0, 0, 0); PG8_LDB(B1, 0, 1); PG8_SCHED; PG8_LDA(At, 0, 0); PG8_STAGE(PG8_SA(1, 1), a1 + hsA, voffA);
;             PG8_WAIT_V(8); PG8_WAIT_L(0); PG8_BAR; PG8_MMA(0, 0, At, B0); PG8_MMA(0, 1, At, B1); PG8_BAR; PG8_SCHED;
;             PG8_LDA(At, 0, 1); PG8_STAGE(PG8_SB(0, 0), b2, voffB); PG8_STAGE(PG8_SB(0, 1), b2 + hsB, voffB); PG8_STAGE(PG8_SA(0, 0), a2, voffA);
;             PG8_WAIT_V(8); PG8_WAIT_L(0); PG8_BAR; PG8_MMA(1, 0, At, B0); PG8_MMA(1, 1, At, B1); PG8_BAR; PG8_SCHED;
.LBB0_1070:
	s_add_i32 s38, s40, -2
	s_cmp_ge_i32 s38, s46
	s_cselect_b32 s78, s47, 0
	s_cselect_b32 s79, s62, 0
	s_cmp_ge_i32 s40, s46
	s_cselect_b32 s39, s47, 0
	s_cselect_b32 s38, s62, 0
	s_add_u32 s39, s4, s39
	s_addc_u32 s38, s5, s38
	s_add_u32 s41, s39, 0x80
	s_addc_u32 s38, s38, 0
	s_add_i32 s77, 0, 0x10000
	s_cmp_eq_u32 s61, s40
	s_cselect_b32 s39, s35, s38
	s_cselect_b32 s38, s34, s41
	s_cselect_b32 s83, s37, s76
	s_cselect_b32 s82, s36, s75
	s_add_i32 s41, 0, 0x14000
	v_add_u32_e32 v144, s77, v217
	v_add_u32_e32 v170, s41, v217
	ds_read_b128 v[116:119], v144
	ds_read_b128 v[120:123], v144 offset:1024
	ds_read_b128 v[140:143], v144 offset:2048
	ds_read_b128 v[144:147], v144 offset:3072
	ds_read_b128 v[148:151], v170
	ds_read_b128 v[152:155], v170 offset:1024
	ds_read_b128 v[156:159], v170 offset:2048
	ds_read_b128 v[170:173], v170 offset:3072
	v_lshl_add_u64 v[190:191], s[4:5], 0, v[168:169]
	v_lshl_add_u64 v[190:191], v[190:191], 0, s[78:79]
	s_add_i32 m0, s51, 0xc000
	ds_read_b128 v[174:177], v219
	ds_read_b128 v[178:181], v219 offset:1024
	ds_read_b128 v[182:185], v219 offset:2048
	ds_read_b128 v[186:189], v219 offset:3072
	ds_read_b128 v[204:207], v219 offset:4096
	ds_read_b128 v[208:211], v219 offset:5120
	ds_read_b128 v[212:215], v219 offset:6144
	ds_read_b128 v[220:223], v219 offset:7168
	global_load_lds_dwordx4 v[190:191], off
	v_lshl_add_u64 v[190:191], s[4:5], 0, v[166:167]
	v_lshl_add_u64 v[190:191], v[190:191], 0, s[78:79]
	s_add_i32 m0, s51, 0xe000
	s_nop 0
	global_load_lds_dwordx4 v[190:191], off
	s_waitcnt vmcnt(8)
	s_waitcnt lgkmcnt(0)
	s_barrier
	s_setprio 1
	s_waitcnt lgkmcnt(0)
	v_mfma_f32_16x16x32_bf16 v[136:139], v[116:119], v[174:177], v[136:139]
	v_mfma_f32_16x16x32_bf16 v[132:135], v[140:143], v[174:177], v[132:135]
	v_mfma_f32_16x16x32_bf16 v[128:131], v[116:119], v[182:185], v[128:131]
	v_mfma_f32_16x16x32_bf16 v[124:127], v[140:143], v[182:185], v[124:127]
	v_mfma_f32_16x16x32_bf16 v[112:115], v[116:119], v[204:207], v[112:115]
	v_mfma_f32_16x16x32_bf16 v[108:111], v[140:143], v[204:207], v[108:111]
	v_mfma_f32_16x16x32_bf16 v[104:107], v[116:119], v[212:215], v[104:107]
	v_mfma_f32_16x16x32_bf16 v[100:103], v[140:143], v[212:215], v[100:103]
	v_mfma_f32_16x16x32_bf16 v[136:139], v[120:123], v[178:181], v[136:139]
	v_mfma_f32_16x16x32_bf16 v[132:135], v[144:147], v[178:181], v[132:135]
	v_mfma_f32_16x16x32_bf16 v[128:131], v[120:123], v[186:189], v[128:131]
	v_mfma_f32_16x16x32_bf16 v[124:127], v[144:147], v[186:189], v[124:127]
	v_mfma_f32_16x16x32_bf16 v[112:115], v[120:123], v[208:211], v[112:115]
	v_mfma_f32_16x16x32_bf16 v[108:111], v[144:147], v[208:211], v[108:111]
	v_mfma_f32_16x16x32_bf16 v[104:107], v[120:123], v[220:223], v[104:107]
	v_mfma_f32_16x16x32_bf16 v[100:103], v[144:147], v[220:223], v[100:103]
	v_mfma_f32_16x16x32_bf16 v[64:67], v[148:151], v[174:177], v[64:67]
	v_mfma_f32_16x16x32_bf16 v[56:59], v[156:159], v[174:177], v[56:59]
	v_mfma_f32_16x16x32_bf16 v[60:63], v[148:151], v[182:185], v[60:63]
	v_mfma_f32_16x16x32_bf16 v[52:55], v[156:159], v[182:185], v[52:55]
	v_mfma_f32_16x16x32_bf16 v[48:51], v[148:151], v[204:207], v[48:51]
	v_mfma_f32_16x16x32_bf16 v[40:43], v[156:159], v[204:207], v[40:43]
	v_mfma_f32_16x16x32_bf16 v[44:47], v[148:151], v[212:215], v[44:47]
	v_mfma_f32_16x16x32_bf16 v[36:39], v[156:159], v[212:215], v[36:39]
	v_mfma_f32_16x16x32_bf16 v[64:67], v[152:155], v[178:181], v[64:67]
	v_mfma_f32_16x16x32_bf16 v[56:59], v[170:173], v[178:181], v[56:59]
	v_mfma_f32_16x16x32_bf16 v[60:63], v[152:155], v[186:189], v[60:63]
	v_mfma_f32_16x16x32_bf16 v[52:55], v[170:173], v[186:189], v[52:55]
	v_mfma_f32_16x16x32_bf16 v[48:51], v[152:155], v[208:211], v[48:51]
	v_mfma_f32_16x16x32_bf16 v[40:43], v[170:173], v[208:211], v[40:43]
	v_mfma_f32_16x16x32_bf16 v[44:47], v[152:155], v[220:223], v[44:47]
	v_mfma_f32_16x16x32_bf16 v[36:39], v[170:173], v[220:223], v[36:39]
	s_setprio 0
	s_barrier
	s_add_i32 s77, s77, s50
	v_lshl_add_u64 v[190:191], s[82:83], 0, v[160:161]
	s_mov_b32 m0, s77
	ds_read_b128 v[174:177], v219 offset:16384
	ds_read_b128 v[178:181], v219 offset:17408
	ds_read_b128 v[182:185], v219 offset:18432
	ds_read_b128 v[186:189], v219 offset:19456
	ds_read_b128 v[204:207], v219 offset:20480
	ds_read_b128 v[208:211], v219 offset:21504
	ds_read_b128 v[212:215], v219 offset:22528
	ds_read_b128 v[220:223], v219 offset:23552
	global_load_lds_dwordx4 v[190:191], off
	s_add_i32 m0, s77, 0x2000
	s_add_u32 s78, s82, s12
	v_lshl_add_u64 v[192:193], s[82:83], 0, v[164:165]
	s_addc_u32 s79, s83, s13
	s_add_i32 s41, s41, s50
	global_load_lds_dwordx4 v[192:193], off
	v_lshl_add_u64 v[196:197], s[78:79], 0, v[160:161]
	s_mov_b32 m0, s41
	v_lshl_add_u64 v[198:199], s[78:79], 0, v[164:165]
	global_load_lds_dwordx4 v[196:197], off
	s_add_i32 m0, s41, 0x2000
	v_lshl_add_u64 v[200:201], s[38:39], 0, v[0:1]
	global_load_lds_dwordx4 v[198:199], off
	s_mov_b32 m0, s51
	v_lshl_add_u64 v[202:203], s[38:39], 0, v[162:163]
	global_load_lds_dwordx4 v[200:201], off
	s_mov_b32 m0, s52
	s_nop 0
	global_load_lds_dwordx4 v[202:203], off
	s_waitcnt vmcnt(8)
	s_waitcnt lgkmcnt(0)
	s_barrier
; #define PG8_STAGE(bufoff, gbase, voff) do { _Pragma("unroll") for (int _i = 0; _i < 2; ++_i) \
;         __builtin_amdgcn_global_load_lds((const unsigned*)((const char*)(gbase) + (voff)[_i]), (PG8_LAS unsigned*)(lds + (bufoff) + ldsw + _i * 8192), 16, 0, 0); } while (0)
; #define PG8_LDA(dst, b, h) do { _Pragma("unroll") for (int m = 0; m < 4; ++m) _Pragma("unroll") for (int k = 0; k < 2; ++k) dst[m][k] = *(const PG8_LAS bf16x8*)(lds + PG8_SA(b, h) + aoff + m * 2048 + k * 1024); } while (0)
; #define PG8_LDB(dst, b, h) do { _Pragma("unroll") for (int n = 0; n < 2; ++n) _Pragma("unroll") for (int k = 0; k < 2; ++k) dst[n][k] = *(const PG8_LAS bf16x8*)(lds + PG8_SB(b, h) + boff + n * 2048 + k * 1024); } while (0)
; #define PG8_MMA(ai, bj, At, Bt) do { __builtin_amdgcn_s_setprio(1); _Pragma("unroll") for (int m = 0; m < 4; ++m) _Pragma("unroll") for (int n = 0; n < 2; ++n) _Pragma("unroll") for (int k = 0; k < 2; ++k) \
;         acc[ai][bj][m][n] = __builtin_amdgcn_mfma_f32_16x16x32_bf16(Bt[n][k], At[m][k], acc[ai][bj][m][n], 0, 0, 0); __builtin_amdgcn_s_setprio(0); } while (0)
; #define PG8_WAIT_V(n) asm volatile("s_waitcnt vmcnt(" #n ")" ::: "memory")
; #define PG8_WAIT_L(n) asm volatile("s_waitcnt lgkmcnt(" #n ")" ::: "memory")
; #define PG8_BAR __builtin_amdgcn_s_barrier()
; #define PG8_SCHED __builtin_amdgcn_sched_barrier(0)
; template <class Epi, class Sched, bool ALIGN_EPI = false, bool SP2 = false>
; __device__ __forceinline__ void gemm_phase(PG8_LAS unsigned char* lds, const Gemm g, const Sched& S, const Epi& E, int tid_in) {
;     ...
;             PG8_WAIT_V(8); PG8_WAIT_L(0); PG8_BAR; PG8_MMA(1, 0, At, B0); PG8_MMA(1, 1, At, B1); PG8_BAR; PG8_SCHED;
;             PG8_LDB(B0, 1, 0); PG8_LDB(B1, 1, 1); PG8_SCHED; PG8_LDA(At, 1, 0); PG8_STAGE(PG8_SA(0, 1), a2 + hsA, voffA);
;             PG8_WAIT_V(8); PG8_WAIT_L(0); PG8_BAR; PG8_MMA(0, 0, At, B0); PG8_MMA(0, 1, At, B1); PG8_BAR; PG8_SCHED;
	s_setprio 1
	s_waitcnt lgkmcnt(0)
	v_mfma_f32_16x16x32_bf16 v[96:99], v[116:119], v[174:177], v[96:99]
	v_mfma_f32_16x16x32_bf16 v[92:95], v[140:143], v[174:177], v[92:95]
	v_mfma_f32_16x16x32_bf16 v[88:91], v[116:119], v[182:185], v[88:91]
	v_mfma_f32_16x16x32_bf16 v[84:87], v[140:143], v[182:185], v[84:87]
	v_mfma_f32_16x16x32_bf16 v[80:83], v[116:119], v[204:207], v[80:83]
	v_mfma_f32_16x16x32_bf16 v[76:79], v[140:143], v[204:207], v[76:79]
	v_mfma_f32_16x16x32_bf16 v[72:75], v[116:119], v[212:215], v[72:75]
	v_mfma_f32_16x16x32_bf16 v[68:71], v[140:143], v[212:215], v[68:71]
	v_mfma_f32_16x16x32_bf16 v[96:99], v[120:123], v[178:181], v[96:99]
	v_mfma_f32_16x16x32_bf16 v[92:95], v[144:147], v[178:181], v[92:95]
	v_mfma_f32_16x16x32_bf16 v[88:91], v[120:123], v[186:189], v[88:91]
	v_mfma_f32_16x16x32_bf16 v[84:87], v[144:147], v[186:189], v[84:87]
	v_mfma_f32_16x16x32_bf16 v[80:83], v[120:123], v[208:211], v[80:83]
	v_mfma_f32_16x16x32_bf16 v[76:79], v[144:147], v[208:211], v[76:79]
	v_mfma_f32_16x16x32_bf16 v[72:75], v[120:123], v[220:223], v[72:75]
	v_mfma_f32_16x16x32_bf16 v[68:71], v[144:147], v[220:223], v[68:71]
	v_mfma_f32_16x16x32_bf16 v[32:35], v[148:151], v[174:177], v[32:35]
	v_mfma_f32_16x16x32_bf16 v[28:31], v[156:159], v[174:177], v[28:31]
	v_mfma_f32_16x16x32_bf16 v[24:27], v[148:151], v[182:185], v[24:27]
	v_mfma_f32_16x16x32_bf16 v[12:15], v[156:159], v[182:185], v[12:15]
	v_mfma_f32_16x16x32_bf16 v[20:23], v[148:151], v[204:207], v[20:23]
	v_mfma_f32_16x16x32_bf16 v[8:11], v[156:159], v[204:207], v[8:11]
	v_mfma_f32_16x16x32_bf16 v[16:19], v[148:151], v[212:215], v[16:19]
	v_mfma_f32_16x16x32_bf16 v[4:7], v[156:159], v[212:215], v[4:7]
	v_mfma_f32_16x16x32_bf16 v[32:35], v[152:155], v[178:181], v[32:35]
	v_mfma_f32_16x16x32_bf16 v[28:31], v[170:173], v[178:181], v[28:31]
	v_mfma_f32_16x16x32_bf16 v[24:27], v[152:155], v[186:189], v[24:27]
	v_mfma_f32_16x16x32_bf16 v[12:15], v[170:173], v[186:189], v[12:15]
	v_mfma_f32_16x16x32_bf16 v[20:23], v[152:155], v[208:211], v[20:23]
	v_mfma_f32_16x16x32_bf16 v[8:11], v[170:173], v[208:211], v[8:11]
	v_mfma_f32_16x16x32_bf16 v[16:19], v[152:155], v[220:223], v[16:19]
	v_mfma_f32_16x16x32_bf16 v[4:7], v[170:173], v[220:223], v[4:7]
	s_setprio 0
	s_barrier
	s_add_i32 s41, 0, 0x18000
	s_add_i32 s77, 0, 0x1c000
	v_add_u32_e32 v144, s41, v217
	v_add_u32_e32 v170, s77, v217
	ds_read_b128 v[116:119], v144
	ds_read_b128 v[120:123], v144 offset:1024
	ds_read_b128 v[140:143], v144 offset:2048
	ds_read_b128 v[144:147], v144 offset:3072
	ds_read_b128 v[148:151], v170
	ds_read_b128 v[152:155], v170 offset:1024
	ds_read_b128 v[156:159], v170 offset:2048
	ds_read_b128 v[170:173], v170 offset:3072
	s_add_u32 s38, s38, s10
	s_addc_u32 s39, s39, s11
	s_mov_b32 m0, s53
	v_lshl_add_u64 v[228:229], s[38:39], 0, v[0:1]
	ds_read_b128 v[174:177], v219 offset:32768
	ds_read_b128 v[178:181], v219 offset:33792
	ds_read_b128 v[182:185], v219 offset:34816
	ds_read_b128 v[186:189], v219 offset:35840
	ds_read_b128 v[204:207], v219 offset:36864
	ds_read_b128 v[208:211], v219 offset:37888
	ds_read_b128 v[212:215], v219 offset:38912
	ds_read_b128 v[220:223], v219 offset:39936
	global_load_lds_dwordx4 v[228:229], off
	v_lshl_add_u64 v[228:229], s[38:39], 0, v[162:163]
	s_mov_b32 m0, s54
	s_nop 0
	global_load_lds_dwordx4 v[228:229], off
	s_waitcnt vmcnt(8)
	s_waitcnt lgkmcnt(0)
	s_barrier
	s_setprio 1
	s_waitcnt lgkmcnt(0)
	v_mfma_f32_16x16x32_bf16 v[136:139], v[116:119], v[174:177], v[136:139]
	v_mfma_f32_16x16x32_bf16 v[132:135], v[140:143], v[174:177], v[132:135]
	v_mfma_f32_16x16x32_bf16 v[128:131], v[116:119], v[182:185], v[128:131]
	v_mfma_f32_16x16x32_bf16 v[124:127], v[140:143], v[182:185], v[124:127]
	v_mfma_f32_16x16x32_bf16 v[112:115], v[116:119], v[204:207], v[112:115]
	v_mfma_f32_16x16x32_bf16 v[108:111], v[140:143], v[204:207], v[108:111]
	v_mfma_f32_16x16x32_bf16 v[104:107], v[116:119], v[212:215], v[104:107]
	v_mfma_f32_16x16x32_bf16 v[100:103], v[140:143], v[212:215], v[100:103]
	v_mfma_f32_16x16x32_bf16 v[136:139], v[120:123], v[178:181], v[136:139]
	v_mfma_f32_16x16x32_bf16 v[132:135], v[144:147], v[178:181], v[132:135]
	v_mfma_f32_16x16x32_bf16 v[128:131], v[120:123], v[186:189], v[128:131]
	v_mfma_f32_16x16x32_bf16 v[124:127], v[144:147], v[186:189], v[124:127]
	v_mfma_f32_16x16x32_bf16 v[112:115], v[120:123], v[208:211], v[112:115]
	v_mfma_f32_16x16x32_bf16 v[108:111], v[144:147], v[208:211], v[108:111]
	v_mfma_f32_16x16x32_bf16 v[104:107], v[120:123], v[220:223], v[104:107]
	v_mfma_f32_16x16x32_bf16 v[100:103], v[144:147], v[220:223], v[100:103]
	v_mfma_f32_16x16x32_bf16 v[64:67], v[148:151], v[174:177], v[64:67]
	v_mfma_f32_16x16x32_bf16 v[56:59], v[156:159], v[174:177], v[56:59]
	v_mfma_f32_16x16x32_bf16 v[60:63], v[148:151], v[182:185], v[60:63]
	v_mfma_f32_16x16x32_bf16 v[52:55], v[156:159], v[182:185], v[52:55]
	v_mfma_f32_16x16x32_bf16 v[48:51], v[148:151], v[204:207], v[48:51]
	v_mfma_f32_16x16x32_bf16 v[40:43], v[156:159], v[204:207], v[40:43]
	v_mfma_f32_16x16x32_bf16 v[44:47], v[148:151], v[212:215], v[44:47]
	v_mfma_f32_16x16x32_bf16 v[36:39], v[156:159], v[212:215], v[36:39]
	v_mfma_f32_16x16x32_bf16 v[64:67], v[152:155], v[178:181], v[64:67]
	v_mfma_f32_16x16x32_bf16 v[56:59], v[170:173], v[178:181], v[56:59]
	v_mfma_f32_16x16x32_bf16 v[60:63], v[152:155], v[186:189], v[60:63]
	v_mfma_f32_16x16x32_bf16 v[52:55], v[170:173], v[186:189], v[52:55]
	v_mfma_f32_16x16x32_bf16 v[48:51], v[152:155], v[208:211], v[48:51]
	v_mfma_f32_16x16x32_bf16 v[40:43], v[170:173], v[208:211], v[40:43]
	v_mfma_f32_16x16x32_bf16 v[44:47], v[152:155], v[220:223], v[44:47]
	v_mfma_f32_16x16x32_bf16 v[36:39], v[170:173], v[220:223], v[36:39]
	s_setprio 0
	s_barrier
; #define PG8_STAGE(bufoff, gbase, voff) do { _Pragma("unroll") for (int _i = 0; _i < 2; ++_i) \
;         __builtin_amdgcn_global_load_lds((const unsigned*)((const char*)(gbase) + (voff)[_i]), (PG8_LAS unsigned*)(lds + (bufoff) + ldsw + _i * 8192), 16, 0, 0); } while (0)
; #define PG8_LDA(dst, b, h) do { _Pragma("unroll") for (int m = 0; m < 4; ++m) _Pragma("unroll") for (int k = 0; k < 2; ++k) dst[m][k] = *(const PG8_LAS bf16x8*)(lds + PG8_SA(b, h) + aoff + m * 2048 + k * 1024); } while (0)
; #define PG8_MMA(ai, bj, At, Bt) do { __builtin_amdgcn_s_setprio(1); _Pragma("unroll") for (int m = 0; m < 4; ++m) _Pragma("unroll") for (int n = 0; n < 2; ++n) _Pragma("unroll") for (int k = 0; k < 2; ++k) \
;         acc[ai][bj][m][n] = __builtin_amdgcn_mfma_f32_16x16x32_bf16(Bt[n][k], At[m][k], acc[ai][bj][m][n], 0, 0, 0); __builtin_amdgcn_s_setprio(0); } while (0)
; #define PG8_WAIT_V(n) asm volatile("s_waitcnt vmcnt(" #n ")" ::: "memory")
; #define PG8_WAIT_L(n) asm volatile("s_waitcnt lgkmcnt(" #n ")" ::: "memory")
; #define PG8_BAR __builtin_amdgcn_s_barrier()
; #define PG8_SCHED __builtin_amdgcn_sched_barrier(0)
; template <class Epi, class Sched, bool ALIGN_EPI = false, bool SP2 = false>
; __device__ __forceinline__ void gemm_phase(PG8_LAS unsigned char* lds, const Gemm g, const Sched& S, const Epi& E, int tid_in) {
;     ...
;         for (int t = 0; t < nt; t += 2) {
;     ...
;             PG8_LDA(At, 1, 1); PG8_STAGE(PG8_SB(1, 0), b3, voffB); PG8_STAGE(PG8_SB(1, 1), b3 + hsB, voffB); PG8_STAGE(PG8_SA(1, 0), a3, voffA);
;             PG8_WAIT_V(8); PG8_WAIT_L(0); PG8_BAR; PG8_MMA(1, 0, At, B0); PG8_MMA(1, 1, At, B1); PG8_BAR; PG8_SCHED;
	s_add_i32 s38, s41, s50
	v_lshl_add_u64 v[190:191], v[190:191], 0, s[80:81]
	s_mov_b32 m0, s38
	ds_read_b128 v[174:177], v219 offset:49152
	ds_read_b128 v[178:181], v219 offset:50176
	ds_read_b128 v[182:185], v219 offset:51200
	ds_read_b128 v[186:189], v219 offset:52224
	ds_read_b128 v[204:207], v219 offset:53248
	ds_read_b128 v[208:211], v219 offset:54272
	ds_read_b128 v[212:215], v219 offset:55296
	ds_read_b128 v[220:223], v219 offset:56320
	global_load_lds_dwordx4 v[190:191], off
	v_lshl_add_u64 v[190:191], v[192:193], 0, s[80:81]
	s_add_i32 m0, s38, 0x2000
	s_add_i32 s38, s77, s50
	global_load_lds_dwordx4 v[190:191], off
	v_lshl_add_u64 v[190:191], v[196:197], 0, s[80:81]
	s_mov_b32 m0, s38
	s_nop 0
	global_load_lds_dwordx4 v[190:191], off
	v_lshl_add_u64 v[190:191], v[198:199], 0, s[80:81]
	s_add_i32 m0, s38, 0x2000
	s_nop 0
	global_load_lds_dwordx4 v[190:191], off
	v_lshl_add_u64 v[190:191], v[200:201], 0, s[80:81]
	s_mov_b32 m0, s59
	s_nop 0
	global_load_lds_dwordx4 v[190:191], off
	v_lshl_add_u64 v[190:191], v[202:203], 0, s[80:81]
	s_mov_b32 m0, s60
	s_nop 0
	global_load_lds_dwordx4 v[190:191], off
	s_waitcnt vmcnt(8)
	s_waitcnt lgkmcnt(0)
	s_barrier
	s_setprio 1
	s_waitcnt lgkmcnt(0)
	v_mfma_f32_16x16x32_bf16 v[96:99], v[116:119], v[174:177], v[96:99]
	v_mfma_f32_16x16x32_bf16 v[92:95], v[140:143], v[174:177], v[92:95]
	v_mfma_f32_16x16x32_bf16 v[88:91], v[116:119], v[182:185], v[88:91]
	v_mfma_f32_16x16x32_bf16 v[84:87], v[140:143], v[182:185], v[84:87]
	v_mfma_f32_16x16x32_bf16 v[80:83], v[116:119], v[204:207], v[80:83]
	v_mfma_f32_16x16x32_bf16 v[76:79], v[140:143], v[204:207], v[76:79]
	v_mfma_f32_16x16x32_bf16 v[72:75], v[116:119], v[212:215], v[72:75]
	v_mfma_f32_16x16x32_bf16 v[68:71], v[140:143], v[212:215], v[68:71]
	v_mfma_f32_16x16x32_bf16 v[96:99], v[120:123], v[178:181], v[96:99]
	v_mfma_f32_16x16x32_bf16 v[92:95], v[144:147], v[178:181], v[92:95]
	v_mfma_f32_16x16x32_bf16 v[88:91], v[120:123], v[186:189], v[88:91]
	v_mfma_f32_16x16x32_bf16 v[84:87], v[144:147], v[186:189], v[84:87]
	v_mfma_f32_16x16x32_bf16 v[80:83], v[120:123], v[208:211], v[80:83]
	v_mfma_f32_16x16x32_bf16 v[76:79], v[144:147], v[208:211], v[76:79]
	v_mfma_f32_16x16x32_bf16 v[72:75], v[120:123], v[220:223], v[72:75]
	v_mfma_f32_16x16x32_bf16 v[68:71], v[144:147], v[220:223], v[68:71]
	v_mfma_f32_16x16x32_bf16 v[32:35], v[148:151], v[174:177], v[32:35]
	v_mfma_f32_16x16x32_bf16 v[28:31], v[156:159], v[174:177], v[28:31]
	v_mfma_f32_16x16x32_bf16 v[24:27], v[148:151], v[182:185], v[24:27]
	v_mfma_f32_16x16x32_bf16 v[12:15], v[156:159], v[182:185], v[12:15]
	v_mfma_f32_16x16x32_bf16 v[20:23], v[148:151], v[204:207], v[20:23]
	v_mfma_f32_16x16x32_bf16 v[8:11], v[156:159], v[204:207], v[8:11]
	v_mfma_f32_16x16x32_bf16 v[16:19], v[148:151], v[212:215], v[16:19]
	v_mfma_f32_16x16x32_bf16 v[4:7], v[156:159], v[212:215], v[4:7]
	v_mfma_f32_16x16x32_bf16 v[32:35], v[152:155], v[178:181], v[32:35]
	v_mfma_f32_16x16x32_bf16 v[28:31], v[170:173], v[178:181], v[28:31]
	v_mfma_f32_16x16x32_bf16 v[24:27], v[152:155], v[186:189], v[24:27]
	v_mfma_f32_16x16x32_bf16 v[12:15], v[170:173], v[186:189], v[12:15]
	v_mfma_f32_16x16x32_bf16 v[20:23], v[152:155], v[208:211], v[20:23]
	v_mfma_f32_16x16x32_bf16 v[8:11], v[170:173], v[208:211], v[8:11]
	v_mfma_f32_16x16x32_bf16 v[16:19], v[152:155], v[220:223], v[16:19]
	v_mfma_f32_16x16x32_bf16 v[4:7], v[170:173], v[220:223], v[4:7]
	s_setprio 0
	s_barrier
	s_add_i32 s38, s40, 2
	s_add_u32 s75, s75, 0x100
	s_addc_u32 s76, s76, 0
	s_add_u32 s4, s4, 0x100
	s_addc_u32 s5, s5, 0
	s_cmp_ge_i32 s40, s61
	s_mov_b32 s40, s38
	s_cbranch_scc0 .LBB0_1070
	s_movk_i32 s83, 0x3000

; #define PG8_STAGE(bufoff, gbase, voff) do { _Pragma("unroll") for (int _i = 0; _i < 2; ++_i) \
;         __builtin_amdgcn_global_load_lds((const unsigned*)((const char*)(gbase) + (voff)[_i]), (PG8_LAS unsigned*)(lds + (bufoff) + ldsw + _i * 8192), 16, 0, 0); } while (0)
; #define PG8_LDA(dst, b, h) do { _Pragma("unroll") for (int m = 0; m < 4; ++m) _Pragma("unroll") for (int k = 0; k < 2; ++k) dst[m][k] = *(const PG8_LAS bf16x8*)(lds + PG8_SA(b, h) + aoff + m * 2048 + k * 1024); } while (0)
; #define PG8_LDB(dst, b, h) do { _Pragma("unroll") for (int n = 0; n < 2; ++n) _Pragma("unroll") for (int k = 0; k < 2; ++k) dst[n][k] = *(const PG8_LAS bf16x8*)(lds + PG8_SB(b, h) + boff + n * 2048 + k * 1024); } while (0)
; #define PG8_MMA(ai, bj, At, Bt) do { __builtin_amdgcn_s_setprio(1); _Pragma("unroll") for (int m = 0; m < 4; ++m) _Pragma("unroll") for (int n = 0; n < 2; ++n) _Pragma("unroll") for (int k = 0; k < 2; ++k) \
;         acc[ai][bj][m][n] = __builtin_amdgcn_mfma_f32_16x16x32_bf16(Bt[n][k], At[m][k], acc[ai][bj][m][n], 0, 0, 0); __builtin_amdgcn_s_setprio(0); } while (0)
; template <class Epi, class Sched, bool ALIGN_EPI = false, bool SP2 = false>
; __device__ __forceinline__ void gemm_phase(PG8_LAS unsigned char* lds, const Gemm g, const Sched& S, const Epi& E, int tid_in) {
;     ...
;             const bool last = (t == nt - 2);
;             if constexpr (mid_hook<Epi>::value) { if (t == Epi::H1 || t == Epi::H2) E.mid(acc, cur, wr, wc, fr, fq, t == Epi::H2); }
;             const char* a1 = cA + (size_t)(t + 1) * kstep + (t >= jt ? jb : 0);
;             const char* a2 = last ? nA : cA + (size_t)(t + 2) * kstep + (t + 2 >= jt ? jb : 0); const char* b2 = last ? nB : cB + (size_t)(t + 2) * kstep;
;             const char* a3 = a2 + kstep; const char* b3 = b2 + kstep;
;             if (last && has_next) S.a_ready(nxt);
;             if constexpr (SP2) {
;             PG8_LDB(B0, 0, 0); PG8_LDB(B1, 0, 1); PG8_SCHED; PG8_LDA(At, 0, 0); PG8_STAGE(PG8_SA(1, 1), a1 + hsA, voffA);
;             PG8_WAIT_V(8); PG8_WAIT_L(0); PG8_BAR; PG8_MMA(0, 0, At, B0); PG8_MMA(0, 1, At, B1); PG8_BAR; PG8_SCHED;
;             PG8_LDA(At, 0, 1); PG8_STAGE(PG8_SB(0, 0), b2, voffB); PG8_STAGE(PG8_SB(0, 1), b2 + hsB, voffB); PG8_STAGE(PG8_SA(0, 0), a2, voffA);
;             PG8_WAIT_V(8); PG8_WAIT_L(0); PG8_BAR; PG8_MMA(1, 0, At, B0); PG8_MMA(1, 1, At, B1); PG8_BAR; PG8_SCHED;
.LBB0_1102:
	s_add_i32 s26, s55, -2
	s_cmp_ge_i32 s26, s28
	s_cselect_b32 s58, s29, 0
	s_cselect_b32 s59, s49, 0
	s_cmp_ge_i32 s55, s28
	s_cselect_b32 s27, s29, 0
	s_cselect_b32 s26, s49, 0
	s_add_u32 s27, s24, s27
	s_addc_u32 s26, s25, s26
	s_add_u32 s60, s27, 0x80
	s_addc_u32 s26, s26, 0
	s_add_i32 s62, 0, 0x10000
	s_cmp_eq_u32 s48, s55
	s_cselect_b32 s27, s5, s26
	s_cselect_b32 s26, s4, s60
	s_cselect_b32 s61, s23, s21
	s_cselect_b32 s60, s22, s17
	s_add_i32 s63, 0, 0x14000
	v_add_u32_e32 v160, s62, v3
	v_add_u32_e32 v176, s63, v3
	ds_read_b128 v[148:151], v160
	ds_read_b128 v[152:155], v160 offset:1024
	ds_read_b128 v[156:159], v160 offset:2048
	ds_read_b128 v[160:163], v160 offset:3072
	ds_read_b128 v[164:167], v176
	ds_read_b128 v[168:171], v176 offset:1024
	ds_read_b128 v[172:175], v176 offset:2048
	ds_read_b128 v[176:179], v176 offset:3072
	v_lshl_add_u64 v[192:193], s[24:25], 0, v[140:141]
	v_lshl_add_u64 v[192:193], v[192:193], 0, s[58:59]
	s_add_i32 m0, s35, 0xc000
	ds_read_b128 v[180:183], v147
	ds_read_b128 v[184:187], v147 offset:1024
	ds_read_b128 v[188:191], v147 offset:2048
	ds_read_b128 v[204:207], v147 offset:3072
	ds_read_b128 v[208:211], v147 offset:4096
	ds_read_b128 v[212:215], v147 offset:5120
	ds_read_b128 v[216:219], v147 offset:6144
	ds_read_b128 v[220:223], v147 offset:7168
	global_load_lds_dwordx4 v[192:193], off
	v_lshl_add_u64 v[192:193], s[24:25], 0, v[138:139]
	v_lshl_add_u64 v[192:193], v[192:193], 0, s[58:59]
	s_add_i32 m0, s35, 0xe000
	s_nop 0
	global_load_lds_dwordx4 v[192:193], off
	s_waitcnt vmcnt(8)
	s_waitcnt lgkmcnt(0)
	s_barrier
	s_setprio 1
	s_waitcnt lgkmcnt(0)
	v_mfma_f32_16x16x32_bf16 v[124:127], v[148:151], v[180:183], v[124:127]
	v_mfma_f32_16x16x32_bf16 v[128:131], v[156:159], v[180:183], v[128:131]
	v_mfma_f32_16x16x32_bf16 v[112:115], v[148:151], v[188:191], v[112:115]
	v_mfma_f32_16x16x32_bf16 v[108:111], v[156:159], v[188:191], v[108:111]
	v_mfma_f32_16x16x32_bf16 v[96:99], v[148:151], v[208:211], v[96:99]
	v_mfma_f32_16x16x32_bf16 v[92:95], v[156:159], v[208:211], v[92:95]
	v_mfma_f32_16x16x32_bf16 v[80:83], v[148:151], v[216:219], v[80:83]
	v_mfma_f32_16x16x32_bf16 v[76:79], v[156:159], v[216:219], v[76:79]
	v_mfma_f32_16x16x32_bf16 v[124:127], v[152:155], v[184:187], v[124:127]
	v_mfma_f32_16x16x32_bf16 v[128:131], v[160:163], v[184:187], v[128:131]
	v_mfma_f32_16x16x32_bf16 v[112:115], v[152:155], v[204:207], v[112:115]
	v_mfma_f32_16x16x32_bf16 v[108:111], v[160:163], v[204:207], v[108:111]
	v_mfma_f32_16x16x32_bf16 v[96:99], v[152:155], v[212:215], v[96:99]
	v_mfma_f32_16x16x32_bf16 v[92:95], v[160:163], v[212:215], v[92:95]
	v_mfma_f32_16x16x32_bf16 v[80:83], v[152:155], v[220:223], v[80:83]
	v_mfma_f32_16x16x32_bf16 v[76:79], v[160:163], v[220:223], v[76:79]
	v_mfma_f32_16x16x32_bf16 v[120:123], v[164:167], v[180:183], v[120:123]
	v_mfma_f32_16x16x32_bf16 v[116:119], v[172:175], v[180:183], v[116:119]
	v_mfma_f32_16x16x32_bf16 v[104:107], v[164:167], v[188:191], v[104:107]
	v_mfma_f32_16x16x32_bf16 v[100:103], v[172:175], v[188:191], v[100:103]
	v_mfma_f32_16x16x32_bf16 v[88:91], v[164:167], v[208:211], v[88:91]
	v_mfma_f32_16x16x32_bf16 v[84:87], v[172:175], v[208:211], v[84:87]
	v_mfma_f32_16x16x32_bf16 v[72:75], v[164:167], v[216:219], v[72:75]
	v_mfma_f32_16x16x32_bf16 v[68:71], v[172:175], v[216:219], v[68:71]
	v_mfma_f32_16x16x32_bf16 v[120:123], v[168:171], v[184:187], v[120:123]
	v_mfma_f32_16x16x32_bf16 v[116:119], v[176:179], v[184:187], v[116:119]
	v_mfma_f32_16x16x32_bf16 v[104:107], v[168:171], v[204:207], v[104:107]
	v_mfma_f32_16x16x32_bf16 v[100:103], v[176:179], v[204:207], v[100:103]
	v_mfma_f32_16x16x32_bf16 v[88:91], v[168:171], v[212:215], v[88:91]
	v_mfma_f32_16x16x32_bf16 v[84:87], v[176:179], v[212:215], v[84:87]
	v_mfma_f32_16x16x32_bf16 v[72:75], v[168:171], v[220:223], v[72:75]
	v_mfma_f32_16x16x32_bf16 v[68:71], v[176:179], v[220:223], v[68:71]
	s_setprio 0
	s_barrier
	s_add_i32 s58, s62, s33
	v_lshl_add_u64 v[192:193], s[60:61], 0, v[134:135]
	s_mov_b32 m0, s58
	ds_read_b128 v[180:183], v147 offset:16384
	ds_read_b128 v[184:187], v147 offset:17408
	ds_read_b128 v[188:191], v147 offset:18432
	ds_read_b128 v[204:207], v147 offset:19456
	ds_read_b128 v[208:211], v147 offset:20480
	ds_read_b128 v[212:215], v147 offset:21504
	ds_read_b128 v[216:219], v147 offset:22528
	ds_read_b128 v[220:223], v147 offset:23552
	global_load_lds_dwordx4 v[192:193], off
	s_add_i32 m0, s58, 0x2000
	s_add_u32 s58, s60, s8
	v_lshl_add_u64 v[196:197], s[60:61], 0, v[0:1]
	s_addc_u32 s59, s61, s9
	s_add_i32 s60, s63, s33
	global_load_lds_dwordx4 v[196:197], off
	v_lshl_add_u64 v[198:199], s[58:59], 0, v[134:135]
	s_mov_b32 m0, s60
	v_lshl_add_u64 v[200:201], s[58:59], 0, v[0:1]
	global_load_lds_dwordx4 v[198:199], off
	s_add_i32 m0, s60, 0x2000
	v_lshl_add_u64 v[202:203], s[26:27], 0, v[136:137]
	global_load_lds_dwordx4 v[200:201], off
	s_mov_b32 m0, s35
	v_lshl_add_u64 v[228:229], s[26:27], 0, v[132:133]
	global_load_lds_dwordx4 v[202:203], off
	s_mov_b32 m0, s36
	s_nop 0
	global_load_lds_dwordx4 v[228:229], off
	s_waitcnt vmcnt(8)
	s_waitcnt lgkmcnt(0)
	s_barrier
; #define PG8_STAGE(bufoff, gbase, voff) do { _Pragma("unroll") for (int _i = 0; _i < 2; ++_i) \
;         __builtin_amdgcn_global_load_lds((const unsigned*)((const char*)(gbase) + (voff)[_i]), (PG8_LAS unsigned*)(lds + (bufoff) + ldsw + _i * 8192), 16, 0, 0); } while (0)
; #define PG8_LDA(dst, b, h) do { _Pragma("unroll") for (int m = 0; m < 4; ++m) _Pragma("unroll") for (int k = 0; k < 2; ++k) dst[m][k] = *(const PG8_LAS bf16x8*)(lds + PG8_SA(b, h) + aoff + m * 2048 + k * 1024); } while (0)
; #define PG8_LDB(dst, b, h) do { _Pragma("unroll") for (int n = 0; n < 2; ++n) _Pragma("unroll") for (int k = 0; k < 2; ++k) dst[n][k] = *(const PG8_LAS bf16x8*)(lds + PG8_SB(b, h) + boff + n * 2048 + k * 1024); } while (0)
; #define PG8_MMA(ai, bj, At, Bt) do { __builtin_amdgcn_s_setprio(1); _Pragma("unroll") for (int m = 0; m < 4; ++m) _Pragma("unroll") for (int n = 0; n < 2; ++n) _Pragma("unroll") for (int k = 0; k < 2; ++k) \
;         acc[ai][bj][m][n] = __builtin_amdgcn_mfma_f32_16x16x32_bf16(Bt[n][k], At[m][k], acc[ai][bj][m][n], 0, 0, 0); __builtin_amdgcn_s_setprio(0); } while (0)
; #define PG8_WAIT_V(n) asm volatile("s_waitcnt vmcnt(" #n ")" ::: "memory")
; #define PG8_WAIT_L(n) asm volatile("s_waitcnt lgkmcnt(" #n ")" ::: "memory")
; #define PG8_BAR __builtin_amdgcn_s_barrier()
; #define PG8_SCHED __builtin_amdgcn_sched_barrier(0)
; template <class Epi, class Sched, bool ALIGN_EPI = false, bool SP2 = false>
; __device__ __forceinline__ void gemm_phase(PG8_LAS unsigned char* lds, const Gemm g, const Sched& S, const Epi& E, int tid_in) {
;     ...
;             PG8_WAIT_V(8); PG8_WAIT_L(0); PG8_BAR; PG8_MMA(1, 0, At, B0); PG8_MMA(1, 1, At, B1); PG8_BAR; PG8_SCHED;
;             PG8_LDB(B0, 1, 0); PG8_LDB(B1, 1, 1); PG8_SCHED; PG8_LDA(At, 1, 0); PG8_STAGE(PG8_SA(0, 1), a2 + hsA, voffA);
;             PG8_WAIT_V(8); PG8_WAIT_L(0); PG8_BAR; PG8_MMA(0, 0, At, B0); PG8_MMA(0, 1, At, B1); PG8_BAR; PG8_SCHED;
	s_setprio 1
	s_waitcnt lgkmcnt(0)
	v_mfma_f32_16x16x32_bf16 v[64:67], v[148:151], v[180:183], v[64:67]
	v_mfma_f32_16x16x32_bf16 v[60:63], v[156:159], v[180:183], v[60:63]
	v_mfma_f32_16x16x32_bf16 v[48:51], v[148:151], v[188:191], v[48:51]
	v_mfma_f32_16x16x32_bf16 v[44:47], v[156:159], v[188:191], v[44:47]
	v_mfma_f32_16x16x32_bf16 v[32:35], v[148:151], v[208:211], v[32:35]
	v_mfma_f32_16x16x32_bf16 v[28:31], v[156:159], v[208:211], v[28:31]
	v_mfma_f32_16x16x32_bf16 v[16:19], v[148:151], v[216:219], v[16:19]
	v_mfma_f32_16x16x32_bf16 v[12:15], v[156:159], v[216:219], v[12:15]
	v_mfma_f32_16x16x32_bf16 v[64:67], v[152:155], v[184:187], v[64:67]
	v_mfma_f32_16x16x32_bf16 v[60:63], v[160:163], v[184:187], v[60:63]
	v_mfma_f32_16x16x32_bf16 v[48:51], v[152:155], v[204:207], v[48:51]
	v_mfma_f32_16x16x32_bf16 v[44:47], v[160:163], v[204:207], v[44:47]
	v_mfma_f32_16x16x32_bf16 v[32:35], v[152:155], v[212:215], v[32:35]
	v_mfma_f32_16x16x32_bf16 v[28:31], v[160:163], v[212:215], v[28:31]
	v_mfma_f32_16x16x32_bf16 v[16:19], v[152:155], v[220:223], v[16:19]
	v_mfma_f32_16x16x32_bf16 v[12:15], v[160:163], v[220:223], v[12:15]
	v_mfma_f32_16x16x32_bf16 v[56:59], v[164:167], v[180:183], v[56:59]
	v_mfma_f32_16x16x32_bf16 v[52:55], v[172:175], v[180:183], v[52:55]
	v_mfma_f32_16x16x32_bf16 v[40:43], v[164:167], v[188:191], v[40:43]
	v_mfma_f32_16x16x32_bf16 v[36:39], v[172:175], v[188:191], v[36:39]
	v_mfma_f32_16x16x32_bf16 v[24:27], v[164:167], v[208:211], v[24:27]
	v_mfma_f32_16x16x32_bf16 v[20:23], v[172:175], v[208:211], v[20:23]
	v_mfma_f32_16x16x32_bf16 v[8:11], v[164:167], v[216:219], v[8:11]
	v_mfma_f32_16x16x32_bf16 v[4:7], v[172:175], v[216:219], v[4:7]
	v_mfma_f32_16x16x32_bf16 v[56:59], v[168:171], v[184:187], v[56:59]
	v_mfma_f32_16x16x32_bf16 v[52:55], v[176:179], v[184:187], v[52:55]
	v_mfma_f32_16x16x32_bf16 v[40:43], v[168:171], v[204:207], v[40:43]
	v_mfma_f32_16x16x32_bf16 v[36:39], v[176:179], v[204:207], v[36:39]
	v_mfma_f32_16x16x32_bf16 v[24:27], v[168:171], v[212:215], v[24:27]
	v_mfma_f32_16x16x32_bf16 v[20:23], v[176:179], v[212:215], v[20:23]
	v_mfma_f32_16x16x32_bf16 v[8:11], v[168:171], v[220:223], v[8:11]
	v_mfma_f32_16x16x32_bf16 v[4:7], v[176:179], v[220:223], v[4:7]
	s_setprio 0
	s_barrier
	s_add_i32 s58, 0, 0x18000
	s_add_i32 s59, 0, 0x1c000
	v_add_u32_e32 v160, s58, v3
	v_add_u32_e32 v176, s59, v3
	ds_read_b128 v[148:151], v160
	ds_read_b128 v[152:155], v160 offset:1024
	ds_read_b128 v[156:159], v160 offset:2048
	ds_read_b128 v[160:163], v160 offset:3072
	ds_read_b128 v[164:167], v176
	ds_read_b128 v[168:171], v176 offset:1024
	ds_read_b128 v[172:175], v176 offset:2048
	ds_read_b128 v[176:179], v176 offset:3072
	s_add_u32 s26, s26, s6
	s_addc_u32 s27, s27, s7
	s_mov_b32 m0, s37
	v_lshl_add_u64 v[230:231], s[26:27], 0, v[136:137]
	ds_read_b128 v[180:183], v147 offset:32768
	ds_read_b128 v[184:187], v147 offset:33792
	ds_read_b128 v[188:191], v147 offset:34816
	ds_read_b128 v[204:207], v147 offset:35840
	ds_read_b128 v[208:211], v147 offset:36864
	ds_read_b128 v[212:215], v147 offset:37888
	ds_read_b128 v[216:219], v147 offset:38912
	ds_read_b128 v[220:223], v147 offset:39936
	global_load_lds_dwordx4 v[230:231], off
	v_lshl_add_u64 v[230:231], s[26:27], 0, v[132:133]
	s_mov_b32 m0, s38
	s_nop 0
	global_load_lds_dwordx4 v[230:231], off
	s_waitcnt vmcnt(8)
	s_waitcnt lgkmcnt(0)
	s_barrier
	s_setprio 1
	s_waitcnt lgkmcnt(0)
	v_mfma_f32_16x16x32_bf16 v[124:127], v[148:151], v[180:183], v[124:127]
	v_mfma_f32_16x16x32_bf16 v[128:131], v[156:159], v[180:183], v[128:131]
	v_mfma_f32_16x16x32_bf16 v[112:115], v[148:151], v[188:191], v[112:115]
	v_mfma_f32_16x16x32_bf16 v[108:111], v[156:159], v[188:191], v[108:111]
	v_mfma_f32_16x16x32_bf16 v[96:99], v[148:151], v[208:211], v[96:99]
	v_mfma_f32_16x16x32_bf16 v[92:95], v[156:159], v[208:211], v[92:95]
	v_mfma_f32_16x16x32_bf16 v[80:83], v[148:151], v[216:219], v[80:83]
	v_mfma_f32_16x16x32_bf16 v[76:79], v[156:159], v[216:219], v[76:79]
	v_mfma_f32_16x16x32_bf16 v[124:127], v[152:155], v[184:187], v[124:127]
	v_mfma_f32_16x16x32_bf16 v[128:131], v[160:163], v[184:187], v[128:131]
	v_mfma_f32_16x16x32_bf16 v[112:115], v[152:155], v[204:207], v[112:115]
	v_mfma_f32_16x16x32_bf16 v[108:111], v[160:163], v[204:207], v[108:111]
	v_mfma_f32_16x16x32_bf16 v[96:99], v[152:155], v[212:215], v[96:99]
	v_mfma_f32_16x16x32_bf16 v[92:95], v[160:163], v[212:215], v[92:95]
	v_mfma_f32_16x16x32_bf16 v[80:83], v[152:155], v[220:223], v[80:83]
	v_mfma_f32_16x16x32_bf16 v[76:79], v[160:163], v[220:223], v[76:79]
	v_mfma_f32_16x16x32_bf16 v[120:123], v[164:167], v[180:183], v[120:123]
	v_mfma_f32_16x16x32_bf16 v[116:119], v[172:175], v[180:183], v[116:119]
	v_mfma_f32_16x16x32_bf16 v[104:107], v[164:167], v[188:191], v[104:107]
	v_mfma_f32_16x16x32_bf16 v[100:103], v[172:175], v[188:191], v[100:103]
	v_mfma_f32_16x16x32_bf16 v[88:91], v[164:167], v[208:211], v[88:91]
	v_mfma_f32_16x16x32_bf16 v[84:87], v[172:175], v[208:211], v[84:87]
	v_mfma_f32_16x16x32_bf16 v[72:75], v[164:167], v[216:219], v[72:75]
	v_mfma_f32_16x16x32_bf16 v[68:71], v[172:175], v[216:219], v[68:71]
	v_mfma_f32_16x16x32_bf16 v[120:123], v[168:171], v[184:187], v[120:123]
	v_mfma_f32_16x16x32_bf16 v[116:119], v[176:179], v[184:187], v[116:119]
	v_mfma_f32_16x16x32_bf16 v[104:107], v[168:171], v[204:207], v[104:107]
	v_mfma_f32_16x16x32_bf16 v[100:103], v[176:179], v[204:207], v[100:103]
	v_mfma_f32_16x16x32_bf16 v[88:91], v[168:171], v[212:215], v[88:91]
	v_mfma_f32_16x16x32_bf16 v[84:87], v[176:179], v[212:215], v[84:87]
	v_mfma_f32_16x16x32_bf16 v[72:75], v[168:171], v[220:223], v[72:75]
	v_mfma_f32_16x16x32_bf16 v[68:71], v[176:179], v[220:223], v[68:71]
	s_setprio 0
	s_barrier
; #define PG8_STAGE(bufoff, gbase, voff) do { _Pragma("unroll") for (int _i = 0; _i < 2; ++_i) \
;         __builtin_amdgcn_global_load_lds((const unsigned*)((const char*)(gbase) + (voff)[_i]), (PG8_LAS unsigned*)(lds + (bufoff) + ldsw + _i * 8192), 16, 0, 0); } while (0)
; #define PG8_LDA(dst, b, h) do { _Pragma("unroll") for (int m = 0; m < 4; ++m) _Pragma("unroll") for (int k = 0; k < 2; ++k) dst[m][k] = *(const PG8_LAS bf16x8*)(lds + PG8_SA(b, h) + aoff + m * 2048 + k * 1024); } while (0)
; #define PG8_MMA(ai, bj, At, Bt) do { __builtin_amdgcn_s_setprio(1); _Pragma("unroll") for (int m = 0; m < 4; ++m) _Pragma("unroll") for (int n = 0; n < 2; ++n) _Pragma("unroll") for (int k = 0; k < 2; ++k) \
;         acc[ai][bj][m][n] = __builtin_amdgcn_mfma_f32_16x16x32_bf16(Bt[n][k], At[m][k], acc[ai][bj][m][n], 0, 0, 0); __builtin_amdgcn_s_setprio(0); } while (0)
; #define PG8_WAIT_V(n) asm volatile("s_waitcnt vmcnt(" #n ")" ::: "memory")
; #define PG8_WAIT_L(n) asm volatile("s_waitcnt lgkmcnt(" #n ")" ::: "memory")
; #define PG8_BAR __builtin_amdgcn_s_barrier()
; #define PG8_SCHED __builtin_amdgcn_sched_barrier(0)
; template <class Epi, class Sched, bool ALIGN_EPI = false, bool SP2 = false>
; __device__ __forceinline__ void gemm_phase(PG8_LAS unsigned char* lds, const Gemm g, const Sched& S, const Epi& E, int tid_in) {
;     ...
;         for (int t = 0; t < nt; t += 2) {
;     ...
;             PG8_LDA(At, 1, 1); PG8_STAGE(PG8_SB(1, 0), b3, voffB); PG8_STAGE(PG8_SB(1, 1), b3 + hsB, voffB); PG8_STAGE(PG8_SA(1, 0), a3, voffA);
;             PG8_WAIT_V(8); PG8_WAIT_L(0); PG8_BAR; PG8_MMA(1, 0, At, B0); PG8_MMA(1, 1, At, B1); PG8_BAR; PG8_SCHED;
	s_add_i32 s26, s58, s33
	v_lshl_add_u64 v[192:193], v[192:193], 0, s[80:81]
	s_mov_b32 m0, s26
	ds_read_b128 v[180:183], v147 offset:49152
	ds_read_b128 v[184:187], v147 offset:50176
	ds_read_b128 v[188:191], v147 offset:51200
	ds_read_b128 v[204:207], v147 offset:52224
	ds_read_b128 v[208:211], v147 offset:53248
	ds_read_b128 v[212:215], v147 offset:54272
	ds_read_b128 v[216:219], v147 offset:55296
	ds_read_b128 v[220:223], v147 offset:56320
	global_load_lds_dwordx4 v[192:193], off
	v_lshl_add_u64 v[192:193], v[196:197], 0, s[80:81]
	s_add_i32 m0, s26, 0x2000
	s_add_i32 s26, s59, s33
	global_load_lds_dwordx4 v[192:193], off
	v_lshl_add_u64 v[192:193], v[198:199], 0, s[80:81]
	s_mov_b32 m0, s26
	s_nop 0
	global_load_lds_dwordx4 v[192:193], off
	v_lshl_add_u64 v[192:193], v[200:201], 0, s[80:81]
	s_add_i32 m0, s26, 0x2000
	s_nop 0
	global_load_lds_dwordx4 v[192:193], off
	v_lshl_add_u64 v[192:193], v[202:203], 0, s[80:81]
	s_mov_b32 m0, s41
	s_nop 0
	global_load_lds_dwordx4 v[192:193], off
	v_lshl_add_u64 v[192:193], v[228:229], 0, s[80:81]
	s_mov_b32 m0, s46
	s_nop 0
	global_load_lds_dwordx4 v[192:193], off
	s_waitcnt vmcnt(8)
	s_waitcnt lgkmcnt(0)
	s_barrier
	s_setprio 1
	s_waitcnt lgkmcnt(0)
	v_mfma_f32_16x16x32_bf16 v[64:67], v[148:151], v[180:183], v[64:67]
	v_mfma_f32_16x16x32_bf16 v[60:63], v[156:159], v[180:183], v[60:63]
	v_mfma_f32_16x16x32_bf16 v[48:51], v[148:151], v[188:191], v[48:51]
	v_mfma_f32_16x16x32_bf16 v[44:47], v[156:159], v[188:191], v[44:47]
	v_mfma_f32_16x16x32_bf16 v[32:35], v[148:151], v[208:211], v[32:35]
	v_mfma_f32_16x16x32_bf16 v[28:31], v[156:159], v[208:211], v[28:31]
	v_mfma_f32_16x16x32_bf16 v[16:19], v[148:151], v[216:219], v[16:19]
	v_mfma_f32_16x16x32_bf16 v[12:15], v[156:159], v[216:219], v[12:15]
	v_mfma_f32_16x16x32_bf16 v[64:67], v[152:155], v[184:187], v[64:67]
	v_mfma_f32_16x16x32_bf16 v[60:63], v[160:163], v[184:187], v[60:63]
	v_mfma_f32_16x16x32_bf16 v[48:51], v[152:155], v[204:207], v[48:51]
	v_mfma_f32_16x16x32_bf16 v[44:47], v[160:163], v[204:207], v[44:47]
	v_mfma_f32_16x16x32_bf16 v[32:35], v[152:155], v[212:215], v[32:35]
	v_mfma_f32_16x16x32_bf16 v[28:31], v[160:163], v[212:215], v[28:31]
	v_mfma_f32_16x16x32_bf16 v[16:19], v[152:155], v[220:223], v[16:19]
	v_mfma_f32_16x16x32_bf16 v[12:15], v[160:163], v[220:223], v[12:15]
	v_mfma_f32_16x16x32_bf16 v[56:59], v[164:167], v[180:183], v[56:59]
	v_mfma_f32_16x16x32_bf16 v[52:55], v[172:175], v[180:183], v[52:55]
	v_mfma_f32_16x16x32_bf16 v[40:43], v[164:167], v[188:191], v[40:43]
	v_mfma_f32_16x16x32_bf16 v[36:39], v[172:175], v[188:191], v[36:39]
	v_mfma_f32_16x16x32_bf16 v[24:27], v[164:167], v[208:211], v[24:27]
	v_mfma_f32_16x16x32_bf16 v[20:23], v[172:175], v[208:211], v[20:23]
	v_mfma_f32_16x16x32_bf16 v[8:11], v[164:167], v[216:219], v[8:11]
	v_mfma_f32_16x16x32_bf16 v[4:7], v[172:175], v[216:219], v[4:7]
	v_mfma_f32_16x16x32_bf16 v[56:59], v[168:171], v[184:187], v[56:59]
	v_mfma_f32_16x16x32_bf16 v[52:55], v[176:179], v[184:187], v[52:55]
	v_mfma_f32_16x16x32_bf16 v[40:43], v[168:171], v[204:207], v[40:43]
	v_mfma_f32_16x16x32_bf16 v[36:39], v[176:179], v[204:207], v[36:39]
	v_mfma_f32_16x16x32_bf16 v[24:27], v[168:171], v[212:215], v[24:27]
	v_mfma_f32_16x16x32_bf16 v[20:23], v[176:179], v[212:215], v[20:23]
	v_mfma_f32_16x16x32_bf16 v[8:11], v[168:171], v[220:223], v[8:11]
	v_mfma_f32_16x16x32_bf16 v[4:7], v[176:179], v[220:223], v[4:7]
	s_setprio 0
	s_barrier
	s_add_i32 s26, s55, 2
	s_add_u32 s17, s17, 0x100
	s_addc_u32 s21, s21, 0
	s_add_u32 s24, s24, 0x100
	s_addc_u32 s25, s25, 0
	s_cmp_ge_i32 s55, s48
	s_mov_b32 s55, s26
	s_cbranch_scc0 .LBB0_1102

; #define PG8_STAGE(bufoff, gbase, voff) do { _Pragma("unroll") for (int _i = 0; _i < 2; ++_i) \
;         __builtin_amdgcn_global_load_lds((const unsigned*)((const char*)(gbase) + (voff)[_i]), (PG8_LAS unsigned*)(lds + (bufoff) + ldsw + _i * 8192), 16, 0, 0); } while (0)
; #define PG8_LDA(dst, b, h) do { _Pragma("unroll") for (int m = 0; m < 4; ++m) _Pragma("unroll") for (int k = 0; k < 2; ++k) dst[m][k] = *(const PG8_LAS bf16x8*)(lds + PG8_SA(b, h) + aoff + m * 2048 + k * 1024); } while (0)
; #define PG8_LDB(dst, b, h) do { _Pragma("unroll") for (int n = 0; n < 2; ++n) _Pragma("unroll") for (int k = 0; k < 2; ++k) dst[n][k] = *(const PG8_LAS bf16x8*)(lds + PG8_SB(b, h) + boff + n * 2048 + k * 1024); } while (0)
; #define PG8_MMA(ai, bj, At, Bt) do { __builtin_amdgcn_s_setprio(1); _Pragma("unroll") for (int m = 0; m < 4; ++m) _Pragma("unroll") for (int n = 0; n < 2; ++n) _Pragma("unroll") for (int k = 0; k < 2; ++k) \
;         acc[ai][bj][m][n] = __builtin_amdgcn_mfma_f32_16x16x32_bf16(Bt[n][k], At[m][k], acc[ai][bj][m][n], 0, 0, 0); __builtin_amdgcn_s_setprio(0); } while (0)
; template <class Epi, class Sched, bool ALIGN_EPI = false, bool SP2 = false>
; __device__ __forceinline__ void gemm_phase(PG8_LAS unsigned char* lds, const Gemm g, const Sched& S, const Epi& E, int tid_in) {
;     ...
;             const bool last = (t == nt - 2);
;             if constexpr (mid_hook<Epi>::value) { if (t == Epi::H1 || t == Epi::H2) E.mid(acc, cur, wr, wc, fr, fq, t == Epi::H2); }
;             const char* a1 = cA + (size_t)(t + 1) * kstep + (t >= jt ? jb : 0);
;             const char* a2 = last ? nA : cA + (size_t)(t + 2) * kstep + (t + 2 >= jt ? jb : 0); const char* b2 = last ? nB : cB + (size_t)(t + 2) * kstep;
;             const char* a3 = a2 + kstep; const char* b3 = b2 + kstep;
;             if (last && has_next) S.a_ready(nxt);
;             if constexpr (SP2) {
;             PG8_LDB(B0, 0, 0); PG8_LDB(B1, 0, 1); PG8_SCHED; PG8_LDA(At, 0, 0); PG8_STAGE(PG8_SA(1, 1), a1 + hsA, voffA);
;             PG8_WAIT_V(8); PG8_WAIT_L(0); PG8_BAR; PG8_MMA(0, 0, At, B0); PG8_MMA(0, 1, At, B1); PG8_BAR; PG8_SCHED;
;             PG8_LDA(At, 0, 1); PG8_STAGE(PG8_SB(0, 0), b2, voffB); PG8_STAGE(PG8_SB(0, 1), b2 + hsB, voffB); PG8_STAGE(PG8_SA(0, 0), a2, voffA);
;             PG8_WAIT_V(8); PG8_WAIT_L(0); PG8_BAR; PG8_MMA(1, 0, At, B0); PG8_MMA(1, 1, At, B1); PG8_BAR; PG8_SCHED;
.LBB0_1255:
	s_add_i32 s24, s58, -2
	s_cmp_ge_i32 s24, s29
	s_cselect_b32 s60, s30, 0
	s_cselect_b32 s61, s47, 0
	s_cmp_ge_i32 s58, s29
	s_cselect_b32 s25, s30, 0
	s_cselect_b32 s24, s47, 0
	s_add_u32 s25, s22, s25
	s_addc_u32 s24, s23, s24
	s_add_u32 s59, s25, 0x80
	s_addc_u32 s24, s24, 0
	s_add_i32 s64, 0, 0x10000
	s_cmp_eq_u32 s46, s58
	s_cselect_b32 s25, s5, s24
	s_cselect_b32 s24, s4, s59
	s_cselect_b32 s63, s21, s55
	s_cselect_b32 s62, s20, s54
	s_add_i32 s59, 0, 0x14000
	v_add_u32_e32 v160, s64, v142
	v_add_u32_e32 v176, s59, v142
	ds_read_b128 v[148:151], v160
	ds_read_b128 v[152:155], v160 offset:1024
	ds_read_b128 v[156:159], v160 offset:2048
	ds_read_b128 v[160:163], v160 offset:3072
	ds_read_b128 v[164:167], v176
	ds_read_b128 v[168:171], v176 offset:1024
	ds_read_b128 v[172:175], v176 offset:2048
	ds_read_b128 v[176:179], v176 offset:3072
	v_lshl_add_u64 v[192:193], s[22:23], 0, v[140:141]
	v_lshl_add_u64 v[192:193], v[192:193], 0, s[60:61]
	s_add_i32 m0, s40, 0xc000
	ds_read_b128 v[180:183], v147
	ds_read_b128 v[184:187], v147 offset:1024
	ds_read_b128 v[188:191], v147 offset:2048
	ds_read_b128 v[204:207], v147 offset:3072
	ds_read_b128 v[208:211], v147 offset:4096
	ds_read_b128 v[212:215], v147 offset:5120
	ds_read_b128 v[216:219], v147 offset:6144
	ds_read_b128 v[220:223], v147 offset:7168
	global_load_lds_dwordx4 v[192:193], off
	v_lshl_add_u64 v[192:193], s[22:23], 0, v[138:139]
	v_lshl_add_u64 v[192:193], v[192:193], 0, s[60:61]
	s_add_i32 m0, s40, 0xe000
	s_nop 0
	global_load_lds_dwordx4 v[192:193], off
	s_waitcnt vmcnt(8)
	s_waitcnt lgkmcnt(0)
	s_barrier
	s_setprio 1
	s_waitcnt lgkmcnt(0)
	v_mfma_f32_16x16x32_bf16 v[124:127], v[148:151], v[180:183], v[124:127]
	v_mfma_f32_16x16x32_bf16 v[120:123], v[156:159], v[180:183], v[120:123]
	v_mfma_f32_16x16x32_bf16 v[112:115], v[148:151], v[188:191], v[112:115]
	v_mfma_f32_16x16x32_bf16 v[104:107], v[156:159], v[188:191], v[104:107]
	v_mfma_f32_16x16x32_bf16 v[96:99], v[148:151], v[208:211], v[96:99]
	v_mfma_f32_16x16x32_bf16 v[88:91], v[156:159], v[208:211], v[88:91]
	v_mfma_f32_16x16x32_bf16 v[80:83], v[148:151], v[216:219], v[80:83]
	v_mfma_f32_16x16x32_bf16 v[72:75], v[156:159], v[216:219], v[72:75]
	v_mfma_f32_16x16x32_bf16 v[124:127], v[152:155], v[184:187], v[124:127]
	v_mfma_f32_16x16x32_bf16 v[120:123], v[160:163], v[184:187], v[120:123]
	v_mfma_f32_16x16x32_bf16 v[112:115], v[152:155], v[204:207], v[112:115]
	v_mfma_f32_16x16x32_bf16 v[104:107], v[160:163], v[204:207], v[104:107]
	v_mfma_f32_16x16x32_bf16 v[96:99], v[152:155], v[212:215], v[96:99]
	v_mfma_f32_16x16x32_bf16 v[88:91], v[160:163], v[212:215], v[88:91]
	v_mfma_f32_16x16x32_bf16 v[80:83], v[152:155], v[220:223], v[80:83]
	v_mfma_f32_16x16x32_bf16 v[72:75], v[160:163], v[220:223], v[72:75]
	v_mfma_f32_16x16x32_bf16 v[128:131], v[164:167], v[180:183], v[128:131]
	v_mfma_f32_16x16x32_bf16 v[116:119], v[172:175], v[180:183], v[116:119]
	v_mfma_f32_16x16x32_bf16 v[108:111], v[164:167], v[188:191], v[108:111]
	v_mfma_f32_16x16x32_bf16 v[100:103], v[172:175], v[188:191], v[100:103]
	v_mfma_f32_16x16x32_bf16 v[92:95], v[164:167], v[208:211], v[92:95]
	v_mfma_f32_16x16x32_bf16 v[84:87], v[172:175], v[208:211], v[84:87]
	v_mfma_f32_16x16x32_bf16 v[76:79], v[164:167], v[216:219], v[76:79]
	v_mfma_f32_16x16x32_bf16 v[68:71], v[172:175], v[216:219], v[68:71]
	v_mfma_f32_16x16x32_bf16 v[128:131], v[168:171], v[184:187], v[128:131]
	v_mfma_f32_16x16x32_bf16 v[116:119], v[176:179], v[184:187], v[116:119]
	v_mfma_f32_16x16x32_bf16 v[108:111], v[168:171], v[204:207], v[108:111]
	v_mfma_f32_16x16x32_bf16 v[100:103], v[176:179], v[204:207], v[100:103]
	v_mfma_f32_16x16x32_bf16 v[92:95], v[168:171], v[212:215], v[92:95]
	v_mfma_f32_16x16x32_bf16 v[84:87], v[176:179], v[212:215], v[84:87]
	v_mfma_f32_16x16x32_bf16 v[76:79], v[168:171], v[220:223], v[76:79]
	v_mfma_f32_16x16x32_bf16 v[68:71], v[176:179], v[220:223], v[68:71]
	s_setprio 0
	s_barrier
	s_add_i32 s60, s64, s36
	v_lshl_add_u64 v[192:193], s[62:63], 0, v[134:135]
	s_mov_b32 m0, s60
	ds_read_b128 v[180:183], v147 offset:16384
	ds_read_b128 v[184:187], v147 offset:17408
	ds_read_b128 v[188:191], v147 offset:18432
	ds_read_b128 v[204:207], v147 offset:19456
	ds_read_b128 v[208:211], v147 offset:20480
	ds_read_b128 v[212:215], v147 offset:21504
	ds_read_b128 v[216:219], v147 offset:22528
	ds_read_b128 v[220:223], v147 offset:23552
	global_load_lds_dwordx4 v[192:193], off
	s_add_i32 m0, s60, 0x2000
	s_add_u32 s60, s62, s6
	v_lshl_add_u64 v[196:197], s[62:63], 0, v[0:1]
	s_addc_u32 s61, s63, s7
	s_add_i32 s59, s59, s36
	global_load_lds_dwordx4 v[196:197], off
	v_lshl_add_u64 v[198:199], s[60:61], 0, v[134:135]
	s_mov_b32 m0, s59
	v_lshl_add_u64 v[200:201], s[60:61], 0, v[0:1]
	global_load_lds_dwordx4 v[198:199], off
	s_add_i32 m0, s59, 0x2000
	v_lshl_add_u64 v[202:203], s[24:25], 0, v[136:137]
	global_load_lds_dwordx4 v[200:201], off
	s_mov_b32 m0, s40
	v_lshl_add_u64 v[228:229], s[24:25], 0, v[132:133]
	global_load_lds_dwordx4 v[202:203], off
	s_mov_b32 m0, s41
	s_nop 0
	global_load_lds_dwordx4 v[228:229], off
	s_waitcnt vmcnt(8)
	s_waitcnt lgkmcnt(0)
	s_barrier
; #define PG8_STAGE(bufoff, gbase, voff) do { _Pragma("unroll") for (int _i = 0; _i < 2; ++_i) \
;         __builtin_amdgcn_global_load_lds((const unsigned*)((const char*)(gbase) + (voff)[_i]), (PG8_LAS unsigned*)(lds + (bufoff) + ldsw + _i * 8192), 16, 0, 0); } while (0)
; #define PG8_LDA(dst, b, h) do { _Pragma("unroll") for (int m = 0; m < 4; ++m) _Pragma("unroll") for (int k = 0; k < 2; ++k) dst[m][k] = *(const PG8_LAS bf16x8*)(lds + PG8_SA(b, h) + aoff + m * 2048 + k * 1024); } while (0)
; #define PG8_LDB(dst, b, h) do { _Pragma("unroll") for (int n = 0; n < 2; ++n) _Pragma("unroll") for (int k = 0; k < 2; ++k) dst[n][k] = *(const PG8_LAS bf16x8*)(lds + PG8_SB(b, h) + boff + n * 2048 + k * 1024); } while (0)
; #define PG8_MMA(ai, bj, At, Bt) do { __builtin_amdgcn_s_setprio(1); _Pragma("unroll") for (int m = 0; m < 4; ++m) _Pragma("unroll") for (int n = 0; n < 2; ++n) _Pragma("unroll") for (int k = 0; k < 2; ++k) \
;         acc[ai][bj][m][n] = __builtin_amdgcn_mfma_f32_16x16x32_bf16(Bt[n][k], At[m][k], acc[ai][bj][m][n], 0, 0, 0); __builtin_amdgcn_s_setprio(0); } while (0)
; #define PG8_WAIT_V(n) asm volatile("s_waitcnt vmcnt(" #n ")" ::: "memory")
; #define PG8_WAIT_L(n) asm volatile("s_waitcnt lgkmcnt(" #n ")" ::: "memory")
; #define PG8_BAR __builtin_amdgcn_s_barrier()
; #define PG8_SCHED __builtin_amdgcn_sched_barrier(0)
; template <class Epi, class Sched, bool ALIGN_EPI = false, bool SP2 = false>
; __device__ __forceinline__ void gemm_phase(PG8_LAS unsigned char* lds, const Gemm g, const Sched& S, const Epi& E, int tid_in) {
;     ...
;             PG8_WAIT_V(8); PG8_WAIT_L(0); PG8_BAR; PG8_MMA(1, 0, At, B0); PG8_MMA(1, 1, At, B1); PG8_BAR; PG8_SCHED;
;             PG8_LDB(B0, 1, 0); PG8_LDB(B1, 1, 1); PG8_SCHED; PG8_LDA(At, 1, 0); PG8_STAGE(PG8_SA(0, 1), a2 + hsA, voffA);
;             PG8_WAIT_V(8); PG8_WAIT_L(0); PG8_BAR; PG8_MMA(0, 0, At, B0); PG8_MMA(0, 1, At, B1); PG8_BAR; PG8_SCHED;
	s_setprio 1
	s_waitcnt lgkmcnt(0)
	v_mfma_f32_16x16x32_bf16 v[64:67], v[148:151], v[180:183], v[64:67]
	v_mfma_f32_16x16x32_bf16 v[56:59], v[156:159], v[180:183], v[56:59]
	v_mfma_f32_16x16x32_bf16 v[48:51], v[148:151], v[188:191], v[48:51]
	v_mfma_f32_16x16x32_bf16 v[40:43], v[156:159], v[188:191], v[40:43]
	v_mfma_f32_16x16x32_bf16 v[32:35], v[148:151], v[208:211], v[32:35]
	v_mfma_f32_16x16x32_bf16 v[24:27], v[156:159], v[208:211], v[24:27]
	v_mfma_f32_16x16x32_bf16 v[16:19], v[148:151], v[216:219], v[16:19]
	v_mfma_f32_16x16x32_bf16 v[8:11], v[156:159], v[216:219], v[8:11]
	v_mfma_f32_16x16x32_bf16 v[64:67], v[152:155], v[184:187], v[64:67]
	v_mfma_f32_16x16x32_bf16 v[56:59], v[160:163], v[184:187], v[56:59]
	v_mfma_f32_16x16x32_bf16 v[48:51], v[152:155], v[204:207], v[48:51]
	v_mfma_f32_16x16x32_bf16 v[40:43], v[160:163], v[204:207], v[40:43]
	v_mfma_f32_16x16x32_bf16 v[32:35], v[152:155], v[212:215], v[32:35]
	v_mfma_f32_16x16x32_bf16 v[24:27], v[160:163], v[212:215], v[24:27]
	v_mfma_f32_16x16x32_bf16 v[16:19], v[152:155], v[220:223], v[16:19]
	v_mfma_f32_16x16x32_bf16 v[8:11], v[160:163], v[220:223], v[8:11]
	v_mfma_f32_16x16x32_bf16 v[60:63], v[164:167], v[180:183], v[60:63]
	v_mfma_f32_16x16x32_bf16 v[52:55], v[172:175], v[180:183], v[52:55]
	v_mfma_f32_16x16x32_bf16 v[44:47], v[164:167], v[188:191], v[44:47]
	v_mfma_f32_16x16x32_bf16 v[36:39], v[172:175], v[188:191], v[36:39]
	v_mfma_f32_16x16x32_bf16 v[28:31], v[164:167], v[208:211], v[28:31]
	v_mfma_f32_16x16x32_bf16 v[20:23], v[172:175], v[208:211], v[20:23]
	v_mfma_f32_16x16x32_bf16 v[12:15], v[164:167], v[216:219], v[12:15]
	v_mfma_f32_16x16x32_bf16 v[4:7], v[172:175], v[216:219], v[4:7]
	v_mfma_f32_16x16x32_bf16 v[60:63], v[168:171], v[184:187], v[60:63]
	v_mfma_f32_16x16x32_bf16 v[52:55], v[176:179], v[184:187], v[52:55]
	v_mfma_f32_16x16x32_bf16 v[44:47], v[168:171], v[204:207], v[44:47]
	v_mfma_f32_16x16x32_bf16 v[36:39], v[176:179], v[204:207], v[36:39]
	v_mfma_f32_16x16x32_bf16 v[28:31], v[168:171], v[212:215], v[28:31]
	v_mfma_f32_16x16x32_bf16 v[20:23], v[176:179], v[212:215], v[20:23]
	v_mfma_f32_16x16x32_bf16 v[12:15], v[168:171], v[220:223], v[12:15]
	v_mfma_f32_16x16x32_bf16 v[4:7], v[176:179], v[220:223], v[4:7]
	s_setprio 0
	s_barrier
	s_add_i32 s59, 0, 0x18000
	s_add_i32 s60, 0, 0x1c000
	v_add_u32_e32 v160, s59, v142
	v_add_u32_e32 v176, s60, v142
	ds_read_b128 v[148:151], v160
	ds_read_b128 v[152:155], v160 offset:1024
	ds_read_b128 v[156:159], v160 offset:2048
	ds_read_b128 v[160:163], v160 offset:3072
	ds_read_b128 v[164:167], v176
	ds_read_b128 v[168:171], v176 offset:1024
	ds_read_b128 v[172:175], v176 offset:2048
	ds_read_b128 v[176:179], v176 offset:3072
	s_add_u32 s24, s24, s0
	s_addc_u32 s25, s25, s1
	s_mov_b32 m0, s42
	v_lshl_add_u64 v[230:231], s[24:25], 0, v[136:137]
	ds_read_b128 v[180:183], v147 offset:32768
	ds_read_b128 v[184:187], v147 offset:33792
	ds_read_b128 v[188:191], v147 offset:34816
	ds_read_b128 v[204:207], v147 offset:35840
	ds_read_b128 v[208:211], v147 offset:36864
	ds_read_b128 v[212:215], v147 offset:37888
	ds_read_b128 v[216:219], v147 offset:38912
	ds_read_b128 v[220:223], v147 offset:39936
	global_load_lds_dwordx4 v[230:231], off
	v_lshl_add_u64 v[230:231], s[24:25], 0, v[132:133]
	s_mov_b32 m0, s43
	s_nop 0
	global_load_lds_dwordx4 v[230:231], off
	s_waitcnt vmcnt(8)
	s_waitcnt lgkmcnt(0)
	s_barrier
	s_setprio 1
	s_waitcnt lgkmcnt(0)
	v_mfma_f32_16x16x32_bf16 v[124:127], v[148:151], v[180:183], v[124:127]
	v_mfma_f32_16x16x32_bf16 v[120:123], v[156:159], v[180:183], v[120:123]
	v_mfma_f32_16x16x32_bf16 v[112:115], v[148:151], v[188:191], v[112:115]
	v_mfma_f32_16x16x32_bf16 v[104:107], v[156:159], v[188:191], v[104:107]
	v_mfma_f32_16x16x32_bf16 v[96:99], v[148:151], v[208:211], v[96:99]
	v_mfma_f32_16x16x32_bf16 v[88:91], v[156:159], v[208:211], v[88:91]
	v_mfma_f32_16x16x32_bf16 v[80:83], v[148:151], v[216:219], v[80:83]
	v_mfma_f32_16x16x32_bf16 v[72:75], v[156:159], v[216:219], v[72:75]
	v_mfma_f32_16x16x32_bf16 v[124:127], v[152:155], v[184:187], v[124:127]
	v_mfma_f32_16x16x32_bf16 v[120:123], v[160:163], v[184:187], v[120:123]
	v_mfma_f32_16x16x32_bf16 v[112:115], v[152:155], v[204:207], v[112:115]
	v_mfma_f32_16x16x32_bf16 v[104:107], v[160:163], v[204:207], v[104:107]
	v_mfma_f32_16x16x32_bf16 v[96:99], v[152:155], v[212:215], v[96:99]
	v_mfma_f32_16x16x32_bf16 v[88:91], v[160:163], v[212:215], v[88:91]
	v_mfma_f32_16x16x32_bf16 v[80:83], v[152:155], v[220:223], v[80:83]
	v_mfma_f32_16x16x32_bf16 v[72:75], v[160:163], v[220:223], v[72:75]
	v_mfma_f32_16x16x32_bf16 v[128:131], v[164:167], v[180:183], v[128:131]
	v_mfma_f32_16x16x32_bf16 v[116:119], v[172:175], v[180:183], v[116:119]
	v_mfma_f32_16x16x32_bf16 v[108:111], v[164:167], v[188:191], v[108:111]
	v_mfma_f32_16x16x32_bf16 v[100:103], v[172:175], v[188:191], v[100:103]
	v_mfma_f32_16x16x32_bf16 v[92:95], v[164:167], v[208:211], v[92:95]
	v_mfma_f32_16x16x32_bf16 v[84:87], v[172:175], v[208:211], v[84:87]
	v_mfma_f32_16x16x32_bf16 v[76:79], v[164:167], v[216:219], v[76:79]
	v_mfma_f32_16x16x32_bf16 v[68:71], v[172:175], v[216:219], v[68:71]
	v_mfma_f32_16x16x32_bf16 v[128:131], v[168:171], v[184:187], v[128:131]
	v_mfma_f32_16x16x32_bf16 v[116:119], v[176:179], v[184:187], v[116:119]
	v_mfma_f32_16x16x32_bf16 v[108:111], v[168:171], v[204:207], v[108:111]
	v_mfma_f32_16x16x32_bf16 v[100:103], v[176:179], v[204:207], v[100:103]
	v_mfma_f32_16x16x32_bf16 v[92:95], v[168:171], v[212:215], v[92:95]
	v_mfma_f32_16x16x32_bf16 v[84:87], v[176:179], v[212:215], v[84:87]
	v_mfma_f32_16x16x32_bf16 v[76:79], v[168:171], v[220:223], v[76:79]
	v_mfma_f32_16x16x32_bf16 v[68:71], v[176:179], v[220:223], v[68:71]
	s_setprio 0
	s_barrier
; #define PG8_STAGE(bufoff, gbase, voff) do { _Pragma("unroll") for (int _i = 0; _i < 2; ++_i) \
;         __builtin_amdgcn_global_load_lds((const unsigned*)((const char*)(gbase) + (voff)[_i]), (PG8_LAS unsigned*)(lds + (bufoff) + ldsw + _i * 8192), 16, 0, 0); } while (0)
; #define PG8_LDA(dst, b, h) do { _Pragma("unroll") for (int m = 0; m < 4; ++m) _Pragma("unroll") for (int k = 0; k < 2; ++k) dst[m][k] = *(const PG8_LAS bf16x8*)(lds + PG8_SA(b, h) + aoff + m * 2048 + k * 1024); } while (0)
; #define PG8_MMA(ai, bj, At, Bt) do { __builtin_amdgcn_s_setprio(1); _Pragma("unroll") for (int m = 0; m < 4; ++m) _Pragma("unroll") for (int n = 0; n < 2; ++n) _Pragma("unroll") for (int k = 0; k < 2; ++k) \
;         acc[ai][bj][m][n] = __builtin_amdgcn_mfma_f32_16x16x32_bf16(Bt[n][k], At[m][k], acc[ai][bj][m][n], 0, 0, 0); __builtin_amdgcn_s_setprio(0); } while (0)
; #define PG8_WAIT_V(n) asm volatile("s_waitcnt vmcnt(" #n ")" ::: "memory")
; #define PG8_WAIT_L(n) asm volatile("s_waitcnt lgkmcnt(" #n ")" ::: "memory")
; #define PG8_BAR __builtin_amdgcn_s_barrier()
; #define PG8_SCHED __builtin_amdgcn_sched_barrier(0)
; template <class Epi, class Sched, bool ALIGN_EPI = false, bool SP2 = false>
; __device__ __forceinline__ void gemm_phase(PG8_LAS unsigned char* lds, const Gemm g, const Sched& S, const Epi& E, int tid_in) {
;     ...
;             PG8_LDA(At, 1, 1); PG8_STAGE(PG8_SB(1, 0), b3, voffB); PG8_STAGE(PG8_SB(1, 1), b3 + hsB, voffB); PG8_STAGE(PG8_SA(1, 0), a3, voffA);
;             PG8_WAIT_V(8); PG8_WAIT_L(0); PG8_BAR; PG8_MMA(1, 0, At, B0); PG8_MMA(1, 1, At, B1); PG8_BAR; PG8_SCHED;
	s_add_i32 s24, s59, s36
	v_lshl_add_u64 v[192:193], v[192:193], 0, s[80:81]
	s_mov_b32 m0, s24
	ds_read_b128 v[180:183], v147 offset:49152
	ds_read_b128 v[184:187], v147 offset:50176
	ds_read_b128 v[188:191], v147 offset:51200
	ds_read_b128 v[204:207], v147 offset:52224
	ds_read_b128 v[208:211], v147 offset:53248
	ds_read_b128 v[212:215], v147 offset:54272
	ds_read_b128 v[216:219], v147 offset:55296
	ds_read_b128 v[220:223], v147 offset:56320
	global_load_lds_dwordx4 v[192:193], off
	v_lshl_add_u64 v[192:193], v[196:197], 0, s[80:81]
	s_add_i32 m0, s24, 0x2000
	s_add_i32 s24, s60, s36
	global_load_lds_dwordx4 v[192:193], off
	v_lshl_add_u64 v[192:193], v[198:199], 0, s[80:81]
	s_mov_b32 m0, s24
	s_nop 0
	global_load_lds_dwordx4 v[192:193], off
	v_lshl_add_u64 v[192:193], v[200:201], 0, s[80:81]
	s_add_i32 m0, s24, 0x2000
	s_nop 0
	global_load_lds_dwordx4 v[192:193], off
	v_lshl_add_u64 v[192:193], v[202:203], 0, s[80:81]
	s_mov_b32 m0, s44
	s_nop 0
	global_load_lds_dwordx4 v[192:193], off
	v_lshl_add_u64 v[192:193], v[228:229], 0, s[80:81]
	s_mov_b32 m0, s45
	s_nop 0
	global_load_lds_dwordx4 v[192:193], off
	s_waitcnt vmcnt(8)
	s_waitcnt lgkmcnt(0)
	s_barrier
	s_setprio 1
	s_waitcnt lgkmcnt(0)
	v_mfma_f32_16x16x32_bf16 v[64:67], v[148:151], v[180:183], v[64:67]
	v_mfma_f32_16x16x32_bf16 v[56:59], v[156:159], v[180:183], v[56:59]
	v_mfma_f32_16x16x32_bf16 v[48:51], v[148:151], v[188:191], v[48:51]
	v_mfma_f32_16x16x32_bf16 v[40:43], v[156:159], v[188:191], v[40:43]
	v_mfma_f32_16x16x32_bf16 v[32:35], v[148:151], v[208:211], v[32:35]
	v_mfma_f32_16x16x32_bf16 v[24:27], v[156:159], v[208:211], v[24:27]
	v_mfma_f32_16x16x32_bf16 v[16:19], v[148:151], v[216:219], v[16:19]
	v_mfma_f32_16x16x32_bf16 v[8:11], v[156:159], v[216:219], v[8:11]
	v_mfma_f32_16x16x32_bf16 v[64:67], v[152:155], v[184:187], v[64:67]
	v_mfma_f32_16x16x32_bf16 v[56:59], v[160:163], v[184:187], v[56:59]
	v_mfma_f32_16x16x32_bf16 v[48:51], v[152:155], v[204:207], v[48:51]
	v_mfma_f32_16x16x32_bf16 v[40:43], v[160:163], v[204:207], v[40:43]
	v_mfma_f32_16x16x32_bf16 v[32:35], v[152:155], v[212:215], v[32:35]
	v_mfma_f32_16x16x32_bf16 v[24:27], v[160:163], v[212:215], v[24:27]
	v_mfma_f32_16x16x32_bf16 v[16:19], v[152:155], v[220:223], v[16:19]
	v_mfma_f32_16x16x32_bf16 v[8:11], v[160:163], v[220:223], v[8:11]
	v_mfma_f32_16x16x32_bf16 v[60:63], v[164:167], v[180:183], v[60:63]
	v_mfma_f32_16x16x32_bf16 v[52:55], v[172:175], v[180:183], v[52:55]
	v_mfma_f32_16x16x32_bf16 v[44:47], v[164:167], v[188:191], v[44:47]
	v_mfma_f32_16x16x32_bf16 v[36:39], v[172:175], v[188:191], v[36:39]
	v_mfma_f32_16x16x32_bf16 v[28:31], v[164:167], v[208:211], v[28:31]
	v_mfma_f32_16x16x32_bf16 v[20:23], v[172:175], v[208:211], v[20:23]
	v_mfma_f32_16x16x32_bf16 v[12:15], v[164:167], v[216:219], v[12:15]
	v_mfma_f32_16x16x32_bf16 v[4:7], v[172:175], v[216:219], v[4:7]
	v_mfma_f32_16x16x32_bf16 v[60:63], v[168:171], v[184:187], v[60:63]
	v_mfma_f32_16x16x32_bf16 v[52:55], v[176:179], v[184:187], v[52:55]
	v_mfma_f32_16x16x32_bf16 v[44:47], v[168:171], v[204:207], v[44:47]
	v_mfma_f32_16x16x32_bf16 v[36:39], v[176:179], v[204:207], v[36:39]
	v_mfma_f32_16x16x32_bf16 v[28:31], v[168:171], v[212:215], v[28:31]
	v_mfma_f32_16x16x32_bf16 v[20:23], v[176:179], v[212:215], v[20:23]
	v_mfma_f32_16x16x32_bf16 v[12:15], v[168:171], v[220:223], v[12:15]
	v_mfma_f32_16x16x32_bf16 v[4:7], v[176:179], v[220:223], v[4:7]
	s_setprio 0
	s_barrier
	s_add_i32 s24, s58, 2
	s_add_u32 s54, s54, 0x100
	s_addc_u32 s55, s55, 0
	s_add_u32 s22, s22, 0x100
	s_addc_u32 s23, s23, 0
	s_cmp_ge_i32 s58, s46
	s_mov_b32 s58, s24
	s_cbranch_scc0 .LBB0_1255

; #define PG8_STAGE(bufoff, gbase, voff) do { _Pragma("unroll") for (int _i = 0; _i < 2; ++_i) \
;         __builtin_amdgcn_global_load_lds((const unsigned*)((const char*)(gbase) + (voff)[_i]), (PG8_LAS unsigned*)(lds + (bufoff) + ldsw + _i * 8192), 16, 0, 0); } while (0)
; #define PG8_LDA(dst, b, h) do { _Pragma("unroll") for (int m = 0; m < 4; ++m) _Pragma("unroll") for (int k = 0; k < 2; ++k) dst[m][k] = *(const PG8_LAS bf16x8*)(lds + PG8_SA(b, h) + aoff + m * 2048 + k * 1024); } while (0)
; #define PG8_LDB(dst, b, h) do { _Pragma("unroll") for (int n = 0; n < 2; ++n) _Pragma("unroll") for (int k = 0; k < 2; ++k) dst[n][k] = *(const PG8_LAS bf16x8*)(lds + PG8_SB(b, h) + boff + n * 2048 + k * 1024); } while (0)
; #define PG8_MMA(ai, bj, At, Bt) do { __builtin_amdgcn_s_setprio(1); _Pragma("unroll") for (int m = 0; m < 4; ++m) _Pragma("unroll") for (int n = 0; n < 2; ++n) _Pragma("unroll") for (int k = 0; k < 2; ++k) \
;         acc[ai][bj][m][n] = __builtin_amdgcn_mfma_f32_16x16x32_bf16(Bt[n][k], At[m][k], acc[ai][bj][m][n], 0, 0, 0); __builtin_amdgcn_s_setprio(0); } while (0)
; #define PG8_WAIT_V(n) asm volatile("s_waitcnt vmcnt(" #n ")" ::: "memory")
; #define PG8_BAR __builtin_amdgcn_s_barrier()
; template <class Epi, class Sched, bool ALIGN_EPI = false, bool SP2 = false>
; __device__ __forceinline__ void gemm_phase(PG8_LAS unsigned char* lds, const Gemm g, const Sched& S, const Epi& E, int tid_in) {
;     ...
;             const bool last = (t == nt - 2);
;             if constexpr (mid_hook<Epi>::value) { if (t == Epi::H1 || t == Epi::H2) E.mid(acc, cur, wr, wc, fr, fq, t == Epi::H2); }
;             const char* a1 = cA + (size_t)(t + 1) * kstep + (t >= jt ? jb : 0);
;             const char* a2 = last ? nA : cA + (size_t)(t + 2) * kstep + (t + 2 >= jt ? jb : 0); const char* b2 = last ? nB : cB + (size_t)(t + 2) * kstep;
;             const char* a3 = a2 + kstep; const char* b3 = b2 + kstep;
;             if (last && has_next) S.a_ready(nxt);
;             if constexpr (SP2) {
;             PG8_LDB(B0, 0, 0); PG8_LDB(B1, 0, 1); PG8_SCHED; PG8_LDA(At, 0, 0); PG8_STAGE(PG8_SA(1, 1), a1 + hsA, voffA);
;             PG8_WAIT_V(8); PG8_WAIT_L(0); PG8_BAR; PG8_MMA(0, 0, At, B0); PG8_MMA(0, 1, At, B1); PG8_BAR; PG8_SCHED;
;             PG8_LDA(At, 0, 1); PG8_STAGE(PG8_SB(0, 0), b2, voffB); PG8_STAGE(PG8_SB(0, 1), b2 + hsB, voffB); PG8_STAGE(PG8_SA(0, 0), a2, voffA);
.LBB0_1331:
	s_add_i32 s38, s40, -2
	s_cmp_ge_i32 s38, s33
	s_cselect_b32 s76, s46, 0
	s_cselect_b32 s77, s61, 0
	s_cmp_ge_i32 s40, s33
	s_cselect_b32 s39, s46, 0
	s_cselect_b32 s38, s61, 0
	s_add_u32 s39, s4, s39
	s_addc_u32 s38, s5, s38
	s_add_u32 s41, s39, 0x80
	s_addc_u32 s38, s38, 0
	s_add_i32 s82, 0, 0x10000
	s_cmp_eq_u32 s60, s40
	s_cselect_b32 s39, s35, s38
	s_cselect_b32 s38, s34, s41
	s_cselect_b32 s79, s37, s75
	s_cselect_b32 s78, s36, s74
	s_add_i32 s41, 0, 0x14000
	v_add_u32_e32 v144, s82, v217
	v_add_u32_e32 v170, s41, v217
	ds_read_b128 v[132:135], v144
	ds_read_b128 v[136:139], v144 offset:1024
	ds_read_b128 v[140:143], v144 offset:2048
	ds_read_b128 v[144:147], v144 offset:3072
	ds_read_b128 v[148:151], v170
	ds_read_b128 v[162:165], v170 offset:1024
	ds_read_b128 v[166:169], v170 offset:2048
	ds_read_b128 v[170:173], v170 offset:3072
	v_lshl_add_u64 v[190:191], s[4:5], 0, v[160:161]
	v_lshl_add_u64 v[190:191], v[190:191], 0, s[76:77]
	s_add_i32 m0, s50, 0xc000
	ds_read_b128 v[174:177], v219
	ds_read_b128 v[178:181], v219 offset:1024
	ds_read_b128 v[182:185], v219 offset:2048
	ds_read_b128 v[186:189], v219 offset:3072
	ds_read_b128 v[204:207], v219 offset:4096
	ds_read_b128 v[208:211], v219 offset:5120
	ds_read_b128 v[212:215], v219 offset:6144
	ds_read_b128 v[220:223], v219 offset:7168
	global_load_lds_dwordx4 v[190:191], off
	v_lshl_add_u64 v[190:191], s[4:5], 0, v[158:159]
	v_lshl_add_u64 v[190:191], v[190:191], 0, s[76:77]
	s_add_i32 m0, s50, 0xe000
	s_nop 0
	global_load_lds_dwordx4 v[190:191], off
	s_waitcnt vmcnt(8)
	s_waitcnt lgkmcnt(0)
	s_barrier
	s_setprio 1
	s_waitcnt lgkmcnt(0)
	v_mfma_f32_16x16x32_bf16 v[128:131], v[132:135], v[174:177], v[128:131]
	v_mfma_f32_16x16x32_bf16 v[124:127], v[140:143], v[174:177], v[124:127]
	v_mfma_f32_16x16x32_bf16 v[120:123], v[132:135], v[182:185], v[120:123]
	v_mfma_f32_16x16x32_bf16 v[116:119], v[140:143], v[182:185], v[116:119]
	v_mfma_f32_16x16x32_bf16 v[112:115], v[132:135], v[204:207], v[112:115]
	v_mfma_f32_16x16x32_bf16 v[108:111], v[140:143], v[204:207], v[108:111]
	v_mfma_f32_16x16x32_bf16 v[104:107], v[132:135], v[212:215], v[104:107]
	v_mfma_f32_16x16x32_bf16 v[100:103], v[140:143], v[212:215], v[100:103]
	v_mfma_f32_16x16x32_bf16 v[128:131], v[136:139], v[178:181], v[128:131]
	v_mfma_f32_16x16x32_bf16 v[124:127], v[144:147], v[178:181], v[124:127]
	v_mfma_f32_16x16x32_bf16 v[120:123], v[136:139], v[186:189], v[120:123]
	v_mfma_f32_16x16x32_bf16 v[116:119], v[144:147], v[186:189], v[116:119]
	v_mfma_f32_16x16x32_bf16 v[112:115], v[136:139], v[208:211], v[112:115]
	v_mfma_f32_16x16x32_bf16 v[108:111], v[144:147], v[208:211], v[108:111]
	v_mfma_f32_16x16x32_bf16 v[104:107], v[136:139], v[220:223], v[104:107]
	v_mfma_f32_16x16x32_bf16 v[100:103], v[144:147], v[220:223], v[100:103]
	v_mfma_f32_16x16x32_bf16 v[64:67], v[148:151], v[174:177], v[64:67]
	v_mfma_f32_16x16x32_bf16 v[56:59], v[166:169], v[174:177], v[56:59]
	v_mfma_f32_16x16x32_bf16 v[60:63], v[148:151], v[182:185], v[60:63]
	v_mfma_f32_16x16x32_bf16 v[52:55], v[166:169], v[182:185], v[52:55]
	v_mfma_f32_16x16x32_bf16 v[48:51], v[148:151], v[204:207], v[48:51]
	v_mfma_f32_16x16x32_bf16 v[40:43], v[166:169], v[204:207], v[40:43]
	v_mfma_f32_16x16x32_bf16 v[44:47], v[148:151], v[212:215], v[44:47]
	v_mfma_f32_16x16x32_bf16 v[36:39], v[166:169], v[212:215], v[36:39]
	v_mfma_f32_16x16x32_bf16 v[64:67], v[162:165], v[178:181], v[64:67]
	v_mfma_f32_16x16x32_bf16 v[56:59], v[170:173], v[178:181], v[56:59]
	v_mfma_f32_16x16x32_bf16 v[60:63], v[162:165], v[186:189], v[60:63]
	v_mfma_f32_16x16x32_bf16 v[52:55], v[170:173], v[186:189], v[52:55]
	v_mfma_f32_16x16x32_bf16 v[48:51], v[162:165], v[208:211], v[48:51]
	v_mfma_f32_16x16x32_bf16 v[40:43], v[170:173], v[208:211], v[40:43]
	v_mfma_f32_16x16x32_bf16 v[44:47], v[162:165], v[220:223], v[44:47]
	v_mfma_f32_16x16x32_bf16 v[36:39], v[170:173], v[220:223], v[36:39]
	s_setprio 0
	s_barrier
	s_add_i32 s76, s82, s49
	v_lshl_add_u64 v[190:191], s[78:79], 0, v[152:153]
	s_mov_b32 m0, s76
	ds_read_b128 v[174:177], v219 offset:16384
	ds_read_b128 v[178:181], v219 offset:17408
	ds_read_b128 v[182:185], v219 offset:18432
	ds_read_b128 v[186:189], v219 offset:19456
	ds_read_b128 v[204:207], v219 offset:20480
	ds_read_b128 v[208:211], v219 offset:21504
	ds_read_b128 v[212:215], v219 offset:22528
	ds_read_b128 v[220:223], v219 offset:23552
	global_load_lds_dwordx4 v[190:191], off
	s_add_i32 m0, s76, 0x2000
	s_add_u32 s76, s78, s12
	v_lshl_add_u64 v[192:193], s[78:79], 0, v[156:157]
	s_addc_u32 s77, s79, s13
	s_add_i32 s41, s41, s49
	global_load_lds_dwordx4 v[192:193], off
	v_lshl_add_u64 v[196:197], s[76:77], 0, v[152:153]
	s_mov_b32 m0, s41
	v_lshl_add_u64 v[198:199], s[76:77], 0, v[156:157]
	global_load_lds_dwordx4 v[196:197], off
	s_add_i32 m0, s41, 0x2000
	v_lshl_add_u64 v[200:201], s[38:39], 0, v[0:1]
	global_load_lds_dwordx4 v[198:199], off
	s_mov_b32 m0, s50
	v_lshl_add_u64 v[202:203], s[38:39], 0, v[154:155]
	global_load_lds_dwordx4 v[200:201], off
	s_mov_b32 m0, s51
	s_nop 0
	global_load_lds_dwordx4 v[202:203], off
	s_waitcnt vmcnt(8)
	s_waitcnt lgkmcnt(0)
	s_barrier
; #define PG8_STAGE(bufoff, gbase, voff) do { _Pragma("unroll") for (int _i = 0; _i < 2; ++_i) \
;         __builtin_amdgcn_global_load_lds((const unsigned*)((const char*)(gbase) + (voff)[_i]), (PG8_LAS unsigned*)(lds + (bufoff) + ldsw + _i * 8192), 16, 0, 0); } while (0)
; #define PG8_LDA(dst, b, h) do { _Pragma("unroll") for (int m = 0; m < 4; ++m) _Pragma("unroll") for (int k = 0; k < 2; ++k) dst[m][k] = *(const PG8_LAS bf16x8*)(lds + PG8_SA(b, h) + aoff + m * 2048 + k * 1024); } while (0)
; #define PG8_LDB(dst, b, h) do { _Pragma("unroll") for (int n = 0; n < 2; ++n) _Pragma("unroll") for (int k = 0; k < 2; ++k) dst[n][k] = *(const PG8_LAS bf16x8*)(lds + PG8_SB(b, h) + boff + n * 2048 + k * 1024); } while (0)
; #define PG8_MMA(ai, bj, At, Bt) do { __builtin_amdgcn_s_setprio(1); _Pragma("unroll") for (int m = 0; m < 4; ++m) _Pragma("unroll") for (int n = 0; n < 2; ++n) _Pragma("unroll") for (int k = 0; k < 2; ++k) \
;         acc[ai][bj][m][n] = __builtin_amdgcn_mfma_f32_16x16x32_bf16(Bt[n][k], At[m][k], acc[ai][bj][m][n], 0, 0, 0); __builtin_amdgcn_s_setprio(0); } while (0)
; #define PG8_WAIT_V(n) asm volatile("s_waitcnt vmcnt(" #n ")" ::: "memory")
; #define PG8_WAIT_L(n) asm volatile("s_waitcnt lgkmcnt(" #n ")" ::: "memory")
; #define PG8_BAR __builtin_amdgcn_s_barrier()
; #define PG8_SCHED __builtin_amdgcn_sched_barrier(0)
; template <class Epi, class Sched, bool ALIGN_EPI = false, bool SP2 = false>
; __device__ __forceinline__ void gemm_phase(PG8_LAS unsigned char* lds, const Gemm g, const Sched& S, const Epi& E, int tid_in) {
;     ...
;             PG8_WAIT_V(8); PG8_WAIT_L(0); PG8_BAR; PG8_MMA(1, 0, At, B0); PG8_MMA(1, 1, At, B1); PG8_BAR; PG8_SCHED;
;             PG8_LDB(B0, 1, 0); PG8_LDB(B1, 1, 1); PG8_SCHED; PG8_LDA(At, 1, 0); PG8_STAGE(PG8_SA(0, 1), a2 + hsA, voffA);
;             PG8_WAIT_V(8); PG8_WAIT_L(0); PG8_BAR; PG8_MMA(0, 0, At, B0); PG8_MMA(0, 1, At, B1); PG8_BAR; PG8_SCHED;
	s_setprio 1
	s_waitcnt lgkmcnt(0)
	v_mfma_f32_16x16x32_bf16 v[96:99], v[132:135], v[174:177], v[96:99]
	v_mfma_f32_16x16x32_bf16 v[92:95], v[140:143], v[174:177], v[92:95]
	v_mfma_f32_16x16x32_bf16 v[88:91], v[132:135], v[182:185], v[88:91]
	v_mfma_f32_16x16x32_bf16 v[84:87], v[140:143], v[182:185], v[84:87]
	v_mfma_f32_16x16x32_bf16 v[80:83], v[132:135], v[204:207], v[80:83]
	v_mfma_f32_16x16x32_bf16 v[76:79], v[140:143], v[204:207], v[76:79]
	v_mfma_f32_16x16x32_bf16 v[72:75], v[132:135], v[212:215], v[72:75]
	v_mfma_f32_16x16x32_bf16 v[68:71], v[140:143], v[212:215], v[68:71]
	v_mfma_f32_16x16x32_bf16 v[96:99], v[136:139], v[178:181], v[96:99]
	v_mfma_f32_16x16x32_bf16 v[92:95], v[144:147], v[178:181], v[92:95]
	v_mfma_f32_16x16x32_bf16 v[88:91], v[136:139], v[186:189], v[88:91]
	v_mfma_f32_16x16x32_bf16 v[84:87], v[144:147], v[186:189], v[84:87]
	v_mfma_f32_16x16x32_bf16 v[80:83], v[136:139], v[208:211], v[80:83]
	v_mfma_f32_16x16x32_bf16 v[76:79], v[144:147], v[208:211], v[76:79]
	v_mfma_f32_16x16x32_bf16 v[72:75], v[136:139], v[220:223], v[72:75]
	v_mfma_f32_16x16x32_bf16 v[68:71], v[144:147], v[220:223], v[68:71]
	v_mfma_f32_16x16x32_bf16 v[32:35], v[148:151], v[174:177], v[32:35]
	v_mfma_f32_16x16x32_bf16 v[28:31], v[166:169], v[174:177], v[28:31]
	v_mfma_f32_16x16x32_bf16 v[24:27], v[148:151], v[182:185], v[24:27]
	v_mfma_f32_16x16x32_bf16 v[12:15], v[166:169], v[182:185], v[12:15]
	v_mfma_f32_16x16x32_bf16 v[20:23], v[148:151], v[204:207], v[20:23]
	v_mfma_f32_16x16x32_bf16 v[8:11], v[166:169], v[204:207], v[8:11]
	v_mfma_f32_16x16x32_bf16 v[16:19], v[148:151], v[212:215], v[16:19]
	v_mfma_f32_16x16x32_bf16 v[4:7], v[166:169], v[212:215], v[4:7]
	v_mfma_f32_16x16x32_bf16 v[32:35], v[162:165], v[178:181], v[32:35]
	v_mfma_f32_16x16x32_bf16 v[28:31], v[170:173], v[178:181], v[28:31]
	v_mfma_f32_16x16x32_bf16 v[24:27], v[162:165], v[186:189], v[24:27]
	v_mfma_f32_16x16x32_bf16 v[12:15], v[170:173], v[186:189], v[12:15]
	v_mfma_f32_16x16x32_bf16 v[20:23], v[162:165], v[208:211], v[20:23]
	v_mfma_f32_16x16x32_bf16 v[8:11], v[170:173], v[208:211], v[8:11]
	v_mfma_f32_16x16x32_bf16 v[16:19], v[162:165], v[220:223], v[16:19]
	v_mfma_f32_16x16x32_bf16 v[4:7], v[170:173], v[220:223], v[4:7]
	s_setprio 0
	s_barrier
	s_add_i32 s41, 0, 0x18000
	s_add_i32 s76, 0, 0x1c000
	v_add_u32_e32 v144, s41, v217
	v_add_u32_e32 v170, s76, v217
	ds_read_b128 v[132:135], v144
	ds_read_b128 v[136:139], v144 offset:1024
	ds_read_b128 v[140:143], v144 offset:2048
	ds_read_b128 v[144:147], v144 offset:3072
	ds_read_b128 v[148:151], v170
	ds_read_b128 v[162:165], v170 offset:1024
	ds_read_b128 v[166:169], v170 offset:2048
	ds_read_b128 v[170:173], v170 offset:3072
	s_add_u32 s38, s38, s10
	s_addc_u32 s39, s39, s11
	s_mov_b32 m0, s52
	v_lshl_add_u64 v[228:229], s[38:39], 0, v[0:1]
	ds_read_b128 v[174:177], v219 offset:32768
	ds_read_b128 v[178:181], v219 offset:33792
	ds_read_b128 v[182:185], v219 offset:34816
	ds_read_b128 v[186:189], v219 offset:35840
	ds_read_b128 v[204:207], v219 offset:36864
	ds_read_b128 v[208:211], v219 offset:37888
	ds_read_b128 v[212:215], v219 offset:38912
	ds_read_b128 v[220:223], v219 offset:39936
	global_load_lds_dwordx4 v[228:229], off
	v_lshl_add_u64 v[228:229], s[38:39], 0, v[154:155]
	s_mov_b32 m0, s53
	s_nop 0
	global_load_lds_dwordx4 v[228:229], off
	s_waitcnt vmcnt(8)
	s_waitcnt lgkmcnt(0)
	s_barrier
	s_setprio 1
	s_waitcnt lgkmcnt(0)
	v_mfma_f32_16x16x32_bf16 v[128:131], v[132:135], v[174:177], v[128:131]
	v_mfma_f32_16x16x32_bf16 v[124:127], v[140:143], v[174:177], v[124:127]
	v_mfma_f32_16x16x32_bf16 v[120:123], v[132:135], v[182:185], v[120:123]
	v_mfma_f32_16x16x32_bf16 v[116:119], v[140:143], v[182:185], v[116:119]
	v_mfma_f32_16x16x32_bf16 v[112:115], v[132:135], v[204:207], v[112:115]
	v_mfma_f32_16x16x32_bf16 v[108:111], v[140:143], v[204:207], v[108:111]
	v_mfma_f32_16x16x32_bf16 v[104:107], v[132:135], v[212:215], v[104:107]
	v_mfma_f32_16x16x32_bf16 v[100:103], v[140:143], v[212:215], v[100:103]
	v_mfma_f32_16x16x32_bf16 v[128:131], v[136:139], v[178:181], v[128:131]
	v_mfma_f32_16x16x32_bf16 v[124:127], v[144:147], v[178:181], v[124:127]
	v_mfma_f32_16x16x32_bf16 v[120:123], v[136:139], v[186:189], v[120:123]
	v_mfma_f32_16x16x32_bf16 v[116:119], v[144:147], v[186:189], v[116:119]
	v_mfma_f32_16x16x32_bf16 v[112:115], v[136:139], v[208:211], v[112:115]
	v_mfma_f32_16x16x32_bf16 v[108:111], v[144:147], v[208:211], v[108:111]
	v_mfma_f32_16x16x32_bf16 v[104:107], v[136:139], v[220:223], v[104:107]
	v_mfma_f32_16x16x32_bf16 v[100:103], v[144:147], v[220:223], v[100:103]
	v_mfma_f32_16x16x32_bf16 v[64:67], v[148:151], v[174:177], v[64:67]
	v_mfma_f32_16x16x32_bf16 v[56:59], v[166:169], v[174:177], v[56:59]
	v_mfma_f32_16x16x32_bf16 v[60:63], v[148:151], v[182:185], v[60:63]
	v_mfma_f32_16x16x32_bf16 v[52:55], v[166:169], v[182:185], v[52:55]
	v_mfma_f32_16x16x32_bf16 v[48:51], v[148:151], v[204:207], v[48:51]
	v_mfma_f32_16x16x32_bf16 v[40:43], v[166:169], v[204:207], v[40:43]
	v_mfma_f32_16x16x32_bf16 v[44:47], v[148:151], v[212:215], v[44:47]
	v_mfma_f32_16x16x32_bf16 v[36:39], v[166:169], v[212:215], v[36:39]
	v_mfma_f32_16x16x32_bf16 v[64:67], v[162:165], v[178:181], v[64:67]
	v_mfma_f32_16x16x32_bf16 v[56:59], v[170:173], v[178:181], v[56:59]
	v_mfma_f32_16x16x32_bf16 v[60:63], v[162:165], v[186:189], v[60:63]
	v_mfma_f32_16x16x32_bf16 v[52:55], v[170:173], v[186:189], v[52:55]
	v_mfma_f32_16x16x32_bf16 v[48:51], v[162:165], v[208:211], v[48:51]
	v_mfma_f32_16x16x32_bf16 v[40:43], v[170:173], v[208:211], v[40:43]
	v_mfma_f32_16x16x32_bf16 v[44:47], v[162:165], v[220:223], v[44:47]
	v_mfma_f32_16x16x32_bf16 v[36:39], v[170:173], v[220:223], v[36:39]
	s_setprio 0
	s_barrier
; #define PG8_STAGE(bufoff, gbase, voff) do { _Pragma("unroll") for (int _i = 0; _i < 2; ++_i) \
;         __builtin_amdgcn_global_load_lds((const unsigned*)((const char*)(gbase) + (voff)[_i]), (PG8_LAS unsigned*)(lds + (bufoff) + ldsw + _i * 8192), 16, 0, 0); } while (0)
; #define PG8_LDA(dst, b, h) do { _Pragma("unroll") for (int m = 0; m < 4; ++m) _Pragma("unroll") for (int k = 0; k < 2; ++k) dst[m][k] = *(const PG8_LAS bf16x8*)(lds + PG8_SA(b, h) + aoff + m * 2048 + k * 1024); } while (0)
; #define PG8_MMA(ai, bj, At, Bt) do { __builtin_amdgcn_s_setprio(1); _Pragma("unroll") for (int m = 0; m < 4; ++m) _Pragma("unroll") for (int n = 0; n < 2; ++n) _Pragma("unroll") for (int k = 0; k < 2; ++k) \
;         acc[ai][bj][m][n] = __builtin_amdgcn_mfma_f32_16x16x32_bf16(Bt[n][k], At[m][k], acc[ai][bj][m][n], 0, 0, 0); __builtin_amdgcn_s_setprio(0); } while (0)
; #define PG8_WAIT_V(n) asm volatile("s_waitcnt vmcnt(" #n ")" ::: "memory")
; #define PG8_WAIT_L(n) asm volatile("s_waitcnt lgkmcnt(" #n ")" ::: "memory")
; #define PG8_BAR __builtin_amdgcn_s_barrier()
; #define PG8_SCHED __builtin_amdgcn_sched_barrier(0)
; template <class Epi, class Sched, bool ALIGN_EPI = false, bool SP2 = false>
; __device__ __forceinline__ void gemm_phase(PG8_LAS unsigned char* lds, const Gemm g, const Sched& S, const Epi& E, int tid_in) {
;     ...
;             PG8_LDA(At, 1, 1); PG8_STAGE(PG8_SB(1, 0), b3, voffB); PG8_STAGE(PG8_SB(1, 1), b3 + hsB, voffB); PG8_STAGE(PG8_SA(1, 0), a3, voffA);
;             PG8_WAIT_V(8); PG8_WAIT_L(0); PG8_BAR; PG8_MMA(1, 0, At, B0); PG8_MMA(1, 1, At, B1); PG8_BAR; PG8_SCHED;
	s_add_i32 s38, s41, s49
	v_lshl_add_u64 v[190:191], v[190:191], 0, s[80:81]
	s_mov_b32 m0, s38
	ds_read_b128 v[174:177], v219 offset:49152
	ds_read_b128 v[178:181], v219 offset:50176
	ds_read_b128 v[182:185], v219 offset:51200
	ds_read_b128 v[186:189], v219 offset:52224
	ds_read_b128 v[204:207], v219 offset:53248
	ds_read_b128 v[208:211], v219 offset:54272
	ds_read_b128 v[212:215], v219 offset:55296
	ds_read_b128 v[220:223], v219 offset:56320
	global_load_lds_dwordx4 v[190:191], off
	v_lshl_add_u64 v[190:191], v[192:193], 0, s[80:81]
	s_add_i32 m0, s38, 0x2000
	s_add_i32 s38, s76, s49
	global_load_lds_dwordx4 v[190:191], off
	v_lshl_add_u64 v[190:191], v[196:197], 0, s[80:81]
	s_mov_b32 m0, s38
	s_nop 0
	global_load_lds_dwordx4 v[190:191], off
	v_lshl_add_u64 v[190:191], v[198:199], 0, s[80:81]
	s_add_i32 m0, s38, 0x2000
	s_nop 0
	global_load_lds_dwordx4 v[190:191], off
	v_lshl_add_u64 v[190:191], v[200:201], 0, s[80:81]
	s_mov_b32 m0, s58
	s_nop 0
	global_load_lds_dwordx4 v[190:191], off
	v_lshl_add_u64 v[190:191], v[202:203], 0, s[80:81]
	s_mov_b32 m0, s59
	s_nop 0
	global_load_lds_dwordx4 v[190:191], off
	s_waitcnt vmcnt(8)
	s_waitcnt lgkmcnt(0)
	s_barrier
	s_setprio 1
	s_waitcnt lgkmcnt(0)
	v_mfma_f32_16x16x32_bf16 v[96:99], v[132:135], v[174:177], v[96:99]
	v_mfma_f32_16x16x32_bf16 v[92:95], v[140:143], v[174:177], v[92:95]
	v_mfma_f32_16x16x32_bf16 v[88:91], v[132:135], v[182:185], v[88:91]
	v_mfma_f32_16x16x32_bf16 v[84:87], v[140:143], v[182:185], v[84:87]
	v_mfma_f32_16x16x32_bf16 v[80:83], v[132:135], v[204:207], v[80:83]
	v_mfma_f32_16x16x32_bf16 v[76:79], v[140:143], v[204:207], v[76:79]
	v_mfma_f32_16x16x32_bf16 v[72:75], v[132:135], v[212:215], v[72:75]
	v_mfma_f32_16x16x32_bf16 v[68:71], v[140:143], v[212:215], v[68:71]
	v_mfma_f32_16x16x32_bf16 v[96:99], v[136:139], v[178:181], v[96:99]
	v_mfma_f32_16x16x32_bf16 v[92:95], v[144:147], v[178:181], v[92:95]
	v_mfma_f32_16x16x32_bf16 v[88:91], v[136:139], v[186:189], v[88:91]
	v_mfma_f32_16x16x32_bf16 v[84:87], v[144:147], v[186:189], v[84:87]
	v_mfma_f32_16x16x32_bf16 v[80:83], v[136:139], v[208:211], v[80:83]
	v_mfma_f32_16x16x32_bf16 v[76:79], v[144:147], v[208:211], v[76:79]
	v_mfma_f32_16x16x32_bf16 v[72:75], v[136:139], v[220:223], v[72:75]
	v_mfma_f32_16x16x32_bf16 v[68:71], v[144:147], v[220:223], v[68:71]
	v_mfma_f32_16x16x32_bf16 v[32:35], v[148:151], v[174:177], v[32:35]
	v_mfma_f32_16x16x32_bf16 v[28:31], v[166:169], v[174:177], v[28:31]
	v_mfma_f32_16x16x32_bf16 v[24:27], v[148:151], v[182:185], v[24:27]
	v_mfma_f32_16x16x32_bf16 v[12:15], v[166:169], v[182:185], v[12:15]
	v_mfma_f32_16x16x32_bf16 v[20:23], v[148:151], v[204:207], v[20:23]
	v_mfma_f32_16x16x32_bf16 v[8:11], v[166:169], v[204:207], v[8:11]
	v_mfma_f32_16x16x32_bf16 v[16:19], v[148:151], v[212:215], v[16:19]
	v_mfma_f32_16x16x32_bf16 v[4:7], v[166:169], v[212:215], v[4:7]
	v_mfma_f32_16x16x32_bf16 v[32:35], v[162:165], v[178:181], v[32:35]
	v_mfma_f32_16x16x32_bf16 v[28:31], v[170:173], v[178:181], v[28:31]
	v_mfma_f32_16x16x32_bf16 v[24:27], v[162:165], v[186:189], v[24:27]
	v_mfma_f32_16x16x32_bf16 v[12:15], v[170:173], v[186:189], v[12:15]
	v_mfma_f32_16x16x32_bf16 v[20:23], v[162:165], v[208:211], v[20:23]
	v_mfma_f32_16x16x32_bf16 v[8:11], v[170:173], v[208:211], v[8:11]
	v_mfma_f32_16x16x32_bf16 v[16:19], v[162:165], v[220:223], v[16:19]
	v_mfma_f32_16x16x32_bf16 v[4:7], v[170:173], v[220:223], v[4:7]
	s_setprio 0
	s_barrier
	s_add_i32 s38, s40, 2
	s_add_u32 s74, s74, 0x100
	s_addc_u32 s75, s75, 0
	s_add_u32 s4, s4, 0x100
	s_addc_u32 s5, s5, 0
	s_cmp_ge_i32 s40, s60
	s_mov_b32 s40, s38
	s_cbranch_scc0 .LBB0_1331
	s_movk_i32 s74, 0x2c00

; #define PG8_STAGE(bufoff, gbase, voff) do { _Pragma("unroll") for (int _i = 0; _i < 2; ++_i) \
;         __builtin_amdgcn_global_load_lds((const unsigned*)((const char*)(gbase) + (voff)[_i]), (PG8_LAS unsigned*)(lds + (bufoff) + ldsw + _i * 8192), 16, 0, 0); } while (0)
; #define PG8_LDA(dst, b, h) do { _Pragma("unroll") for (int m = 0; m < 4; ++m) _Pragma("unroll") for (int k = 0; k < 2; ++k) dst[m][k] = *(const PG8_LAS bf16x8*)(lds + PG8_SA(b, h) + aoff + m * 2048 + k * 1024); } while (0)
; #define PG8_LDB(dst, b, h) do { _Pragma("unroll") for (int n = 0; n < 2; ++n) _Pragma("unroll") for (int k = 0; k < 2; ++k) dst[n][k] = *(const PG8_LAS bf16x8*)(lds + PG8_SB(b, h) + boff + n * 2048 + k * 1024); } while (0)
; #define PG8_MMA(ai, bj, At, Bt) do { __builtin_amdgcn_s_setprio(1); _Pragma("unroll") for (int m = 0; m < 4; ++m) _Pragma("unroll") for (int n = 0; n < 2; ++n) _Pragma("unroll") for (int k = 0; k < 2; ++k) \
;         acc[ai][bj][m][n] = __builtin_amdgcn_mfma_f32_16x16x32_bf16(Bt[n][k], At[m][k], acc[ai][bj][m][n], 0, 0, 0); __builtin_amdgcn_s_setprio(0); } while (0)
; #define PG8_WAIT_V(n) asm volatile("s_waitcnt vmcnt(" #n ")" ::: "memory")
; #define PG8_BAR __builtin_amdgcn_s_barrier()
; template <class Epi, class Sched, bool ALIGN_EPI = false, bool SP2 = false>
; __device__ __forceinline__ void gemm_phase(PG8_LAS unsigned char* lds, const Gemm g, const Sched& S, const Epi& E, int tid_in) {
;     ...
;             const bool last = (t == nt - 2);
;             if constexpr (mid_hook<Epi>::value) { if (t == Epi::H1 || t == Epi::H2) E.mid(acc, cur, wr, wc, fr, fq, t == Epi::H2); }
;             const char* a1 = cA + (size_t)(t + 1) * kstep + (t >= jt ? jb : 0);
;             const char* a2 = last ? nA : cA + (size_t)(t + 2) * kstep + (t + 2 >= jt ? jb : 0); const char* b2 = last ? nB : cB + (size_t)(t + 2) * kstep;
;             const char* a3 = a2 + kstep; const char* b3 = b2 + kstep;
;             if (last && has_next) S.a_ready(nxt);
;             if constexpr (SP2) {
;             PG8_LDB(B0, 0, 0); PG8_LDB(B1, 0, 1); PG8_SCHED; PG8_LDA(At, 0, 0); PG8_STAGE(PG8_SA(1, 1), a1 + hsA, voffA);
;             PG8_WAIT_V(8); PG8_WAIT_L(0); PG8_BAR; PG8_MMA(0, 0, At, B0); PG8_MMA(0, 1, At, B1); PG8_BAR; PG8_SCHED;
;             PG8_LDA(At, 0, 1); PG8_STAGE(PG8_SB(0, 0), b2, voffB); PG8_STAGE(PG8_SB(0, 1), b2 + hsB, voffB); PG8_STAGE(PG8_SA(0, 0), a2, voffA);
.LBB0_1362:
	s_add_i32 s24, s55, -2
	s_cmp_ge_i32 s24, s26
	s_cselect_b32 s58, s27, 0
	s_cselect_b32 s59, s47, 0
	s_cmp_ge_i32 s55, s26
	s_cselect_b32 s25, s27, 0
	s_cselect_b32 s24, s47, 0
	s_add_u32 s25, s22, s25
	s_addc_u32 s24, s23, s24
	s_add_u32 s60, s25, 0x80
	s_addc_u32 s24, s24, 0
	s_add_i32 s62, 0, 0x10000
	s_cmp_eq_u32 s46, s55
	s_cselect_b32 s25, s5, s24
	s_cselect_b32 s24, s4, s60
	s_cselect_b32 s61, s21, s54
	s_cselect_b32 s60, s20, s53
	s_add_i32 s63, 0, 0x14000
	v_add_u32_e32 v160, s62, v3
	v_add_u32_e32 v176, s63, v3
	ds_read_b128 v[148:151], v160
	ds_read_b128 v[152:155], v160 offset:1024
	ds_read_b128 v[156:159], v160 offset:2048
	ds_read_b128 v[160:163], v160 offset:3072
	ds_read_b128 v[164:167], v176
	ds_read_b128 v[168:171], v176 offset:1024
	ds_read_b128 v[172:175], v176 offset:2048
	ds_read_b128 v[176:179], v176 offset:3072
	v_lshl_add_u64 v[192:193], s[22:23], 0, v[140:141]
	v_lshl_add_u64 v[192:193], v[192:193], 0, s[58:59]
	s_add_i32 m0, s33, 0xc000
	ds_read_b128 v[180:183], v147
	ds_read_b128 v[184:187], v147 offset:1024
	ds_read_b128 v[188:191], v147 offset:2048
	ds_read_b128 v[204:207], v147 offset:3072
	ds_read_b128 v[208:211], v147 offset:4096
	ds_read_b128 v[212:215], v147 offset:5120
	ds_read_b128 v[216:219], v147 offset:6144
	ds_read_b128 v[220:223], v147 offset:7168
	global_load_lds_dwordx4 v[192:193], off
	v_lshl_add_u64 v[192:193], s[22:23], 0, v[138:139]
	v_lshl_add_u64 v[192:193], v[192:193], 0, s[58:59]
	s_add_i32 m0, s33, 0xe000
	s_nop 0
	global_load_lds_dwordx4 v[192:193], off
	s_waitcnt vmcnt(8)
	s_waitcnt lgkmcnt(0)
	s_barrier
	s_setprio 1
	s_waitcnt lgkmcnt(0)
	v_mfma_f32_16x16x32_bf16 v[124:127], v[148:151], v[180:183], v[124:127]
	v_mfma_f32_16x16x32_bf16 v[128:131], v[156:159], v[180:183], v[128:131]
	v_mfma_f32_16x16x32_bf16 v[112:115], v[148:151], v[188:191], v[112:115]
	v_mfma_f32_16x16x32_bf16 v[108:111], v[156:159], v[188:191], v[108:111]
	v_mfma_f32_16x16x32_bf16 v[96:99], v[148:151], v[208:211], v[96:99]
	v_mfma_f32_16x16x32_bf16 v[92:95], v[156:159], v[208:211], v[92:95]
	v_mfma_f32_16x16x32_bf16 v[80:83], v[148:151], v[216:219], v[80:83]
	v_mfma_f32_16x16x32_bf16 v[76:79], v[156:159], v[216:219], v[76:79]
	v_mfma_f32_16x16x32_bf16 v[124:127], v[152:155], v[184:187], v[124:127]
	v_mfma_f32_16x16x32_bf16 v[128:131], v[160:163], v[184:187], v[128:131]
	v_mfma_f32_16x16x32_bf16 v[112:115], v[152:155], v[204:207], v[112:115]
	v_mfma_f32_16x16x32_bf16 v[108:111], v[160:163], v[204:207], v[108:111]
	v_mfma_f32_16x16x32_bf16 v[96:99], v[152:155], v[212:215], v[96:99]
	v_mfma_f32_16x16x32_bf16 v[92:95], v[160:163], v[212:215], v[92:95]
	v_mfma_f32_16x16x32_bf16 v[80:83], v[152:155], v[220:223], v[80:83]
	v_mfma_f32_16x16x32_bf16 v[76:79], v[160:163], v[220:223], v[76:79]
	v_mfma_f32_16x16x32_bf16 v[120:123], v[164:167], v[180:183], v[120:123]
	v_mfma_f32_16x16x32_bf16 v[116:119], v[172:175], v[180:183], v[116:119]
	v_mfma_f32_16x16x32_bf16 v[104:107], v[164:167], v[188:191], v[104:107]
	v_mfma_f32_16x16x32_bf16 v[100:103], v[172:175], v[188:191], v[100:103]
	v_mfma_f32_16x16x32_bf16 v[88:91], v[164:167], v[208:211], v[88:91]
	v_mfma_f32_16x16x32_bf16 v[84:87], v[172:175], v[208:211], v[84:87]
	v_mfma_f32_16x16x32_bf16 v[72:75], v[164:167], v[216:219], v[72:75]
	v_mfma_f32_16x16x32_bf16 v[68:71], v[172:175], v[216:219], v[68:71]
	v_mfma_f32_16x16x32_bf16 v[120:123], v[168:171], v[184:187], v[120:123]
	v_mfma_f32_16x16x32_bf16 v[116:119], v[176:179], v[184:187], v[116:119]
	v_mfma_f32_16x16x32_bf16 v[104:107], v[168:171], v[204:207], v[104:107]
	v_mfma_f32_16x16x32_bf16 v[100:103], v[176:179], v[204:207], v[100:103]
	v_mfma_f32_16x16x32_bf16 v[88:91], v[168:171], v[212:215], v[88:91]
	v_mfma_f32_16x16x32_bf16 v[84:87], v[176:179], v[212:215], v[84:87]
	v_mfma_f32_16x16x32_bf16 v[72:75], v[168:171], v[220:223], v[72:75]
	v_mfma_f32_16x16x32_bf16 v[68:71], v[176:179], v[220:223], v[68:71]
	s_setprio 0
	s_barrier
	s_add_i32 s58, s62, s30
	v_lshl_add_u64 v[192:193], s[60:61], 0, v[134:135]
	s_mov_b32 m0, s58
	ds_read_b128 v[180:183], v147 offset:16384
	ds_read_b128 v[184:187], v147 offset:17408
	ds_read_b128 v[188:191], v147 offset:18432
	ds_read_b128 v[204:207], v147 offset:19456
	ds_read_b128 v[208:211], v147 offset:20480
	ds_read_b128 v[212:215], v147 offset:21504
	ds_read_b128 v[216:219], v147 offset:22528
	ds_read_b128 v[220:223], v147 offset:23552
	global_load_lds_dwordx4 v[192:193], off
	s_add_i32 m0, s58, 0x2000
	s_add_u32 s58, s60, s8
	v_lshl_add_u64 v[196:197], s[60:61], 0, v[0:1]
	s_addc_u32 s59, s61, s9
	s_add_i32 s60, s63, s30
	global_load_lds_dwordx4 v[196:197], off
	v_lshl_add_u64 v[198:199], s[58:59], 0, v[134:135]
	s_mov_b32 m0, s60
	v_lshl_add_u64 v[200:201], s[58:59], 0, v[0:1]
	global_load_lds_dwordx4 v[198:199], off
	s_add_i32 m0, s60, 0x2000
	v_lshl_add_u64 v[202:203], s[24:25], 0, v[136:137]
	global_load_lds_dwordx4 v[200:201], off
	s_mov_b32 m0, s33
	v_lshl_add_u64 v[228:229], s[24:25], 0, v[132:133]
	global_load_lds_dwordx4 v[202:203], off
	s_mov_b32 m0, s34
	s_nop 0
	global_load_lds_dwordx4 v[228:229], off
	s_waitcnt vmcnt(8)
	s_waitcnt lgkmcnt(0)
	s_barrier
; #define PG8_STAGE(bufoff, gbase, voff) do { _Pragma("unroll") for (int _i = 0; _i < 2; ++_i) \
;         __builtin_amdgcn_global_load_lds((const unsigned*)((const char*)(gbase) + (voff)[_i]), (PG8_LAS unsigned*)(lds + (bufoff) + ldsw + _i * 8192), 16, 0, 0); } while (0)
; #define PG8_LDA(dst, b, h) do { _Pragma("unroll") for (int m = 0; m < 4; ++m) _Pragma("unroll") for (int k = 0; k < 2; ++k) dst[m][k] = *(const PG8_LAS bf16x8*)(lds + PG8_SA(b, h) + aoff + m * 2048 + k * 1024); } while (0)
; #define PG8_LDB(dst, b, h) do { _Pragma("unroll") for (int n = 0; n < 2; ++n) _Pragma("unroll") for (int k = 0; k < 2; ++k) dst[n][k] = *(const PG8_LAS bf16x8*)(lds + PG8_SB(b, h) + boff + n * 2048 + k * 1024); } while (0)
; #define PG8_MMA(ai, bj, At, Bt) do { __builtin_amdgcn_s_setprio(1); _Pragma("unroll") for (int m = 0; m < 4; ++m) _Pragma("unroll") for (int n = 0; n < 2; ++n) _Pragma("unroll") for (int k = 0; k < 2; ++k) \
;         acc[ai][bj][m][n] = __builtin_amdgcn_mfma_f32_16x16x32_bf16(Bt[n][k], At[m][k], acc[ai][bj][m][n], 0, 0, 0); __builtin_amdgcn_s_setprio(0); } while (0)
; #define PG8_WAIT_V(n) asm volatile("s_waitcnt vmcnt(" #n ")" ::: "memory")
; #define PG8_WAIT_L(n) asm volatile("s_waitcnt lgkmcnt(" #n ")" ::: "memory")
; #define PG8_BAR __builtin_amdgcn_s_barrier()
; #define PG8_SCHED __builtin_amdgcn_sched_barrier(0)
; template <class Epi, class Sched, bool ALIGN_EPI = false, bool SP2 = false>
; __device__ __forceinline__ void gemm_phase(PG8_LAS unsigned char* lds, const Gemm g, const Sched& S, const Epi& E, int tid_in) {
;     ...
;             PG8_WAIT_V(8); PG8_WAIT_L(0); PG8_BAR; PG8_MMA(1, 0, At, B0); PG8_MMA(1, 1, At, B1); PG8_BAR; PG8_SCHED;
;             PG8_LDB(B0, 1, 0); PG8_LDB(B1, 1, 1); PG8_SCHED; PG8_LDA(At, 1, 0); PG8_STAGE(PG8_SA(0, 1), a2 + hsA, voffA);
;             PG8_WAIT_V(8); PG8_WAIT_L(0); PG8_BAR; PG8_MMA(0, 0, At, B0); PG8_MMA(0, 1, At, B1); PG8_BAR; PG8_SCHED;
	s_setprio 1
	s_waitcnt lgkmcnt(0)
	v_mfma_f32_16x16x32_bf16 v[64:67], v[148:151], v[180:183], v[64:67]
	v_mfma_f32_16x16x32_bf16 v[60:63], v[156:159], v[180:183], v[60:63]
	v_mfma_f32_16x16x32_bf16 v[48:51], v[148:151], v[188:191], v[48:51]
	v_mfma_f32_16x16x32_bf16 v[44:47], v[156:159], v[188:191], v[44:47]
	v_mfma_f32_16x16x32_bf16 v[32:35], v[148:151], v[208:211], v[32:35]
	v_mfma_f32_16x16x32_bf16 v[28:31], v[156:159], v[208:211], v[28:31]
	v_mfma_f32_16x16x32_bf16 v[16:19], v[148:151], v[216:219], v[16:19]
	v_mfma_f32_16x16x32_bf16 v[12:15], v[156:159], v[216:219], v[12:15]
	v_mfma_f32_16x16x32_bf16 v[64:67], v[152:155], v[184:187], v[64:67]
	v_mfma_f32_16x16x32_bf16 v[60:63], v[160:163], v[184:187], v[60:63]
	v_mfma_f32_16x16x32_bf16 v[48:51], v[152:155], v[204:207], v[48:51]
	v_mfma_f32_16x16x32_bf16 v[44:47], v[160:163], v[204:207], v[44:47]
	v_mfma_f32_16x16x32_bf16 v[32:35], v[152:155], v[212:215], v[32:35]
	v_mfma_f32_16x16x32_bf16 v[28:31], v[160:163], v[212:215], v[28:31]
	v_mfma_f32_16x16x32_bf16 v[16:19], v[152:155], v[220:223], v[16:19]
	v_mfma_f32_16x16x32_bf16 v[12:15], v[160:163], v[220:223], v[12:15]
	v_mfma_f32_16x16x32_bf16 v[56:59], v[164:167], v[180:183], v[56:59]
	v_mfma_f32_16x16x32_bf16 v[52:55], v[172:175], v[180:183], v[52:55]
	v_mfma_f32_16x16x32_bf16 v[40:43], v[164:167], v[188:191], v[40:43]
	v_mfma_f32_16x16x32_bf16 v[36:39], v[172:175], v[188:191], v[36:39]
	v_mfma_f32_16x16x32_bf16 v[24:27], v[164:167], v[208:211], v[24:27]
	v_mfma_f32_16x16x32_bf16 v[20:23], v[172:175], v[208:211], v[20:23]
	v_mfma_f32_16x16x32_bf16 v[8:11], v[164:167], v[216:219], v[8:11]
	v_mfma_f32_16x16x32_bf16 v[4:7], v[172:175], v[216:219], v[4:7]
	v_mfma_f32_16x16x32_bf16 v[56:59], v[168:171], v[184:187], v[56:59]
	v_mfma_f32_16x16x32_bf16 v[52:55], v[176:179], v[184:187], v[52:55]
	v_mfma_f32_16x16x32_bf16 v[40:43], v[168:171], v[204:207], v[40:43]
	v_mfma_f32_16x16x32_bf16 v[36:39], v[176:179], v[204:207], v[36:39]
	v_mfma_f32_16x16x32_bf16 v[24:27], v[168:171], v[212:215], v[24:27]
	v_mfma_f32_16x16x32_bf16 v[20:23], v[176:179], v[212:215], v[20:23]
	v_mfma_f32_16x16x32_bf16 v[8:11], v[168:171], v[220:223], v[8:11]
	v_mfma_f32_16x16x32_bf16 v[4:7], v[176:179], v[220:223], v[4:7]
	s_setprio 0
	s_barrier
	s_add_i32 s58, 0, 0x18000
	s_add_i32 s59, 0, 0x1c000
	v_add_u32_e32 v160, s58, v3
	v_add_u32_e32 v176, s59, v3
	ds_read_b128 v[148:151], v160
	ds_read_b128 v[152:155], v160 offset:1024
	ds_read_b128 v[156:159], v160 offset:2048
	ds_read_b128 v[160:163], v160 offset:3072
	ds_read_b128 v[164:167], v176
	ds_read_b128 v[168:171], v176 offset:1024
	ds_read_b128 v[172:175], v176 offset:2048
	ds_read_b128 v[176:179], v176 offset:3072
	s_add_u32 s24, s24, s6
	s_addc_u32 s25, s25, s7
	s_mov_b32 m0, s35
	v_lshl_add_u64 v[230:231], s[24:25], 0, v[136:137]
	ds_read_b128 v[180:183], v147 offset:32768
	ds_read_b128 v[184:187], v147 offset:33792
	ds_read_b128 v[188:191], v147 offset:34816
	ds_read_b128 v[204:207], v147 offset:35840
	ds_read_b128 v[208:211], v147 offset:36864
	ds_read_b128 v[212:215], v147 offset:37888
	ds_read_b128 v[216:219], v147 offset:38912
	ds_read_b128 v[220:223], v147 offset:39936
	global_load_lds_dwordx4 v[230:231], off
	v_lshl_add_u64 v[230:231], s[24:25], 0, v[132:133]
	s_mov_b32 m0, s36
	s_nop 0
	global_load_lds_dwordx4 v[230:231], off
	s_waitcnt vmcnt(8)
	s_waitcnt lgkmcnt(0)
	s_barrier
	s_setprio 1
	s_waitcnt lgkmcnt(0)
	v_mfma_f32_16x16x32_bf16 v[124:127], v[148:151], v[180:183], v[124:127]
	v_mfma_f32_16x16x32_bf16 v[128:131], v[156:159], v[180:183], v[128:131]
	v_mfma_f32_16x16x32_bf16 v[112:115], v[148:151], v[188:191], v[112:115]
	v_mfma_f32_16x16x32_bf16 v[108:111], v[156:159], v[188:191], v[108:111]
	v_mfma_f32_16x16x32_bf16 v[96:99], v[148:151], v[208:211], v[96:99]
	v_mfma_f32_16x16x32_bf16 v[92:95], v[156:159], v[208:211], v[92:95]
	v_mfma_f32_16x16x32_bf16 v[80:83], v[148:151], v[216:219], v[80:83]
	v_mfma_f32_16x16x32_bf16 v[76:79], v[156:159], v[216:219], v[76:79]
	v_mfma_f32_16x16x32_bf16 v[124:127], v[152:155], v[184:187], v[124:127]
	v_mfma_f32_16x16x32_bf16 v[128:131], v[160:163], v[184:187], v[128:131]
	v_mfma_f32_16x16x32_bf16 v[112:115], v[152:155], v[204:207], v[112:115]
	v_mfma_f32_16x16x32_bf16 v[108:111], v[160:163], v[204:207], v[108:111]
	v_mfma_f32_16x16x32_bf16 v[96:99], v[152:155], v[212:215], v[96:99]
	v_mfma_f32_16x16x32_bf16 v[92:95], v[160:163], v[212:215], v[92:95]
	v_mfma_f32_16x16x32_bf16 v[80:83], v[152:155], v[220:223], v[80:83]
	v_mfma_f32_16x16x32_bf16 v[76:79], v[160:163], v[220:223], v[76:79]
	v_mfma_f32_16x16x32_bf16 v[120:123], v[164:167], v[180:183], v[120:123]
	v_mfma_f32_16x16x32_bf16 v[116:119], v[172:175], v[180:183], v[116:119]
	v_mfma_f32_16x16x32_bf16 v[104:107], v[164:167], v[188:191], v[104:107]
	v_mfma_f32_16x16x32_bf16 v[100:103], v[172:175], v[188:191], v[100:103]
	v_mfma_f32_16x16x32_bf16 v[88:91], v[164:167], v[208:211], v[88:91]
	v_mfma_f32_16x16x32_bf16 v[84:87], v[172:175], v[208:211], v[84:87]
	v_mfma_f32_16x16x32_bf16 v[72:75], v[164:167], v[216:219], v[72:75]
	v_mfma_f32_16x16x32_bf16 v[68:71], v[172:175], v[216:219], v[68:71]
	v_mfma_f32_16x16x32_bf16 v[120:123], v[168:171], v[184:187], v[120:123]
	v_mfma_f32_16x16x32_bf16 v[116:119], v[176:179], v[184:187], v[116:119]
	v_mfma_f32_16x16x32_bf16 v[104:107], v[168:171], v[204:207], v[104:107]
	v_mfma_f32_16x16x32_bf16 v[100:103], v[176:179], v[204:207], v[100:103]
	v_mfma_f32_16x16x32_bf16 v[88:91], v[168:171], v[212:215], v[88:91]
	v_mfma_f32_16x16x32_bf16 v[84:87], v[176:179], v[212:215], v[84:87]
	v_mfma_f32_16x16x32_bf16 v[72:75], v[168:171], v[220:223], v[72:75]
	v_mfma_f32_16x16x32_bf16 v[68:71], v[176:179], v[220:223], v[68:71]
	s_setprio 0
	s_barrier
; #define PG8_STAGE(bufoff, gbase, voff) do { _Pragma("unroll") for (int _i = 0; _i < 2; ++_i) \
;         __builtin_amdgcn_global_load_lds((const unsigned*)((const char*)(gbase) + (voff)[_i]), (PG8_LAS unsigned*)(lds + (bufoff) + ldsw + _i * 8192), 16, 0, 0); } while (0)
; #define PG8_LDA(dst, b, h) do { _Pragma("unroll") for (int m = 0; m < 4; ++m) _Pragma("unroll") for (int k = 0; k < 2; ++k) dst[m][k] = *(const PG8_LAS bf16x8*)(lds + PG8_SA(b, h) + aoff + m * 2048 + k * 1024); } while (0)
; #define PG8_MMA(ai, bj, At, Bt) do { __builtin_amdgcn_s_setprio(1); _Pragma("unroll") for (int m = 0; m < 4; ++m) _Pragma("unroll") for (int n = 0; n < 2; ++n) _Pragma("unroll") for (int k = 0; k < 2; ++k) \
;         acc[ai][bj][m][n] = __builtin_amdgcn_mfma_f32_16x16x32_bf16(Bt[n][k], At[m][k], acc[ai][bj][m][n], 0, 0, 0); __builtin_amdgcn_s_setprio(0); } while (0)
; #define PG8_WAIT_V(n) asm volatile("s_waitcnt vmcnt(" #n ")" ::: "memory")
; #define PG8_WAIT_L(n) asm volatile("s_waitcnt lgkmcnt(" #n ")" ::: "memory")
; #define PG8_BAR __builtin_amdgcn_s_barrier()
; #define PG8_SCHED __builtin_amdgcn_sched_barrier(0)
; template <class Epi, class Sched, bool ALIGN_EPI = false, bool SP2 = false>
; __device__ __forceinline__ void gemm_phase(PG8_LAS unsigned char* lds, const Gemm g, const Sched& S, const Epi& E, int tid_in) {
;     ...
;             PG8_LDA(At, 1, 1); PG8_STAGE(PG8_SB(1, 0), b3, voffB); PG8_STAGE(PG8_SB(1, 1), b3 + hsB, voffB); PG8_STAGE(PG8_SA(1, 0), a3, voffA);
;             PG8_WAIT_V(8); PG8_WAIT_L(0); PG8_BAR; PG8_MMA(1, 0, At, B0); PG8_MMA(1, 1, At, B1); PG8_BAR; PG8_SCHED;
	s_add_i32 s24, s58, s30
	v_lshl_add_u64 v[192:193], v[192:193], 0, s[80:81]
	s_mov_b32 m0, s24
	ds_read_b128 v[180:183], v147 offset:49152
	ds_read_b128 v[184:187], v147 offset:50176
	ds_read_b128 v[188:191], v147 offset:51200
	ds_read_b128 v[204:207], v147 offset:52224
	ds_read_b128 v[208:211], v147 offset:53248
	ds_read_b128 v[212:215], v147 offset:54272
	ds_read_b128 v[216:219], v147 offset:55296
	ds_read_b128 v[220:223], v147 offset:56320
	global_load_lds_dwordx4 v[192:193], off
	v_lshl_add_u64 v[192:193], v[196:197], 0, s[80:81]
	s_add_i32 m0, s24, 0x2000
	s_add_i32 s24, s59, s30
	global_load_lds_dwordx4 v[192:193], off
	v_lshl_add_u64 v[192:193], v[198:199], 0, s[80:81]
	s_mov_b32 m0, s24
	s_nop 0
	global_load_lds_dwordx4 v[192:193], off
	v_lshl_add_u64 v[192:193], v[200:201], 0, s[80:81]
	s_add_i32 m0, s24, 0x2000
	s_nop 0
	global_load_lds_dwordx4 v[192:193], off
	v_lshl_add_u64 v[192:193], v[202:203], 0, s[80:81]
	s_mov_b32 m0, s39
	s_nop 0
	global_load_lds_dwordx4 v[192:193], off
	v_lshl_add_u64 v[192:193], v[228:229], 0, s[80:81]
	s_mov_b32 m0, s40
	s_nop 0
	global_load_lds_dwordx4 v[192:193], off
	s_waitcnt vmcnt(8)
	s_waitcnt lgkmcnt(0)
	s_barrier
	s_setprio 1
	s_waitcnt lgkmcnt(0)
	v_mfma_f32_16x16x32_bf16 v[64:67], v[148:151], v[180:183], v[64:67]
	v_mfma_f32_16x16x32_bf16 v[60:63], v[156:159], v[180:183], v[60:63]
	v_mfma_f32_16x16x32_bf16 v[48:51], v[148:151], v[188:191], v[48:51]
	v_mfma_f32_16x16x32_bf16 v[44:47], v[156:159], v[188:191], v[44:47]
	v_mfma_f32_16x16x32_bf16 v[32:35], v[148:151], v[208:211], v[32:35]
	v_mfma_f32_16x16x32_bf16 v[28:31], v[156:159], v[208:211], v[28:31]
	v_mfma_f32_16x16x32_bf16 v[16:19], v[148:151], v[216:219], v[16:19]
	v_mfma_f32_16x16x32_bf16 v[12:15], v[156:159], v[216:219], v[12:15]
	v_mfma_f32_16x16x32_bf16 v[64:67], v[152:155], v[184:187], v[64:67]
	v_mfma_f32_16x16x32_bf16 v[60:63], v[160:163], v[184:187], v[60:63]
	v_mfma_f32_16x16x32_bf16 v[48:51], v[152:155], v[204:207], v[48:51]
	v_mfma_f32_16x16x32_bf16 v[44:47], v[160:163], v[204:207], v[44:47]
	v_mfma_f32_16x16x32_bf16 v[32:35], v[152:155], v[212:215], v[32:35]
	v_mfma_f32_16x16x32_bf16 v[28:31], v[160:163], v[212:215], v[28:31]
	v_mfma_f32_16x16x32_bf16 v[16:19], v[152:155], v[220:223], v[16:19]
	v_mfma_f32_16x16x32_bf16 v[12:15], v[160:163], v[220:223], v[12:15]
	v_mfma_f32_16x16x32_bf16 v[56:59], v[164:167], v[180:183], v[56:59]
	v_mfma_f32_16x16x32_bf16 v[52:55], v[172:175], v[180:183], v[52:55]
	v_mfma_f32_16x16x32_bf16 v[40:43], v[164:167], v[188:191], v[40:43]
	v_mfma_f32_16x16x32_bf16 v[36:39], v[172:175], v[188:191], v[36:39]
	v_mfma_f32_16x16x32_bf16 v[24:27], v[164:167], v[208:211], v[24:27]
	v_mfma_f32_16x16x32_bf16 v[20:23], v[172:175], v[208:211], v[20:23]
	v_mfma_f32_16x16x32_bf16 v[8:11], v[164:167], v[216:219], v[8:11]
	v_mfma_f32_16x16x32_bf16 v[4:7], v[172:175], v[216:219], v[4:7]
	v_mfma_f32_16x16x32_bf16 v[56:59], v[168:171], v[184:187], v[56:59]
	v_mfma_f32_16x16x32_bf16 v[52:55], v[176:179], v[184:187], v[52:55]
	v_mfma_f32_16x16x32_bf16 v[40:43], v[168:171], v[204:207], v[40:43]
	v_mfma_f32_16x16x32_bf16 v[36:39], v[176:179], v[204:207], v[36:39]
	v_mfma_f32_16x16x32_bf16 v[24:27], v[168:171], v[212:215], v[24:27]
	v_mfma_f32_16x16x32_bf16 v[20:23], v[176:179], v[212:215], v[20:23]
	v_mfma_f32_16x16x32_bf16 v[8:11], v[168:171], v[220:223], v[8:11]
	v_mfma_f32_16x16x32_bf16 v[4:7], v[176:179], v[220:223], v[4:7]
	s_setprio 0
	s_barrier
	s_add_i32 s24, s55, 2
	s_add_u32 s53, s53, 0x100
	s_addc_u32 s54, s54, 0
	s_add_u32 s22, s22, 0x100
	s_addc_u32 s23, s23, 0
	s_cmp_ge_i32 s55, s46
	s_mov_b32 s55, s24
	s_cbranch_scc0 .LBB0_1362
